# GLA stage 3 body: loads hoisted/counted waits + rcp; GLA stage 1 Wa loads batched; compression stage-2 loop software-pipelined; top-k popcount compare scalarised; remaining 1/x divisions -> v_rcp_f32
# speedup vs baseline: 1.0324x; 1.0324x over previous
; DI unsigned cvtpk(float lo, float hi) { f32x2 v = {lo, hi}; bf16x2_t b = __builtin_convertvector(v, bf16x2_t); return __builtin_bit_cast(unsigned, b); }
; DI void rms_row_bf16(const float* xrow, const float* g, bf16* orow, int lane) {
;     f32x4 v[4]; float s = 0.f;
; #pragma unroll
;     for (int j = 0; j < 4; ++j) { v[j] = ((const f32x4*)xrow)[lane + 64 * j]; s += (v[j].x * v[j].x + v[j].y * v[j].y) + (v[j].z * v[j].z + v[j].w * v[j].w); }
;     const float r = 1.f / sqrtf(wave_sum(s) * (1.f / 1024.f) + EPS);
; #pragma unroll
;     for (int j = 0; j < 4; ++j) { const f32x4 gg = ((const f32x4*)g)[lane + 64 * j]; u32x2 o; o.x = cvtpk(v[j].x * r * gg.x, v[j].y * r * gg.y); o.y = cvtpk(v[j].z * r * gg.z, v[j].w * r * gg.w);
;         ((u32x2*)orow)[lane + 64 * j] = o; }
; }
.LBB0_218:
	global_load_dwordx4 v[16:19], v[6:7], off offset:-3072
	global_load_dwordx4 v[20:23], v[6:7], off offset:-2048
	global_load_dwordx4 v[24:27], v[6:7], off offset:-1024
	global_load_dwordx4 v[28:31], v[6:7], off
	global_load_dwordx4 v[32:35], v[2:3], off
	s_add_i32 s7, s7, s74
	v_lshl_add_u64 v[6:7], v[6:7], 0, s[2:3]
	s_cmp_lt_i32 s7, 0x8000
	s_waitcnt vmcnt(0)
	v_pk_mul_f32 v[36:37], v[18:19], v[18:19]
	v_pk_mul_f32 v[38:39], v[16:17], v[16:17]
	v_pk_mul_f32 v[40:41], v[22:23], v[22:23]
	v_pk_mul_f32 v[42:43], v[20:21], v[20:21]
	v_pk_mov_b32 v[48:49], v[38:39], v[36:37] op_sel:[1,0]
	v_mov_b32_e32 v39, v37
	v_pk_mov_b32 v[36:37], v[42:43], v[40:41] op_sel:[1,0]
	v_mov_b32_e32 v43, v41
	v_mul_f32_e32 v47, v29, v29
	v_mul_f32_e32 v44, v25, v25
	v_mul_f32_e32 v46, v27, v27
	v_pk_add_f32 v[38:39], v[48:49], v[38:39]
	v_pk_add_f32 v[36:37], v[36:37], v[42:43]
	v_mul_f32_e32 v15, v28, v28
	v_mul_f32_e32 v50, v30, v30
	v_mul_f32_e32 v51, v31, v31
	v_pk_fma_f32 v[40:41], v[24:25], v[24:25], v[44:45] op_sel_hi:[1,1,0]
	v_pk_fma_f32 v[44:45], v[26:27], v[26:27], v[46:47] op_sel_hi:[1,1,0]
	v_pk_add_f32 v[38:39], v[38:39], v[38:39] op_sel:[0,1] op_sel_hi:[1,0]
	v_pk_add_f32 v[36:37], v[36:37], v[36:37] op_sel:[0,1] op_sel_hi:[1,0]
	v_mov_b32_e32 v41, v50
	v_mov_b32_e32 v45, v51
	v_mov_b32_e32 v39, v15
	v_mov_b32_e32 v37, v47
	v_pk_add_f32 v[40:41], v[40:41], v[44:45]
	v_pk_add_f32 v[36:37], v[38:39], v[36:37]
	s_nop 0
	v_pk_add_f32 v[36:37], v[36:37], v[40:41]
	s_nop 0
	v_add_f32_e32 v15, v36, v37
	ds_bpermute_b32 v36, v1, v15
	s_waitcnt lgkmcnt(0)
	v_add_f32_e32 v15, v15, v36
	ds_bpermute_b32 v36, v8, v15
	s_waitcnt lgkmcnt(0)
	v_add_f32_e32 v15, v15, v36
	ds_bpermute_b32 v36, v9, v15
	s_waitcnt lgkmcnt(0)
	v_add_f32_e32 v15, v15, v36
	ds_bpermute_b32 v36, v10, v15
	s_waitcnt lgkmcnt(0)
	v_add_f32_e32 v15, v15, v36
	ds_bpermute_b32 v36, v11, v15
	s_waitcnt lgkmcnt(0)
	v_add_f32_e32 v15, v15, v36
	ds_bpermute_b32 v36, v12, v15
	s_waitcnt lgkmcnt(0)
	v_add_f32_e32 v15, v15, v36
	v_fmamk_f32 v15, v15, 0x3a800000, v13
	v_mul_f32_e32 v36, 0x4f800000, v15
	v_cmp_gt_f32_e32 vcc, s6, v15
	s_nop 1
	v_cndmask_b32_e32 v15, v15, v36, vcc
	v_sqrt_f32_e32 v36, v15
	s_nop 0
	v_add_u32_e32 v37, -1, v36
	v_add_u32_e32 v38, 1, v36
	v_fma_f32 v39, -v37, v36, v15
	v_fma_f32 v40, -v38, v36, v15
	v_cmp_ge_f32_e64 s[4:5], 0, v39
	s_nop 1
	v_cndmask_b32_e64 v36, v36, v37, s[4:5]
	v_cmp_lt_f32_e64 s[4:5], 0, v40
	s_nop 1
	v_cndmask_b32_e64 v36, v36, v38, s[4:5]
	v_mul_f32_e32 v37, 0x37800000, v36
	v_cndmask_b32_e32 v36, v36, v37, vcc
	v_cmp_class_f32_e32 vcc, v15, v14
	s_nop 1
	v_cndmask_b32_e32 v15, v36, v15, vcc
	v_div_scale_f32 v36, s[4:5], v15, v15, 1.0
	v_div_scale_f32 v37, vcc, 1.0, v15, 1.0
	v_rcp_f32_e32 v36, v15
	s_nop 0
	v_pk_mul_f32 v[16:17], v[16:17], v[36:37] op_sel_hi:[1,0]
	v_pk_mul_f32 v[18:19], v[18:19], v[36:37] op_sel_hi:[1,0]
	v_pk_mul_f32 v[16:17], v[32:33], v[16:17]
	v_pk_mul_f32 v[18:19], v[34:35], v[18:19]
	v_cvt_pk_bf16_f32 v16, v16, v17
	v_cvt_pk_bf16_f32 v17, v18, v19
	global_store_dwordx2 v[4:5], v[16:17], off
	global_load_dwordx4 v[16:19], v[2:3], off offset:1024
	v_pk_mul_f32 v[20:21], v[20:21], v[36:37] op_sel_hi:[1,0]
	v_pk_mul_f32 v[22:23], v[22:23], v[36:37] op_sel_hi:[1,0]
	s_waitcnt vmcnt(0)
	v_pk_mul_f32 v[16:17], v[16:17], v[20:21]
	v_pk_mul_f32 v[18:19], v[18:19], v[22:23]
	v_cvt_pk_bf16_f32 v16, v16, v17
	v_cvt_pk_bf16_f32 v17, v18, v19
	global_store_dwordx2 v[4:5], v[16:17], off offset:512
	global_load_dwordx4 v[16:19], v[2:3], off offset:2048
	v_pk_mul_f32 v[20:21], v[24:25], v[36:37] op_sel_hi:[1,0]
	v_pk_mul_f32 v[22:23], v[26:27], v[36:37] op_sel_hi:[1,0]
	s_waitcnt vmcnt(0)
	v_pk_mul_f32 v[16:17], v[16:17], v[20:21]
	v_pk_mul_f32 v[18:19], v[18:19], v[22:23]
	v_cvt_pk_bf16_f32 v16, v16, v17
	v_cvt_pk_bf16_f32 v17, v18, v19
	global_store_dwordx2 v[4:5], v[16:17], off offset:1024
	global_load_dwordx4 v[16:19], v[2:3], off offset:3072
	v_pk_mul_f32 v[20:21], v[28:29], v[36:37] op_sel_hi:[1,0]
	v_pk_mul_f32 v[22:23], v[30:31], v[36:37] op_sel_hi:[1,0]
	s_waitcnt vmcnt(0)
	v_pk_mul_f32 v[16:17], v[16:17], v[20:21]
	v_pk_mul_f32 v[18:19], v[18:19], v[22:23]
	v_cvt_pk_bf16_f32 v16, v16, v17
	v_cvt_pk_bf16_f32 v17, v18, v19
	global_store_dwordx2 v[4:5], v[16:17], off offset:1536
	v_lshl_add_u64 v[4:5], v[4:5], 0, s[0:1]
	s_cbranch_scc1 .LBB0_218

; #define LAS __attribute__((address_space(3)))
; DI float bflo(unsigned w) { return __uint_as_float(w << 16); }
; DI float bfhi(unsigned w) { return __uint_as_float(w & 0xffff0000u); }
; DI void gla_stage1(const Ctx& c0, int layer, int unit, LAS unsigned char* lds) {
;     ...
;     const int cc = tid >> 3, ch = tid & 7;
; #pragma unroll
;     for (int it = 0; it < 2; ++it) { const int idx = tid + 512 * it, vc_ = idx & 15, c_ = idx >> 4;
;         const u32x4 v = *(const u32x4*)(gv + (row0 + c_) * 512 + h * 128 + vc_ * 8);
;         *(LAS u32x4*)(lds + G1_VI + (vc_ >> 2) * 4096 + c_ * 64 + (vc_ & 3) * 16) = v; }
;     {
;         float ga[16];
;         { const u32x4 g0 = *(const u32x4*)(misc + (row0 + cc) * 64 + 32), g1 = *(const u32x4*)(misc + (row0 + cc) * 64 + 40);
;           ga[0] = bflo(g0.x); ga[1] = bfhi(g0.x); ga[2] = bflo(g0.y); ga[3] = bfhi(g0.y); ga[4] = bflo(g0.z); ga[5] = bfhi(g0.z); ga[6] = bflo(g0.w); ga[7] = bfhi(g0.w);
;           ga[8] = bflo(g1.x); ga[9] = bfhi(g1.x); ga[10] = bflo(g1.y); ga[11] = bfhi(g1.y); ga[12] = bflo(g1.z); ga[13] = bfhi(g1.z); ga[14] = bflo(g1.w); ga[15] = bfhi(g1.w); }
;         f32x4 a0 = *(const f32x4*)(ba + 8 * ch), a1 = *(const f32x4*)(ba + 8 * ch + 4);
;         const float* wap = Wa + 8 * ch; asm volatile("" : "+v"(wap));
; #pragma unroll
;         for (int rr = 0; rr < 16; ++rr) { const f32x4 w0 = *(const f32x4*)(wap + rr * 256), w1 = *(const f32x4*)(wap + rr * 256 + 4); a0 += w0 * ga[rr]; a1 += w1 * ga[rr]; }
.LBB0_400:
	s_mov_b64 s[98:99], 0x1000
	v_mov_b32_e32 v10, v151
	s_mov_b64 s[72:73], s[84:85]
	s_mov_b64 s[82:83], s[86:87]
	s_ashr_i32 s72, s80, 8
	s_ashr_i32 s73, s72, 31
	s_lshl_b32 s0, s80, 6
	s_bfe_u32 s89, s80, 0x20006
	s_lshl_b64 s[84:85], s[72:73], 12
	s_and_b32 s0, s0, 0xfc0
	s_or_b32 s84, s84, s0
	s_lshl_b32 s0, s89, 8
	v_and_b32_e32 v2, 15, v10
	s_add_u32 s72, s82, s0
	s_addc_u32 s73, s83, 0
	v_lshlrev_b32_e32 v48, 4, v2
	v_lshl_add_u64 v[2:3], s[72:73], 0, v[48:49]
	s_mov_b64 s[72:73], 0xf500000
	v_lshl_add_u64 v[6:7], v[2:3], 0, s[72:73]
	v_lshlrev_b32_e32 v2, 10, v10
	v_lshlrev_b32_e32 v3, 4, v10
	v_ashrrev_i32_e32 v8, 4, v10
	v_and_b32_e32 v2, 0x3000, v2
	v_and_b32_e32 v11, 48, v3
	v_ashrrev_i32_e32 v9, 31, v8
	v_add3_u32 v13, 0, v2, v11
	v_lshl_add_u64 v[2:3], s[84:85], 0, v[8:9]
	v_lshlrev_b64 v[2:3], 10, v[2:3]
	v_lshl_add_u64 v[2:3], v[6:7], 0, v[2:3]
	global_load_dwordx4 v[2:5], v[2:3], off
	v_add_u32_e32 v80, 0x200, v10
	v_ashrrev_i32_e32 v78, 4, v80
	v_ashrrev_i32_e32 v79, 31, v78
	v_lshl_add_u64 v[68:69], s[84:85], 0, v[78:79]
	v_lshlrev_b64 v[76:77], 10, v[68:69]
	v_lshl_add_u64 v[74:75], v[6:7], 0, v[76:77]
	global_load_dwordx4 v[70:73], v[74:75], off
	v_lshl_add_u32 v8, v8, 6, v13
	v_ashrrev_i32_e32 v12, 3, v10
	s_mov_b64 vcc, 0x1b500000
	s_waitcnt lgkmcnt(0)
	s_add_u32 s72, s76, s0
	s_addc_u32 s73, s77, 0
	v_and_b32_e32 v32, 7, v10
	v_lshlrev_b32_e32 v48, 5, v32
	v_lshl_add_u64 v[24:25], s[72:73], 0, v[48:49]
	global_load_dwordx4 v[54:57], v[24:25], off offset:16
	global_load_dwordx4 v[42:45], v[24:25], off
	s_add_u32 s86, s78, s0
	s_addc_u32 s87, s79, 0
	global_load_dwordx4 v[38:41], v48, s[86:87]
	global_load_dwordx4 v[74:77], v48, s[86:87] offset:16
	v_lshl_add_u64 v[244:245], v[24:25], 0, s[98:99]
	v_lshl_add_u64 v[246:247], v[244:245], 0, s[98:99]
	v_lshl_add_u64 v[248:249], v[246:247], 0, s[98:99]
	s_movk_i32 s0, 0x104
	v_lshl_add_u32 v33, v10, 2, 0
	s_waitcnt vmcnt(5)
	global_load_dwordx4 v[196:199], v[248:249], off offset:3072
	global_load_dwordx4 v[180:183], v[248:249], off offset:2064
	global_load_dwordx4 v[176:179], v[248:249], off offset:2048
	global_load_dwordx4 v[172:175], v[248:249], off offset:1040
	global_load_dwordx4 v[168:171], v[248:249], off offset:1024
	global_load_dwordx4 v[118:121], v[244:245], off offset:3088
	global_load_dwordx4 v[114:117], v[244:245], off offset:3072
	global_load_dwordx4 v[110:113], v[244:245], off offset:2064
	global_load_dwordx4 v[106:109], v[244:245], off offset:2048
	global_load_dwordx4 v[96:99], v[244:245], off offset:1040
	global_load_dwordx4 v[90:93], v[244:245], off offset:1024
	ds_write_b128 v8, v[2:5] offset:43264
	v_lshl_add_u32 v6, v78, 6, v13
	v_ashrrev_i32_e32 v13, 31, v12
	s_waitcnt vmcnt(15) lgkmcnt(0)
	global_load_dwordx4 v[142:145], v[246:247], off offset:2064
	global_load_dwordx4 v[138:141], v[246:247], off offset:2048
	global_load_dwordx4 v[134:137], v[246:247], off offset:1040
	global_load_dwordx4 v[130:133], v[246:247], off offset:1024
	global_load_dwordx4 v[126:129], v[246:247], off offset:16
	global_load_dwordx4 v[122:125], v[246:247], off
	ds_write_b128 v6, v[70:73] offset:43264
	v_lshl_add_u64 v[2:3], s[84:85], 0, v[12:13]
	v_lshlrev_b64 v[4:5], 7, v[2:3]
	v_lshl_add_u64 v[4:5], s[82:83], 0, v[4:5]
	v_lshl_add_u64 v[8:9], v[4:5], 0, vcc
	global_load_dwordx4 v[4:7], v[8:9], off offset:64
	global_load_dwordx4 v[34:37], v[8:9], off offset:80
	v_mul_lo_u32 v13, v12, s0
	v_add3_u32 v13, 0, v13, v48
	s_movk_i32 s0, 0x820
	s_waitcnt vmcnt(0) lgkmcnt(0)
	global_load_dwordx4 v[164:167], v[248:249], off offset:16
	global_load_dwordx4 v[160:163], v[248:249], off
	global_load_dwordx4 v[156:159], v[246:247], off offset:3088
	global_load_dwordx4 v[146:149], v[246:247], off offset:3072
	global_load_dwordx4 v[78:81], v[24:25], off offset:1040
	global_load_dwordx4 v[68:71], v[24:25], off offset:1024
	v_lshlrev_b32_e32 v58, 16, v4
	v_and_b32_e32 v60, 0xffff0000, v4
	v_lshlrev_b32_e32 v66, 16, v6
	v_and_b32_e32 v30, 0xffff0000, v6
	v_lshlrev_b32_e32 v22, 16, v34
	v_and_b32_e32 v20, 0xffff0000, v34
	v_lshlrev_b32_e32 v18, 16, v35
	v_and_b32_e32 v16, 0xffff0000, v35
	v_lshlrev_b32_e32 v14, 16, v36
	v_and_b32_e32 v8, 0xffff0000, v36
	v_lshlrev_b32_e32 v4, 16, v37
	v_and_b32_e32 v6, 0xffff0000, v37
	v_lshlrev_b32_e32 v62, 16, v5
	v_and_b32_e32 v64, 0xffff0000, v5
	v_lshlrev_b32_e32 v28, 16, v7
	v_and_b32_e32 v26, 0xffff0000, v7
	s_waitcnt vmcnt(6) lgkmcnt(0)
	global_load_dwordx4 v[82:85], v[24:25], off offset:2064
	global_load_dwordx4 v[34:37], v[24:25], off offset:2048
	v_pk_fma_f32 v[42:43], v[58:59], v[42:43], v[38:39] op_sel_hi:[0,1,1]
	v_pk_fma_f32 v[44:45], v[58:59], v[44:45], v[40:41] op_sel_hi:[0,1,1]
	v_pk_fma_f32 v[54:55], v[58:59], v[54:55], v[74:75] op_sel_hi:[0,1,1]
	v_pk_fma_f32 v[56:57], v[58:59], v[56:57], v[76:77] op_sel_hi:[0,1,1]
	v_lshl_add_u64 v[58:59], v[24:25], 0, s[98:99]
	s_waitcnt vmcnt(2) lgkmcnt(0)
	global_load_dwordx4 v[38:41], v[24:25], off offset:3088
	global_load_dwordx4 v[72:75], v[24:25], off offset:3072
	v_pk_fma_f32 v[44:45], v[60:61], v[70:71], v[44:45] op_sel_hi:[0,1,1]
	v_pk_fma_f32 v[42:43], v[60:61], v[68:69], v[42:43] op_sel_hi:[0,1,1]
	v_pk_fma_f32 v[56:57], v[60:61], v[80:81], v[56:57] op_sel_hi:[0,1,1]
	v_pk_fma_f32 v[54:55], v[60:61], v[78:79], v[54:55] op_sel_hi:[0,1,1]
	s_waitcnt vmcnt(2) lgkmcnt(0)
	global_load_dwordx4 v[76:79], v[244:245], off offset:16
	global_load_dwordx4 v[68:71], v[244:245], off
	v_pk_fma_f32 v[42:43], v[62:63], v[34:35], v[42:43] op_sel_hi:[0,1,1]
	v_pk_fma_f32 v[44:45], v[62:63], v[36:37], v[44:45] op_sel_hi:[0,1,1]
	v_pk_fma_f32 v[54:55], v[62:63], v[82:83], v[54:55] op_sel_hi:[0,1,1]
	v_pk_fma_f32 v[56:57], v[62:63], v[84:85], v[56:57] op_sel_hi:[0,1,1]
	s_waitcnt vmcnt(2) lgkmcnt(0)
; DI void gla_stage1(const Ctx& c0, int layer, int unit, LAS unsigned char* lds) {
;     ...
;         for (int rr = 0; rr < 16; ++rr) { const f32x4 w0 = *(const f32x4*)(wap + rr * 256), w1 = *(const f32x4*)(wap + rr * 256 + 4); a0 += w0 * ga[rr]; a1 += w1 * ga[rr]; }
	v_pk_fma_f32 v[44:45], v[64:65], v[74:75], v[44:45] op_sel_hi:[0,1,1]
	v_pk_fma_f32 v[42:43], v[64:65], v[72:73], v[42:43] op_sel_hi:[0,1,1]
	v_pk_fma_f32 v[56:57], v[64:65], v[40:41], v[56:57] op_sel_hi:[0,1,1]
	v_pk_fma_f32 v[54:55], v[64:65], v[38:39], v[54:55] op_sel_hi:[0,1,1]
	s_waitcnt vmcnt(0) lgkmcnt(0)
	v_pk_fma_f32 v[42:43], v[66:67], v[68:69], v[42:43] op_sel_hi:[0,1,1]
	v_pk_fma_f32 v[44:45], v[66:67], v[70:71], v[44:45] op_sel_hi:[0,1,1]
	v_pk_fma_f32 v[54:55], v[66:67], v[76:77], v[54:55] op_sel_hi:[0,1,1]
	v_pk_fma_f32 v[56:57], v[66:67], v[78:79], v[56:57] op_sel_hi:[0,1,1]
	s_waitcnt vmcnt(20) lgkmcnt(0)
	v_pk_fma_f32 v[44:45], v[30:31], v[92:93], v[44:45] op_sel_hi:[0,1,1]
	v_pk_fma_f32 v[42:43], v[30:31], v[90:91], v[42:43] op_sel_hi:[0,1,1]
	v_pk_fma_f32 v[56:57], v[30:31], v[98:99], v[56:57] op_sel_hi:[0,1,1]
	v_pk_fma_f32 v[30:31], v[30:31], v[96:97], v[54:55] op_sel_hi:[0,1,1]
	s_waitcnt vmcnt(3) lgkmcnt(0)
	v_pk_fma_f32 v[42:43], v[28:29], v[106:107], v[42:43] op_sel_hi:[0,1,1]
	v_pk_fma_f32 v[44:45], v[28:29], v[108:109], v[44:45] op_sel_hi:[0,1,1]
	v_pk_fma_f32 v[38:39], v[28:29], v[110:111], v[30:31] op_sel_hi:[0,1,1]
	v_pk_fma_f32 v[40:41], v[28:29], v[112:113], v[56:57] op_sel_hi:[0,1,1]
	s_waitcnt vmcnt(3) lgkmcnt(0)
	v_pk_fma_f32 v[30:31], v[26:27], v[116:117], v[44:45] op_sel_hi:[0,1,1]
	v_lshl_add_u64 v[44:45], v[58:59], 0, s[98:99]
	v_pk_fma_f32 v[42:43], v[26:27], v[114:115], v[42:43] op_sel_hi:[0,1,1]
	s_nop 0
	v_pk_fma_f32 v[40:41], v[26:27], v[120:121], v[40:41] op_sel_hi:[0,1,1]
	v_pk_fma_f32 v[38:39], v[26:27], v[118:119], v[38:39] op_sel_hi:[0,1,1]
	v_lshl_add_u64 v[24:25], v[44:45], 0, s[98:99]
	s_waitcnt vmcnt(3) lgkmcnt(0)
	v_pk_fma_f32 v[42:43], v[22:23], v[122:123], v[42:43] op_sel_hi:[0,1,1]
	v_pk_fma_f32 v[30:31], v[22:23], v[124:125], v[30:31] op_sel_hi:[0,1,1]
	v_pk_fma_f32 v[38:39], v[22:23], v[126:127], v[38:39] op_sel_hi:[0,1,1]
	v_pk_fma_f32 v[22:23], v[22:23], v[128:129], v[40:41] op_sel_hi:[0,1,1]
	s_waitcnt vmcnt(3) lgkmcnt(0)
	v_pk_fma_f32 v[30:31], v[20:21], v[132:133], v[30:31] op_sel_hi:[0,1,1]
	v_pk_fma_f32 v[40:41], v[20:21], v[130:131], v[42:43] op_sel_hi:[0,1,1]
	v_pk_fma_f32 v[36:37], v[20:21], v[136:137], v[22:23] op_sel_hi:[0,1,1]
	v_pk_fma_f32 v[34:35], v[20:21], v[134:135], v[38:39] op_sel_hi:[0,1,1]
	s_waitcnt vmcnt(3) lgkmcnt(0)
	v_pk_fma_f32 v[38:39], v[18:19], v[138:139], v[40:41] op_sel_hi:[0,1,1]
	v_pk_fma_f32 v[22:23], v[18:19], v[140:141], v[30:31] op_sel_hi:[0,1,1]
	v_pk_fma_f32 v[30:31], v[18:19], v[142:143], v[34:35] op_sel_hi:[0,1,1]
	v_pk_fma_f32 v[34:35], v[18:19], v[144:145], v[36:37] op_sel_hi:[0,1,1]
	s_waitcnt vmcnt(3) lgkmcnt(0)
	v_pk_fma_f32 v[36:37], v[16:17], v[148:149], v[22:23] op_sel_hi:[0,1,1]
	v_pk_fma_f32 v[38:39], v[16:17], v[146:147], v[38:39] op_sel_hi:[0,1,1]
	v_pk_fma_f32 v[28:29], v[16:17], v[158:159], v[34:35] op_sel_hi:[0,1,1]
	v_pk_fma_f32 v[26:27], v[16:17], v[156:157], v[30:31] op_sel_hi:[0,1,1]
	s_waitcnt vmcnt(3) lgkmcnt(0)
	v_pk_fma_f32 v[30:31], v[14:15], v[160:161], v[38:39] op_sel_hi:[0,1,1]
	v_pk_fma_f32 v[34:35], v[14:15], v[162:163], v[36:37] op_sel_hi:[0,1,1]
	v_pk_fma_f32 v[26:27], v[14:15], v[164:165], v[26:27] op_sel_hi:[0,1,1]
	v_pk_fma_f32 v[22:23], v[14:15], v[166:167], v[28:29] op_sel_hi:[0,1,1]
	s_waitcnt vmcnt(4) lgkmcnt(0)
	v_pk_fma_f32 v[28:29], v[8:9], v[170:171], v[34:35] op_sel_hi:[0,1,1]
	v_pk_fma_f32 v[30:31], v[8:9], v[168:169], v[30:31] op_sel_hi:[0,1,1]
	v_pk_fma_f32 v[22:23], v[8:9], v[174:175], v[22:23] op_sel_hi:[0,1,1]
	v_pk_fma_f32 v[8:9], v[8:9], v[172:173], v[26:27] op_sel_hi:[0,1,1]
	s_waitcnt vmcnt(13) lgkmcnt(0)
	v_pk_fma_f32 v[26:27], v[4:5], v[176:177], v[30:31] op_sel_hi:[0,1,1]
	v_pk_fma_f32 v[28:29], v[4:5], v[178:179], v[28:29] op_sel_hi:[0,1,1]
	v_pk_fma_f32 v[30:31], v[4:5], v[180:181], v[8:9] op_sel_hi:[0,1,1]
	v_pk_fma_f32 v[4:5], v[4:5], v[182:183], v[22:23] op_sel_hi:[0,1,1]
	global_load_dwordx4 v[18:21], v[248:249], off offset:3088
	s_waitcnt vmcnt(0) lgkmcnt(0)
; DI void gla_stage1(const Ctx& c0, int layer, int unit, LAS unsigned char* lds) {
;     ...
;         for (int rr = 0; rr < 16; ++rr) { const f32x4 w0 = *(const f32x4*)(wap + rr * 256), w1 = *(const f32x4*)(wap + rr * 256 + 4); a0 += w0 * ga[rr]; a1 += w1 * ga[rr]; }
; #pragma unroll
;         for (int j = 0; j < 8; ++j) { const float x = j < 4 ? a0[j & 3] : a1[j & 3];
;             const float ls = fminf(x, 0.f) - __logf(1.f + __expf(-fabsf(x)));
;             LA[cc * 65 + 8 * ch + j] = ls * (1.f / 16.f); }
;     }
;     __syncthreads();
;     {
;         const int d = tid & 63, part = tid >> 6; float v[8]; float run = 0.f;
; #pragma unroll
;         for (int j = 0; j < 8; ++j) { run += LA[(8 * part + j) * 65 + d]; v[j] = run; }
;         PART[part * 64 + d] = run;
;         __syncthreads();
;         float off = 0.f;
; #pragma unroll
;         for (int p = 0; p < 8; ++p) off += (p < part) ? PART[p * 64 + d] : 0.f;
	v_pk_fma_f32 v[14:15], v[6:7], v[196:197], v[26:27] op_sel_hi:[0,1,1]
	v_pk_fma_f32 v[8:9], v[6:7], v[198:199], v[28:29] op_sel_hi:[0,1,1]
	v_min_f32_e32 v16, 0, v14
	v_mul_f32_e64 v14, |v14|, s93
	v_exp_f32_e32 v14, v14
	v_pk_fma_f32 v[4:5], v[6:7], v[20:21], v[4:5] op_sel_hi:[0,1,1]
	v_pk_fma_f32 v[6:7], v[6:7], v[18:19], v[30:31] op_sel_hi:[0,1,1]
	v_mov_b32_e32 v20, 0
	v_add_f32_e32 v14, 1.0, v14
	v_cmp_gt_f32_e32 vcc, s94, v14
	v_mov_b32_e32 v21, 0
	s_nop 0
	v_cndmask_b32_e64 v17, 0, 32, vcc
	v_ldexp_f32 v14, v14, v17
	v_log_f32_e32 v14, v14
	s_nop 0
	v_mul_f32_e32 v17, 0x3f317217, v14
	v_fma_f32 v17, v14, s95, -v17
	v_fmac_f32_e32 v17, 0x3377d1cf, v14
	v_fmac_f32_e32 v17, 0x3f317217, v14
	v_cmp_lt_f32_e64 s[72:73], |v14|, s96
	s_nop 1
	v_cndmask_b32_e64 v14, v14, v17, s[72:73]
	v_cndmask_b32_e32 v17, 0, v47, vcc
	v_sub_f32_e32 v14, v14, v17
	v_min_f32_e32 v17, 0, v15
	v_mul_f32_e64 v15, |v15|, s93
	v_exp_f32_e32 v15, v15
	s_nop 0
	v_add_f32_e32 v15, 1.0, v15
	v_cmp_gt_f32_e32 vcc, s94, v15
	s_nop 1
	v_cndmask_b32_e64 v18, 0, 32, vcc
	v_ldexp_f32 v15, v15, v18
	v_log_f32_e32 v15, v15
	s_nop 0
	v_mul_f32_e32 v18, 0x3f317217, v15
	v_fma_f32 v18, v15, s95, -v18
	v_fmac_f32_e32 v18, 0x3377d1cf, v15
	v_fmac_f32_e32 v18, 0x3f317217, v15
	v_cmp_lt_f32_e64 s[72:73], |v15|, s96
	s_nop 1
	v_cndmask_b32_e64 v15, v15, v18, s[72:73]
	v_cndmask_b32_e32 v18, 0, v47, vcc
	v_sub_f32_e32 v15, v15, v18
	v_pk_add_f32 v[14:15], v[16:17], v[14:15] neg_lo:[0,1] neg_hi:[0,1]
	v_ashrrev_i32_e32 v17, 6, v10
	v_pk_mul_f32 v[14:15], v[14:15], s[8:9] op_sel_hi:[1,0]
	ds_write2_b32 v13, v14, v15 offset1:1
	v_min_f32_e32 v14, 0, v8
	v_mul_f32_e64 v8, |v8|, s93
	v_exp_f32_e32 v8, v8
	s_nop 0
	v_add_f32_e32 v8, 1.0, v8
	v_cmp_gt_f32_e32 vcc, s94, v8
	s_nop 1
	v_cndmask_b32_e64 v15, 0, 32, vcc
	v_ldexp_f32 v8, v8, v15
	v_log_f32_e32 v8, v8
	s_nop 0
	v_mul_f32_e32 v15, 0x3f317217, v8
	v_fma_f32 v15, v8, s95, -v15
	v_fmac_f32_e32 v15, 0x3377d1cf, v8
	v_fmac_f32_e32 v15, 0x3f317217, v8
	v_cmp_lt_f32_e64 s[72:73], |v8|, s96
	s_nop 1
	v_cndmask_b32_e64 v8, v8, v15, s[72:73]
	v_cndmask_b32_e32 v15, 0, v47, vcc
	v_sub_f32_e32 v8, v8, v15
	v_min_f32_e32 v15, 0, v9
	v_mul_f32_e64 v9, |v9|, s93
	v_exp_f32_e32 v9, v9
	s_nop 0
	v_add_f32_e32 v9, 1.0, v9
	v_cmp_gt_f32_e32 vcc, s94, v9
	s_nop 1
	v_cndmask_b32_e64 v16, 0, 32, vcc
	v_ldexp_f32 v9, v9, v16
	v_log_f32_e32 v9, v9
	s_nop 0
	v_mul_f32_e32 v16, 0x3f317217, v9
	v_fma_f32 v16, v9, s95, -v16
	v_fmac_f32_e32 v16, 0x3377d1cf, v9
	v_fmac_f32_e32 v16, 0x3f317217, v9
	v_cmp_lt_f32_e64 s[72:73], |v9|, s96
	s_nop 1
	v_cndmask_b32_e64 v9, v9, v16, s[72:73]
	v_cndmask_b32_e32 v16, 0, v47, vcc
	v_sub_f32_e32 v9, v9, v16
	v_pk_add_f32 v[8:9], v[14:15], v[8:9] neg_lo:[0,1] neg_hi:[0,1]
	s_nop 0
	v_pk_mul_f32 v[8:9], v[8:9], s[8:9] op_sel_hi:[1,0]
	ds_write2_b32 v13, v8, v9 offset0:2 offset1:3
	v_min_f32_e32 v8, 0, v6
	v_mul_f32_e64 v6, |v6|, s93
	v_exp_f32_e32 v6, v6
	s_nop 0
	v_add_f32_e32 v6, 1.0, v6
	v_cmp_gt_f32_e32 vcc, s94, v6
	s_nop 1
	v_cndmask_b32_e64 v9, 0, 32, vcc
	v_ldexp_f32 v6, v6, v9
	v_log_f32_e32 v6, v6
	s_nop 0
	v_mul_f32_e32 v9, 0x3f317217, v6
	v_fma_f32 v9, v6, s95, -v9
	v_fmac_f32_e32 v9, 0x3377d1cf, v6
	v_fmac_f32_e32 v9, 0x3f317217, v6
	v_cmp_lt_f32_e64 s[72:73], |v6|, s96
	s_nop 1
	v_cndmask_b32_e64 v6, v6, v9, s[72:73]
	v_cndmask_b32_e32 v9, 0, v47, vcc
	v_sub_f32_e32 v6, v6, v9
	v_min_f32_e32 v9, 0, v7
	v_mul_f32_e64 v7, |v7|, s93
	v_exp_f32_e32 v7, v7
	s_nop 0
	v_add_f32_e32 v7, 1.0, v7
	v_cmp_gt_f32_e32 vcc, s94, v7
	s_nop 1
	v_cndmask_b32_e64 v14, 0, 32, vcc
	v_ldexp_f32 v7, v7, v14
	v_log_f32_e32 v7, v7
	s_nop 0
	v_mul_f32_e32 v14, 0x3f317217, v7
	v_fma_f32 v14, v7, s95, -v14
	v_fmac_f32_e32 v14, 0x3377d1cf, v7
	v_fmac_f32_e32 v14, 0x3f317217, v7
	v_cmp_lt_f32_e64 s[72:73], |v7|, s96
	s_nop 1
	v_cndmask_b32_e64 v7, v7, v14, s[72:73]
	v_cndmask_b32_e32 v14, 0, v47, vcc
	v_sub_f32_e32 v7, v7, v14
	v_pk_add_f32 v[6:7], v[8:9], v[6:7] neg_lo:[0,1] neg_hi:[0,1]
	s_nop 0
	v_pk_mul_f32 v[6:7], v[6:7], s[8:9] op_sel_hi:[1,0]
	ds_write2_b32 v13, v6, v7 offset0:4 offset1:5
	v_min_f32_e32 v6, 0, v4
	v_mul_f32_e64 v4, |v4|, s93
	v_exp_f32_e32 v4, v4
	s_nop 0
	v_add_f32_e32 v4, 1.0, v4
	v_cmp_gt_f32_e32 vcc, s94, v4
	s_nop 1
	v_cndmask_b32_e64 v7, 0, 32, vcc
	v_ldexp_f32 v4, v4, v7
	v_log_f32_e32 v4, v4
	s_nop 0
	v_mul_f32_e32 v7, 0x3f317217, v4
	v_fma_f32 v7, v4, s95, -v7
	v_fmac_f32_e32 v7, 0x3377d1cf, v4
	v_fmac_f32_e32 v7, 0x3f317217, v4
	v_cmp_lt_f32_e64 s[72:73], |v4|, s96
	s_nop 1
	v_cndmask_b32_e64 v4, v4, v7, s[72:73]
	v_cndmask_b32_e32 v7, 0, v47, vcc
	v_sub_f32_e32 v4, v4, v7
	v_min_f32_e32 v7, 0, v5
	v_mul_f32_e64 v5, |v5|, s93
	v_exp_f32_e32 v5, v5
	s_nop 0
	v_add_f32_e32 v5, 1.0, v5
	v_cmp_gt_f32_e32 vcc, s94, v5
	s_nop 1
	v_cndmask_b32_e64 v8, 0, 32, vcc
	v_ldexp_f32 v5, v5, v8
	v_log_f32_e32 v5, v5
	s_nop 0
	v_mul_f32_e32 v8, 0x3f317217, v5
	v_fma_f32 v8, v5, s95, -v8
	v_fmac_f32_e32 v8, 0x3377d1cf, v5
	v_fmac_f32_e32 v8, 0x3f317217, v5
	v_cmp_lt_f32_e64 s[72:73], |v5|, s96
	s_nop 1
	v_cndmask_b32_e64 v5, v5, v8, s[72:73]
	v_cndmask_b32_e32 v8, 0, v47, vcc
	v_sub_f32_e32 v5, v5, v8
	v_pk_add_f32 v[4:5], v[6:7], v[4:5] neg_lo:[0,1] neg_hi:[0,1]
	v_cmp_lt_i32_e32 vcc, 0, v17
	v_pk_mul_f32 v[4:5], v[4:5], s[8:9] op_sel_hi:[1,0]
	ds_write2_b32 v13, v4, v5 offset0:6 offset1:7
	v_and_b32_e32 v4, 63, v10
	v_lshl_add_u32 v14, v4, 2, 0
	v_mul_lo_u32 v4, v17, s0
	v_add_u32_e32 v4, v14, v4
	s_waitcnt lgkmcnt(0)
	s_barrier
	ds_read2_b32 v[6:7], v4 offset1:65
	ds_read2_b32 v[8:9], v4 offset0:130 offset1:195
	s_waitcnt lgkmcnt(1)
	v_add_f32_e32 v5, 0, v6
	v_add_f32_e32 v6, v5, v7
	s_waitcnt lgkmcnt(0)
	v_add_f32_e32 v7, v6, v8
	v_add_f32_e32 v8, v7, v9
	v_add_u32_e32 v9, 0x400, v4
	ds_read2_b32 v[18:19], v9 offset0:4 offset1:69
	s_waitcnt lgkmcnt(0)
	v_add_f32_e32 v15, v8, v18
	v_add_f32_e32 v16, v15, v19
	ds_read2_b32 v[18:19], v9 offset0:134 offset1:199
	s_waitcnt lgkmcnt(0)
	v_add_f32_e32 v18, v16, v18
	v_add_f32_e32 v19, v18, v19
	ds_write_b32 v33, v19 offset:16640
	s_waitcnt lgkmcnt(0)
	s_barrier
	s_and_saveexec_b64 s[72:73], vcc
	s_cbranch_execz .LBB0_402
	ds_read_b32 v21, v14 offset:16640
	s_waitcnt lgkmcnt(0)
	v_add_f32_e32 v21, 0, v21

; DI float siluf_(float x) { return x / (1.f + __expf(-x)); }
; DI void cmp_stage2(const Ctx& c0, int layer) {
;     ...
;         for (int h4 = 0; h4 < 128; h4 += 4) {
;             f32x4 s = *(const f32x4*)(p0 + h4);
; #pragma unroll
;             for (int ks = 1; ks < 4; ++ks) s += *(const f32x4*)(p0 + (size_t)ks * 4 * 2048 * 128 + h4);
;             s += *(const f32x4*)(cb + kv * 128 + h4);
; #pragma unroll
;             for (int j = 0; j < 4; ++j) { const float hv = siluf_(s[j]); const f32x4 w0 = *(const f32x4*)(w2 + (size_t)(h4 + j) * 64), w1 = *(const f32x4*)(w2 + (size_t)(h4 + j) * 64 + 4);
;                 acc[0] += hv * w0[0]; acc[1] += hv * w0[1]; acc[2] += hv * w0[2]; acc[3] += hv * w0[3]; acc[4] += hv * w1[0]; acc[5] += hv * w1[1]; acc[6] += hv * w1[2]; acc[7] += hv * w1[3]; }
;         }
.Lc2p_loop_LBB0_476:
	s_waitcnt vmcnt(0) lgkmcnt(0)
	v_lshl_add_u64 v[126:127], s[14:15], 0, v[12:13]
	v_add_co_u32_e32 v114, vcc, s20, v126
	global_load_dwordx4 v[90:93], v[18:19], off offset:16
	global_load_dwordx4 v[96:99], v[18:19], off
	global_load_dwordx4 v[106:109], v[18:19], off offset:272
	global_load_dwordx4 v[110:113], v[18:19], off offset:256
	v_addc_co_u32_e32 v115, vcc, 0, v127, vcc
	v_add_co_u32_e32 v118, vcc, s21, v126
	v_lshl_add_u64 v[130:131], s[14:15], 0, v[14:15]
	s_nop 0
	v_addc_co_u32_e32 v119, vcc, 0, v127, vcc
	v_add_co_u32_e32 v122, vcc, s22, v126
	global_load_dwordx4 v[114:117], v[114:115], off
	s_nop 0
	global_load_dwordx4 v[118:121], v[118:119], off
	v_addc_co_u32_e32 v123, vcc, 0, v127, vcc
	global_load_dwordx4 v[122:125], v[122:123], off
	v_add_co_u32_e32 v126, vcc, s23, v126
	s_add_i32 s25, s25, 4
	s_nop 0
	v_addc_co_u32_e32 v127, vcc, 0, v127, vcc
	global_load_dwordx4 v[126:129], v[126:127], off
	s_nop 0
	global_load_dwordx4 v[130:133], v[130:131], off
	s_nop 0
	global_load_dwordx4 v[134:137], v[18:19], off offset:528
	global_load_dwordx4 v[138:141], v[18:19], off offset:512
	global_load_dwordx4 v[142:145], v[18:19], off offset:784
	global_load_dwordx4 v[146:149], v[18:19], off offset:768
	s_add_u32 s14, s14, 16
	s_addc_u32 s15, s15, 0
	v_lshl_add_u64 v[18:19], v[18:19], 0, s[12:13]
	v_pk_add_f32 v[42:43], v[42:43], v[46:47]
	v_pk_add_f32 v[44:45], v[44:45], v[48:49]
	v_pk_add_f32 v[42:43], v[42:43], v[50:51]
	v_pk_add_f32 v[44:45], v[44:45], v[52:53]
	v_pk_add_f32 v[42:43], v[42:43], v[54:55]
	v_pk_add_f32 v[44:45], v[44:45], v[56:57]
	v_add_f32_e32 v4, v42, v58
	v_add_f32_e32 v42, v43, v59
	v_add_f32_e32 v43, v44, v60
	v_add_f32_e32 v44, v45, v61
	v_mul_f32_e32 v45, 0xbfb8aa3b, v4
	v_mul_f32_e32 v46, 0xbfb8aa3b, v42
	v_exp_f32_e32 v45, v45
	v_mul_f32_e32 v47, 0xbfb8aa3b, v43
	v_exp_f32_e32 v46, v46
	v_mul_f32_e32 v48, 0xbfb8aa3b, v44
	v_exp_f32_e32 v47, v47
	v_exp_f32_e32 v48, v48
	v_add_f32_e32 v45, 1.0, v45
	v_add_f32_e32 v46, 1.0, v46
	v_add_f32_e32 v47, 1.0, v47
	v_add_f32_e32 v48, 1.0, v48
	v_rcp_f32_e32 v49, v45
	s_nop 0
	v_mul_f32_e32 v4, v4, v49
	v_rcp_f32_e32 v45, v46
	s_nop 0
	v_mul_f32_e32 v42, v42, v45
	v_pk_fma_f32 v[22:23], v[30:31], v[4:5], v[22:23] op_sel_hi:[1,0,1]
	v_pk_fma_f32 v[20:21], v[32:33], v[4:5], v[20:21] op_sel_hi:[1,0,1]
	v_pk_fma_f32 v[16:17], v[26:27], v[4:5], v[16:17] op_sel_hi:[1,0,1]
	v_pk_fma_f32 v[10:11], v[28:29], v[4:5], v[10:11] op_sel_hi:[1,0,1]
	v_rcp_f32_e32 v4, v47
	s_nop 0
	v_mul_f32_e32 v4, v43, v4
	v_pk_fma_f32 v[22:23], v[38:39], v[42:43], v[22:23] op_sel_hi:[1,0,1]
	v_pk_fma_f32 v[20:21], v[40:41], v[42:43], v[20:21] op_sel_hi:[1,0,1]
	v_pk_fma_f32 v[16:17], v[34:35], v[42:43], v[16:17] op_sel_hi:[1,0,1]
	v_pk_fma_f32 v[10:11], v[36:37], v[42:43], v[10:11] op_sel_hi:[1,0,1]
	v_rcp_f32_e32 v26, v48
	s_nop 0
	v_mul_f32_e32 v26, v44, v26
	v_pk_fma_f32 v[22:23], v[4:5], v[66:67], v[22:23] op_sel_hi:[0,1,1]
	v_pk_fma_f32 v[20:21], v[4:5], v[68:69], v[20:21] op_sel_hi:[0,1,1]
	v_pk_fma_f32 v[16:17], v[4:5], v[62:63], v[16:17] op_sel_hi:[0,1,1]
	v_pk_fma_f32 v[10:11], v[4:5], v[64:65], v[10:11] op_sel_hi:[0,1,1]
	v_pk_fma_f32 v[22:23], v[26:27], v[74:75], v[22:23] op_sel_hi:[0,1,1]
	v_pk_fma_f32 v[20:21], v[26:27], v[76:77], v[20:21] op_sel_hi:[0,1,1]
	v_pk_fma_f32 v[16:17], v[26:27], v[70:71], v[16:17] op_sel_hi:[0,1,1]
	v_pk_fma_f32 v[10:11], v[26:27], v[72:73], v[10:11] op_sel_hi:[0,1,1]
	s_waitcnt vmcnt(0)
	s_cmpk_gt_u32 s25, 0x7b
	s_cselect_b32 s100, 1, 0
	s_cbranch_scc1 .Lc2p_skip_LBB0_476
	v_lshl_add_u64 v[54:55], s[14:15], 0, v[12:13]
	v_add_co_u32_e32 v42, vcc, s20, v54
	global_load_dwordx4 v[26:29], v[18:19], off offset:16
	global_load_dwordx4 v[30:33], v[18:19], off
	global_load_dwordx4 v[34:37], v[18:19], off offset:272
	global_load_dwordx4 v[38:41], v[18:19], off offset:256
	v_addc_co_u32_e32 v43, vcc, 0, v55, vcc
	v_add_co_u32_e32 v46, vcc, s21, v54
	v_lshl_add_u64 v[58:59], s[14:15], 0, v[14:15]
	s_nop 0
	v_addc_co_u32_e32 v47, vcc, 0, v55, vcc
	v_add_co_u32_e32 v50, vcc, s22, v54
	global_load_dwordx4 v[42:45], v[42:43], off
	s_nop 0
	global_load_dwordx4 v[46:49], v[46:47], off
	v_addc_co_u32_e32 v51, vcc, 0, v55, vcc
	global_load_dwordx4 v[50:53], v[50:51], off
	v_add_co_u32_e32 v54, vcc, s23, v54
	s_add_i32 s25, s25, 4
	s_nop 0
	v_addc_co_u32_e32 v55, vcc, 0, v55, vcc
	global_load_dwordx4 v[54:57], v[54:55], off
	s_nop 0
	global_load_dwordx4 v[58:61], v[58:59], off
	s_nop 0
	global_load_dwordx4 v[62:65], v[18:19], off offset:528
	global_load_dwordx4 v[66:69], v[18:19], off offset:512
	global_load_dwordx4 v[70:73], v[18:19], off offset:784
	global_load_dwordx4 v[74:77], v[18:19], off offset:768
	s_add_u32 s14, s14, 16
	s_addc_u32 s15, s15, 0
	v_lshl_add_u64 v[18:19], v[18:19], 0, s[12:13]
; DI unsigned cvtpk(float lo, float hi) { f32x2 v = {lo, hi}; bf16x2_t b = __builtin_convertvector(v, bf16x2_t); return __builtin_bit_cast(unsigned, b); }
; DI float siluf_(float x) { return x / (1.f + __expf(-x)); }
; DI void cmp_stage2(const Ctx& c0, int layer) {
;     ...
;         for (int h4 = 0; h4 < 128; h4 += 4) {
;             f32x4 s = *(const f32x4*)(p0 + h4);
; #pragma unroll
;             for (int ks = 1; ks < 4; ++ks) s += *(const f32x4*)(p0 + (size_t)ks * 4 * 2048 * 128 + h4);
;             s += *(const f32x4*)(cb + kv * 128 + h4);
; #pragma unroll
;             for (int j = 0; j < 4; ++j) { const float hv = siluf_(s[j]); const f32x4 w0 = *(const f32x4*)(w2 + (size_t)(h4 + j) * 64), w1 = *(const f32x4*)(w2 + (size_t)(h4 + j) * 64 + 4);
;                 acc[0] += hv * w0[0]; acc[1] += hv * w0[1]; acc[2] += hv * w0[2]; acc[3] += hv * w0[3]; acc[4] += hv * w1[0]; acc[5] += hv * w1[1]; acc[6] += hv * w1[2]; acc[7] += hv * w1[3]; }
;         }
;         u32x4 w; w.x = cvtpk(acc[0], acc[1]); w.y = cvtpk(acc[2], acc[3]); w.z = cvtpk(acc[4], acc[5]); w.w = cvtpk(acc[6], acc[7]);
;         *(u32x4*)(out + ((size_t)which * 2048 + row) * 64 + 8 * oct) = w;
.Lc2p_skip_LBB0_476:
	v_pk_add_f32 v[114:115], v[114:115], v[118:119]
	v_pk_add_f32 v[116:117], v[116:117], v[120:121]
	v_pk_add_f32 v[114:115], v[114:115], v[122:123]
	v_pk_add_f32 v[116:117], v[116:117], v[124:125]
	v_pk_add_f32 v[114:115], v[114:115], v[126:127]
	v_pk_add_f32 v[116:117], v[116:117], v[128:129]
	v_add_f32_e32 v4, v114, v130
	v_add_f32_e32 v114, v115, v131
	v_add_f32_e32 v115, v116, v132
	v_add_f32_e32 v116, v117, v133
	v_mul_f32_e32 v117, 0xbfb8aa3b, v4
	v_mul_f32_e32 v118, 0xbfb8aa3b, v114
	v_exp_f32_e32 v117, v117
	v_mul_f32_e32 v119, 0xbfb8aa3b, v115
	v_exp_f32_e32 v118, v118
	v_mul_f32_e32 v120, 0xbfb8aa3b, v116
	v_exp_f32_e32 v119, v119
	v_exp_f32_e32 v120, v120
	v_add_f32_e32 v117, 1.0, v117
	v_add_f32_e32 v118, 1.0, v118
	v_add_f32_e32 v119, 1.0, v119
	v_add_f32_e32 v120, 1.0, v120
	v_rcp_f32_e32 v121, v117
	s_nop 0
	v_mul_f32_e32 v4, v4, v121
	v_rcp_f32_e32 v117, v118
	s_nop 0
	v_mul_f32_e32 v114, v114, v117
	v_pk_fma_f32 v[22:23], v[96:97], v[4:5], v[22:23] op_sel_hi:[1,0,1]
	v_pk_fma_f32 v[20:21], v[98:99], v[4:5], v[20:21] op_sel_hi:[1,0,1]
	v_pk_fma_f32 v[16:17], v[90:91], v[4:5], v[16:17] op_sel_hi:[1,0,1]
	v_pk_fma_f32 v[10:11], v[92:93], v[4:5], v[10:11] op_sel_hi:[1,0,1]
	v_rcp_f32_e32 v4, v119
	s_nop 0
	v_mul_f32_e32 v4, v115, v4
	v_pk_fma_f32 v[22:23], v[110:111], v[114:115], v[22:23] op_sel_hi:[1,0,1]
	v_pk_fma_f32 v[20:21], v[112:113], v[114:115], v[20:21] op_sel_hi:[1,0,1]
	v_pk_fma_f32 v[16:17], v[106:107], v[114:115], v[16:17] op_sel_hi:[1,0,1]
	v_pk_fma_f32 v[10:11], v[108:109], v[114:115], v[10:11] op_sel_hi:[1,0,1]
	v_rcp_f32_e32 v90, v120
	s_nop 0
	v_mul_f32_e32 v90, v116, v90
	v_pk_fma_f32 v[22:23], v[4:5], v[138:139], v[22:23] op_sel_hi:[0,1,1]
	v_pk_fma_f32 v[20:21], v[4:5], v[140:141], v[20:21] op_sel_hi:[0,1,1]
	v_pk_fma_f32 v[16:17], v[4:5], v[134:135], v[16:17] op_sel_hi:[0,1,1]
	v_pk_fma_f32 v[10:11], v[4:5], v[136:137], v[10:11] op_sel_hi:[0,1,1]
	v_pk_fma_f32 v[22:23], v[90:91], v[146:147], v[22:23] op_sel_hi:[0,1,1]
	v_pk_fma_f32 v[20:21], v[90:91], v[148:149], v[20:21] op_sel_hi:[0,1,1]
	v_pk_fma_f32 v[16:17], v[90:91], v[142:143], v[16:17] op_sel_hi:[0,1,1]
	v_pk_fma_f32 v[10:11], v[90:91], v[144:145], v[10:11] op_sel_hi:[0,1,1]
	s_cmp_lg_u32 s100, 0
	s_cbranch_scc0 .Lc2p_loop_LBB0_476
	v_and_b32_e32 v4, 0x7ff, v25
	v_lshlrev_b64 v[8:9], 18, v[8:9]
	v_lshl_or_b32 v8, v4, 7, v8
	v_lshlrev_b32_e32 v4, 4, v1
	v_add_u32_e32 v1, s16, v1
	v_lshl_add_u64 v[8:9], v[2:3], 0, v[8:9]
	v_and_b32_e32 v4, 0x70, v4
	v_cmp_lt_i32_e32 vcc, s24, v1
	v_cvt_pk_bf16_f32 v12, v22, v23
	v_cvt_pk_bf16_f32 v13, v20, v21
	v_cvt_pk_bf16_f32 v14, v16, v17
	v_cvt_pk_bf16_f32 v15, v10, v11
	v_lshl_add_u64 v[8:9], v[8:9], 0, v[4:5]
	s_or_b64 s[8:9], vcc, s[8:9]
	v_add_u32_e32 v24, s17, v24
	global_store_dwordx4 v[8:9], v[12:15], off
	s_andn2_b64 exec, exec, s[8:9]
	s_cbranch_execnz .LBB0_475

; #define LAS __attribute__((address_space(3)))
; #define LDS_WAIT() asm volatile("s_waitcnt lgkmcnt(0)" ::: "memory")
; DI float bflo(unsigned w) { return __uint_as_float(w << 16); }
; DI float bfhi(unsigned w) { return __uint_as_float(w & 0xffff0000u); }
; DI void branch_fold(ASt& st, float gate, bool may_be_empty, LAS float* wsf, int lane) {
;     const int r = lane & 31, hi = lane >> 5;
;     const float lt = st.l + __shfl_xor(st.l, 32);
;     float inv = 1.f / lt; if (may_be_empty && !(st.m > -1e29f)) inv = 0.f;
;     if (hi == 0) { wsf[r] = inv * gate; wsf[32 + r] = inv; }
;     LDS_WAIT();
; #pragma unroll
;     for (int g4 = 0; g4 < 4; ++g4) { const f32x4 f = *(const LAS f32x4*)(wsf + 8 * g4 + 4 * hi);
; #pragma unroll
;         for (int k = 0; k < 4; ++k) { st.o0[4 * g4 + k] *= f[k]; st.o1[4 * g4 + k] *= f[k]; } }
; DI void nsa_unit(const Ctx& c0, int b, int g, int i, LAS unsigned char* lds) {
;     ...
;         branch_fold(st, g_w2, false, wsf, lane);
; #pragma unroll
;         for (int rg = 0; rg < 16; ++rg) { const unsigned w = OC[rg * 64]; ca0[rg] = (OACC[rg * 64] + st.o0[rg]) + bflo(w); ca1[rg] = (OACC[(16 + rg) * 64] + st.o1[rg]) + bfhi(w); }
;         __syncthreads();
;     }
;     ...
;     { const size_t g0 = ((size_t)b * SEQ + i * 64 + 32 * qh) * 512 + head * 64;
;       const bf16* nzg = (const bf16*)(c.ws + O_NZ) + g0; bf16* ong = (bf16*)(c.ws + O_ONSA) + g0;
;       LAS unsigned char* S = lds + A_OC + wid * 4096;
.LBB0_540:
	s_or_b64 exec, exec, s[12:13]
	s_waitcnt lgkmcnt(0)
	ds_read_b128 v[48:51], v205 offset:32768
	ds_read_b128 v[44:47], v205 offset:32800
	ds_read_b128 v[40:43], v205 offset:32832
	ds_read_b128 v[36:39], v205 offset:32864
	ds_read2st64_b32 v[52:53], v203 offset1:1
	ds_read2st64_b32 v[54:55], v214 offset0:144 offset1:145
	ds_read2st64_b32 v[56:57], v214 offset0:160 offset1:161
	s_or_b32 s3, s24, s33
	s_add_u32 s12, s8, s3
	s_waitcnt lgkmcnt(0)
	v_lshlrev_b32_e32 v2, 16, v52
	v_fma_f32 v1, v20, v48, v54
	v_add_f32_e32 v60, v1, v2
	v_fma_f32 v1, v4, v48, v56
	v_fmac_f32_e32 v55, v21, v49
	v_fmac_f32_e32 v57, v5, v49
	ds_read2st64_b32 v[4:5], v203 offset0:2 offset1:3
	ds_read2st64_b32 v[20:21], v214 offset0:146 offset1:147
	ds_read2st64_b32 v[48:49], v214 offset0:162 offset1:163
	v_and_b32_e32 v2, 0xffff0000, v52
	v_add_f32_e32 v59, v1, v2
	v_lshlrev_b32_e32 v1, 16, v53
	v_add_f32_e32 v58, v55, v1
	v_and_b32_e32 v1, 0xffff0000, v53
	v_add_f32_e32 v57, v57, v1
	s_waitcnt lgkmcnt(0)
	v_fma_f32 v1, v22, v50, v20
	v_lshlrev_b32_e32 v2, 16, v4
	v_add_f32_e32 v56, v1, v2
	v_fma_f32 v1, v6, v50, v48
	v_and_b32_e32 v2, 0xffff0000, v4
	v_add_f32_e32 v55, v1, v2
	v_fmac_f32_e32 v21, v23, v51
	v_lshlrev_b32_e32 v1, 16, v5
	v_add_f32_e32 v54, v21, v1
	v_fmac_f32_e32 v49, v7, v51
	v_and_b32_e32 v1, 0xffff0000, v5
	ds_read2st64_b32 v[4:5], v203 offset0:4 offset1:5
	ds_read2st64_b32 v[6:7], v214 offset0:148 offset1:149
	ds_read2st64_b32 v[20:21], v214 offset0:164 offset1:165
	v_add_f32_e32 v53, v49, v1
	s_addc_u32 s13, s9, 0
	s_waitcnt lgkmcnt(0)
	v_lshlrev_b32_e32 v2, 16, v4
	v_fma_f32 v1, v24, v44, v6
	v_add_f32_e32 v52, v1, v2
	v_fma_f32 v1, v8, v44, v20
	v_and_b32_e32 v2, 0xffff0000, v4
	v_add_f32_e32 v51, v1, v2
	v_fmac_f32_e32 v7, v25, v45
	v_lshlrev_b32_e32 v1, 16, v5
	v_add_f32_e32 v50, v7, v1
	v_and_b32_e32 v1, 0xffff0000, v5
	ds_read2st64_b32 v[4:5], v203 offset0:6 offset1:7
	ds_read2st64_b32 v[6:7], v214 offset0:150 offset1:151
	v_fmac_f32_e32 v21, v9, v45
	ds_read2st64_b32 v[8:9], v214 offset0:166 offset1:167
	v_add_f32_e32 v49, v21, v1
	s_waitcnt lgkmcnt(0)
	v_lshlrev_b32_e32 v2, 16, v4
	v_fma_f32 v1, v26, v46, v6
	v_add_f32_e32 v48, v1, v2
	v_fma_f32 v1, v10, v46, v8
	v_and_b32_e32 v2, 0xffff0000, v4
	v_add_f32_e32 v46, v1, v2
	v_fmac_f32_e32 v7, v27, v47
	v_lshlrev_b32_e32 v1, 16, v5
	v_add_f32_e32 v45, v7, v1
	v_fmac_f32_e32 v9, v11, v47
	v_and_b32_e32 v1, 0xffff0000, v5
	ds_read2st64_b32 v[4:5], v203 offset0:8 offset1:9
	ds_read2st64_b32 v[6:7], v214 offset0:152 offset1:153
	v_add_f32_e32 v44, v9, v1
	ds_read2st64_b32 v[8:9], v214 offset0:168 offset1:169
	s_lshl_b64 s[12:13], s[12:13], 9
	s_waitcnt lgkmcnt(0)
	v_lshlrev_b32_e32 v2, 16, v4
	v_fma_f32 v1, v28, v40, v6
	v_add_f32_e32 v27, v1, v2
	v_fma_f32 v1, v12, v40, v8
	v_and_b32_e32 v2, 0xffff0000, v4
	v_add_f32_e32 v26, v1, v2
	v_fmac_f32_e32 v7, v29, v41
	v_lshlrev_b32_e32 v1, 16, v5
	v_add_f32_e32 v25, v7, v1
	v_fmac_f32_e32 v9, v13, v41
	v_and_b32_e32 v1, 0xffff0000, v5
	ds_read2st64_b32 v[4:5], v203 offset0:10 offset1:11
	ds_read2st64_b32 v[6:7], v214 offset0:154 offset1:155
	v_add_f32_e32 v24, v9, v1
	ds_read2st64_b32 v[8:9], v214 offset0:170 offset1:171
	s_add_u32 s12, s12, s20
	s_waitcnt lgkmcnt(0)
	v_lshlrev_b32_e32 v2, 16, v4
	v_fma_f32 v1, v30, v42, v6
	v_add_f32_e32 v23, v1, v2
	v_fma_f32 v1, v14, v42, v8
	v_and_b32_e32 v2, 0xffff0000, v4
	v_add_f32_e32 v22, v1, v2
	v_fmac_f32_e32 v7, v31, v43
	v_lshlrev_b32_e32 v1, 16, v5
	v_add_f32_e32 v21, v7, v1
	v_fmac_f32_e32 v9, v15, v43
	v_and_b32_e32 v1, 0xffff0000, v5
	ds_read2st64_b32 v[4:5], v203 offset0:12 offset1:13
	ds_read2st64_b32 v[6:7], v214 offset0:156 offset1:157
	v_add_f32_e32 v15, v9, v1
	ds_read2st64_b32 v[8:9], v214 offset0:172 offset1:173
	s_addc_u32 s13, s13, 0
	s_waitcnt lgkmcnt(0)
	v_lshlrev_b32_e32 v2, 16, v4
	v_fma_f32 v1, v32, v36, v6
	v_add_f32_e32 v20, v1, v2
	v_fma_f32 v1, v16, v36, v8
	v_and_b32_e32 v2, 0xffff0000, v4
	v_add_f32_e32 v14, v1, v2
	v_fmac_f32_e32 v7, v33, v37
	v_lshlrev_b32_e32 v1, 16, v5
	v_add_f32_e32 v13, v7, v1
	v_fmac_f32_e32 v9, v17, v37
	v_and_b32_e32 v1, 0xffff0000, v5
	ds_read2st64_b32 v[4:5], v203 offset0:14 offset1:15
	ds_read2st64_b32 v[6:7], v214 offset0:158 offset1:159
	v_add_f32_e32 v12, v9, v1
	ds_read2st64_b32 v[8:9], v214 offset0:174 offset1:175
	s_lshl_b64 s[12:13], s[12:13], 1
	s_waitcnt lgkmcnt(0)
	v_lshlrev_b32_e32 v2, 16, v4
	v_fma_f32 v1, v34, v38, v6
	v_add_f32_e32 v10, v1, v2
	v_fma_f32 v1, v18, v38, v8
	v_and_b32_e32 v2, 0xffff0000, v4
	v_add_f32_e32 v11, v1, v2
	v_fmac_f32_e32 v7, v35, v39
	v_lshlrev_b32_e32 v1, 16, v5
	s_add_u32 s0, s0, s12
	v_add_f32_e32 v2, v7, v1
	v_fmac_f32_e32 v9, v19, v39
	v_and_b32_e32 v1, 0xffff0000, v5
	v_mov_b32_e32 v135, v3
	s_addc_u32 s1, s1, s13
	v_add_f32_e32 v1, v9, v1
	v_lshl_add_u64 v[8:9], s[0:1], 0, v[134:135]
	s_mov_b64 s[0:1], 0xb500000
	v_lshl_add_u64 v[16:17], v[8:9], 0, s[0:1]
	v_lshl_add_u64 v[4:5], v[16:17], 0, v[126:127]
	s_barrier
; #define LAS __attribute__((address_space(3)))
; #define LDS_WAIT() asm volatile("s_waitcnt lgkmcnt(0)" ::: "memory")
; DI unsigned cvtpk(float lo, float hi) { f32x2 v = {lo, hi}; bf16x2_t b = __builtin_convertvector(v, bf16x2_t); return __builtin_bit_cast(unsigned, b); }
; DI float bf2f(bf16 b) { return __uint_as_float(((unsigned)b) << 16); }
; DI float siluf_(float x) { return x / (1.f + __expf(-x)); }
; DI void nsa_unit(const Ctx& c0, int b, int g, int i, LAS unsigned char* lds) {
;     ...
;       for (int it = 0; it < 4; ++it) { const int rw = 8 * it + (lane >> 3), ch = lane & 7;
;           *(LAS u32x4*)(S + rw * 128 + ch * 16) = *(const u32x4*)(nzg + (size_t)rw * 512 + ch * 8); }
;       LDS_WAIT();
; #pragma unroll
;       for (int rg = 0; rg < 16; ++rg) { LAS bf16* e = (LAS bf16*)(S + ((rg & 3) + 8 * (rg >> 2) + 4 * hi) * 128 + r * 2);
;           const float z0 = bf2f(e[0]), z1 = bf2f(e[32]);
;           e[0] = (bf16)(cvtpk(ca0[rg] * siluf_(z0), 0.f) & 0xffffu);
;           e[32] = (bf16)(cvtpk(ca1[rg] * siluf_(z1), 0.f) & 0xffffu); }
	global_load_dwordx4 v[4:7], v[4:5], off
	s_add_i32 s23, s23, 1
	s_cmp_eq_u32 s23, 4
	s_waitcnt vmcnt(0) lgkmcnt(0)
	ds_write_b128 v216, v[4:7]
	v_lshl_add_u64 v[4:5], v[16:17], 0, v[128:129]
	global_load_dwordx4 v[4:7], v[4:5], off
	s_waitcnt vmcnt(0) lgkmcnt(0)
	ds_write_b128 v217, v[4:7]
	v_lshl_add_u64 v[4:5], v[16:17], 0, v[130:131]
	global_load_dwordx4 v[4:7], v[4:5], off
	s_waitcnt vmcnt(0) lgkmcnt(0)
	ds_write_b128 v218, v[4:7]
	v_lshl_add_u64 v[4:5], v[16:17], 0, v[132:133]
	global_load_dwordx4 v[4:7], v[4:5], off
	s_waitcnt vmcnt(0) lgkmcnt(0)
	ds_write_b128 v219, v[4:7]
	s_waitcnt lgkmcnt(0)
	ds_read_u16 v4, v220
	ds_read_u16 v5, v220 offset:64
	s_waitcnt lgkmcnt(1)
	v_lshlrev_b32_e32 v4, 16, v4
	v_mul_f32_e32 v6, 0xbfb8aa3b, v4
	v_exp_f32_e32 v6, v6
	s_waitcnt lgkmcnt(0)
	v_lshlrev_b32_e32 v5, 16, v5
	v_add_f32_e32 v6, 1.0, v6
	v_div_scale_f32 v7, s[0:1], v6, v6, v4
	s_nop 0
	v_rcp_f32_e32 v7, v6
	s_nop 0
	v_mul_f32_e32 v4, v4, v7
	v_mul_f32_e32 v4, v60, v4
	v_cvt_pk_bf16_f32 v4, v4, s0
	ds_write_b16 v220, v4
	v_mul_f32_e32 v4, 0xbfb8aa3b, v5
	v_exp_f32_e32 v4, v4
	s_nop 0
	v_add_f32_e32 v4, 1.0, v4
	v_div_scale_f32 v6, s[0:1], v4, v4, v5
	s_nop 0
	v_rcp_f32_e32 v4, v4
	s_nop 0
	v_mul_f32_e32 v4, v5, v4
	v_mul_f32_e32 v4, v59, v4
	v_cvt_pk_bf16_f32 v4, v4, s0
	ds_write_b16 v220, v4 offset:64
	ds_read_u16 v4, v220 offset:128
	ds_read_u16 v5, v220 offset:192
	s_waitcnt lgkmcnt(1)
	v_lshlrev_b32_e32 v4, 16, v4
	v_mul_f32_e32 v6, 0xbfb8aa3b, v4
	v_exp_f32_e32 v6, v6
	s_waitcnt lgkmcnt(0)
	v_lshlrev_b32_e32 v5, 16, v5
	v_add_f32_e32 v6, 1.0, v6
	v_div_scale_f32 v7, s[0:1], v6, v6, v4
	s_nop 0
	v_rcp_f32_e32 v7, v6
	s_nop 0
	v_mul_f32_e32 v4, v4, v7
	v_mul_f32_e32 v4, v58, v4
	v_cvt_pk_bf16_f32 v4, v4, s0
	ds_write_b16 v220, v4 offset:128
	v_mul_f32_e32 v4, 0xbfb8aa3b, v5
	v_exp_f32_e32 v4, v4
	s_nop 0
	v_add_f32_e32 v4, 1.0, v4
	v_div_scale_f32 v6, s[0:1], v4, v4, v5
	s_nop 0
	v_rcp_f32_e32 v4, v4
	s_nop 0
	v_mul_f32_e32 v4, v5, v4
	v_mul_f32_e32 v4, v57, v4
	v_cvt_pk_bf16_f32 v4, v4, s0
	ds_write_b16 v220, v4 offset:192
	ds_read_u16 v4, v220 offset:256
	ds_read_u16 v5, v220 offset:320
	s_waitcnt lgkmcnt(1)
	v_lshlrev_b32_e32 v4, 16, v4
	v_mul_f32_e32 v6, 0xbfb8aa3b, v4
	v_exp_f32_e32 v6, v6
	s_waitcnt lgkmcnt(0)
	v_lshlrev_b32_e32 v5, 16, v5
	v_add_f32_e32 v6, 1.0, v6
	v_div_scale_f32 v7, s[0:1], v6, v6, v4
	s_nop 0
	v_rcp_f32_e32 v7, v6
	s_nop 0
	v_mul_f32_e32 v4, v4, v7
	v_mul_f32_e32 v4, v56, v4
	v_cvt_pk_bf16_f32 v4, v4, s0
	ds_write_b16 v220, v4 offset:256
	v_mul_f32_e32 v4, 0xbfb8aa3b, v5
	v_exp_f32_e32 v4, v4
	s_nop 0
	v_add_f32_e32 v4, 1.0, v4
	v_div_scale_f32 v6, s[0:1], v4, v4, v5
	s_nop 0
	v_rcp_f32_e32 v4, v4
	s_nop 0
	v_mul_f32_e32 v4, v5, v4
	v_mul_f32_e32 v4, v55, v4
	v_cvt_pk_bf16_f32 v4, v4, s0
	ds_write_b16 v220, v4 offset:320
	ds_read_u16 v4, v220 offset:384
	ds_read_u16 v5, v220 offset:448
	s_waitcnt lgkmcnt(1)
	v_lshlrev_b32_e32 v4, 16, v4
	v_mul_f32_e32 v6, 0xbfb8aa3b, v4
	v_exp_f32_e32 v6, v6
	s_waitcnt lgkmcnt(0)
	v_lshlrev_b32_e32 v5, 16, v5
	v_add_f32_e32 v6, 1.0, v6
	v_div_scale_f32 v7, s[0:1], v6, v6, v4
	s_nop 0
	v_rcp_f32_e32 v7, v6
	s_nop 0
	v_mul_f32_e32 v4, v4, v7
	v_mul_f32_e32 v4, v54, v4
	v_cvt_pk_bf16_f32 v4, v4, s0
	ds_write_b16 v220, v4 offset:384
	v_mul_f32_e32 v4, 0xbfb8aa3b, v5
	v_exp_f32_e32 v4, v4
	s_nop 0
	v_add_f32_e32 v4, 1.0, v4
	v_div_scale_f32 v6, s[0:1], v4, v4, v5
	s_nop 0
	v_rcp_f32_e32 v4, v4
	s_nop 0
	v_mul_f32_e32 v4, v5, v4
	v_mul_f32_e32 v4, v53, v4
	v_cvt_pk_bf16_f32 v4, v4, s0
	ds_write_b16 v220, v4 offset:448
	ds_read_u16 v4, v220 offset:1024
	ds_read_u16 v5, v220 offset:1088
	s_waitcnt lgkmcnt(1)
	v_lshlrev_b32_e32 v4, 16, v4
	v_mul_f32_e32 v6, 0xbfb8aa3b, v4
	v_exp_f32_e32 v6, v6
	s_waitcnt lgkmcnt(0)
	v_lshlrev_b32_e32 v5, 16, v5
	v_add_f32_e32 v6, 1.0, v6
	v_div_scale_f32 v7, s[0:1], v6, v6, v4
	s_nop 0
	v_rcp_f32_e32 v7, v6
	s_nop 0
	v_mul_f32_e32 v4, v4, v7
	v_mul_f32_e32 v4, v52, v4
	v_cvt_pk_bf16_f32 v4, v4, s0
	ds_write_b16 v220, v4 offset:1024
	v_mul_f32_e32 v4, 0xbfb8aa3b, v5
	v_exp_f32_e32 v4, v4
	s_nop 0
	v_add_f32_e32 v4, 1.0, v4
	v_div_scale_f32 v6, s[0:1], v4, v4, v5
	s_nop 0
	v_rcp_f32_e32 v4, v4
	s_nop 0
	v_mul_f32_e32 v4, v5, v4
	v_mul_f32_e32 v4, v51, v4
	v_cvt_pk_bf16_f32 v4, v4, s0
	ds_write_b16 v220, v4 offset:1088
	ds_read_u16 v4, v220 offset:1152
	ds_read_u16 v5, v220 offset:1216
	s_waitcnt lgkmcnt(1)
	v_lshlrev_b32_e32 v4, 16, v4
	v_mul_f32_e32 v6, 0xbfb8aa3b, v4
	v_exp_f32_e32 v6, v6
	s_waitcnt lgkmcnt(0)
	v_lshlrev_b32_e32 v5, 16, v5
	v_add_f32_e32 v6, 1.0, v6
	v_div_scale_f32 v7, s[0:1], v6, v6, v4
	s_nop 0
	v_rcp_f32_e32 v7, v6
	s_nop 0
	v_mul_f32_e32 v4, v4, v7
	v_mul_f32_e32 v4, v50, v4
	v_cvt_pk_bf16_f32 v4, v4, s0
	ds_write_b16 v220, v4 offset:1152
	v_mul_f32_e32 v4, 0xbfb8aa3b, v5
	v_exp_f32_e32 v4, v4
	s_nop 0
	v_add_f32_e32 v4, 1.0, v4
	v_div_scale_f32 v6, s[0:1], v4, v4, v5
	s_nop 0
	v_rcp_f32_e32 v4, v4
	s_nop 0
	v_mul_f32_e32 v4, v5, v4
	v_mul_f32_e32 v4, v49, v4
	v_cvt_pk_bf16_f32 v4, v4, s0
	ds_write_b16 v220, v4 offset:1216
	ds_read_u16 v4, v220 offset:1280
	ds_read_u16 v5, v220 offset:1344
	s_waitcnt lgkmcnt(1)
	v_lshlrev_b32_e32 v4, 16, v4
	v_mul_f32_e32 v6, 0xbfb8aa3b, v4
	v_exp_f32_e32 v6, v6
	s_waitcnt lgkmcnt(0)
	v_lshlrev_b32_e32 v5, 16, v5
	v_add_f32_e32 v6, 1.0, v6
	v_div_scale_f32 v7, s[0:1], v6, v6, v4
	s_nop 0
	v_rcp_f32_e32 v7, v6
	s_nop 0
	v_mul_f32_e32 v4, v4, v7
	v_mul_f32_e32 v4, v48, v4
	v_cvt_pk_bf16_f32 v4, v4, s0
	ds_write_b16 v220, v4 offset:1280
	v_mul_f32_e32 v4, 0xbfb8aa3b, v5
	v_exp_f32_e32 v4, v4
	s_nop 0
	v_add_f32_e32 v4, 1.0, v4
	v_div_scale_f32 v6, s[0:1], v4, v4, v5
	s_nop 0
	v_rcp_f32_e32 v4, v4
	s_nop 0
	v_mul_f32_e32 v4, v5, v4
	v_mul_f32_e32 v4, v46, v4
	v_cvt_pk_bf16_f32 v4, v4, s0
	ds_write_b16 v220, v4 offset:1344
	ds_read_u16 v4, v220 offset:1408
	s_waitcnt lgkmcnt(0)
; #define LAS __attribute__((address_space(3)))
; DI unsigned cvtpk(float lo, float hi) { f32x2 v = {lo, hi}; bf16x2_t b = __builtin_convertvector(v, bf16x2_t); return __builtin_bit_cast(unsigned, b); }
; DI float bf2f(bf16 b) { return __uint_as_float(((unsigned)b) << 16); }
; DI float siluf_(float x) { return x / (1.f + __expf(-x)); }
; DI void nsa_unit(const Ctx& c0, int b, int g, int i, LAS unsigned char* lds) {
;     ...
;       for (int rg = 0; rg < 16; ++rg) { LAS bf16* e = (LAS bf16*)(S + ((rg & 3) + 8 * (rg >> 2) + 4 * hi) * 128 + r * 2);
;           const float z0 = bf2f(e[0]), z1 = bf2f(e[32]);
;           e[0] = (bf16)(cvtpk(ca0[rg] * siluf_(z0), 0.f) & 0xffffu);
;           e[32] = (bf16)(cvtpk(ca1[rg] * siluf_(z1), 0.f) & 0xffffu); }
	v_lshlrev_b32_e32 v5, 16, v4
	v_mul_f32_e32 v6, 0xbfb8aa3b, v5
	v_exp_f32_e32 v6, v6
	ds_read_u16 v4, v220 offset:1472
	v_add_f32_e32 v6, 1.0, v6
	v_div_scale_f32 v7, s[0:1], v6, v6, v5
	s_waitcnt lgkmcnt(0)
	v_lshlrev_b32_e32 v4, 16, v4
	v_rcp_f32_e32 v7, v6
	s_nop 0
	v_mul_f32_e32 v5, v5, v7
	v_mul_f32_e32 v5, v45, v5
	v_cvt_pk_bf16_f32 v5, v5, s0
	ds_write_b16 v220, v5 offset:1408
	v_mul_f32_e32 v5, 0xbfb8aa3b, v4
	v_exp_f32_e32 v5, v5
	s_nop 0
	v_add_f32_e32 v5, 1.0, v5
	v_div_scale_f32 v6, s[0:1], v5, v5, v4
	s_nop 0
	v_rcp_f32_e32 v6, v5
	s_nop 0
	v_mul_f32_e32 v4, v4, v6
	v_mul_f32_e32 v4, v44, v4
	v_cvt_pk_bf16_f32 v4, v4, s0
	ds_write_b16 v220, v4 offset:1472
	ds_read_u16 v4, v220 offset:2048
	ds_read_u16 v5, v220 offset:2112
	s_waitcnt lgkmcnt(1)
	v_lshlrev_b32_e32 v4, 16, v4
	v_mul_f32_e32 v6, 0xbfb8aa3b, v4
	v_exp_f32_e32 v6, v6
	s_waitcnt lgkmcnt(0)
	v_lshlrev_b32_e32 v5, 16, v5
	v_add_f32_e32 v6, 1.0, v6
	v_div_scale_f32 v7, s[0:1], v6, v6, v4
	s_nop 0
	v_rcp_f32_e32 v7, v6
	s_nop 0
	v_mul_f32_e32 v4, v4, v7
	v_mul_f32_e32 v4, v27, v4
	v_cvt_pk_bf16_f32 v4, v4, s0
	ds_write_b16 v220, v4 offset:2048
	v_mul_f32_e32 v4, 0xbfb8aa3b, v5
	v_exp_f32_e32 v4, v4
	s_nop 0
	v_add_f32_e32 v4, 1.0, v4
	v_div_scale_f32 v6, s[0:1], v4, v4, v5
	s_nop 0
	v_rcp_f32_e32 v4, v4
	s_nop 0
	v_mul_f32_e32 v4, v5, v4
	v_mul_f32_e32 v4, v26, v4
	v_cvt_pk_bf16_f32 v4, v4, s0
	ds_write_b16 v220, v4 offset:2112
	ds_read_u16 v4, v220 offset:2176
	ds_read_u16 v5, v220 offset:2240
	s_waitcnt lgkmcnt(1)
	v_lshlrev_b32_e32 v4, 16, v4
	v_mul_f32_e32 v6, 0xbfb8aa3b, v4
	v_exp_f32_e32 v6, v6
	s_waitcnt lgkmcnt(0)
	v_lshlrev_b32_e32 v5, 16, v5
	v_add_f32_e32 v6, 1.0, v6
	v_div_scale_f32 v7, s[0:1], v6, v6, v4
	s_nop 0
	v_rcp_f32_e32 v7, v6
	s_nop 0
	v_mul_f32_e32 v4, v4, v7
	v_mul_f32_e32 v4, v25, v4
	v_cvt_pk_bf16_f32 v4, v4, s0
	ds_write_b16 v220, v4 offset:2176
	v_mul_f32_e32 v4, 0xbfb8aa3b, v5
	v_exp_f32_e32 v4, v4
	s_nop 0
	v_add_f32_e32 v4, 1.0, v4
	v_div_scale_f32 v6, s[0:1], v4, v4, v5
	s_nop 0
	v_rcp_f32_e32 v4, v4
	s_nop 0
	v_mul_f32_e32 v4, v5, v4
	v_mul_f32_e32 v4, v24, v4
	v_cvt_pk_bf16_f32 v4, v4, s0
	ds_write_b16 v220, v4 offset:2240
	ds_read_u16 v4, v220 offset:2304
	ds_read_u16 v5, v220 offset:2368
	s_waitcnt lgkmcnt(1)
	v_lshlrev_b32_e32 v4, 16, v4
	v_mul_f32_e32 v6, 0xbfb8aa3b, v4
	v_exp_f32_e32 v6, v6
	s_waitcnt lgkmcnt(0)
	v_lshlrev_b32_e32 v5, 16, v5
	v_add_f32_e32 v6, 1.0, v6
	v_div_scale_f32 v7, s[0:1], v6, v6, v4
	s_nop 0
	v_rcp_f32_e32 v7, v6
	s_nop 0
	v_mul_f32_e32 v4, v4, v7
	v_mul_f32_e32 v4, v23, v4
	v_cvt_pk_bf16_f32 v4, v4, s0
	ds_write_b16 v220, v4 offset:2304
	v_mul_f32_e32 v4, 0xbfb8aa3b, v5
	v_exp_f32_e32 v4, v4
	s_nop 0
	v_add_f32_e32 v4, 1.0, v4
	v_div_scale_f32 v6, s[0:1], v4, v4, v5
	s_nop 0
	v_rcp_f32_e32 v4, v4
	s_nop 0
	v_mul_f32_e32 v4, v5, v4
	v_mul_f32_e32 v4, v22, v4
	v_cvt_pk_bf16_f32 v4, v4, s0
	ds_write_b16 v220, v4 offset:2368
	ds_read_u16 v4, v220 offset:2432
	ds_read_u16 v5, v220 offset:2496
	s_waitcnt lgkmcnt(1)
	v_lshlrev_b32_e32 v4, 16, v4
	v_mul_f32_e32 v6, 0xbfb8aa3b, v4
	v_exp_f32_e32 v6, v6
	s_waitcnt lgkmcnt(0)
	v_lshlrev_b32_e32 v5, 16, v5
	v_add_f32_e32 v6, 1.0, v6
	v_div_scale_f32 v7, s[0:1], v6, v6, v4
	s_nop 0
	v_rcp_f32_e32 v7, v6
	s_nop 0
	v_mul_f32_e32 v4, v4, v7
	v_mul_f32_e32 v4, v21, v4
	v_cvt_pk_bf16_f32 v4, v4, s0
	ds_write_b16 v220, v4 offset:2432
	v_mul_f32_e32 v4, 0xbfb8aa3b, v5
	v_exp_f32_e32 v4, v4
	s_nop 0
	v_add_f32_e32 v4, 1.0, v4
	v_div_scale_f32 v6, s[0:1], v4, v4, v5
	s_nop 0
	v_rcp_f32_e32 v4, v4
	s_nop 0
	v_mul_f32_e32 v4, v5, v4
	v_mul_f32_e32 v4, v15, v4
	v_cvt_pk_bf16_f32 v4, v4, s0
	ds_write_b16 v220, v4 offset:2496
	ds_read_u16 v4, v220 offset:3072
	ds_read_u16 v5, v220 offset:3136
	s_waitcnt lgkmcnt(1)
; #define LAS __attribute__((address_space(3)))
; #define LDS_WAIT() asm volatile("s_waitcnt lgkmcnt(0)" ::: "memory")
; DI unsigned cvtpk(float lo, float hi) { f32x2 v = {lo, hi}; bf16x2_t b = __builtin_convertvector(v, bf16x2_t); return __builtin_bit_cast(unsigned, b); }
; DI float bf2f(bf16 b) { return __uint_as_float(((unsigned)b) << 16); }
; DI float siluf_(float x) { return x / (1.f + __expf(-x)); }
; DI void nsa_unit(const Ctx& c0, int b, int g, int i, LAS unsigned char* lds) {
;     ...
;       for (int rg = 0; rg < 16; ++rg) { LAS bf16* e = (LAS bf16*)(S + ((rg & 3) + 8 * (rg >> 2) + 4 * hi) * 128 + r * 2);
;           const float z0 = bf2f(e[0]), z1 = bf2f(e[32]);
;           e[0] = (bf16)(cvtpk(ca0[rg] * siluf_(z0), 0.f) & 0xffffu);
;           e[32] = (bf16)(cvtpk(ca1[rg] * siluf_(z1), 0.f) & 0xffffu); }
;       LDS_WAIT();
; #pragma unroll
;       for (int it = 0; it < 4; ++it) { const int rw = 8 * it + (lane >> 3), ch = lane & 7;
;           *(u32x4*)(ong + (size_t)rw * 512 + ch * 8) = *(const LAS u32x4*)(S + rw * 128 + ch * 16); }
;       LDS_WAIT(); }
	v_lshlrev_b32_e32 v4, 16, v4
	v_mul_f32_e32 v6, 0xbfb8aa3b, v4
	v_exp_f32_e32 v6, v6
	s_waitcnt lgkmcnt(0)
	v_lshlrev_b32_e32 v5, 16, v5
	v_add_f32_e32 v6, 1.0, v6
	v_div_scale_f32 v7, s[0:1], v6, v6, v4
	s_nop 0
	v_rcp_f32_e32 v7, v6
	s_nop 0
	v_mul_f32_e32 v4, v4, v7
	v_mul_f32_e32 v4, v20, v4
	v_cvt_pk_bf16_f32 v4, v4, s0
	ds_write_b16 v220, v4 offset:3072
	v_mul_f32_e32 v4, 0xbfb8aa3b, v5
	v_exp_f32_e32 v4, v4
	s_nop 0
	v_add_f32_e32 v4, 1.0, v4
	v_div_scale_f32 v6, s[0:1], v4, v4, v5
	s_nop 0
	v_rcp_f32_e32 v4, v4
	s_nop 0
	v_mul_f32_e32 v4, v5, v4
	v_mul_f32_e32 v4, v14, v4
	v_cvt_pk_bf16_f32 v4, v4, s0
	ds_write_b16 v220, v4 offset:3136
	ds_read_u16 v4, v220 offset:3200
	ds_read_u16 v5, v220 offset:3264
	s_waitcnt lgkmcnt(1)
	v_lshlrev_b32_e32 v4, 16, v4
	v_mul_f32_e32 v6, 0xbfb8aa3b, v4
	v_exp_f32_e32 v6, v6
	s_waitcnt lgkmcnt(0)
	v_lshlrev_b32_e32 v5, 16, v5
	v_add_f32_e32 v6, 1.0, v6
	v_div_scale_f32 v7, s[0:1], v6, v6, v4
	s_nop 0
	v_rcp_f32_e32 v7, v6
	s_nop 0
	v_mul_f32_e32 v4, v4, v7
	v_mul_f32_e32 v4, v13, v4
	v_cvt_pk_bf16_f32 v4, v4, s0
	ds_write_b16 v220, v4 offset:3200
	v_mul_f32_e32 v4, 0xbfb8aa3b, v5
	v_exp_f32_e32 v4, v4
	s_nop 0
	v_add_f32_e32 v4, 1.0, v4
	v_div_scale_f32 v6, s[0:1], v4, v4, v5
	s_nop 0
	v_rcp_f32_e32 v4, v4
	s_nop 0
	v_mul_f32_e32 v4, v5, v4
	v_mul_f32_e32 v4, v12, v4
	v_cvt_pk_bf16_f32 v4, v4, s0
	ds_write_b16 v220, v4 offset:3264
	ds_read_u16 v4, v220 offset:3328
	ds_read_u16 v5, v220 offset:3392
	s_waitcnt lgkmcnt(1)
	v_lshlrev_b32_e32 v4, 16, v4
	v_mul_f32_e32 v6, 0xbfb8aa3b, v4
	v_exp_f32_e32 v6, v6
	s_waitcnt lgkmcnt(0)
	v_lshlrev_b32_e32 v5, 16, v5
	v_add_f32_e32 v6, 1.0, v6
	v_div_scale_f32 v7, s[0:1], v6, v6, v4
	s_nop 0
	v_rcp_f32_e32 v7, v6
	s_nop 0
	v_mul_f32_e32 v4, v4, v7
	v_mul_f32_e32 v4, v10, v4
	v_cvt_pk_bf16_f32 v4, v4, s0
	ds_write_b16 v220, v4 offset:3328
	v_mul_f32_e32 v4, 0xbfb8aa3b, v5
	v_exp_f32_e32 v4, v4
	s_nop 0
	v_add_f32_e32 v4, 1.0, v4
	v_div_scale_f32 v6, s[0:1], v4, v4, v5
	s_nop 0
	v_rcp_f32_e32 v4, v4
	s_nop 0
	v_mul_f32_e32 v4, v5, v4
	v_mul_f32_e32 v4, v11, v4
	v_cvt_pk_bf16_f32 v4, v4, s0
	ds_write_b16 v220, v4 offset:3392
	ds_read_u16 v4, v220 offset:3456
	ds_read_u16 v5, v220 offset:3520
	s_waitcnt lgkmcnt(1)
	v_lshlrev_b32_e32 v4, 16, v4
	v_mul_f32_e32 v6, 0xbfb8aa3b, v4
	v_exp_f32_e32 v6, v6
	s_waitcnt lgkmcnt(0)
	v_lshlrev_b32_e32 v5, 16, v5
	v_add_f32_e32 v6, 1.0, v6
	v_div_scale_f32 v7, s[0:1], v6, v6, v4
	s_nop 0
	v_rcp_f32_e32 v7, v6
	s_nop 0
	v_mul_f32_e32 v4, v4, v7
	v_mul_f32_e32 v2, v2, v4
	v_cvt_pk_bf16_f32 v2, v2, s0
	ds_write_b16 v220, v2 offset:3456
	v_mul_f32_e32 v2, 0xbfb8aa3b, v5
	v_exp_f32_e32 v2, v2
	s_nop 0
	v_add_f32_e32 v2, 1.0, v2
	v_div_scale_f32 v4, s[0:1], v2, v2, v5
	s_nop 0
	v_rcp_f32_e32 v2, v2
	s_nop 0
	v_mul_f32_e32 v2, v5, v2
	v_mul_f32_e32 v1, v1, v2
	v_cvt_pk_bf16_f32 v1, v1, s0
	ds_write_b16 v220, v1 offset:3520
	s_waitcnt lgkmcnt(0)
	ds_read_b128 v[4:7], v216
	s_mov_b64 s[0:1], 0xd500000
	v_lshl_add_u64 v[8:9], v[8:9], 0, s[0:1]
	v_lshl_add_u64 v[10:11], v[8:9], 0, v[126:127]
	s_waitcnt lgkmcnt(0)
	global_store_dwordx4 v[10:11], v[4:7], off
	ds_read_b128 v[4:7], v217
	v_lshl_add_u64 v[10:11], v[8:9], 0, v[128:129]
	s_waitcnt lgkmcnt(0)
	global_store_dwordx4 v[10:11], v[4:7], off
	ds_read_b128 v[4:7], v218
	v_lshl_add_u64 v[10:11], v[8:9], 0, v[130:131]
	v_lshl_add_u64 v[8:9], v[8:9], 0, v[132:133]
	s_waitcnt lgkmcnt(0)
	global_store_dwordx4 v[10:11], v[4:7], off
	ds_read_b128 v[4:7], v219
	s_waitcnt lgkmcnt(0)
	global_store_dwordx4 v[8:9], v[4:7], off
	s_waitcnt lgkmcnt(0)
	s_cbranch_scc1 .LBB0_538

; #define LAS __attribute__((address_space(3)))
; DI float bf2f(bf16 b) { return __uint_as_float(((unsigned)b) << 16); }
; DI float sigmoidf_(float x) { return 1.f / (1.f + __expf(-x)); }
; DI void branch_fold(ASt& st, float gate, bool may_be_empty, LAS float* wsf, int lane) {
;     const int r = lane & 31, hi = lane >> 5;
;     const float lt = st.l + __shfl_xor(st.l, 32);
;     float inv = 1.f / lt; if (may_be_empty && !(st.m > -1e29f)) inv = 0.f;
;     if (hi == 0) { wsf[r] = inv * gate; wsf[32 + r] = inv; }
; DI void nsa_unit(const Ctx& c0, int b, int g, int i, LAS unsigned char* lds) {
;     ...
;     const float g_c = sigmoidf_(bf2f(misc[row * 64 + head * 3 + 0])), g_s = sigmoidf_(bf2f(misc[row * 64 + head * 3 + 1])), g_w = sigmoidf_(bf2f(misc[row * 64 + head * 3 + 2]));
.LBB0_557:
	ds_bpermute_b32 v68, v135, v84
	s_waitcnt vmcnt(0)
	v_add_u32_e32 v118, 0x8000, v204
	s_and_saveexec_b64 s[12:13], s[4:5]
	s_cbranch_execz .LBB0_559
	v_lshlrev_b32_e32 v69, 16, v142
	v_mul_f32_e32 v69, 0xbfb8aa3b, v69
	v_exp_f32_e32 v69, v69
	s_waitcnt lgkmcnt(0)
	v_add_f32_e32 v68, v84, v68
	v_add_f32_e32 v69, 1.0, v69
	v_div_scale_f32 v70, s[14:15], v69, v69, 1.0
	s_mov_b32 s3, 0xefa18f08
	v_rcp_f32_e32 v69, v69
	v_div_scale_f32 v70, vcc, 1.0, v68, 1.0
	v_rcp_f32_e32 v68, v68
	v_cmp_lt_f32_e32 vcc, s3, v141
	s_nop 1
	v_cndmask_b32_e32 v68, 0, v68, vcc
	v_mul_f32_e32 v69, v69, v68
	ds_write2_b32 v118, v69, v68 offset1:32

; DI void nsa_unit(const Ctx& c0, int b, int g, int i, LAS unsigned char* lds) {
;     ...
;             for (int qq = 8 * wid; qq < 8 * wid + 8; ++qq) {
;                 const int n = lane;
;                 const float v = ((IMP[(0 * 64 + qq) * 64 + n] + IMP[(1 * 64 + qq) * 64 + n]) + IMP[(2 * 64 + qq) * 64 + n]) + IMP[(3 * 64 + qq) * 64 + n];
;                 unsigned key = (__float_as_uint(fmaxf(v, 0.f)) & ~63u) | (unsigned)(63 - n);
;                 if (n == 0 || n == i || n == i - 1) key = 0xFFFFFFFFu;
;                 if (n > i) key = 0u;
;                 unsigned thr = 0u;
;     ...
;                     const int cnt = __builtin_popcountll(__builtin_amdgcn_ballot_w64(key >= cand)); if (cnt >= 16) thr = cand; }
;                 const unsigned long long sm = __builtin_amdgcn_ballot_w64(key >= thr) & validm;
;                 if (lane == 0) SEL[qq] = sm;
.LBB0_562:
	v_add_u32_e32 v5, 0, v4
	ds_read2st64_b32 v[6:7], v5 offset0:144 offset1:208
	s_waitcnt lgkmcnt(0)
	v_add_f32_e32 v6, v6, v7
	v_add_u32_e32 v7, 0x11000, v5
	ds_read_b32 v7, v7
	v_add_u32_e32 v5, 0x15000, v5
	ds_read_b32 v5, v5
	s_waitcnt lgkmcnt(1)
	v_add_f32_e32 v6, v6, v7
	s_waitcnt lgkmcnt(0)
	v_add_f32_e32 v5, v6, v5
	v_max_f32_e32 v5, 0, v5
	v_and_b32_e32 v5, 0xffffffc0, v5
	v_bitop3_b32 v5, v5, 63, v150 bitop3:0x36
	v_cndmask_b32_e64 v5, v5, -1, s[80:81]
	v_cndmask_b32_e64 v5, v5, 0, vcc
	v_cmp_gt_i32_e64 s[78:79], 0, v5
	s_bcnt1_i32_b64 s84, s[78:79]
	s_cmp_gt_u32 s84, 15
	s_cselect_b32 s83, 0x80000000, 0
	s_or_b32 s88, s83, 2.0
	v_cmp_le_u32_e64 s[78:79], s88, v5
	s_bcnt1_i32_b64 s84, s[78:79]
	s_cmp_gt_u32 s84, 15
	s_cselect_b32 s83, s88, s83
	s_or_b32 s88, s83, 0x20000000
	v_cmp_le_u32_e64 s[78:79], s88, v5
	s_bcnt1_i32_b64 s84, s[78:79]
	s_cmp_gt_u32 s84, 15
	s_cselect_b32 s83, s88, s83
	s_or_b32 s88, s83, 0x10000000
	v_cmp_le_u32_e64 s[78:79], s88, v5
	s_bcnt1_i32_b64 s84, s[78:79]
	s_cmp_gt_u32 s84, 15
	s_cselect_b32 s83, s88, s83
	s_or_b32 s88, s83, 0x8000000
	v_cmp_le_u32_e64 s[78:79], s88, v5
	s_bcnt1_i32_b64 s84, s[78:79]
	s_cmp_gt_u32 s84, 15
	s_cselect_b32 s83, s88, s83
	s_or_b32 s88, s83, 0x4000000
	v_cmp_le_u32_e64 s[78:79], s88, v5
	s_bcnt1_i32_b64 s84, s[78:79]
	s_cmp_gt_u32 s84, 15
	s_cselect_b32 s83, s88, s83
	s_or_b32 s88, s83, 0x2000000
	v_cmp_le_u32_e64 s[78:79], s88, v5
	s_bcnt1_i32_b64 s84, s[78:79]
	s_cmp_gt_u32 s84, 15
	s_cselect_b32 s83, s88, s83
	s_or_b32 s88, s83, 0x1000000
	v_cmp_le_u32_e64 s[78:79], s88, v5
	s_bcnt1_i32_b64 s84, s[78:79]
	s_cmp_gt_u32 s84, 15
	s_cselect_b32 s83, s88, s83
	s_or_b32 s88, s83, 0x800000
	v_cmp_le_u32_e64 s[78:79], s88, v5
	s_bcnt1_i32_b64 s84, s[78:79]
	s_cmp_gt_u32 s84, 15
	s_cselect_b32 s83, s88, s83
	s_or_b32 s88, s83, 0x400000
	v_cmp_le_u32_e64 s[78:79], s88, v5
	s_bcnt1_i32_b64 s84, s[78:79]
	s_cmp_gt_u32 s84, 15
	s_cselect_b32 s83, s88, s83
	s_or_b32 s88, s83, 0x200000
	v_cmp_le_u32_e64 s[78:79], s88, v5
	s_bcnt1_i32_b64 s84, s[78:79]
	s_cmp_gt_u32 s84, 15
	s_cselect_b32 s83, s88, s83
	s_or_b32 s88, s83, 0x100000
	v_cmp_le_u32_e64 s[78:79], s88, v5
	s_bcnt1_i32_b64 s84, s[78:79]
	s_cmp_gt_u32 s84, 15
	s_cselect_b32 s83, s88, s83
	s_or_b32 s88, s83, 0x80000
	v_cmp_le_u32_e64 s[78:79], s88, v5
	s_bcnt1_i32_b64 s84, s[78:79]
	s_cmp_gt_u32 s84, 15
	s_cselect_b32 s83, s88, s83
	s_or_b32 s88, s83, 0x40000
	v_cmp_le_u32_e64 s[78:79], s88, v5
	s_bcnt1_i32_b64 s84, s[78:79]
	s_cmp_gt_u32 s84, 15
	s_cselect_b32 s83, s88, s83
	s_or_b32 s88, s83, 0x20000
	v_cmp_le_u32_e64 s[78:79], s88, v5
	s_bcnt1_i32_b64 s84, s[78:79]
	s_cmp_gt_u32 s84, 15
	s_cselect_b32 s83, s88, s83
	s_or_b32 s88, s83, 0x10000
	v_cmp_le_u32_e64 s[78:79], s88, v5
	s_bcnt1_i32_b64 s84, s[78:79]
	s_cmp_gt_u32 s84, 15
	s_cselect_b32 s83, s88, s83
	s_or_b32 s88, s83, 0x8000
	v_cmp_le_u32_e64 s[78:79], s88, v5
	s_bcnt1_i32_b64 s84, s[78:79]
	s_cmp_gt_u32 s84, 15
	s_cselect_b32 s83, s88, s83
	s_or_b32 s88, s83, 0x4000
	v_cmp_le_u32_e64 s[78:79], s88, v5
	s_bcnt1_i32_b64 s84, s[78:79]
	s_cmp_gt_u32 s84, 15
	s_cselect_b32 s83, s88, s83
	s_or_b32 s88, s83, 0x2000
	v_cmp_le_u32_e64 s[78:79], s88, v5
	s_bcnt1_i32_b64 s84, s[78:79]
	s_cmp_gt_u32 s84, 15
	s_cselect_b32 s83, s88, s83
	s_or_b32 s88, s83, 0x1000
	v_cmp_le_u32_e64 s[78:79], s88, v5
	s_bcnt1_i32_b64 s84, s[78:79]
	s_cmp_gt_u32 s84, 15
	s_cselect_b32 s83, s88, s83
	s_or_b32 s88, s83, 0x800
	v_cmp_le_u32_e64 s[78:79], s88, v5
	s_bcnt1_i32_b64 s84, s[78:79]
	s_cmp_gt_u32 s84, 15
	s_cselect_b32 s83, s88, s83
	s_or_b32 s88, s83, 0x400
	v_cmp_le_u32_e64 s[78:79], s88, v5
	s_bcnt1_i32_b64 s84, s[78:79]
	s_cmp_gt_u32 s84, 15
	s_cselect_b32 s83, s88, s83
	s_or_b32 s88, s83, 0x200
	v_cmp_le_u32_e64 s[78:79], s88, v5
	s_bcnt1_i32_b64 s84, s[78:79]
	s_cmp_gt_u32 s84, 15
	s_cselect_b32 s83, s88, s83
	s_or_b32 s88, s83, 0x100
	v_cmp_le_u32_e64 s[78:79], s88, v5
	s_bcnt1_i32_b64 s84, s[78:79]
	s_cmp_gt_u32 s84, 15
	s_cselect_b32 s83, s88, s83
	s_or_b32 s88, s83, 0x80
	v_cmp_le_u32_e64 s[78:79], s88, v5
	s_bcnt1_i32_b64 s84, s[78:79]
	s_cmp_gt_u32 s84, 15
	s_cselect_b32 s83, s88, s83
	s_or_b32 s88, s83, 64
	v_cmp_le_u32_e64 s[78:79], s88, v5
	s_bcnt1_i32_b64 s84, s[78:79]
	s_cmp_gt_u32 s84, 15
	s_cselect_b32 s83, s88, s83
	s_or_b32 s88, s83, 32
	v_cmp_le_u32_e64 s[78:79], s88, v5
	s_bcnt1_i32_b64 s84, s[78:79]
	s_cmp_gt_u32 s84, 15
	s_cselect_b32 s83, s88, s83
	s_or_b32 s88, s83, 16
	v_cmp_le_u32_e64 s[78:79], s88, v5
	s_bcnt1_i32_b64 s84, s[78:79]
	s_cmp_gt_u32 s84, 15
	s_cselect_b32 s83, s88, s83
	s_or_b32 s88, s83, 8
	v_cmp_le_u32_e64 s[78:79], s88, v5
	s_bcnt1_i32_b64 s84, s[78:79]
	s_cmp_gt_u32 s84, 15
	s_cselect_b32 s83, s88, s83
	s_or_b32 s88, s83, 4
	v_cmp_le_u32_e64 s[78:79], s88, v5
	s_bcnt1_i32_b64 s84, s[78:79]
	s_cmp_gt_u32 s84, 15
	s_cselect_b32 s83, s88, s83
	s_or_b32 s88, s83, 2
	v_cmp_le_u32_e64 s[78:79], s88, v5
	s_bcnt1_i32_b64 s84, s[78:79]
	s_cmp_gt_u32 s84, 15
	s_cselect_b32 s83, s88, s83
	s_or_b32 s88, s83, 1
	v_cmp_le_u32_e64 s[78:79], s88, v5
	s_bcnt1_i32_b64 s84, s[78:79]
	s_cmp_gt_u32 s84, 15
	s_cselect_b32 s14, s88, s83
	v_cmp_le_u32_e64 s[78:79], s14, v5
	s_and_saveexec_b64 s[14:15], s[6:7]
	s_cbranch_execz .LBB0_561
	s_and_b64 s[78:79], s[78:79], s[12:13]
	s_add_i32 s83, s82, 0
	v_mov_b32_e32 v5, s83
	v_mov_b64_e32 v[6:7], s[78:79]
	ds_write_b64 v5, v[6:7]
	s_branch .LBB0_561

; #define LAS __attribute__((address_space(3)))
; DI float bf2f(bf16 b) { return __uint_as_float(((unsigned)b) << 16); }
; DI float sigmoidf_(float x) { return 1.f / (1.f + __expf(-x)); }
; DI void branch_fold(ASt& st, float gate, bool may_be_empty, LAS float* wsf, int lane) {
;     const int r = lane & 31, hi = lane >> 5;
;     const float lt = st.l + __shfl_xor(st.l, 32);
;     float inv = 1.f / lt; if (may_be_empty && !(st.m > -1e29f)) inv = 0.f;
;     if (hi == 0) { wsf[r] = inv * gate; wsf[32 + r] = inv; }
; DI void nsa_unit(const Ctx& c0, int b, int g, int i, LAS unsigned char* lds) {
;     ...
;     const float g_c = sigmoidf_(bf2f(misc[row * 64 + head * 3 + 0])), g_s = sigmoidf_(bf2f(misc[row * 64 + head * 3 + 1])), g_w = sigmoidf_(bf2f(misc[row * 64 + head * 3 + 2]));
.LBB0_575:
	s_or_b64 exec, exec, s[12:13]
	ds_bpermute_b32 v2, v135, v11
	s_and_saveexec_b64 s[12:13], s[4:5]
	s_cbranch_execz .LBB0_577
	v_and_b32_e32 v4, 0xffff0000, v142
	v_mul_f32_e32 v4, 0xbfb8aa3b, v4
	v_exp_f32_e32 v4, v4
	s_waitcnt lgkmcnt(0)
	v_add_f32_e32 v2, v11, v2
	v_add_f32_e32 v4, 1.0, v4
	v_div_scale_f32 v5, s[14:15], v4, v4, 1.0
	v_rcp_f32_e32 v4, v4
	v_rcp_f32_e32 v2, v2
	s_nop 0
	v_mul_f32_e32 v4, v4, v2
	ds_write2_b32 v118, v4, v2 offset1:32

; #define LAS __attribute__((address_space(3)))
; DI float bf2f(bf16 b) { return __uint_as_float(((unsigned)b) << 16); }
; DI float sigmoidf_(float x) { return 1.f / (1.f + __expf(-x)); }
; DI void branch_fold(ASt& st, float gate, bool may_be_empty, LAS float* wsf, int lane) {
;     const int r = lane & 31, hi = lane >> 5;
;     const float lt = st.l + __shfl_xor(st.l, 32);
;     float inv = 1.f / lt; if (may_be_empty && !(st.m > -1e29f)) inv = 0.f;
;     if (hi == 0) { wsf[r] = inv * gate; wsf[32 + r] = inv; }
; DI void nsa_unit(const Ctx& c0, int b, int g, int i, LAS unsigned char* lds) {
;     ...
;     const float g_c = sigmoidf_(bf2f(misc[row * 64 + head * 3 + 0])), g_s = sigmoidf_(bf2f(misc[row * 64 + head * 3 + 1])), g_w = sigmoidf_(bf2f(misc[row * 64 + head * 3 + 2]));
.LBB0_599:
	ds_bpermute_b32 v2, v135, v40
	s_and_saveexec_b64 s[12:13], s[4:5]
	s_cbranch_execz .LBB0_540
	v_lshlrev_b32_e32 v1, 16, v1
	v_mul_f32_e32 v1, 0xbfb8aa3b, v1
	v_exp_f32_e32 v1, v1
	s_waitcnt lgkmcnt(0)
	v_add_f32_e32 v2, v40, v2
	v_add_f32_e32 v1, 1.0, v1
	v_div_scale_f32 v36, s[14:15], v1, v1, 1.0
	v_rcp_f32_e32 v1, v1
	v_rcp_f32_e32 v2, v2
	s_nop 0
	v_mul_f32_e32 v1, v1, v2
	ds_write2_b32 v118, v1, v2 offset1:32
	s_branch .LBB0_540

; #define MFMA32(a, b, c) __builtin_amdgcn_mfma_f32_32x32x16_bf16((a), (b), (c), 0, 0, 0)
; DI void gla_stage3(const Ctx& c0, int layer, int unit, int cb, LAS unsigned char* lds) {
;     ...
;     const bf16* qgp = (const bf16*)(c.ws + O_QG) + (row0 + r) * 256 + h * 64 + 8 * hi;
;     const float* sp = (const float*)(c.ws + O_UPD) + (size_t)unit * 8192;
;     const float* gn = c.a->in[I_GNORM] + (size_t)layer * 128;
;     bf16x8 qf[4];
; #pragma unroll
;     for (int s = 0; s < 4; ++s) qf[s] = *(const bf16x8*)(qgp + 16 * s);
;     f32x16 o[4];
; #pragma unroll
;     for (int vb = 0; vb < 4; ++vb) {
;         o[vb] = f32x16{};
; #pragma unroll
;         for (int s = 0; s < 4; ++s) { const float* s0 = sp + (size_t)(16 * s + 8 * hi) * 128 + 32 * vb + r;
;             const bf16x8 bfv = pack8(s0[0], s0[128], s0[256], s0[384], s0[512], s0[640], s0[768], s0[896]);
;             o[vb] = MFMA32(qf[s], bfv, o[vb]); }
.LBB0_604:
	s_mov_b64 s[2:3], s[84:85]
	s_mov_b64 s[0:1], s[86:87]
	s_ashr_i32 s2, s35, 8
	s_ashr_i32 s3, s2, 31
	s_lshl_b64 s[2:3], s[2:3], 12
	s_and_b32 s5, s8, 0xfc0
	s_or_b32 s2, s2, s5
	s_or_b64 s[2:3], s[2:3], s[6:7]
	v_mov_b32_e32 v3, s3
	v_or_b32_e32 v2, s2, v152
	s_bfe_u32 s4, s35, 0x20006
	v_lshlrev_b64 v[2:3], 9, v[2:3]
	v_lshl_add_u64 v[2:3], s[0:1], 0, v[2:3]
	s_lshl_b32 s10, s4, 7
	v_lshl_add_u64 v[2:3], v[2:3], 0, s[10:11]
	v_lshl_add_u64 v[2:3], v[2:3], 0, v[86:87]
	v_lshl_add_u64 v[4:5], v[2:3], 0, s[16:17]
	v_add_co_u32_e32 v2, vcc, s13, v2
	v_lshl_add_u64 v[90:91], s[0:1], 0, v[84:85]
	s_nop 0
	v_addc_co_u32_e32 v3, vcc, 0, v3, vcc
	global_load_dwordx4 v[50:53], v[2:3], off
	global_load_dwordx4 v[110:113], v[4:5], off offset:96
	global_load_dwordx4 v[106:109], v[4:5], off offset:64
	global_load_dwordx4 v[102:105], v[4:5], off offset:32
	v_add_co_u32_e32 v2, vcc, s24, v90
	s_lshl_b64 s[2:3], s[2:3], 10
	s_nop 0
	v_addc_co_u32_e32 v3, vcc, -1, v91, vcc
	v_add_co_u32_e32 v58, vcc, s28, v90
	global_load_dword v2, v[2:3], off
	s_nop 0
	v_addc_co_u32_e32 v59, vcc, -1, v91, vcc
	global_load_dword v3, v[58:59], off offset:384
	global_load_dword v4, v[58:59], off offset:896
	global_load_dword v5, v[58:59], off offset:1408
	global_load_dword v6, v[58:59], off offset:1920
	global_load_dword v7, v[58:59], off offset:2432
	global_load_dword v8, v[58:59], off offset:2944
	global_load_dword v9, v[58:59], off offset:3456
	v_add_co_u32_e32 v18, vcc, s25, v90
	s_lshl_b32 s4, s4, 8
	s_nop 0
	v_addc_co_u32_e32 v19, vcc, -1, v91, vcc
	v_add_co_u32_e32 v114, vcc, s29, v90
	global_load_dword v18, v[18:19], off
	s_nop 0
	v_addc_co_u32_e32 v115, vcc, -1, v91, vcc
	global_load_dword v19, v[114:115], off offset:384
	global_load_dword v20, v[114:115], off offset:896
	global_load_dword v21, v[114:115], off offset:1408
	global_load_dword v22, v[114:115], off offset:1920
	global_load_dword v23, v[114:115], off offset:2432
	global_load_dword v24, v[114:115], off offset:2944
	global_load_dword v25, v[114:115], off offset:3456
	s_add_u32 s0, s0, s2
	s_addc_u32 s1, s1, s3
	s_add_u32 s0, s0, s4
	s_addc_u32 s1, s1, 0
	s_add_i32 s35, s35, s12
	s_add_i32 s8, s8, s9
	v_lshl_add_u64 v[84:85], v[84:85], 0, s[14:15]
	s_cmpk_lt_i32 s35, 0x800
	s_waitcnt vmcnt(0) lgkmcnt(0)
	global_load_dword v41, v[114:115], off offset:3584
	global_load_dword v40, v[114:115], off offset:3072
	global_load_dword v39, v[114:115], off offset:2560
	global_load_dword v38, v[114:115], off offset:2048
	global_load_dword v37, v[114:115], off offset:1536
	global_load_dword v36, v[114:115], off offset:1024
	global_load_dword v35, v[114:115], off offset:512
	global_load_dword v34, v[114:115], off
	global_load_dword v145, v[58:59], off offset:3584
	global_load_dword v146, v[58:59], off offset:3072
	global_load_dword v143, v[58:59], off offset:2560
	global_load_dword v144, v[58:59], off offset:2048
	global_load_dword v141, v[58:59], off offset:1536
	global_load_dword v142, v[58:59], off offset:1024
	global_load_dword v139, v[58:59], off offset:512
	global_load_dword v140, v[58:59], off
	v_cvt_pk_bf16_f32 v2, v2, v3
	v_cvt_pk_bf16_f32 v3, v4, v5
	v_cvt_pk_bf16_f32 v4, v6, v7
	v_cvt_pk_bf16_f32 v5, v8, v9
	v_cvt_pk_bf16_f32 v18, v18, v19
	s_nop 0
	v_mfma_f32_32x32x16_bf16 v[2:17], v[50:53], v[2:5], 0
	v_cvt_pk_bf16_f32 v19, v20, v21
	v_cvt_pk_bf16_f32 v20, v22, v23
	v_cvt_pk_bf16_f32 v21, v24, v25
	s_nop 1
	v_mfma_f32_32x32x16_bf16 v[2:17], v[102:105], v[18:21], v[2:17]
	v_add_co_u32_e32 v18, vcc, s26, v90
	s_nop 1
	v_addc_co_u32_e32 v19, vcc, -1, v91, vcc
	v_add_co_u32_e32 v118, vcc, s30, v90
	global_load_dword v18, v[18:19], off
	s_nop 0
	v_addc_co_u32_e32 v119, vcc, -1, v91, vcc
	global_load_dword v19, v[118:119], off offset:384
	global_load_dword v20, v[118:119], off offset:896
	global_load_dword v21, v[118:119], off offset:1408
	global_load_dword v22, v[118:119], off offset:1920
	global_load_dword v23, v[118:119], off offset:2432
	global_load_dword v24, v[118:119], off offset:2944
	global_load_dword v25, v[118:119], off offset:3456
	s_waitcnt vmcnt(0) lgkmcnt(0)
	global_load_dword v63, v[114:115], off offset:3712
	global_load_dword v62, v[114:115], off offset:3200
	global_load_dword v61, v[114:115], off offset:2688
	global_load_dword v60, v[114:115], off offset:2176
	global_load_dword v57, v[114:115], off offset:1664
	global_load_dword v56, v[114:115], off offset:1152
	global_load_dword v55, v[114:115], off offset:640
	global_load_dword v54, v[114:115], off offset:128
	global_load_dword v173, v[58:59], off offset:3712
	global_load_dword v176, v[58:59], off offset:3200
	global_load_dword v171, v[58:59], off offset:2688
	global_load_dword v174, v[58:59], off offset:2176
	global_load_dword v169, v[58:59], off offset:1664
	global_load_dword v172, v[58:59], off offset:1152
	global_load_dword v167, v[58:59], off offset:640
	global_load_dword v170, v[58:59], off offset:128
	global_load_dword v157, v[118:119], off offset:3584
	global_load_dword v160, v[118:119], off offset:3072
	global_load_dword v155, v[118:119], off offset:2560
	global_load_dword v158, v[118:119], off offset:2048
	global_load_dword v149, v[118:119], off offset:1536
	global_load_dword v156, v[118:119], off offset:1024
	global_load_dword v147, v[118:119], off offset:512
	global_load_dword v148, v[118:119], off
	v_cvt_pk_bf16_f32 v18, v18, v19
	v_cvt_pk_bf16_f32 v19, v20, v21
	v_cvt_pk_bf16_f32 v20, v22, v23
	v_cvt_pk_bf16_f32 v21, v24, v25
	s_nop 1
	v_mfma_f32_32x32x16_bf16 v[2:17], v[106:109], v[18:21], v[2:17]
	v_add_co_u32_e32 v18, vcc, s27, v90
	s_nop 1
	v_addc_co_u32_e32 v19, vcc, -1, v91, vcc
	v_add_co_u32_e32 v120, vcc, s31, v90
	global_load_dword v18, v[18:19], off
	s_nop 0
	v_addc_co_u32_e32 v121, vcc, -1, v91, vcc
	global_load_dword v19, v[120:121], off offset:384
	global_load_dword v20, v[120:121], off offset:896
	global_load_dword v21, v[120:121], off offset:1408
	global_load_dword v22, v[120:121], off offset:1920
	global_load_dword v23, v[120:121], off offset:2432
	global_load_dword v24, v[120:121], off offset:2944
	global_load_dword v25, v[120:121], off offset:3456
	v_cmp_lt_i32_e32 vcc, v94, v95
	s_waitcnt vmcnt(0) lgkmcnt(0)
; #define MFMA32(a, b, c) __builtin_amdgcn_mfma_f32_32x32x16_bf16((a), (b), (c), 0, 0, 0)
; DI void gla_stage3(const Ctx& c0, int layer, int unit, int cb, LAS unsigned char* lds) {
;     ...
;     for (int s = 0; s < 4; ++s) qf[s] = *(const bf16x8*)(qgp + 16 * s);
;     f32x16 o[4];
; #pragma unroll
;     for (int vb = 0; vb < 4; ++vb) {
;         o[vb] = f32x16{};
; #pragma unroll
;         for (int s = 0; s < 4; ++s) { const float* s0 = sp + (size_t)(16 * s + 8 * hi) * 128 + 32 * vb + r;
;             const bf16x8 bfv = pack8(s0[0], s0[128], s0[256], s0[384], s0[512], s0[640], s0[768], s0[896]);
;             o[vb] = MFMA32(qf[s], bfv, o[vb]); }
;     ...
;     for (int vb = 0; vb < 4; ++vb) { const float g = gn[32 * vb + r];
	global_load_dword v127, v[114:115], off offset:3840
	global_load_dword v126, v[114:115], off offset:3328
	global_load_dword v125, v[114:115], off offset:2816
	global_load_dword v124, v[114:115], off offset:2304
	global_load_dword v123, v[114:115], off offset:1792
	global_load_dword v122, v[114:115], off offset:1280
	global_load_dword v117, v[114:115], off offset:768
	global_load_dword v116, v[114:115], off offset:256
	global_load_dword v214, v[58:59], off offset:3840
	global_load_dword v212, v[58:59], off offset:3328
	global_load_dword v205, v[58:59], off offset:2816
	global_load_dword v210, v[58:59], off offset:2304
	global_load_dword v203, v[58:59], off offset:1792
	global_load_dword v208, v[58:59], off offset:1280
	global_load_dword v201, v[58:59], off offset:768
	global_load_dword v206, v[58:59], off offset:256
	global_load_dword v199, v[120:121], off offset:3712
	global_load_dword v204, v[120:121], off offset:3200
	global_load_dword v197, v[120:121], off offset:2688
	global_load_dword v202, v[120:121], off offset:2176
	global_load_dword v195, v[120:121], off offset:1664
	global_load_dword v200, v[120:121], off offset:1152
	global_load_dword v183, v[120:121], off offset:640
	global_load_dword v198, v[120:121], off offset:128
	global_load_dword v181, v[118:119], off offset:3712
	global_load_dword v196, v[118:119], off offset:3200
	global_load_dword v179, v[118:119], off offset:2688
	global_load_dword v182, v[118:119], off offset:2176
	global_load_dword v177, v[118:119], off offset:1664
	global_load_dword v180, v[118:119], off offset:1152
	global_load_dword v175, v[118:119], off offset:640
	global_load_dword v178, v[118:119], off offset:128
	global_load_dword v165, v[120:121], off offset:3584
	global_load_dword v168, v[120:121], off offset:3072
	global_load_dword v163, v[120:121], off offset:2560
	global_load_dword v166, v[120:121], off offset:2048
	global_load_dword v161, v[120:121], off offset:1536
	global_load_dword v164, v[120:121], off offset:1024
	global_load_dword v159, v[120:121], off offset:512
	global_load_dword v162, v[120:121], off
	v_cvt_pk_bf16_f32 v18, v18, v19
	v_cvt_pk_bf16_f32 v19, v20, v21
	v_cvt_pk_bf16_f32 v20, v22, v23
	v_cvt_pk_bf16_f32 v21, v24, v25
	s_nop 1
	v_mfma_f32_32x32x16_bf16 v[2:17], v[110:113], v[18:21], v[2:17]
	s_waitcnt vmcnt(40) lgkmcnt(0)
	global_load_dword v238, v[82:83], off offset:384
	global_load_dword v236, v[82:83], off offset:256
	global_load_dword v234, v[82:83], off offset:128
	global_load_dword v232, v[82:83], off
	global_load_dword v90, v[90:91], off
	global_load_dword v230, v[120:121], off offset:3328
	global_load_dword v219, v[120:121], off offset:2816
	global_load_dword v228, v[120:121], off offset:2304
	global_load_dword v217, v[120:121], off offset:1792
	global_load_dword v226, v[120:121], off offset:1280
	global_load_dword v215, v[120:121], off offset:768
	global_load_dword v224, v[120:121], off offset:256
	global_load_dword v213, v[118:119], off offset:3840
	global_load_dword v222, v[118:119], off offset:3328
	global_load_dword v211, v[118:119], off offset:2816
	global_load_dword v220, v[118:119], off offset:2304
	global_load_dword v209, v[118:119], off offset:1792
	global_load_dword v218, v[118:119], off offset:1280
	global_load_dword v207, v[118:119], off offset:768
	global_load_dword v216, v[118:119], off offset:256
	v_cvt_pk_bf16_f32 v18, v140, v139
	v_cvt_pk_bf16_f32 v34, v34, v35
	v_cvt_pk_bf16_f32 v19, v142, v141
	v_cvt_pk_bf16_f32 v35, v36, v37
	v_cvt_pk_bf16_f32 v20, v144, v143
	v_cvt_pk_bf16_f32 v36, v38, v39
	v_cvt_pk_bf16_f32 v21, v146, v145
	v_cvt_pk_bf16_f32 v37, v40, v41
	s_nop 0
	v_mfma_f32_32x32x16_bf16 v[18:33], v[50:53], v[18:21], 0
	v_mfma_f32_32x32x16_bf16 v[18:33], v[102:105], v[34:37], v[18:33]
	s_waitcnt vmcnt(60) lgkmcnt(0)
	v_cvt_pk_bf16_f32 v34, v148, v147
	v_cvt_pk_bf16_f32 v35, v156, v149
	v_cvt_pk_bf16_f32 v36, v158, v155
	v_cvt_pk_bf16_f32 v37, v160, v157
	s_nop 1
	v_mfma_f32_32x32x16_bf16 v[18:33], v[106:109], v[34:37], v[18:33]
	s_waitcnt vmcnt(20) lgkmcnt(0)
	v_cvt_pk_bf16_f32 v34, v162, v159
	v_cvt_pk_bf16_f32 v35, v164, v161
	v_cvt_pk_bf16_f32 v36, v166, v163
	v_cvt_pk_bf16_f32 v37, v168, v165
	s_nop 1
	v_mfma_f32_32x32x16_bf16 v[18:33], v[110:113], v[34:37], v[18:33]
	s_waitcnt vmcnt(62) lgkmcnt(0)
	v_cvt_pk_bf16_f32 v34, v170, v167
	v_cvt_pk_bf16_f32 v54, v54, v55
	v_cvt_pk_bf16_f32 v35, v172, v169
	v_cvt_pk_bf16_f32 v55, v56, v57
	v_cvt_pk_bf16_f32 v36, v174, v171
	v_cvt_pk_bf16_f32 v56, v60, v61
	v_cvt_pk_bf16_f32 v37, v176, v173
	v_cvt_pk_bf16_f32 v57, v62, v63
	s_nop 0
	v_mfma_f32_32x32x16_bf16 v[34:49], v[50:53], v[34:37], 0
	v_mfma_f32_32x32x16_bf16 v[34:49], v[102:105], v[54:57], v[34:49]
	s_waitcnt vmcnt(28) lgkmcnt(0)
	v_cvt_pk_bf16_f32 v54, v178, v175
	v_cvt_pk_bf16_f32 v55, v180, v177
	v_cvt_pk_bf16_f32 v56, v182, v179
	v_cvt_pk_bf16_f32 v57, v196, v181
	s_nop 1
	v_mfma_f32_32x32x16_bf16 v[34:49], v[106:109], v[54:57], v[34:49]
	s_waitcnt vmcnt(36) lgkmcnt(0)
	v_cvt_pk_bf16_f32 v54, v198, v183
	v_cvt_pk_bf16_f32 v55, v200, v195
	v_cvt_pk_bf16_f32 v56, v202, v197
	v_cvt_pk_bf16_f32 v57, v204, v199
	s_nop 1
	v_mfma_f32_32x32x16_bf16 v[34:49], v[110:113], v[54:57], v[34:49]
	s_nop 0
	s_nop 0
	s_waitcnt vmcnt(44) lgkmcnt(0)
	v_cvt_pk_bf16_f32 v54, v206, v201
	v_cvt_pk_bf16_f32 v114, v116, v117
	v_cvt_pk_bf16_f32 v55, v208, v203
	v_cvt_pk_bf16_f32 v115, v122, v123
	v_cvt_pk_bf16_f32 v56, v210, v205
	v_cvt_pk_bf16_f32 v116, v124, v125
	v_cvt_pk_bf16_f32 v57, v212, v214
	v_cvt_pk_bf16_f32 v117, v126, v127
	s_nop 0
	v_mfma_f32_32x32x16_bf16 v[50:65], v[50:53], v[54:57], 0
	v_mfma_f32_32x32x16_bf16 v[50:65], v[102:105], v[114:117], v[50:65]
	s_waitcnt vmcnt(0) lgkmcnt(0)
; #define LAS __attribute__((address_space(3)))
; #define LDS_WAIT() asm volatile("s_waitcnt lgkmcnt(0)" ::: "memory")
; DI float bf2f(bf16 b) { return __uint_as_float(((unsigned)b) << 16); }
; DI void g3_tile_in(const bf16* g, LAS unsigned char* R, int lane) {
; #pragma unroll
;     for (int it = 0; it < 8; ++it) { const int row = 4 * it + (lane >> 4), ch = lane & 15;
;         *(LAS u32x4*)(R + row * G3_PITCH + ch * 16) = *(const u32x4*)(g + (size_t)row * 512 + ch * 8); }
;     LDS_WAIT();
; }
; DI void gla_stage3(const Ctx& c0, int layer, int unit, int cb, LAS unsigned char* lds) {
;     ...
;     g3_tile_in((const bf16*)(c.ws + O_OINTRA) + row0 * 512 + h * 128, R, lane);
; #pragma unroll
;     for (int vb = 0; vb < 4; ++vb) {
; #pragma unroll
;         for (int rg = 0; rg < 16; ++rg) o[vb][rg] += bf2f(*(const LAS bf16*)(Re + ((rg & 3) + 8 * (rg >> 2)) * G3_PITCH + 64 * vb));
;         asm volatile("" ::: "memory");
;     }
;     ...
;     g3_tile_in((const bf16*)(c.ws + O_GR) + row0 * 512 + h * 128, R, lane);
	v_cvt_pk_bf16_f32 v102, v216, v207
	v_cvt_pk_bf16_f32 v103, v218, v209
	v_cvt_pk_bf16_f32 v104, v220, v211
	v_cvt_pk_bf16_f32 v105, v222, v213
	s_nop 1
	v_mfma_f32_32x32x16_bf16 v[50:65], v[106:109], v[102:105], v[50:65]
	s_nop 0
	s_waitcnt vmcnt(8) lgkmcnt(0)
	v_cvt_pk_bf16_f32 v102, v224, v215
	v_cvt_pk_bf16_f32 v103, v226, v217
	v_cvt_pk_bf16_f32 v104, v228, v219
	v_cvt_pk_bf16_f32 v105, v230, v90
	v_lshl_add_u64 v[90:91], s[0:1], 0, v[88:89]
	v_lshl_add_u64 v[106:107], v[90:91], 0, s[18:19]
	v_mfma_f32_32x32x16_bf16 v[50:65], v[110:113], v[102:105], v[50:65]
	v_lshl_add_u64 v[102:103], v[106:107], 0, v[66:67]
	global_load_dwordx4 v[102:105], v[102:103], off
	s_waitcnt vmcnt(0) lgkmcnt(0)
	v_lshl_add_u64 v[168:169], v[90:91], 0, s[20:21]
	v_lshl_add_u64 v[140:141], v[168:169], 0, v[70:71]
	global_load_dwordx4 v[174:177], v[140:141], off
	v_lshl_add_u64 v[140:141], v[106:107], 0, v[70:71]
	global_load_dwordx4 v[146:149], v[140:141], off
	v_lshl_add_u64 v[144:145], v[106:107], 0, v[68:69]
	global_load_dwordx4 v[140:143], v[144:145], off
	ds_write_b128 v92, v[102:105]
	s_waitcnt vmcnt(0) lgkmcnt(0)
	v_lshl_add_u64 v[144:145], v[168:169], 0, v[76:77]
	global_load_dwordx4 v[200:203], v[144:145], off
	v_lshl_add_u64 v[144:145], v[168:169], 0, v[74:75]
	global_load_dwordx4 v[196:199], v[144:145], off
	v_lshl_add_u64 v[144:145], v[168:169], 0, v[72:73]
	global_load_dwordx4 v[178:181], v[144:145], off
	v_lshl_add_u64 v[144:145], v[106:107], 0, v[74:75]
	global_load_dwordx4 v[156:159], v[144:145], off
	v_lshl_add_u64 v[102:103], v[106:107], 0, v[72:73]
	global_load_dwordx4 v[102:105], v[102:103], off
	ds_write_b128 v92, v[140:143] offset:1088
	s_waitcnt vmcnt(5) lgkmcnt(0)
	v_lshl_add_u64 v[140:141], v[168:169], 0, v[78:79]
	global_load_dwordx4 v[204:207], v[140:141], off
	v_lshl_add_u64 v[140:141], v[106:107], 0, v[78:79]
	global_load_dwordx4 v[160:163], v[140:141], off
	v_lshl_add_u64 v[144:145], v[106:107], 0, v[76:77]
	global_load_dwordx4 v[140:143], v[144:145], off
	ds_write_b128 v92, v[146:149] offset:2176
	s_waitcnt vmcnt(3) lgkmcnt(0)
	v_lshl_add_u64 v[144:145], v[168:169], 0, v[66:67]
	global_load_dwordx4 v[164:167], v[144:145], off
	v_lshl_add_u64 v[148:149], v[106:107], 0, v[80:81]
	global_load_dwordx4 v[144:147], v[148:149], off
	ds_write_b128 v92, v[102:105] offset:3264
	s_waitcnt vmcnt(6) lgkmcnt(0)
	v_lshl_add_u64 v[148:149], v[168:169], 0, v[68:69]
	global_load_dwordx4 v[170:173], v[148:149], off
	ds_write_b128 v92, v[156:159] offset:4352
	s_waitcnt vmcnt(3) lgkmcnt(0)
	ds_write_b128 v92, v[140:143] offset:5440
	s_waitcnt vmcnt(4) lgkmcnt(0)
	ds_write_b128 v92, v[160:163] offset:6528
	s_waitcnt vmcnt(1) lgkmcnt(0)
	ds_write_b128 v92, v[144:147] offset:7616
	s_waitcnt lgkmcnt(0)
	ds_read_u16 v102, v1
	s_waitcnt lgkmcnt(0)
	v_lshlrev_b32_e32 v102, 16, v102
	v_add_f32_e32 v138, v2, v102
	ds_read_u16 v2, v1 offset:272
	s_waitcnt lgkmcnt(0)
	v_lshlrev_b32_e32 v2, 16, v2
	v_add_f32_e32 v137, v3, v2
	ds_read_u16 v2, v1 offset:544
	s_waitcnt lgkmcnt(0)
	v_lshlrev_b32_e32 v2, 16, v2
	v_add_f32_e32 v136, v4, v2
	ds_read_u16 v2, v1 offset:816
	s_waitcnt lgkmcnt(0)
	v_lshlrev_b32_e32 v2, 16, v2
	v_add_f32_e32 v135, v5, v2
	ds_read_u16 v2, v1 offset:2176
	s_waitcnt lgkmcnt(0)
	v_lshlrev_b32_e32 v2, 16, v2
	v_add_f32_e32 v134, v6, v2
	ds_read_u16 v2, v1 offset:2448
	s_waitcnt lgkmcnt(0)
	v_lshlrev_b32_e32 v2, 16, v2
	v_add_f32_e32 v133, v7, v2
	ds_read_u16 v2, v1 offset:2720
	s_waitcnt lgkmcnt(0)
	v_lshlrev_b32_e32 v2, 16, v2
	v_add_f32_e32 v132, v8, v2
	ds_read_u16 v2, v1 offset:2992
	s_waitcnt lgkmcnt(0)
	v_lshlrev_b32_e32 v2, 16, v2
	v_add_f32_e32 v131, v9, v2
	ds_read_u16 v2, v1 offset:4352
	s_waitcnt lgkmcnt(0)
	v_lshlrev_b32_e32 v2, 16, v2
	v_add_f32_e32 v130, v10, v2
	ds_read_u16 v2, v1 offset:4624
	s_waitcnt lgkmcnt(0)
	v_lshlrev_b32_e32 v2, 16, v2
	v_add_f32_e32 v129, v11, v2
	ds_read_u16 v2, v1 offset:4896
	s_waitcnt lgkmcnt(0)
	v_lshlrev_b32_e32 v2, 16, v2
	v_add_f32_e32 v128, v12, v2
	ds_read_u16 v2, v1 offset:5168
	s_waitcnt lgkmcnt(0)
	v_lshlrev_b32_e32 v2, 16, v2
	v_add_f32_e32 v127, v13, v2
	ds_read_u16 v2, v1 offset:6528
	s_waitcnt lgkmcnt(0)
	v_lshlrev_b32_e32 v2, 16, v2
	v_add_f32_e32 v126, v14, v2
	ds_read_u16 v2, v1 offset:6800
	s_waitcnt lgkmcnt(0)
	v_lshlrev_b32_e32 v2, 16, v2
	v_add_f32_e32 v125, v15, v2
	ds_read_u16 v2, v1 offset:7072
	s_waitcnt lgkmcnt(0)
	v_lshlrev_b32_e32 v2, 16, v2
	v_add_f32_e32 v124, v16, v2
	ds_read_u16 v2, v1 offset:7344
	s_waitcnt lgkmcnt(0)
	v_lshlrev_b32_e32 v2, 16, v2
	v_add_f32_e32 v123, v17, v2
	ds_read_u16 v2, v1 offset:64
	s_waitcnt lgkmcnt(0)
	v_lshlrev_b32_e32 v2, 16, v2
	v_add_f32_e32 v122, v18, v2
	ds_read_u16 v2, v1 offset:336
	s_waitcnt lgkmcnt(0)
	v_lshlrev_b32_e32 v2, 16, v2
	v_add_f32_e32 v121, v19, v2
	ds_read_u16 v2, v1 offset:608
	s_waitcnt lgkmcnt(0)
	v_lshlrev_b32_e32 v2, 16, v2
	v_add_f32_e32 v120, v20, v2
	ds_read_u16 v2, v1 offset:880
	s_waitcnt lgkmcnt(0)
	v_lshlrev_b32_e32 v2, 16, v2
	v_add_f32_e32 v119, v21, v2
	ds_read_u16 v2, v1 offset:2240
	s_waitcnt lgkmcnt(0)
	v_lshlrev_b32_e32 v2, 16, v2
	v_add_f32_e32 v118, v22, v2
	ds_read_u16 v2, v1 offset:2512
	s_waitcnt lgkmcnt(0)
	v_lshlrev_b32_e32 v2, 16, v2
	v_add_f32_e32 v117, v23, v2
	ds_read_u16 v2, v1 offset:2784
	s_waitcnt lgkmcnt(0)
	v_lshlrev_b32_e32 v2, 16, v2
	v_add_f32_e32 v116, v24, v2
	ds_read_u16 v2, v1 offset:3056
	s_waitcnt lgkmcnt(0)
	v_lshlrev_b32_e32 v2, 16, v2
	v_add_f32_e32 v115, v25, v2
	ds_read_u16 v2, v1 offset:4416
	s_waitcnt lgkmcnt(0)
	v_lshlrev_b32_e32 v2, 16, v2
	v_add_f32_e32 v114, v26, v2
	ds_read_u16 v2, v1 offset:4688
	s_waitcnt lgkmcnt(0)
; #define LAS __attribute__((address_space(3)))
; DI float bf2f(bf16 b) { return __uint_as_float(((unsigned)b) << 16); }
; DI void gla_stage3(const Ctx& c0, int layer, int unit, int cb, LAS unsigned char* lds) {
;     ...
;         for (int rg = 0; rg < 16; ++rg) o[vb][rg] += bf2f(*(const LAS bf16*)(Re + ((rg & 3) + 8 * (rg >> 2)) * G3_PITCH + 64 * vb));
;         asm volatile("" ::: "memory");
;     }
;     float rs[16];
; #pragma unroll
;     for (int rg = 0; rg < 16; ++rg) { float ss = o[0][rg] * o[0][rg] + o[1][rg] * o[1][rg] + o[2][rg] * o[2][rg] + o[3][rg] * o[3][rg];
;         ss += __shfl_xor(ss, 1); ss += __shfl_xor(ss, 2); ss += __shfl_xor(ss, 4); ss += __shfl_xor(ss, 8); ss += __shfl_xor(ss, 16);
;         rs[rg] = 1.f / sqrtf(ss * (1.f / 128.f) + EPS); }
	v_lshlrev_b32_e32 v2, 16, v2
	v_add_f32_e32 v113, v27, v2
	ds_read_u16 v2, v1 offset:4960
	s_waitcnt lgkmcnt(0)
	v_lshlrev_b32_e32 v2, 16, v2
	v_add_f32_e32 v112, v28, v2
	ds_read_u16 v2, v1 offset:5232
	s_waitcnt lgkmcnt(0)
	v_lshlrev_b32_e32 v2, 16, v2
	v_add_f32_e32 v111, v29, v2
	ds_read_u16 v2, v1 offset:6592
	s_waitcnt lgkmcnt(0)
	v_lshlrev_b32_e32 v2, 16, v2
	v_add_f32_e32 v110, v30, v2
	ds_read_u16 v2, v1 offset:6864
	s_waitcnt lgkmcnt(0)
	v_lshlrev_b32_e32 v2, 16, v2
	v_add_f32_e32 v109, v31, v2
	ds_read_u16 v2, v1 offset:7136
	s_waitcnt lgkmcnt(0)
	v_lshlrev_b32_e32 v2, 16, v2
	v_add_f32_e32 v108, v32, v2
	ds_read_u16 v2, v1 offset:7408
	s_waitcnt lgkmcnt(0)
	v_lshlrev_b32_e32 v2, 16, v2
	v_add_f32_e32 v107, v33, v2
	ds_read_u16 v2, v1 offset:128
	s_waitcnt lgkmcnt(0)
	v_lshlrev_b32_e32 v2, 16, v2
	v_add_f32_e32 v106, v34, v2
	ds_read_u16 v2, v1 offset:400
	s_waitcnt lgkmcnt(0)
	v_lshlrev_b32_e32 v2, 16, v2
	v_add_f32_e32 v105, v35, v2
	ds_read_u16 v2, v1 offset:672
	s_waitcnt lgkmcnt(0)
	v_lshlrev_b32_e32 v2, 16, v2
	v_add_f32_e32 v104, v36, v2
	ds_read_u16 v2, v1 offset:944
	s_waitcnt lgkmcnt(0)
	v_lshlrev_b32_e32 v2, 16, v2
	v_add_f32_e32 v103, v37, v2
	ds_read_u16 v2, v1 offset:2304
	s_waitcnt lgkmcnt(0)
	v_lshlrev_b32_e32 v2, 16, v2
	v_add_f32_e32 v102, v38, v2
	ds_read_u16 v2, v1 offset:2576
	s_waitcnt lgkmcnt(0)
	v_lshlrev_b32_e32 v2, 16, v2
	v_add_f32_e32 v39, v39, v2
	ds_read_u16 v2, v1 offset:2848
	s_waitcnt lgkmcnt(0)
	v_lshlrev_b32_e32 v2, 16, v2
	v_add_f32_e32 v38, v40, v2
	ds_read_u16 v2, v1 offset:3120
	s_waitcnt lgkmcnt(0)
	v_lshlrev_b32_e32 v2, 16, v2
	v_add_f32_e32 v37, v41, v2
	ds_read_u16 v2, v1 offset:4480
	s_waitcnt lgkmcnt(0)
	v_lshlrev_b32_e32 v2, 16, v2
	v_add_f32_e32 v36, v42, v2
	ds_read_u16 v2, v1 offset:4752
	s_waitcnt lgkmcnt(0)
	v_lshlrev_b32_e32 v2, 16, v2
	v_add_f32_e32 v34, v43, v2
	ds_read_u16 v2, v1 offset:5024
	s_waitcnt lgkmcnt(0)
	v_lshlrev_b32_e32 v2, 16, v2
	v_add_f32_e32 v33, v44, v2
	ds_read_u16 v2, v1 offset:5296
	s_waitcnt lgkmcnt(0)
	v_lshlrev_b32_e32 v2, 16, v2
	v_add_f32_e32 v32, v45, v2
	ds_read_u16 v2, v1 offset:6656
	s_waitcnt lgkmcnt(0)
	v_lshlrev_b32_e32 v2, 16, v2
	v_add_f32_e32 v30, v46, v2
	ds_read_u16 v2, v1 offset:6928
	s_waitcnt lgkmcnt(0)
	v_lshlrev_b32_e32 v2, 16, v2
	v_add_f32_e32 v29, v47, v2
	ds_read_u16 v2, v1 offset:7200
	s_waitcnt lgkmcnt(0)
	v_lshlrev_b32_e32 v2, 16, v2
	v_add_f32_e32 v28, v48, v2
	ds_read_u16 v2, v1 offset:7472
	s_waitcnt lgkmcnt(0)
	v_lshlrev_b32_e32 v2, 16, v2
	v_add_f32_e32 v26, v49, v2
	ds_read_u16 v2, v1 offset:192
	s_waitcnt lgkmcnt(0)
	v_lshlrev_b32_e32 v2, 16, v2
	v_add_f32_e32 v19, v50, v2
	ds_read_u16 v2, v1 offset:464
	s_waitcnt lgkmcnt(0)
	v_lshlrev_b32_e32 v2, 16, v2
	v_add_f32_e32 v18, v51, v2
	ds_read_u16 v2, v1 offset:736
	s_waitcnt lgkmcnt(0)
	v_lshlrev_b32_e32 v2, 16, v2
	v_add_f32_e32 v17, v52, v2
	ds_read_u16 v2, v1 offset:1008
	s_waitcnt lgkmcnt(0)
	v_lshlrev_b32_e32 v2, 16, v2
	v_add_f32_e32 v16, v53, v2
	ds_read_u16 v2, v1 offset:2368
	s_waitcnt lgkmcnt(0)
	v_lshlrev_b32_e32 v2, 16, v2
	v_add_f32_e32 v15, v54, v2
	ds_read_u16 v2, v1 offset:2640
	s_waitcnt lgkmcnt(0)
	v_lshlrev_b32_e32 v2, 16, v2
	v_add_f32_e32 v14, v55, v2
	ds_read_u16 v2, v1 offset:2912
	s_waitcnt lgkmcnt(0)
	v_lshlrev_b32_e32 v2, 16, v2
	v_add_f32_e32 v13, v56, v2
	ds_read_u16 v2, v1 offset:3184
	s_waitcnt lgkmcnt(0)
	v_lshlrev_b32_e32 v2, 16, v2
	v_add_f32_e32 v12, v57, v2
	ds_read_u16 v2, v1 offset:4544
	s_waitcnt lgkmcnt(0)
	v_lshlrev_b32_e32 v2, 16, v2
	v_add_f32_e32 v11, v58, v2
	ds_read_u16 v2, v1 offset:4816
	s_waitcnt lgkmcnt(0)
	v_lshlrev_b32_e32 v2, 16, v2
	v_add_f32_e32 v10, v59, v2
	ds_read_u16 v2, v1 offset:5088
	s_waitcnt lgkmcnt(0)
	v_lshlrev_b32_e32 v2, 16, v2
	v_add_f32_e32 v9, v60, v2
	ds_read_u16 v2, v1 offset:5360
	s_waitcnt lgkmcnt(0)
	v_lshlrev_b32_e32 v2, 16, v2
	v_add_f32_e32 v8, v61, v2
	ds_read_u16 v2, v1 offset:6720
	s_waitcnt lgkmcnt(0)
	v_lshlrev_b32_e32 v2, 16, v2
	v_add_f32_e32 v7, v62, v2
	ds_read_u16 v2, v1 offset:6992
	s_waitcnt lgkmcnt(0)
	v_lshlrev_b32_e32 v2, 16, v2
	v_add_f32_e32 v6, v63, v2
	ds_read_u16 v2, v1 offset:7264
	s_waitcnt lgkmcnt(0)
	v_lshlrev_b32_e32 v2, 16, v2
	v_add_f32_e32 v5, v64, v2
	ds_read_u16 v2, v1 offset:7536
	s_waitcnt lgkmcnt(0)
	s_waitcnt lgkmcnt(0)
	v_lshlrev_b32_e32 v2, 16, v2
	v_add_f32_e32 v4, v65, v2
	v_cndmask_b32_e32 v2, v93, v94, vcc
	v_cmp_lt_i32_e32 vcc, v96, v95
	v_lshlrev_b32_e32 v2, 2, v2
	s_nop 0
	v_cndmask_b32_e32 v3, v93, v96, vcc
	v_cmp_lt_i32_e32 vcc, v97, v95
	v_lshlrev_b32_e32 v3, 2, v3
	s_nop 0
	v_cndmask_b32_e32 v20, v93, v97, vcc
	v_cmp_lt_i32_e32 vcc, v98, v95
	v_lshlrev_b32_e32 v20, 2, v20
	s_nop 0
	v_cndmask_b32_e32 v21, v93, v98, vcc
	v_cmp_lt_i32_e32 vcc, v99, v95
	v_lshlrev_b32_e32 v47, 2, v21
	s_nop 0
	v_cndmask_b32_e32 v21, v93, v99, vcc
	v_lshlrev_b32_e32 v48, 2, v21
	v_mul_f32_e32 v21, v122, v122
	v_fmac_f32_e32 v21, v138, v138
	v_fmac_f32_e32 v21, v106, v106
	v_fmac_f32_e32 v21, v19, v19
	ds_bpermute_b32 v22, v2, v21
	s_waitcnt lgkmcnt(0)
	v_add_f32_e32 v21, v21, v22
	ds_bpermute_b32 v22, v3, v21
	s_waitcnt lgkmcnt(0)
	v_add_f32_e32 v21, v21, v22
	ds_bpermute_b32 v22, v20, v21
	s_waitcnt lgkmcnt(0)
	v_add_f32_e32 v21, v21, v22
	ds_bpermute_b32 v22, v47, v21
	s_waitcnt lgkmcnt(0)
	v_add_f32_e32 v21, v21, v22
	ds_bpermute_b32 v22, v48, v21
	s_waitcnt lgkmcnt(0)
; DI void gla_stage3(const Ctx& c0, int layer, int unit, int cb, LAS unsigned char* lds) {
;     ...
;     for (int rg = 0; rg < 16; ++rg) { float ss = o[0][rg] * o[0][rg] + o[1][rg] * o[1][rg] + o[2][rg] * o[2][rg] + o[3][rg] * o[3][rg];
;         ss += __shfl_xor(ss, 1); ss += __shfl_xor(ss, 2); ss += __shfl_xor(ss, 4); ss += __shfl_xor(ss, 8); ss += __shfl_xor(ss, 16);
;         rs[rg] = 1.f / sqrtf(ss * (1.f / 128.f) + EPS); }
	v_add_f32_e32 v21, v21, v22
	v_fmamk_f32 v21, v21, 0x3c000000, v100
	v_cmp_gt_f32_e32 vcc, s34, v21
	v_mul_f32_e32 v22, 0x4f800000, v21
	s_nop 0
	v_cndmask_b32_e32 v21, v21, v22, vcc
	v_sqrt_f32_e32 v22, v21
	s_nop 0
	v_add_u32_e32 v23, -1, v22
	v_fma_f32 v24, -v23, v22, v21
	v_cmp_ge_f32_e64 s[4:5], 0, v24
	v_add_u32_e32 v24, 1, v22
	s_nop 0
	v_cndmask_b32_e64 v23, v22, v23, s[4:5]
	v_fma_f32 v22, -v24, v22, v21
	v_cmp_lt_f32_e64 s[4:5], 0, v22
	s_nop 1
	v_cndmask_b32_e64 v22, v23, v24, s[4:5]
	v_mul_f32_e32 v23, 0x37800000, v22
	v_cndmask_b32_e32 v22, v22, v23, vcc
	v_cmp_class_f32_e32 vcc, v21, v101
	s_nop 1
	v_cndmask_b32_e32 v21, v22, v21, vcc
	s_nop 0
	v_div_scale_f32 v24, vcc, 1.0, v21, 1.0
	v_rcp_f32_e32 v46, v21
	v_mul_f32_e32 v21, v121, v121
	v_fmac_f32_e32 v21, v137, v137
	v_fmac_f32_e32 v21, v105, v105
	v_fmac_f32_e32 v21, v18, v18
	ds_bpermute_b32 v22, v2, v21
	v_mul_f32_e32 v19, v19, v46
	s_waitcnt lgkmcnt(0)
	v_add_f32_e32 v21, v21, v22
	ds_bpermute_b32 v22, v3, v21
	s_waitcnt lgkmcnt(0)
	v_add_f32_e32 v21, v21, v22
	ds_bpermute_b32 v22, v20, v21
	s_waitcnt lgkmcnt(0)
	v_add_f32_e32 v21, v21, v22
	ds_bpermute_b32 v22, v47, v21
	s_waitcnt lgkmcnt(0)
	v_add_f32_e32 v21, v21, v22
	ds_bpermute_b32 v22, v48, v21
	s_waitcnt lgkmcnt(0)
	v_add_f32_e32 v21, v21, v22
	v_fmamk_f32 v21, v21, 0x3c000000, v100
	v_cmp_gt_f32_e32 vcc, s34, v21
	v_mul_f32_e32 v22, 0x4f800000, v21
	s_nop 0
	v_cndmask_b32_e32 v21, v21, v22, vcc
	v_sqrt_f32_e32 v22, v21
	s_nop 0
	v_add_u32_e32 v23, -1, v22
	v_fma_f32 v24, -v23, v22, v21
	v_cmp_ge_f32_e64 s[4:5], 0, v24
	v_add_u32_e32 v24, 1, v22
	s_nop 0
	v_cndmask_b32_e64 v23, v22, v23, s[4:5]
	v_fma_f32 v22, -v24, v22, v21
	v_cmp_lt_f32_e64 s[4:5], 0, v22
	s_nop 1
	v_cndmask_b32_e64 v22, v23, v24, s[4:5]
	v_mul_f32_e32 v23, 0x37800000, v22
	v_cndmask_b32_e32 v22, v22, v23, vcc
	v_cmp_class_f32_e32 vcc, v21, v101
	s_nop 1
	v_cndmask_b32_e32 v21, v22, v21, vcc
	s_nop 0
	v_div_scale_f32 v24, vcc, 1.0, v21, 1.0
	v_rcp_f32_e32 v45, v21
	v_mul_f32_e32 v21, v120, v120
	v_fmac_f32_e32 v21, v136, v136
	v_fmac_f32_e32 v21, v104, v104
	v_fmac_f32_e32 v21, v17, v17
	ds_bpermute_b32 v22, v2, v21
	v_mul_f32_e32 v18, v18, v45
	s_waitcnt lgkmcnt(0)
	v_add_f32_e32 v21, v21, v22
	ds_bpermute_b32 v22, v3, v21
	s_waitcnt lgkmcnt(0)
	v_add_f32_e32 v21, v21, v22
	ds_bpermute_b32 v22, v20, v21
	s_waitcnt lgkmcnt(0)
	v_add_f32_e32 v21, v21, v22
	ds_bpermute_b32 v22, v47, v21
	s_waitcnt lgkmcnt(0)
	v_add_f32_e32 v21, v21, v22
	ds_bpermute_b32 v22, v48, v21
	s_waitcnt lgkmcnt(0)
	v_add_f32_e32 v21, v21, v22
	v_fmamk_f32 v21, v21, 0x3c000000, v100
	v_cmp_gt_f32_e32 vcc, s34, v21
	v_mul_f32_e32 v22, 0x4f800000, v21
	s_nop 0
	v_cndmask_b32_e32 v21, v21, v22, vcc
	v_sqrt_f32_e32 v22, v21
	s_nop 0
	v_add_u32_e32 v23, -1, v22
	v_fma_f32 v24, -v23, v22, v21
	v_cmp_ge_f32_e64 s[4:5], 0, v24
	v_add_u32_e32 v24, 1, v22
	s_nop 0
	v_cndmask_b32_e64 v23, v22, v23, s[4:5]
	v_fma_f32 v22, -v24, v22, v21
	v_cmp_lt_f32_e64 s[4:5], 0, v22
	s_nop 1
	v_cndmask_b32_e64 v22, v23, v24, s[4:5]
	v_mul_f32_e32 v23, 0x37800000, v22
	v_cndmask_b32_e32 v22, v22, v23, vcc
	v_cmp_class_f32_e32 vcc, v21, v101
	s_nop 1
	v_cndmask_b32_e32 v21, v22, v21, vcc
	s_nop 0
	v_div_scale_f32 v24, vcc, 1.0, v21, 1.0
	v_rcp_f32_e32 v44, v21
	v_mul_f32_e32 v21, v119, v119
	v_fmac_f32_e32 v21, v135, v135
	v_fmac_f32_e32 v21, v103, v103
	v_fmac_f32_e32 v21, v16, v16
	ds_bpermute_b32 v22, v2, v21
	v_mul_f32_e32 v17, v17, v44
	s_waitcnt lgkmcnt(0)
	v_add_f32_e32 v21, v21, v22
	ds_bpermute_b32 v22, v3, v21
	s_waitcnt lgkmcnt(0)
	v_add_f32_e32 v21, v21, v22
	ds_bpermute_b32 v22, v20, v21
	s_waitcnt lgkmcnt(0)
	v_add_f32_e32 v21, v21, v22
	ds_bpermute_b32 v22, v47, v21
	s_waitcnt lgkmcnt(0)
	v_add_f32_e32 v21, v21, v22
	ds_bpermute_b32 v22, v48, v21
	s_waitcnt lgkmcnt(0)
	v_add_f32_e32 v21, v21, v22
	v_fmamk_f32 v21, v21, 0x3c000000, v100
	v_cmp_gt_f32_e32 vcc, s34, v21
	v_mul_f32_e32 v22, 0x4f800000, v21
	s_nop 0
	v_cndmask_b32_e32 v21, v21, v22, vcc
	v_sqrt_f32_e32 v22, v21
	s_nop 0
	v_add_u32_e32 v23, -1, v22
	v_fma_f32 v24, -v23, v22, v21
	v_cmp_ge_f32_e64 s[4:5], 0, v24
	v_add_u32_e32 v24, 1, v22
	s_nop 0
	v_cndmask_b32_e64 v23, v22, v23, s[4:5]
	v_fma_f32 v22, -v24, v22, v21
	v_cmp_lt_f32_e64 s[4:5], 0, v22
	s_nop 1
	v_cndmask_b32_e64 v22, v23, v24, s[4:5]
	v_mul_f32_e32 v23, 0x37800000, v22
	v_cndmask_b32_e32 v22, v22, v23, vcc
	v_cmp_class_f32_e32 vcc, v21, v101
	s_nop 1
	v_cndmask_b32_e32 v21, v22, v21, vcc
	s_nop 0
	v_div_scale_f32 v24, vcc, 1.0, v21, 1.0
	v_rcp_f32_e32 v43, v21
	v_mul_f32_e32 v21, v118, v118
	v_fmac_f32_e32 v21, v134, v134
	v_fmac_f32_e32 v21, v102, v102
	v_fmac_f32_e32 v21, v15, v15
	ds_bpermute_b32 v22, v2, v21
	v_mul_f32_e32 v16, v16, v43
	s_waitcnt lgkmcnt(0)
	v_add_f32_e32 v21, v21, v22
	ds_bpermute_b32 v22, v3, v21
	s_waitcnt lgkmcnt(0)
	v_add_f32_e32 v21, v21, v22
	ds_bpermute_b32 v22, v20, v21
	s_waitcnt lgkmcnt(0)
	v_add_f32_e32 v21, v21, v22
	ds_bpermute_b32 v22, v47, v21
	s_waitcnt lgkmcnt(0)
	v_add_f32_e32 v21, v21, v22
	ds_bpermute_b32 v22, v48, v21
	s_waitcnt lgkmcnt(0)
	v_add_f32_e32 v21, v21, v22
	v_fmamk_f32 v21, v21, 0x3c000000, v100
	v_cmp_gt_f32_e32 vcc, s34, v21
	v_mul_f32_e32 v22, 0x4f800000, v21
	s_nop 0
	v_cndmask_b32_e32 v21, v21, v22, vcc
	v_sqrt_f32_e32 v22, v21
	s_nop 0
	v_add_u32_e32 v23, -1, v22
	v_fma_f32 v24, -v23, v22, v21
	v_cmp_ge_f32_e64 s[4:5], 0, v24
	v_add_u32_e32 v24, 1, v22
	s_nop 0
	v_cndmask_b32_e64 v23, v22, v23, s[4:5]
	v_fma_f32 v22, -v24, v22, v21
	v_cmp_lt_f32_e64 s[4:5], 0, v22
	s_nop 1
	v_cndmask_b32_e64 v22, v23, v24, s[4:5]
	v_mul_f32_e32 v23, 0x37800000, v22
	v_cndmask_b32_e32 v22, v22, v23, vcc
	v_cmp_class_f32_e32 vcc, v21, v101
	s_nop 1
	v_cndmask_b32_e32 v21, v22, v21, vcc
	s_nop 0
	v_div_scale_f32 v24, vcc, 1.0, v21, 1.0
	v_rcp_f32_e32 v42, v21
	v_mul_f32_e32 v21, v117, v117
	v_fmac_f32_e32 v21, v133, v133
	v_fmac_f32_e32 v21, v39, v39
	v_fmac_f32_e32 v21, v14, v14
	ds_bpermute_b32 v22, v2, v21
	v_mul_f32_e32 v15, v15, v42
	s_waitcnt lgkmcnt(0)
; DI void gla_stage3(const Ctx& c0, int layer, int unit, int cb, LAS unsigned char* lds) {
;     ...
;     for (int rg = 0; rg < 16; ++rg) { float ss = o[0][rg] * o[0][rg] + o[1][rg] * o[1][rg] + o[2][rg] * o[2][rg] + o[3][rg] * o[3][rg];
;         ss += __shfl_xor(ss, 1); ss += __shfl_xor(ss, 2); ss += __shfl_xor(ss, 4); ss += __shfl_xor(ss, 8); ss += __shfl_xor(ss, 16);
;         rs[rg] = 1.f / sqrtf(ss * (1.f / 128.f) + EPS); }
	v_add_f32_e32 v21, v21, v22
	ds_bpermute_b32 v22, v3, v21
	s_waitcnt lgkmcnt(0)
	v_add_f32_e32 v21, v21, v22
	ds_bpermute_b32 v22, v20, v21
	s_waitcnt lgkmcnt(0)
	v_add_f32_e32 v21, v21, v22
	ds_bpermute_b32 v22, v47, v21
	s_waitcnt lgkmcnt(0)
	v_add_f32_e32 v21, v21, v22
	ds_bpermute_b32 v22, v48, v21
	s_waitcnt lgkmcnt(0)
	v_add_f32_e32 v21, v21, v22
	v_fmamk_f32 v21, v21, 0x3c000000, v100
	v_cmp_gt_f32_e32 vcc, s34, v21
	v_mul_f32_e32 v22, 0x4f800000, v21
	s_nop 0
	v_cndmask_b32_e32 v21, v21, v22, vcc
	v_sqrt_f32_e32 v22, v21
	s_nop 0
	v_add_u32_e32 v23, -1, v22
	v_fma_f32 v24, -v23, v22, v21
	v_cmp_ge_f32_e64 s[4:5], 0, v24
	v_add_u32_e32 v24, 1, v22
	s_nop 0
	v_cndmask_b32_e64 v23, v22, v23, s[4:5]
	v_fma_f32 v22, -v24, v22, v21
	v_cmp_lt_f32_e64 s[4:5], 0, v22
	s_nop 1
	v_cndmask_b32_e64 v22, v23, v24, s[4:5]
	v_mul_f32_e32 v23, 0x37800000, v22
	v_cndmask_b32_e32 v22, v22, v23, vcc
	v_cmp_class_f32_e32 vcc, v21, v101
	s_nop 1
	v_cndmask_b32_e32 v21, v22, v21, vcc
	s_nop 0
	v_div_scale_f32 v24, vcc, 1.0, v21, 1.0
	v_rcp_f32_e32 v41, v21
	v_mul_f32_e32 v21, v116, v116
	v_fmac_f32_e32 v21, v132, v132
	v_fmac_f32_e32 v21, v38, v38
	v_fmac_f32_e32 v21, v13, v13
	ds_bpermute_b32 v22, v2, v21
	v_mul_f32_e32 v39, v39, v41
	v_mul_f32_e32 v14, v14, v41
	s_waitcnt lgkmcnt(0)
	v_add_f32_e32 v21, v21, v22
	ds_bpermute_b32 v22, v3, v21
	s_waitcnt lgkmcnt(0)
	v_add_f32_e32 v21, v21, v22
	ds_bpermute_b32 v22, v20, v21
	s_waitcnt lgkmcnt(0)
	v_add_f32_e32 v21, v21, v22
	ds_bpermute_b32 v22, v47, v21
	s_waitcnt lgkmcnt(0)
	v_add_f32_e32 v21, v21, v22
	ds_bpermute_b32 v22, v48, v21
	s_waitcnt lgkmcnt(0)
	v_add_f32_e32 v21, v21, v22
	v_fmamk_f32 v21, v21, 0x3c000000, v100
	v_cmp_gt_f32_e32 vcc, s34, v21
	v_mul_f32_e32 v22, 0x4f800000, v21
	s_nop 0
	v_cndmask_b32_e32 v21, v21, v22, vcc
	v_sqrt_f32_e32 v22, v21
	s_nop 0
	v_add_u32_e32 v23, -1, v22
	v_fma_f32 v24, -v23, v22, v21
	v_cmp_ge_f32_e64 s[4:5], 0, v24
	v_add_u32_e32 v24, 1, v22
	s_nop 0
	v_cndmask_b32_e64 v23, v22, v23, s[4:5]
	v_fma_f32 v22, -v24, v22, v21
	v_cmp_lt_f32_e64 s[4:5], 0, v22
	s_nop 1
	v_cndmask_b32_e64 v22, v23, v24, s[4:5]
	v_mul_f32_e32 v23, 0x37800000, v22
	v_cndmask_b32_e32 v22, v22, v23, vcc
	v_cmp_class_f32_e32 vcc, v21, v101
	s_nop 1
	v_cndmask_b32_e32 v21, v22, v21, vcc
	s_nop 0
	v_div_scale_f32 v24, vcc, 1.0, v21, 1.0
	v_rcp_f32_e32 v40, v21
	v_mul_f32_e32 v21, v115, v115
	v_fmac_f32_e32 v21, v131, v131
	v_fmac_f32_e32 v21, v37, v37
	v_fmac_f32_e32 v21, v12, v12
	ds_bpermute_b32 v22, v2, v21
	v_mul_f32_e32 v38, v38, v40
	v_mul_f32_e32 v13, v13, v40
	s_waitcnt lgkmcnt(0)
	v_add_f32_e32 v21, v21, v22
	ds_bpermute_b32 v22, v3, v21
	s_waitcnt lgkmcnt(0)
	v_add_f32_e32 v21, v21, v22
	ds_bpermute_b32 v22, v20, v21
	s_waitcnt lgkmcnt(0)
	v_add_f32_e32 v21, v21, v22
	ds_bpermute_b32 v22, v47, v21
	s_waitcnt lgkmcnt(0)
	v_add_f32_e32 v21, v21, v22
	ds_bpermute_b32 v22, v48, v21
	s_waitcnt lgkmcnt(0)
	v_add_f32_e32 v21, v21, v22
	v_fmamk_f32 v21, v21, 0x3c000000, v100
	v_cmp_gt_f32_e32 vcc, s34, v21
	v_mul_f32_e32 v22, 0x4f800000, v21
	s_nop 0
	v_cndmask_b32_e32 v21, v21, v22, vcc
	v_sqrt_f32_e32 v22, v21
	s_nop 0
	v_add_u32_e32 v23, -1, v22
	v_fma_f32 v24, -v23, v22, v21
	v_cmp_ge_f32_e64 s[4:5], 0, v24
	v_add_u32_e32 v24, 1, v22
	s_nop 0
	v_cndmask_b32_e64 v23, v22, v23, s[4:5]
	v_fma_f32 v22, -v24, v22, v21
	v_cmp_lt_f32_e64 s[4:5], 0, v22
	s_nop 1
	v_cndmask_b32_e64 v22, v23, v24, s[4:5]
	v_mul_f32_e32 v23, 0x37800000, v22
	v_cndmask_b32_e32 v22, v22, v23, vcc
	v_cmp_class_f32_e32 vcc, v21, v101
	s_nop 1
	v_cndmask_b32_e32 v21, v22, v21, vcc
	s_nop 0
	v_div_scale_f32 v24, vcc, 1.0, v21, 1.0
	v_rcp_f32_e32 v35, v21
	v_mul_f32_e32 v21, v114, v114
	v_fmac_f32_e32 v21, v130, v130
	v_fmac_f32_e32 v21, v36, v36
	v_fmac_f32_e32 v21, v11, v11
	ds_bpermute_b32 v22, v2, v21
	v_mul_f32_e32 v37, v37, v35
	v_mul_f32_e32 v12, v12, v35
	s_waitcnt lgkmcnt(0)
	v_add_f32_e32 v21, v21, v22
	ds_bpermute_b32 v22, v3, v21
	s_waitcnt lgkmcnt(0)
	v_add_f32_e32 v21, v21, v22
	ds_bpermute_b32 v22, v20, v21
	s_waitcnt lgkmcnt(0)
	v_add_f32_e32 v21, v21, v22
	ds_bpermute_b32 v22, v47, v21
	s_waitcnt lgkmcnt(0)
	v_add_f32_e32 v21, v21, v22
	ds_bpermute_b32 v22, v48, v21
	s_waitcnt lgkmcnt(0)
	v_add_f32_e32 v21, v21, v22
	v_fmamk_f32 v21, v21, 0x3c000000, v100
	v_cmp_gt_f32_e32 vcc, s34, v21
	v_mul_f32_e32 v22, 0x4f800000, v21
	s_nop 0
	v_cndmask_b32_e32 v21, v21, v22, vcc
	v_sqrt_f32_e32 v22, v21
	s_nop 0
	v_add_u32_e32 v23, -1, v22
	v_fma_f32 v24, -v23, v22, v21
	v_cmp_ge_f32_e64 s[4:5], 0, v24
	v_add_u32_e32 v24, 1, v22
	s_nop 0
	v_cndmask_b32_e64 v23, v22, v23, s[4:5]
	v_fma_f32 v22, -v24, v22, v21
	v_cmp_lt_f32_e64 s[4:5], 0, v22
	s_nop 1
	v_cndmask_b32_e64 v22, v23, v24, s[4:5]
	v_mul_f32_e32 v23, 0x37800000, v22
	v_cndmask_b32_e32 v22, v22, v23, vcc
	v_cmp_class_f32_e32 vcc, v21, v101
	s_nop 1
	v_cndmask_b32_e32 v21, v22, v21, vcc
	s_nop 0
	v_div_scale_f32 v24, vcc, 1.0, v21, 1.0
	v_rcp_f32_e32 v31, v21
	v_mul_f32_e32 v21, v113, v113
	v_fmac_f32_e32 v21, v129, v129
	v_fmac_f32_e32 v21, v34, v34
	v_fmac_f32_e32 v21, v10, v10
	ds_bpermute_b32 v22, v2, v21
	v_mul_f32_e32 v36, v36, v31
	v_mul_f32_e32 v11, v11, v31
	s_waitcnt lgkmcnt(0)
	v_add_f32_e32 v21, v21, v22
	ds_bpermute_b32 v22, v3, v21
	s_waitcnt lgkmcnt(0)
	v_add_f32_e32 v21, v21, v22
	ds_bpermute_b32 v22, v20, v21
	s_waitcnt lgkmcnt(0)
	v_add_f32_e32 v21, v21, v22
	ds_bpermute_b32 v22, v47, v21
	s_waitcnt lgkmcnt(0)
	v_add_f32_e32 v21, v21, v22
	ds_bpermute_b32 v22, v48, v21
	s_waitcnt lgkmcnt(0)
; DI void gla_stage3(const Ctx& c0, int layer, int unit, int cb, LAS unsigned char* lds) {
;     ...
;     float rs[16];
; #pragma unroll
;     for (int rg = 0; rg < 16; ++rg) { float ss = o[0][rg] * o[0][rg] + o[1][rg] * o[1][rg] + o[2][rg] * o[2][rg] + o[3][rg] * o[3][rg];
;         ss += __shfl_xor(ss, 1); ss += __shfl_xor(ss, 2); ss += __shfl_xor(ss, 4); ss += __shfl_xor(ss, 8); ss += __shfl_xor(ss, 16);
;         rs[rg] = 1.f / sqrtf(ss * (1.f / 128.f) + EPS); }
	v_add_f32_e32 v21, v21, v22
	v_fmamk_f32 v21, v21, 0x3c000000, v100
	v_cmp_gt_f32_e32 vcc, s34, v21
	v_mul_f32_e32 v22, 0x4f800000, v21
	s_nop 0
	v_cndmask_b32_e32 v21, v21, v22, vcc
	v_sqrt_f32_e32 v22, v21
	s_nop 0
	v_add_u32_e32 v23, -1, v22
	v_fma_f32 v24, -v23, v22, v21
	v_cmp_ge_f32_e64 s[4:5], 0, v24
	v_add_u32_e32 v24, 1, v22
	s_nop 0
	v_cndmask_b32_e64 v23, v22, v23, s[4:5]
	v_fma_f32 v22, -v24, v22, v21
	v_cmp_lt_f32_e64 s[4:5], 0, v22
	s_nop 1
	v_cndmask_b32_e64 v22, v23, v24, s[4:5]
	v_mul_f32_e32 v23, 0x37800000, v22
	v_cndmask_b32_e32 v22, v22, v23, vcc
	v_cmp_class_f32_e32 vcc, v21, v101
	s_nop 1
	v_cndmask_b32_e32 v21, v22, v21, vcc
	s_nop 0
	v_div_scale_f32 v24, vcc, 1.0, v21, 1.0
	v_rcp_f32_e32 v27, v21
	v_mul_f32_e32 v21, v112, v112
	v_fmac_f32_e32 v21, v128, v128
	v_fmac_f32_e32 v21, v33, v33
	v_fmac_f32_e32 v21, v9, v9
	ds_bpermute_b32 v22, v2, v21
	v_mul_f32_e32 v34, v34, v27
	v_mul_f32_e32 v10, v10, v27
	s_waitcnt lgkmcnt(0)
	v_add_f32_e32 v21, v21, v22
	ds_bpermute_b32 v22, v3, v21
	s_waitcnt lgkmcnt(0)
	v_add_f32_e32 v21, v21, v22
	ds_bpermute_b32 v22, v20, v21
	s_waitcnt lgkmcnt(0)
	v_add_f32_e32 v21, v21, v22
	ds_bpermute_b32 v22, v47, v21
	s_waitcnt lgkmcnt(0)
	v_add_f32_e32 v21, v21, v22
	ds_bpermute_b32 v22, v48, v21
	s_waitcnt lgkmcnt(0)
	v_add_f32_e32 v21, v21, v22
	v_fmamk_f32 v21, v21, 0x3c000000, v100
	v_cmp_gt_f32_e32 vcc, s34, v21
	v_mul_f32_e32 v22, 0x4f800000, v21
	s_nop 0
	v_cndmask_b32_e32 v21, v21, v22, vcc
	v_sqrt_f32_e32 v22, v21
	s_nop 0
	v_add_u32_e32 v23, -1, v22
	v_fma_f32 v24, -v23, v22, v21
	v_cmp_ge_f32_e64 s[4:5], 0, v24
	v_add_u32_e32 v24, 1, v22
	s_nop 0
	v_cndmask_b32_e64 v23, v22, v23, s[4:5]
	v_fma_f32 v22, -v24, v22, v21
	v_cmp_lt_f32_e64 s[4:5], 0, v22
	s_nop 1
	v_cndmask_b32_e64 v22, v23, v24, s[4:5]
	v_mul_f32_e32 v23, 0x37800000, v22
	v_cndmask_b32_e32 v22, v22, v23, vcc
	v_cmp_class_f32_e32 vcc, v21, v101
	s_nop 1
	v_cndmask_b32_e32 v21, v22, v21, vcc
	s_nop 0
	v_div_scale_f32 v24, vcc, 1.0, v21, 1.0
	v_rcp_f32_e32 v25, v21
	v_mul_f32_e32 v21, v111, v111
	v_fmac_f32_e32 v21, v127, v127
	v_fmac_f32_e32 v21, v32, v32
	v_fmac_f32_e32 v21, v8, v8
	ds_bpermute_b32 v22, v2, v21
	v_mul_f32_e32 v33, v33, v25
	v_mul_f32_e32 v9, v9, v25
	s_waitcnt lgkmcnt(0)
	v_add_f32_e32 v21, v21, v22
	ds_bpermute_b32 v22, v3, v21
	s_waitcnt lgkmcnt(0)
	v_add_f32_e32 v21, v21, v22
	ds_bpermute_b32 v22, v20, v21
	s_waitcnt lgkmcnt(0)
	v_add_f32_e32 v21, v21, v22
	ds_bpermute_b32 v22, v47, v21
	s_waitcnt lgkmcnt(0)
	v_add_f32_e32 v21, v21, v22
	ds_bpermute_b32 v22, v48, v21
	s_waitcnt lgkmcnt(0)
	v_add_f32_e32 v21, v21, v22
	v_fmamk_f32 v21, v21, 0x3c000000, v100
	v_cmp_gt_f32_e32 vcc, s34, v21
	v_mul_f32_e32 v22, 0x4f800000, v21
	s_nop 0
	v_cndmask_b32_e32 v21, v21, v22, vcc
	v_sqrt_f32_e32 v22, v21
	s_nop 0
	v_add_u32_e32 v23, -1, v22
	v_fma_f32 v24, -v23, v22, v21
	v_cmp_ge_f32_e64 s[4:5], 0, v24
	v_add_u32_e32 v24, 1, v22
	s_nop 0
	v_cndmask_b32_e64 v23, v22, v23, s[4:5]
	v_fma_f32 v22, -v24, v22, v21
	v_cmp_lt_f32_e64 s[4:5], 0, v22
	s_nop 1
	v_cndmask_b32_e64 v22, v23, v24, s[4:5]
	v_mul_f32_e32 v23, 0x37800000, v22
	v_cndmask_b32_e32 v22, v22, v23, vcc
	v_cmp_class_f32_e32 vcc, v21, v101
	s_nop 1
	v_cndmask_b32_e32 v21, v22, v21, vcc
	s_nop 0
	v_div_scale_f32 v24, vcc, 1.0, v21, 1.0
	v_rcp_f32_e32 v24, v21
	v_mul_f32_e32 v21, v110, v110
	v_fmac_f32_e32 v21, v126, v126
	v_fmac_f32_e32 v21, v30, v30
	v_fmac_f32_e32 v21, v7, v7
	ds_bpermute_b32 v22, v2, v21
	v_mul_f32_e32 v32, v32, v24
	v_mul_f32_e32 v8, v8, v24
	s_waitcnt lgkmcnt(0)
	v_add_f32_e32 v21, v21, v22
	ds_bpermute_b32 v22, v3, v21
	s_waitcnt lgkmcnt(0)
	v_add_f32_e32 v21, v21, v22
	ds_bpermute_b32 v22, v20, v21
	s_waitcnt lgkmcnt(0)
	v_add_f32_e32 v21, v21, v22
	ds_bpermute_b32 v22, v47, v21
	s_waitcnt lgkmcnt(0)
	v_add_f32_e32 v21, v21, v22
	ds_bpermute_b32 v22, v48, v21
	s_waitcnt lgkmcnt(0)
	v_add_f32_e32 v21, v21, v22
	v_fmamk_f32 v21, v21, 0x3c000000, v100
	v_cmp_gt_f32_e32 vcc, s34, v21
	v_mul_f32_e32 v22, 0x4f800000, v21
	s_nop 0
	v_cndmask_b32_e32 v21, v21, v22, vcc
	v_sqrt_f32_e32 v22, v21
	s_nop 0
	v_add_u32_e32 v23, -1, v22
	v_fma_f32 v49, -v23, v22, v21
	v_cmp_ge_f32_e64 s[4:5], 0, v49
	v_add_u32_e32 v49, 1, v22
	s_nop 0
	v_cndmask_b32_e64 v23, v22, v23, s[4:5]
	v_fma_f32 v22, -v49, v22, v21
	v_cmp_lt_f32_e64 s[4:5], 0, v22
	s_nop 1
	v_cndmask_b32_e64 v22, v23, v49, s[4:5]
	v_mul_f32_e32 v23, 0x37800000, v22
	v_cndmask_b32_e32 v22, v22, v23, vcc
	v_cmp_class_f32_e32 vcc, v21, v101
	s_nop 1
	v_cndmask_b32_e32 v21, v22, v21, vcc
	s_nop 0
	v_div_scale_f32 v49, vcc, 1.0, v21, 1.0
	v_rcp_f32_e32 v23, v21
	v_mul_f32_e32 v21, v109, v109
	v_fmac_f32_e32 v21, v125, v125
	v_fmac_f32_e32 v21, v29, v29
	v_fmac_f32_e32 v21, v6, v6
	ds_bpermute_b32 v22, v2, v21
	v_mul_f32_e32 v30, v30, v23
	v_mul_f32_e32 v7, v7, v23
	s_waitcnt lgkmcnt(0)
	v_add_f32_e32 v21, v21, v22
	ds_bpermute_b32 v22, v3, v21
	s_waitcnt lgkmcnt(0)
	v_add_f32_e32 v21, v21, v22
	ds_bpermute_b32 v22, v20, v21
	s_waitcnt lgkmcnt(0)
	v_add_f32_e32 v21, v21, v22
	ds_bpermute_b32 v22, v47, v21
	s_waitcnt lgkmcnt(0)
	v_add_f32_e32 v21, v21, v22
	ds_bpermute_b32 v22, v48, v21
	s_waitcnt lgkmcnt(0)
	v_add_f32_e32 v21, v21, v22
	v_fmamk_f32 v21, v21, 0x3c000000, v100
	v_cmp_gt_f32_e32 vcc, s34, v21
	v_mul_f32_e32 v22, 0x4f800000, v21
	s_nop 0
	v_cndmask_b32_e32 v21, v21, v22, vcc
	v_sqrt_f32_e32 v22, v21
	s_nop 0
	v_add_u32_e32 v49, -1, v22
	v_fma_f32 v50, -v49, v22, v21
	v_cmp_ge_f32_e64 s[4:5], 0, v50
	v_add_u32_e32 v50, 1, v22
	s_nop 0
	v_cndmask_b32_e64 v49, v22, v49, s[4:5]
	v_fma_f32 v22, -v50, v22, v21
	v_cmp_lt_f32_e64 s[4:5], 0, v22
	s_nop 1
	v_cndmask_b32_e64 v22, v49, v50, s[4:5]
	v_mul_f32_e32 v49, 0x37800000, v22
	v_cndmask_b32_e32 v22, v22, v49, vcc
	v_cmp_class_f32_e32 vcc, v21, v101
	s_nop 1
	v_cndmask_b32_e32 v21, v22, v21, vcc
	s_nop 0
	v_div_scale_f32 v50, vcc, 1.0, v21, 1.0
	v_rcp_f32_e32 v22, v21
	v_mul_f32_e32 v21, v108, v108
	v_fmac_f32_e32 v21, v124, v124
	v_fmac_f32_e32 v21, v28, v28
	v_fmac_f32_e32 v21, v5, v5
	ds_bpermute_b32 v49, v2, v21
	v_mul_f32_e32 v29, v29, v22
	v_mul_f32_e32 v6, v6, v22
	s_waitcnt lgkmcnt(0)
; #define LAS __attribute__((address_space(3)))
; #define LDS_WAIT() asm volatile("s_waitcnt lgkmcnt(0)" ::: "memory")
; DI unsigned cvtpk(float lo, float hi) { f32x2 v = {lo, hi}; bf16x2_t b = __builtin_convertvector(v, bf16x2_t); return __builtin_bit_cast(unsigned, b); }
; DI float bf2f(bf16 b) { return __uint_as_float(((unsigned)b) << 16); }
; DI float siluf_(float x) { return x / (1.f + __expf(-x)); }
; DI void gla_stage3(const Ctx& c0, int layer, int unit, int cb, LAS unsigned char* lds) {
;     ...
;     float rs[16];
; #pragma unroll
;     for (int rg = 0; rg < 16; ++rg) { float ss = o[0][rg] * o[0][rg] + o[1][rg] * o[1][rg] + o[2][rg] * o[2][rg] + o[3][rg] * o[3][rg];
;         ss += __shfl_xor(ss, 1); ss += __shfl_xor(ss, 2); ss += __shfl_xor(ss, 4); ss += __shfl_xor(ss, 8); ss += __shfl_xor(ss, 16);
;         rs[rg] = 1.f / sqrtf(ss * (1.f / 128.f) + EPS); }
;     LDS_WAIT();
;     g3_tile_in((const bf16*)(c.ws + O_GR) + row0 * 512 + h * 128, R, lane);
; #pragma unroll
;     for (int vb = 0; vb < 4; ++vb) { const float g = gn[32 * vb + r];
; #pragma unroll
;         for (int rg = 0; rg < 16; ++rg) { LAS bf16* e = (LAS bf16*)(R + (4 * hi) * G3_PITCH + r * 2 + ((rg & 3) + 8 * (rg >> 2)) * G3_PITCH + 64 * vb);
;             const float z = bf2f(*e);
;             *e = (bf16)(cvtpk(o[vb][rg] * rs[rg] * g * siluf_(z), 0.f) & 0xffffu); }
	v_add_f32_e32 v21, v21, v49
	ds_bpermute_b32 v49, v3, v21
	s_waitcnt lgkmcnt(0)
	v_add_f32_e32 v21, v21, v49
	ds_bpermute_b32 v49, v20, v21
	s_waitcnt lgkmcnt(0)
	v_add_f32_e32 v21, v21, v49
	ds_bpermute_b32 v49, v47, v21
	s_waitcnt lgkmcnt(0)
	v_add_f32_e32 v21, v21, v49
	ds_bpermute_b32 v49, v48, v21
	s_waitcnt lgkmcnt(0)
	v_add_f32_e32 v21, v21, v49
	v_fmamk_f32 v21, v21, 0x3c000000, v100
	v_cmp_gt_f32_e32 vcc, s34, v21
	v_mul_f32_e32 v49, 0x4f800000, v21
	s_nop 0
	v_cndmask_b32_e32 v21, v21, v49, vcc
	v_sqrt_f32_e32 v49, v21
	s_nop 0
	v_add_u32_e32 v50, -1, v49
	v_fma_f32 v51, -v50, v49, v21
	v_cmp_ge_f32_e64 s[4:5], 0, v51
	v_add_u32_e32 v51, 1, v49
	s_nop 0
	v_cndmask_b32_e64 v50, v49, v50, s[4:5]
	v_fma_f32 v49, -v51, v49, v21
	v_cmp_lt_f32_e64 s[4:5], 0, v49
	s_nop 1
	v_cndmask_b32_e64 v49, v50, v51, s[4:5]
	v_mul_f32_e32 v50, 0x37800000, v49
	v_cndmask_b32_e32 v49, v49, v50, vcc
	v_cmp_class_f32_e32 vcc, v21, v101
	s_nop 1
	v_cndmask_b32_e32 v21, v49, v21, vcc
	s_nop 0
	v_div_scale_f32 v51, vcc, 1.0, v21, 1.0
	v_rcp_f32_e32 v21, v21
	v_mul_f32_e32 v49, v107, v107
	v_fmac_f32_e32 v49, v123, v123
	v_fmac_f32_e32 v49, v26, v26
	v_fmac_f32_e32 v49, v4, v4
	ds_bpermute_b32 v2, v2, v49
	v_mul_f32_e32 v28, v28, v21
	v_mul_f32_e32 v5, v5, v21
	s_waitcnt lgkmcnt(0)
	v_add_f32_e32 v2, v49, v2
	ds_bpermute_b32 v3, v3, v2
	s_waitcnt lgkmcnt(0)
	v_add_f32_e32 v2, v2, v3
	ds_bpermute_b32 v3, v20, v2
	s_waitcnt lgkmcnt(0)
	v_add_f32_e32 v2, v2, v3
	ds_bpermute_b32 v3, v47, v2
	s_waitcnt lgkmcnt(0)
	v_add_f32_e32 v2, v2, v3
	ds_bpermute_b32 v3, v48, v2
	s_waitcnt lgkmcnt(0)
	v_add_f32_e32 v2, v2, v3
	v_fmamk_f32 v2, v2, 0x3c000000, v100
	v_cmp_gt_f32_e32 vcc, s34, v2
	v_mul_f32_e32 v3, 0x4f800000, v2
	s_nop 0
	v_cndmask_b32_e32 v2, v2, v3, vcc
	v_sqrt_f32_e32 v3, v2
	s_nop 0
	v_add_u32_e32 v20, -1, v3
	v_fma_f32 v47, -v20, v3, v2
	v_cmp_ge_f32_e64 s[4:5], 0, v47
	v_add_u32_e32 v47, 1, v3
	s_nop 0
	v_cndmask_b32_e64 v20, v3, v20, s[4:5]
	v_fma_f32 v3, -v47, v3, v2
	v_cmp_lt_f32_e64 s[4:5], 0, v3
	s_nop 1
	v_cndmask_b32_e64 v3, v20, v47, s[4:5]
	v_mul_f32_e32 v20, 0x37800000, v3
	v_cndmask_b32_e32 v3, v3, v20, vcc
	v_cmp_class_f32_e32 vcc, v2, v101
	s_nop 1
	v_cndmask_b32_e32 v2, v3, v2, vcc
	s_nop 0
	v_rcp_f32_e32 v20, v2
	v_mul_f32_e32 v47, v138, v46
	v_mul_f32_e32 v26, v26, v20
	v_mul_f32_e32 v4, v4, v20
	s_waitcnt vmcnt(2) lgkmcnt(0)
	ds_write_b128 v92, v[164:167]
	s_waitcnt vmcnt(0) lgkmcnt(0)
	ds_write_b128 v92, v[170:173] offset:1088
	s_waitcnt vmcnt(13) lgkmcnt(0)
	ds_write_b128 v92, v[174:177] offset:2176
	s_waitcnt vmcnt(8) lgkmcnt(0)
	ds_write_b128 v92, v[178:181] offset:3264
	s_waitcnt vmcnt(9) lgkmcnt(0)
	ds_write_b128 v92, v[196:199] offset:4352
	s_waitcnt vmcnt(10) lgkmcnt(0)
	ds_write_b128 v92, v[200:203] offset:5440
	v_lshl_add_u64 v[2:3], v[168:169], 0, v[80:81]
	s_waitcnt vmcnt(5) lgkmcnt(0)
	ds_write_b128 v92, v[204:207] offset:6528
	global_load_dwordx4 v[48:51], v[2:3], off
	s_waitcnt vmcnt(0) lgkmcnt(0)
	ds_write_b128 v92, v[48:51] offset:7616
	s_waitcnt lgkmcnt(0)
	ds_read_u16 v3, v1
	s_waitcnt lgkmcnt(0)
	v_lshlrev_b32_e32 v3, 16, v3
	v_mul_f32_e32 v48, 0xbfb8aa3b, v3
	v_exp_f32_e32 v48, v48
	s_waitcnt vmcnt(0)
	v_mul_f32_e32 v47, v47, v232
	v_add_f32_e32 v48, 1.0, v48
	v_div_scale_f32 v49, s[0:1], v48, v48, v3
	s_nop 0
	v_rcp_f32_e32 v49, v48
	s_nop 0
	v_mul_f32_e32 v3, v3, v49
	v_mul_f32_e32 v3, v47, v3
	v_cvt_pk_bf16_f32 v3, v3, s0
	ds_write_b16 v1, v3
	ds_read_u16 v3, v1 offset:272
	v_mul_f32_e32 v47, v137, v45
	v_mul_f32_e32 v47, v47, v232
	s_waitcnt lgkmcnt(0)
	v_lshlrev_b32_e32 v3, 16, v3
	v_mul_f32_e32 v48, 0xbfb8aa3b, v3
	v_exp_f32_e32 v48, v48
	s_nop 0
	v_add_f32_e32 v48, 1.0, v48
	v_div_scale_f32 v49, s[0:1], v48, v48, v3
	s_nop 0
	v_rcp_f32_e32 v49, v48
	s_nop 0
	v_mul_f32_e32 v3, v3, v49
	v_mul_f32_e32 v3, v47, v3
	v_cvt_pk_bf16_f32 v3, v3, s0
	ds_write_b16 v1, v3 offset:272
	ds_read_u16 v3, v1 offset:544
	v_mul_f32_e32 v47, v136, v44
	v_mul_f32_e32 v47, v47, v232
	s_waitcnt lgkmcnt(0)
	v_lshlrev_b32_e32 v3, 16, v3
	v_mul_f32_e32 v48, 0xbfb8aa3b, v3
	v_exp_f32_e32 v48, v48
	s_nop 0
	v_add_f32_e32 v48, 1.0, v48
	v_div_scale_f32 v49, s[0:1], v48, v48, v3
	s_nop 0
	v_rcp_f32_e32 v49, v48
	s_nop 0
	v_mul_f32_e32 v3, v3, v49
	v_mul_f32_e32 v3, v47, v3
	v_cvt_pk_bf16_f32 v3, v3, s0
	ds_write_b16 v1, v3 offset:544
	ds_read_u16 v3, v1 offset:816
	v_mul_f32_e32 v47, v135, v43
	v_mul_f32_e32 v47, v47, v232
	s_waitcnt lgkmcnt(0)
	v_lshlrev_b32_e32 v3, 16, v3
	v_mul_f32_e32 v48, 0xbfb8aa3b, v3
	v_exp_f32_e32 v48, v48
	s_nop 0
	v_add_f32_e32 v48, 1.0, v48
	v_div_scale_f32 v49, s[0:1], v48, v48, v3
	s_nop 0
	v_rcp_f32_e32 v49, v48
	s_nop 0
	v_mul_f32_e32 v3, v3, v49
	v_mul_f32_e32 v3, v47, v3
	v_cvt_pk_bf16_f32 v3, v3, s0
	ds_write_b16 v1, v3 offset:816
	ds_read_u16 v3, v1 offset:2176
	v_mul_f32_e32 v47, v134, v42
	v_mul_f32_e32 v47, v47, v232
	s_waitcnt lgkmcnt(0)
	v_lshlrev_b32_e32 v3, 16, v3
	v_mul_f32_e32 v48, 0xbfb8aa3b, v3
	v_exp_f32_e32 v48, v48
	s_nop 0
	v_add_f32_e32 v48, 1.0, v48
	v_div_scale_f32 v49, s[0:1], v48, v48, v3
	s_nop 0
	v_rcp_f32_e32 v49, v48
	s_nop 0
	v_mul_f32_e32 v3, v3, v49
	v_mul_f32_e32 v3, v47, v3
	v_cvt_pk_bf16_f32 v3, v3, s0
	ds_write_b16 v1, v3 offset:2176
	ds_read_u16 v3, v1 offset:2448
	v_mul_f32_e32 v47, v133, v41
	v_mul_f32_e32 v47, v47, v232
	s_waitcnt lgkmcnt(0)
	v_lshlrev_b32_e32 v3, 16, v3
	v_mul_f32_e32 v48, 0xbfb8aa3b, v3
	v_exp_f32_e32 v48, v48
	s_nop 0
	v_add_f32_e32 v48, 1.0, v48
	v_div_scale_f32 v49, s[0:1], v48, v48, v3
	s_nop 0
	v_rcp_f32_e32 v49, v48
	s_nop 0
	v_mul_f32_e32 v3, v3, v49
	v_mul_f32_e32 v3, v47, v3
	v_cvt_pk_bf16_f32 v3, v3, s0
	ds_write_b16 v1, v3 offset:2448
	ds_read_u16 v3, v1 offset:2720
	v_mul_f32_e32 v47, v132, v40
	v_mul_f32_e32 v47, v47, v232
	s_waitcnt lgkmcnt(0)
; #define LAS __attribute__((address_space(3)))
; DI unsigned cvtpk(float lo, float hi) { f32x2 v = {lo, hi}; bf16x2_t b = __builtin_convertvector(v, bf16x2_t); return __builtin_bit_cast(unsigned, b); }
; DI float bf2f(bf16 b) { return __uint_as_float(((unsigned)b) << 16); }
; DI float siluf_(float x) { return x / (1.f + __expf(-x)); }
; DI void gla_stage3(const Ctx& c0, int layer, int unit, int cb, LAS unsigned char* lds) {
;     ...
; #pragma unroll
;     for (int vb = 0; vb < 4; ++vb) { const float g = gn[32 * vb + r];
; #pragma unroll
;         for (int rg = 0; rg < 16; ++rg) { LAS bf16* e = (LAS bf16*)(R + (4 * hi) * G3_PITCH + r * 2 + ((rg & 3) + 8 * (rg >> 2)) * G3_PITCH + 64 * vb);
;             const float z = bf2f(*e);
;             *e = (bf16)(cvtpk(o[vb][rg] * rs[rg] * g * siluf_(z), 0.f) & 0xffffu); }
	v_lshlrev_b32_e32 v3, 16, v3
	v_mul_f32_e32 v48, 0xbfb8aa3b, v3
	v_exp_f32_e32 v48, v48
	s_nop 0
	v_add_f32_e32 v48, 1.0, v48
	v_div_scale_f32 v49, s[0:1], v48, v48, v3
	s_nop 0
	v_rcp_f32_e32 v49, v48
	s_nop 0
	v_mul_f32_e32 v3, v3, v49
	v_mul_f32_e32 v3, v47, v3
	v_cvt_pk_bf16_f32 v3, v3, s0
	ds_write_b16 v1, v3 offset:2720
	ds_read_u16 v3, v1 offset:2992
	v_mul_f32_e32 v47, v131, v35
	v_mul_f32_e32 v47, v47, v232
	s_waitcnt lgkmcnt(0)
	v_lshlrev_b32_e32 v3, 16, v3
	v_mul_f32_e32 v48, 0xbfb8aa3b, v3
	v_exp_f32_e32 v48, v48
	s_nop 0
	v_add_f32_e32 v48, 1.0, v48
	v_div_scale_f32 v49, s[0:1], v48, v48, v3
	s_nop 0
	v_rcp_f32_e32 v49, v48
	s_nop 0
	v_mul_f32_e32 v3, v3, v49
	v_mul_f32_e32 v3, v47, v3
	v_cvt_pk_bf16_f32 v3, v3, s0
	ds_write_b16 v1, v3 offset:2992
	ds_read_u16 v3, v1 offset:4352
	v_mul_f32_e32 v47, v130, v31
	v_mul_f32_e32 v47, v47, v232
	s_waitcnt lgkmcnt(0)
	v_lshlrev_b32_e32 v3, 16, v3
	v_mul_f32_e32 v48, 0xbfb8aa3b, v3
	v_exp_f32_e32 v48, v48
	s_nop 0
	v_add_f32_e32 v48, 1.0, v48
	v_div_scale_f32 v49, s[0:1], v48, v48, v3
	s_nop 0
	v_rcp_f32_e32 v49, v48
	s_nop 0
	v_mul_f32_e32 v3, v3, v49
	v_mul_f32_e32 v3, v47, v3
	v_cvt_pk_bf16_f32 v3, v3, s0
	ds_write_b16 v1, v3 offset:4352
	ds_read_u16 v3, v1 offset:4624
	v_mul_f32_e32 v47, v129, v27
	v_mul_f32_e32 v47, v47, v232
	s_waitcnt lgkmcnt(0)
	v_lshlrev_b32_e32 v3, 16, v3
	v_mul_f32_e32 v48, 0xbfb8aa3b, v3
	v_exp_f32_e32 v48, v48
	s_nop 0
	v_add_f32_e32 v48, 1.0, v48
	v_div_scale_f32 v49, s[0:1], v48, v48, v3
	s_nop 0
	v_rcp_f32_e32 v49, v48
	s_nop 0
	v_mul_f32_e32 v3, v3, v49
	v_mul_f32_e32 v3, v47, v3
	v_cvt_pk_bf16_f32 v3, v3, s0
	ds_write_b16 v1, v3 offset:4624
	ds_read_u16 v3, v1 offset:4896
	v_mul_f32_e32 v47, v128, v25
	v_mul_f32_e32 v47, v47, v232
	s_waitcnt lgkmcnt(0)
	v_lshlrev_b32_e32 v3, 16, v3
	v_mul_f32_e32 v48, 0xbfb8aa3b, v3
	v_exp_f32_e32 v48, v48
	s_nop 0
	v_add_f32_e32 v48, 1.0, v48
	v_div_scale_f32 v49, s[0:1], v48, v48, v3
	s_nop 0
	v_rcp_f32_e32 v49, v48
	s_nop 0
	v_mul_f32_e32 v3, v3, v49
	v_mul_f32_e32 v3, v47, v3
	v_cvt_pk_bf16_f32 v3, v3, s0
	ds_write_b16 v1, v3 offset:4896
	ds_read_u16 v3, v1 offset:5168
	v_mul_f32_e32 v47, v127, v24
	v_mul_f32_e32 v47, v47, v232
	s_waitcnt lgkmcnt(0)
	v_lshlrev_b32_e32 v3, 16, v3
	v_mul_f32_e32 v48, 0xbfb8aa3b, v3
	v_exp_f32_e32 v48, v48
	s_nop 0
	v_add_f32_e32 v48, 1.0, v48
	v_div_scale_f32 v49, s[0:1], v48, v48, v3
	s_nop 0
	v_rcp_f32_e32 v49, v48
	s_nop 0
	v_mul_f32_e32 v3, v3, v49
	v_mul_f32_e32 v3, v47, v3
	v_cvt_pk_bf16_f32 v3, v3, s0
	ds_write_b16 v1, v3 offset:5168
	ds_read_u16 v3, v1 offset:6528
	v_mul_f32_e32 v47, v126, v23
	v_mul_f32_e32 v47, v47, v232
	s_waitcnt lgkmcnt(0)
	v_lshlrev_b32_e32 v3, 16, v3
	v_mul_f32_e32 v48, 0xbfb8aa3b, v3
	v_exp_f32_e32 v48, v48
	s_nop 0
	v_add_f32_e32 v48, 1.0, v48
	v_div_scale_f32 v49, s[0:1], v48, v48, v3
	s_nop 0
	v_rcp_f32_e32 v49, v48
	s_nop 0
	v_mul_f32_e32 v3, v3, v49
	v_mul_f32_e32 v3, v47, v3
	v_cvt_pk_bf16_f32 v3, v3, s0
	ds_write_b16 v1, v3 offset:6528
	ds_read_u16 v3, v1 offset:6800
	v_mul_f32_e32 v47, v125, v22
	v_mul_f32_e32 v47, v47, v232
	s_waitcnt lgkmcnt(0)
	v_lshlrev_b32_e32 v3, 16, v3
	v_mul_f32_e32 v48, 0xbfb8aa3b, v3
	v_exp_f32_e32 v48, v48
	s_nop 0
	v_add_f32_e32 v48, 1.0, v48
	v_div_scale_f32 v49, s[0:1], v48, v48, v3
	s_nop 0
	v_rcp_f32_e32 v49, v48
	s_nop 0
	v_mul_f32_e32 v3, v3, v49
	v_mul_f32_e32 v3, v47, v3
	v_cvt_pk_bf16_f32 v3, v3, s0
	ds_write_b16 v1, v3 offset:6800
	ds_read_u16 v3, v1 offset:7072
	v_mul_f32_e32 v47, v124, v21
	v_mul_f32_e32 v47, v47, v232
	s_waitcnt lgkmcnt(0)
	v_lshlrev_b32_e32 v3, 16, v3
	v_mul_f32_e32 v48, 0xbfb8aa3b, v3
	v_exp_f32_e32 v48, v48
	s_nop 0
	v_add_f32_e32 v48, 1.0, v48
	v_div_scale_f32 v49, s[0:1], v48, v48, v3
	s_nop 0
	v_rcp_f32_e32 v49, v48
	s_nop 0
	v_mul_f32_e32 v3, v3, v49
	v_mul_f32_e32 v3, v47, v3
	v_cvt_pk_bf16_f32 v3, v3, s0
	ds_write_b16 v1, v3 offset:7072
	ds_read_u16 v3, v1 offset:7344
	v_mul_f32_e32 v47, v123, v20
	v_mul_f32_e32 v2, v47, v232
	s_waitcnt lgkmcnt(0)
	v_lshlrev_b32_e32 v3, 16, v3
	v_mul_f32_e32 v47, 0xbfb8aa3b, v3
	v_exp_f32_e32 v47, v47
	s_nop 0
	v_add_f32_e32 v47, 1.0, v47
	v_div_scale_f32 v48, s[0:1], v47, v47, v3
	s_nop 0
	v_rcp_f32_e32 v48, v47
	s_nop 0
	v_mul_f32_e32 v3, v3, v48
	v_mul_f32_e32 v2, v2, v3
	v_cvt_pk_bf16_f32 v2, v2, s0
	ds_write_b16 v1, v2 offset:7344
	ds_read_u16 v3, v1 offset:64
	v_mul_f32_e32 v47, v122, v46
	s_waitcnt lgkmcnt(0)
	v_lshlrev_b32_e32 v3, 16, v3
	v_mul_f32_e32 v48, 0xbfb8aa3b, v3
	v_exp_f32_e32 v48, v48
	s_waitcnt vmcnt(0)
	v_mul_f32_e32 v47, v47, v234
	v_add_f32_e32 v48, 1.0, v48
	v_div_scale_f32 v49, s[0:1], v48, v48, v3
	s_nop 0
	v_rcp_f32_e32 v49, v48
	s_nop 0
	v_mul_f32_e32 v3, v3, v49
	v_mul_f32_e32 v3, v47, v3
	v_cvt_pk_bf16_f32 v3, v3, s0
	ds_write_b16 v1, v3 offset:64
	ds_read_u16 v3, v1 offset:336
	v_mul_f32_e32 v47, v121, v45
	v_mul_f32_e32 v47, v47, v234
	s_waitcnt lgkmcnt(0)
	v_lshlrev_b32_e32 v3, 16, v3
	v_mul_f32_e32 v48, 0xbfb8aa3b, v3
	v_exp_f32_e32 v48, v48
	s_nop 0
	v_add_f32_e32 v48, 1.0, v48
	v_div_scale_f32 v49, s[0:1], v48, v48, v3
	s_nop 0
	v_rcp_f32_e32 v49, v48
	s_nop 0
	v_mul_f32_e32 v3, v3, v49
	v_mul_f32_e32 v3, v47, v3
	v_cvt_pk_bf16_f32 v3, v3, s0
	ds_write_b16 v1, v3 offset:336
	ds_read_u16 v3, v1 offset:608
	v_mul_f32_e32 v47, v120, v44
	v_mul_f32_e32 v47, v47, v234
	s_waitcnt lgkmcnt(0)
	v_lshlrev_b32_e32 v3, 16, v3
	v_mul_f32_e32 v48, 0xbfb8aa3b, v3
	v_exp_f32_e32 v48, v48
	s_nop 0
	v_add_f32_e32 v48, 1.0, v48
	v_div_scale_f32 v49, s[0:1], v48, v48, v3
	s_nop 0
	v_rcp_f32_e32 v49, v48
	s_nop 0
	v_mul_f32_e32 v3, v3, v49
	v_mul_f32_e32 v3, v47, v3
	v_cvt_pk_bf16_f32 v3, v3, s0
	ds_write_b16 v1, v3 offset:608
	ds_read_u16 v3, v1 offset:880
	v_mul_f32_e32 v47, v119, v43
	v_mul_f32_e32 v47, v47, v234
	s_waitcnt lgkmcnt(0)
; #define LAS __attribute__((address_space(3)))
; DI unsigned cvtpk(float lo, float hi) { f32x2 v = {lo, hi}; bf16x2_t b = __builtin_convertvector(v, bf16x2_t); return __builtin_bit_cast(unsigned, b); }
; DI float bf2f(bf16 b) { return __uint_as_float(((unsigned)b) << 16); }
; DI float siluf_(float x) { return x / (1.f + __expf(-x)); }
; DI void gla_stage3(const Ctx& c0, int layer, int unit, int cb, LAS unsigned char* lds) {
;     ...
; #pragma unroll
;     for (int vb = 0; vb < 4; ++vb) { const float g = gn[32 * vb + r];
; #pragma unroll
;         for (int rg = 0; rg < 16; ++rg) { LAS bf16* e = (LAS bf16*)(R + (4 * hi) * G3_PITCH + r * 2 + ((rg & 3) + 8 * (rg >> 2)) * G3_PITCH + 64 * vb);
;             const float z = bf2f(*e);
;             *e = (bf16)(cvtpk(o[vb][rg] * rs[rg] * g * siluf_(z), 0.f) & 0xffffu); }
	v_lshlrev_b32_e32 v3, 16, v3
	v_mul_f32_e32 v48, 0xbfb8aa3b, v3
	v_exp_f32_e32 v48, v48
	s_nop 0
	v_add_f32_e32 v48, 1.0, v48
	v_div_scale_f32 v49, s[0:1], v48, v48, v3
	s_nop 0
	v_rcp_f32_e32 v49, v48
	s_nop 0
	v_mul_f32_e32 v3, v3, v49
	v_mul_f32_e32 v3, v47, v3
	v_cvt_pk_bf16_f32 v3, v3, s0
	ds_write_b16 v1, v3 offset:880
	ds_read_u16 v3, v1 offset:2240
	v_mul_f32_e32 v47, v118, v42
	v_mul_f32_e32 v47, v47, v234
	s_waitcnt lgkmcnt(0)
	v_lshlrev_b32_e32 v3, 16, v3
	v_mul_f32_e32 v48, 0xbfb8aa3b, v3
	v_exp_f32_e32 v48, v48
	s_nop 0
	v_add_f32_e32 v48, 1.0, v48
	v_div_scale_f32 v49, s[0:1], v48, v48, v3
	s_nop 0
	v_rcp_f32_e32 v49, v48
	s_nop 0
	v_mul_f32_e32 v3, v3, v49
	v_mul_f32_e32 v3, v47, v3
	v_cvt_pk_bf16_f32 v3, v3, s0
	ds_write_b16 v1, v3 offset:2240
	ds_read_u16 v3, v1 offset:2512
	v_mul_f32_e32 v47, v117, v41
	v_mul_f32_e32 v47, v47, v234
	s_waitcnt lgkmcnt(0)
	v_lshlrev_b32_e32 v3, 16, v3
	v_mul_f32_e32 v48, 0xbfb8aa3b, v3
	v_exp_f32_e32 v48, v48
	s_nop 0
	v_add_f32_e32 v48, 1.0, v48
	v_div_scale_f32 v49, s[0:1], v48, v48, v3
	s_nop 0
	v_rcp_f32_e32 v49, v48
	s_nop 0
	v_mul_f32_e32 v3, v3, v49
	v_mul_f32_e32 v3, v47, v3
	v_cvt_pk_bf16_f32 v3, v3, s0
	ds_write_b16 v1, v3 offset:2512
	ds_read_u16 v3, v1 offset:2784
	v_mul_f32_e32 v47, v116, v40
	v_mul_f32_e32 v47, v47, v234
	s_waitcnt lgkmcnt(0)
	v_lshlrev_b32_e32 v3, 16, v3
	v_mul_f32_e32 v48, 0xbfb8aa3b, v3
	v_exp_f32_e32 v48, v48
	s_nop 0
	v_add_f32_e32 v48, 1.0, v48
	v_div_scale_f32 v49, s[0:1], v48, v48, v3
	s_nop 0
	v_rcp_f32_e32 v49, v48
	s_nop 0
	v_mul_f32_e32 v3, v3, v49
	v_mul_f32_e32 v3, v47, v3
	v_cvt_pk_bf16_f32 v3, v3, s0
	ds_write_b16 v1, v3 offset:2784
	ds_read_u16 v3, v1 offset:3056
	v_mul_f32_e32 v47, v115, v35
	v_mul_f32_e32 v47, v47, v234
	s_waitcnt lgkmcnt(0)
	v_lshlrev_b32_e32 v3, 16, v3
	v_mul_f32_e32 v48, 0xbfb8aa3b, v3
	v_exp_f32_e32 v48, v48
	s_nop 0
	v_add_f32_e32 v48, 1.0, v48
	v_div_scale_f32 v49, s[0:1], v48, v48, v3
	s_nop 0
	v_rcp_f32_e32 v49, v48
	s_nop 0
	v_mul_f32_e32 v3, v3, v49
	v_mul_f32_e32 v3, v47, v3
	v_cvt_pk_bf16_f32 v3, v3, s0
	ds_write_b16 v1, v3 offset:3056
	ds_read_u16 v3, v1 offset:4416
	v_mul_f32_e32 v47, v114, v31
	v_mul_f32_e32 v47, v47, v234
	s_waitcnt lgkmcnt(0)
	v_lshlrev_b32_e32 v3, 16, v3
	v_mul_f32_e32 v48, 0xbfb8aa3b, v3
	v_exp_f32_e32 v48, v48
	s_nop 0
	v_add_f32_e32 v48, 1.0, v48
	v_div_scale_f32 v49, s[0:1], v48, v48, v3
	s_nop 0
	v_rcp_f32_e32 v49, v48
	s_nop 0
	v_mul_f32_e32 v3, v3, v49
	v_mul_f32_e32 v3, v47, v3
	v_cvt_pk_bf16_f32 v3, v3, s0
	ds_write_b16 v1, v3 offset:4416
	ds_read_u16 v3, v1 offset:4688
	v_mul_f32_e32 v47, v113, v27
	v_mul_f32_e32 v47, v47, v234
	s_waitcnt lgkmcnt(0)
	v_lshlrev_b32_e32 v3, 16, v3
	v_mul_f32_e32 v48, 0xbfb8aa3b, v3
	v_exp_f32_e32 v48, v48
	s_nop 0
	v_add_f32_e32 v48, 1.0, v48
	v_div_scale_f32 v49, s[0:1], v48, v48, v3
	s_nop 0
	v_rcp_f32_e32 v49, v48
	s_nop 0
	v_mul_f32_e32 v3, v3, v49
	v_mul_f32_e32 v3, v47, v3
	v_cvt_pk_bf16_f32 v3, v3, s0
	ds_write_b16 v1, v3 offset:4688
	ds_read_u16 v3, v1 offset:4960
	v_mul_f32_e32 v47, v112, v25
	v_mul_f32_e32 v47, v47, v234
	s_waitcnt lgkmcnt(0)
	v_lshlrev_b32_e32 v3, 16, v3
	v_mul_f32_e32 v48, 0xbfb8aa3b, v3
	v_exp_f32_e32 v48, v48
	s_nop 0
	v_add_f32_e32 v48, 1.0, v48
	v_div_scale_f32 v49, s[0:1], v48, v48, v3
	s_nop 0
	v_rcp_f32_e32 v49, v48
	s_nop 0
	v_mul_f32_e32 v3, v3, v49
	v_mul_f32_e32 v3, v47, v3
	v_cvt_pk_bf16_f32 v3, v3, s0
	ds_write_b16 v1, v3 offset:4960
	ds_read_u16 v3, v1 offset:5232
	v_mul_f32_e32 v47, v111, v24
	v_mul_f32_e32 v47, v47, v234
	s_waitcnt lgkmcnt(0)
	v_lshlrev_b32_e32 v3, 16, v3
	v_mul_f32_e32 v48, 0xbfb8aa3b, v3
	v_exp_f32_e32 v48, v48
	s_nop 0
	v_add_f32_e32 v48, 1.0, v48
	v_div_scale_f32 v49, s[0:1], v48, v48, v3
	s_nop 0
	v_rcp_f32_e32 v49, v48
	s_nop 0
	v_mul_f32_e32 v3, v3, v49
	v_mul_f32_e32 v3, v47, v3
	v_cvt_pk_bf16_f32 v3, v3, s0
	ds_write_b16 v1, v3 offset:5232
	ds_read_u16 v3, v1 offset:6592
	v_mul_f32_e32 v47, v110, v23
	v_mul_f32_e32 v47, v47, v234
	s_waitcnt lgkmcnt(0)
	v_lshlrev_b32_e32 v3, 16, v3
	v_mul_f32_e32 v48, 0xbfb8aa3b, v3
	v_exp_f32_e32 v48, v48
	s_nop 0
	v_add_f32_e32 v48, 1.0, v48
	v_div_scale_f32 v49, s[0:1], v48, v48, v3
	s_nop 0
	v_rcp_f32_e32 v49, v48
	s_nop 0
	v_mul_f32_e32 v3, v3, v49
	v_mul_f32_e32 v3, v47, v3
	v_cvt_pk_bf16_f32 v3, v3, s0
	ds_write_b16 v1, v3 offset:6592
	ds_read_u16 v3, v1 offset:6864
	v_mul_f32_e32 v47, v109, v22
	v_mul_f32_e32 v47, v47, v234
	s_waitcnt lgkmcnt(0)
	v_lshlrev_b32_e32 v3, 16, v3
	v_mul_f32_e32 v48, 0xbfb8aa3b, v3
	v_exp_f32_e32 v48, v48
	s_nop 0
	v_add_f32_e32 v48, 1.0, v48
	v_div_scale_f32 v49, s[0:1], v48, v48, v3
	s_nop 0
	v_rcp_f32_e32 v49, v48
	s_nop 0
	v_mul_f32_e32 v3, v3, v49
	v_mul_f32_e32 v3, v47, v3
	v_cvt_pk_bf16_f32 v3, v3, s0
	ds_write_b16 v1, v3 offset:6864
	ds_read_u16 v3, v1 offset:7136
	v_mul_f32_e32 v47, v108, v21
	v_mul_f32_e32 v47, v47, v234
	s_waitcnt lgkmcnt(0)
	v_lshlrev_b32_e32 v3, 16, v3
	v_mul_f32_e32 v48, 0xbfb8aa3b, v3
	v_exp_f32_e32 v48, v48
	s_nop 0
	v_add_f32_e32 v48, 1.0, v48
	v_div_scale_f32 v49, s[0:1], v48, v48, v3
	s_nop 0
	v_rcp_f32_e32 v49, v48
	s_nop 0
	v_mul_f32_e32 v3, v3, v49
	v_mul_f32_e32 v3, v47, v3
	v_cvt_pk_bf16_f32 v3, v3, s0
	ds_write_b16 v1, v3 offset:7136
	ds_read_u16 v3, v1 offset:7408
	v_mul_f32_e32 v47, v107, v20
	v_mul_f32_e32 v2, v47, v234
	s_waitcnt lgkmcnt(0)
	v_lshlrev_b32_e32 v3, 16, v3
	v_mul_f32_e32 v47, 0xbfb8aa3b, v3
	v_exp_f32_e32 v47, v47
	s_nop 0
	v_add_f32_e32 v47, 1.0, v47
	v_div_scale_f32 v48, s[0:1], v47, v47, v3
	s_nop 0
	v_rcp_f32_e32 v48, v47
	s_nop 0
	v_mul_f32_e32 v3, v3, v48
	v_mul_f32_e32 v2, v2, v3
	v_cvt_pk_bf16_f32 v2, v2, s0
	ds_write_b16 v1, v2 offset:7408
	ds_read_u16 v3, v1 offset:128
	v_mul_f32_e32 v47, v106, v46
	s_waitcnt lgkmcnt(0)
; #define LAS __attribute__((address_space(3)))
; DI unsigned cvtpk(float lo, float hi) { f32x2 v = {lo, hi}; bf16x2_t b = __builtin_convertvector(v, bf16x2_t); return __builtin_bit_cast(unsigned, b); }
; DI float bf2f(bf16 b) { return __uint_as_float(((unsigned)b) << 16); }
; DI float siluf_(float x) { return x / (1.f + __expf(-x)); }
; DI void gla_stage3(const Ctx& c0, int layer, int unit, int cb, LAS unsigned char* lds) {
;     ...
;     for (int vb = 0; vb < 4; ++vb) { const float g = gn[32 * vb + r];
; #pragma unroll
;         for (int rg = 0; rg < 16; ++rg) { LAS bf16* e = (LAS bf16*)(R + (4 * hi) * G3_PITCH + r * 2 + ((rg & 3) + 8 * (rg >> 2)) * G3_PITCH + 64 * vb);
;             const float z = bf2f(*e);
;             *e = (bf16)(cvtpk(o[vb][rg] * rs[rg] * g * siluf_(z), 0.f) & 0xffffu); }
	v_lshlrev_b32_e32 v3, 16, v3
	v_mul_f32_e32 v48, 0xbfb8aa3b, v3
	v_exp_f32_e32 v48, v48
	s_waitcnt vmcnt(0)
	v_mul_f32_e32 v47, v47, v236
	v_add_f32_e32 v48, 1.0, v48
	v_div_scale_f32 v49, s[0:1], v48, v48, v3
	v_mul_f32_e32 v39, v39, v236
	v_mul_f32_e32 v38, v38, v236
	v_mul_f32_e32 v37, v37, v236
	v_rcp_f32_e32 v49, v48
	s_nop 0
	v_mul_f32_e32 v3, v3, v49
	v_mul_f32_e32 v3, v47, v3
	v_cvt_pk_bf16_f32 v3, v3, s0
	ds_write_b16 v1, v3 offset:128
	ds_read_u16 v3, v1 offset:400
	v_mul_f32_e32 v47, v105, v45
	v_mul_f32_e32 v47, v47, v236
	v_mul_f32_e32 v36, v36, v236
	v_mul_f32_e32 v34, v34, v236
	s_waitcnt lgkmcnt(0)
	v_lshlrev_b32_e32 v3, 16, v3
	v_mul_f32_e32 v48, 0xbfb8aa3b, v3
	v_exp_f32_e32 v48, v48
	v_mul_f32_e32 v33, v33, v236
	v_mul_f32_e32 v32, v32, v236
	v_mul_f32_e32 v30, v30, v236
	v_add_f32_e32 v48, 1.0, v48
	v_div_scale_f32 v49, s[0:1], v48, v48, v3
	v_mul_f32_e32 v29, v29, v236
	v_mul_f32_e32 v28, v28, v236
	v_rcp_f32_e32 v49, v48
	s_nop 0
	v_mul_f32_e32 v3, v3, v49
	v_mul_f32_e32 v3, v47, v3
	v_cvt_pk_bf16_f32 v3, v3, s0
	ds_write_b16 v1, v3 offset:400
	ds_read_u16 v3, v1 offset:672
	v_mul_f32_e32 v47, v104, v44
	v_mul_f32_e32 v47, v47, v236
	s_waitcnt lgkmcnt(0)
	v_lshlrev_b32_e32 v3, 16, v3
	v_mul_f32_e32 v48, 0xbfb8aa3b, v3
	v_exp_f32_e32 v48, v48
	s_nop 0
	v_add_f32_e32 v48, 1.0, v48
	v_div_scale_f32 v49, s[0:1], v48, v48, v3
	s_nop 0
	v_rcp_f32_e32 v49, v48
	s_nop 0
	v_mul_f32_e32 v3, v3, v49
	v_mul_f32_e32 v3, v47, v3
	v_cvt_pk_bf16_f32 v3, v3, s0
	ds_write_b16 v1, v3 offset:672
	ds_read_u16 v3, v1 offset:944
	v_mul_f32_e32 v47, v103, v43
	v_mul_f32_e32 v47, v47, v236
	s_waitcnt lgkmcnt(0)
	v_lshlrev_b32_e32 v3, 16, v3
	v_mul_f32_e32 v48, 0xbfb8aa3b, v3
	v_exp_f32_e32 v48, v48
	s_nop 0
	v_add_f32_e32 v48, 1.0, v48
	v_div_scale_f32 v49, s[0:1], v48, v48, v3
	s_nop 0
	v_rcp_f32_e32 v49, v48
	s_nop 0
	v_mul_f32_e32 v3, v3, v49
	v_mul_f32_e32 v3, v47, v3
	v_cvt_pk_bf16_f32 v3, v3, s0
	ds_write_b16 v1, v3 offset:944
	ds_read_u16 v3, v1 offset:2304
	v_mul_f32_e32 v47, v102, v42
	v_mul_f32_e32 v47, v47, v236
	v_mul_f32_e32 v2, v26, v236
	s_waitcnt lgkmcnt(0)
	v_lshlrev_b32_e32 v3, 16, v3
	v_mul_f32_e32 v48, 0xbfb8aa3b, v3
	v_exp_f32_e32 v48, v48
	s_nop 0
	v_add_f32_e32 v48, 1.0, v48
	v_div_scale_f32 v49, s[0:1], v48, v48, v3
	s_nop 0
	v_rcp_f32_e32 v49, v48
	s_nop 0
	v_mul_f32_e32 v3, v3, v49
	v_mul_f32_e32 v3, v47, v3
	v_cvt_pk_bf16_f32 v3, v3, s0
	ds_write_b16 v1, v3 offset:2304
	ds_read_u16 v3, v1 offset:2576
	s_waitcnt lgkmcnt(0)
	v_lshlrev_b32_e32 v3, 16, v3
	v_mul_f32_e32 v47, 0xbfb8aa3b, v3
	v_exp_f32_e32 v47, v47
	s_nop 0
	v_add_f32_e32 v47, 1.0, v47
	v_div_scale_f32 v48, s[0:1], v47, v47, v3
	s_nop 0
	v_rcp_f32_e32 v48, v47
	s_nop 0
	v_mul_f32_e32 v3, v3, v48
	v_mul_f32_e32 v3, v39, v3
	v_cvt_pk_bf16_f32 v3, v3, s0
	ds_write_b16 v1, v3 offset:2576
	ds_read_u16 v3, v1 offset:2848
	s_waitcnt lgkmcnt(0)
	v_lshlrev_b32_e32 v3, 16, v3
	v_mul_f32_e32 v39, 0xbfb8aa3b, v3
	v_exp_f32_e32 v39, v39
	s_nop 0
	v_add_f32_e32 v39, 1.0, v39
	v_div_scale_f32 v47, s[0:1], v39, v39, v3
	s_nop 0
	v_rcp_f32_e32 v47, v39
	s_nop 0
	v_mul_f32_e32 v3, v3, v47
	v_mul_f32_e32 v3, v38, v3
	v_cvt_pk_bf16_f32 v3, v3, s0
	ds_write_b16 v1, v3 offset:2848
	ds_read_u16 v3, v1 offset:3120
	s_waitcnt lgkmcnt(0)
	v_lshlrev_b32_e32 v3, 16, v3
	v_mul_f32_e32 v38, 0xbfb8aa3b, v3
	v_exp_f32_e32 v38, v38
	s_nop 0
	v_add_f32_e32 v38, 1.0, v38
	v_div_scale_f32 v39, s[0:1], v38, v38, v3
	s_nop 0
	v_rcp_f32_e32 v39, v38
	s_nop 0
	v_mul_f32_e32 v3, v3, v39
	v_mul_f32_e32 v3, v37, v3
	v_cvt_pk_bf16_f32 v3, v3, s0
	ds_write_b16 v1, v3 offset:3120
	ds_read_u16 v3, v1 offset:4480
	s_waitcnt lgkmcnt(0)
	v_lshlrev_b32_e32 v3, 16, v3
	v_mul_f32_e32 v37, 0xbfb8aa3b, v3
	v_exp_f32_e32 v37, v37
	s_nop 0
	v_add_f32_e32 v37, 1.0, v37
	v_div_scale_f32 v38, s[0:1], v37, v37, v3
	s_nop 0
	v_rcp_f32_e32 v38, v37
	s_nop 0
	v_mul_f32_e32 v3, v3, v38
	v_mul_f32_e32 v3, v36, v3
	v_cvt_pk_bf16_f32 v3, v3, s0
	ds_write_b16 v1, v3 offset:4480
	ds_read_u16 v3, v1 offset:4752
	s_waitcnt lgkmcnt(0)
	v_lshlrev_b32_e32 v3, 16, v3
	v_mul_f32_e32 v36, 0xbfb8aa3b, v3
	v_exp_f32_e32 v36, v36
	s_nop 0
	v_add_f32_e32 v36, 1.0, v36
	v_div_scale_f32 v37, s[0:1], v36, v36, v3
	s_nop 0
	v_rcp_f32_e32 v37, v36
	s_nop 0
	v_mul_f32_e32 v3, v3, v37
	v_mul_f32_e32 v3, v34, v3
	v_cvt_pk_bf16_f32 v3, v3, s0
	ds_write_b16 v1, v3 offset:4752
	ds_read_u16 v3, v1 offset:5024
	s_waitcnt lgkmcnt(0)
	v_lshlrev_b32_e32 v3, 16, v3
	v_mul_f32_e32 v34, 0xbfb8aa3b, v3
	v_exp_f32_e32 v34, v34
	s_nop 0
	v_add_f32_e32 v34, 1.0, v34
	v_div_scale_f32 v36, s[0:1], v34, v34, v3
	s_nop 0
	v_rcp_f32_e32 v36, v34
	s_nop 0
	v_mul_f32_e32 v3, v3, v36
	v_mul_f32_e32 v3, v33, v3
	v_cvt_pk_bf16_f32 v3, v3, s0
	ds_write_b16 v1, v3 offset:5024
	ds_read_u16 v3, v1 offset:5296
	s_waitcnt lgkmcnt(0)
	v_lshlrev_b32_e32 v3, 16, v3
	v_mul_f32_e32 v33, 0xbfb8aa3b, v3
	v_exp_f32_e32 v33, v33
	s_nop 0
	v_add_f32_e32 v33, 1.0, v33
	v_div_scale_f32 v34, s[0:1], v33, v33, v3
	s_nop 0
	v_rcp_f32_e32 v34, v33
	s_nop 0
	v_mul_f32_e32 v3, v3, v34
	v_mul_f32_e32 v3, v32, v3
	v_cvt_pk_bf16_f32 v3, v3, s0
	ds_write_b16 v1, v3 offset:5296
	ds_read_u16 v3, v1 offset:6656
	s_waitcnt lgkmcnt(0)
	v_lshlrev_b32_e32 v3, 16, v3
	v_mul_f32_e32 v32, 0xbfb8aa3b, v3
	v_exp_f32_e32 v32, v32
	s_nop 0
	v_add_f32_e32 v32, 1.0, v32
	v_div_scale_f32 v33, s[0:1], v32, v32, v3
	s_nop 0
	v_rcp_f32_e32 v33, v32
	s_nop 0
	v_mul_f32_e32 v3, v3, v33
	v_mul_f32_e32 v3, v30, v3
	v_cvt_pk_bf16_f32 v3, v3, s0
	ds_write_b16 v1, v3 offset:6656
	ds_read_u16 v3, v1 offset:6928
	s_waitcnt lgkmcnt(0)
; #define LAS __attribute__((address_space(3)))
; DI unsigned cvtpk(float lo, float hi) { f32x2 v = {lo, hi}; bf16x2_t b = __builtin_convertvector(v, bf16x2_t); return __builtin_bit_cast(unsigned, b); }
; DI float bf2f(bf16 b) { return __uint_as_float(((unsigned)b) << 16); }
; DI float siluf_(float x) { return x / (1.f + __expf(-x)); }
; DI void gla_stage3(const Ctx& c0, int layer, int unit, int cb, LAS unsigned char* lds) {
;     ...
;     for (int vb = 0; vb < 4; ++vb) { const float g = gn[32 * vb + r];
; #pragma unroll
;         for (int rg = 0; rg < 16; ++rg) { LAS bf16* e = (LAS bf16*)(R + (4 * hi) * G3_PITCH + r * 2 + ((rg & 3) + 8 * (rg >> 2)) * G3_PITCH + 64 * vb);
;             const float z = bf2f(*e);
;             *e = (bf16)(cvtpk(o[vb][rg] * rs[rg] * g * siluf_(z), 0.f) & 0xffffu); }
	v_lshlrev_b32_e32 v3, 16, v3
	v_mul_f32_e32 v30, 0xbfb8aa3b, v3
	v_exp_f32_e32 v30, v30
	s_nop 0
	v_add_f32_e32 v30, 1.0, v30
	v_div_scale_f32 v32, s[0:1], v30, v30, v3
	s_nop 0
	v_rcp_f32_e32 v32, v30
	s_nop 0
	v_mul_f32_e32 v3, v3, v32
	v_mul_f32_e32 v3, v29, v3
	v_cvt_pk_bf16_f32 v3, v3, s0
	ds_write_b16 v1, v3 offset:6928
	ds_read_u16 v3, v1 offset:7200
	s_waitcnt lgkmcnt(0)
	v_lshlrev_b32_e32 v3, 16, v3
	v_mul_f32_e32 v29, 0xbfb8aa3b, v3
	v_exp_f32_e32 v29, v29
	s_nop 0
	v_add_f32_e32 v29, 1.0, v29
	v_div_scale_f32 v30, s[0:1], v29, v29, v3
	s_nop 0
	v_rcp_f32_e32 v30, v29
	s_nop 0
	v_mul_f32_e32 v3, v3, v30
	v_mul_f32_e32 v3, v28, v3
	v_cvt_pk_bf16_f32 v3, v3, s0
	ds_write_b16 v1, v3 offset:7200
	ds_read_u16 v3, v1 offset:7472
	s_waitcnt lgkmcnt(0)
	v_lshlrev_b32_e32 v3, 16, v3
	v_mul_f32_e32 v26, 0xbfb8aa3b, v3
	v_exp_f32_e32 v26, v26
	s_nop 0
	v_add_f32_e32 v26, 1.0, v26
	v_div_scale_f32 v28, s[0:1], v26, v26, v3
	s_nop 0
	v_rcp_f32_e32 v28, v26
	s_nop 0
	v_mul_f32_e32 v3, v3, v28
	v_mul_f32_e32 v2, v2, v3
	v_cvt_pk_bf16_f32 v2, v2, s0
	ds_write_b16 v1, v2 offset:7472
	ds_read_u16 v3, v1 offset:192
	s_waitcnt lgkmcnt(0)
	v_lshlrev_b32_e32 v3, 16, v3
	v_mul_f32_e32 v26, 0xbfb8aa3b, v3
	v_exp_f32_e32 v26, v26
	s_waitcnt vmcnt(31)
	v_mul_f32_e32 v19, v19, v238
	v_add_f32_e32 v26, 1.0, v26
	v_div_scale_f32 v28, s[0:1], v26, v26, v3
	v_mul_f32_e32 v18, v18, v238
	v_mul_f32_e32 v17, v17, v238
	v_mul_f32_e32 v16, v16, v238
	v_rcp_f32_e32 v28, v26
	s_nop 0
	v_mul_f32_e32 v3, v3, v28
	v_mul_f32_e32 v3, v19, v3
	v_cvt_pk_bf16_f32 v3, v3, s0
	ds_write_b16 v1, v3 offset:192
	ds_read_u16 v3, v1 offset:464
	v_mul_f32_e32 v15, v15, v238
	v_mul_f32_e32 v14, v14, v238
	v_mul_f32_e32 v13, v13, v238
	v_mul_f32_e32 v12, v12, v238
	s_waitcnt lgkmcnt(0)
	v_lshlrev_b32_e32 v3, 16, v3
	v_mul_f32_e32 v19, 0xbfb8aa3b, v3
	v_exp_f32_e32 v19, v19
	v_mul_f32_e32 v11, v11, v238
	v_mul_f32_e32 v10, v10, v238
	v_mul_f32_e32 v9, v9, v238
	v_add_f32_e32 v19, 1.0, v19
	v_div_scale_f32 v26, s[0:1], v19, v19, v3
	v_mul_f32_e32 v8, v8, v238
	v_mul_f32_e32 v7, v7, v238
	v_mul_f32_e32 v6, v6, v238
	v_rcp_f32_e32 v26, v19
	s_nop 0
	v_mul_f32_e32 v3, v3, v26
	v_mul_f32_e32 v3, v18, v3
	v_cvt_pk_bf16_f32 v3, v3, s0
	ds_write_b16 v1, v3 offset:464
	ds_read_u16 v3, v1 offset:736
	v_mul_f32_e32 v5, v5, v238
	v_mul_f32_e32 v2, v4, v238
	s_waitcnt lgkmcnt(0)
	v_lshlrev_b32_e32 v3, 16, v3
	v_mul_f32_e32 v18, 0xbfb8aa3b, v3
	v_exp_f32_e32 v18, v18
	s_nop 0
	v_add_f32_e32 v18, 1.0, v18
	v_div_scale_f32 v19, s[0:1], v18, v18, v3
	s_nop 0
	v_rcp_f32_e32 v19, v18
	s_nop 0
	v_mul_f32_e32 v3, v3, v19
	v_mul_f32_e32 v3, v17, v3
	v_cvt_pk_bf16_f32 v3, v3, s0
	ds_write_b16 v1, v3 offset:736
	ds_read_u16 v3, v1 offset:1008
	s_waitcnt lgkmcnt(0)
	v_lshlrev_b32_e32 v3, 16, v3
	v_mul_f32_e32 v17, 0xbfb8aa3b, v3
	v_exp_f32_e32 v17, v17
	s_nop 0
	v_add_f32_e32 v17, 1.0, v17
	v_div_scale_f32 v18, s[0:1], v17, v17, v3
	s_nop 0
	v_rcp_f32_e32 v18, v17
	s_nop 0
	v_mul_f32_e32 v3, v3, v18
	v_mul_f32_e32 v3, v16, v3
	v_cvt_pk_bf16_f32 v3, v3, s0
	ds_write_b16 v1, v3 offset:1008
	ds_read_u16 v3, v1 offset:2368
	s_waitcnt lgkmcnt(0)
	v_lshlrev_b32_e32 v3, 16, v3
	v_mul_f32_e32 v16, 0xbfb8aa3b, v3
	v_exp_f32_e32 v16, v16
	s_nop 0
	v_add_f32_e32 v16, 1.0, v16
	v_div_scale_f32 v17, s[0:1], v16, v16, v3
	s_nop 0
	v_rcp_f32_e32 v17, v16
	s_nop 0
	v_mul_f32_e32 v3, v3, v17
	v_mul_f32_e32 v3, v15, v3
	v_cvt_pk_bf16_f32 v3, v3, s0
	ds_write_b16 v1, v3 offset:2368
	ds_read_u16 v3, v1 offset:2640
	s_waitcnt lgkmcnt(0)
	v_lshlrev_b32_e32 v3, 16, v3
	v_mul_f32_e32 v15, 0xbfb8aa3b, v3
	v_exp_f32_e32 v15, v15
	s_nop 0
	v_add_f32_e32 v15, 1.0, v15
	v_div_scale_f32 v16, s[0:1], v15, v15, v3
	s_nop 0
	v_rcp_f32_e32 v16, v15
	s_nop 0
	v_mul_f32_e32 v3, v3, v16
	v_mul_f32_e32 v3, v14, v3
	v_cvt_pk_bf16_f32 v3, v3, s0
	ds_write_b16 v1, v3 offset:2640
	ds_read_u16 v3, v1 offset:2912
	s_waitcnt lgkmcnt(0)
	v_lshlrev_b32_e32 v3, 16, v3
	v_mul_f32_e32 v14, 0xbfb8aa3b, v3
	v_exp_f32_e32 v14, v14
	s_nop 0
	v_add_f32_e32 v14, 1.0, v14
	v_div_scale_f32 v15, s[0:1], v14, v14, v3
	s_nop 0
	v_rcp_f32_e32 v15, v14
	s_nop 0
	v_mul_f32_e32 v3, v3, v15
	v_mul_f32_e32 v3, v13, v3
	v_cvt_pk_bf16_f32 v3, v3, s0
	ds_write_b16 v1, v3 offset:2912
	ds_read_u16 v3, v1 offset:3184
	s_waitcnt lgkmcnt(0)
; #define LAS __attribute__((address_space(3)))
; #define LDS_WAIT() asm volatile("s_waitcnt lgkmcnt(0)" ::: "memory")
; DI unsigned cvtpk(float lo, float hi) { f32x2 v = {lo, hi}; bf16x2_t b = __builtin_convertvector(v, bf16x2_t); return __builtin_bit_cast(unsigned, b); }
; DI float bf2f(bf16 b) { return __uint_as_float(((unsigned)b) << 16); }
; DI float siluf_(float x) { return x / (1.f + __expf(-x)); }
; DI void g3_tile_out(bf16* g, const LAS unsigned char* R, int lane) {
;     LDS_WAIT();
; #pragma unroll
;     for (int it = 0; it < 8; ++it) { const int row = 4 * it + (lane >> 4), ch = lane & 15;
;         *(u32x4*)(g + (size_t)row * 512 + ch * 8) = *(const LAS u32x4*)(R + row * G3_PITCH + ch * 16); }
;     LDS_WAIT();
; DI void gla_stage3(const Ctx& c0, int layer, int unit, int cb, LAS unsigned char* lds) {
;     ...
;     for (int vb = 0; vb < 4; ++vb) { const float g = gn[32 * vb + r];
; #pragma unroll
;         for (int rg = 0; rg < 16; ++rg) { LAS bf16* e = (LAS bf16*)(R + (4 * hi) * G3_PITCH + r * 2 + ((rg & 3) + 8 * (rg >> 2)) * G3_PITCH + 64 * vb);
;             const float z = bf2f(*e);
;             *e = (bf16)(cvtpk(o[vb][rg] * rs[rg] * g * siluf_(z), 0.f) & 0xffffu); }
;         asm volatile("" ::: "memory"); }
;     g3_tile_out((bf16*)(c.ws + O_OGLA) + row0 * 512 + h * 128, R, lane);
	v_lshlrev_b32_e32 v3, 16, v3
	v_mul_f32_e32 v13, 0xbfb8aa3b, v3
	v_exp_f32_e32 v13, v13
	s_nop 0
	v_add_f32_e32 v13, 1.0, v13
	v_div_scale_f32 v14, s[0:1], v13, v13, v3
	s_nop 0
	v_rcp_f32_e32 v14, v13
	s_nop 0
	v_mul_f32_e32 v3, v3, v14
	v_mul_f32_e32 v3, v12, v3
	v_cvt_pk_bf16_f32 v3, v3, s0
	ds_write_b16 v1, v3 offset:3184
	ds_read_u16 v3, v1 offset:4544
	s_waitcnt lgkmcnt(0)
	v_lshlrev_b32_e32 v3, 16, v3
	v_mul_f32_e32 v12, 0xbfb8aa3b, v3
	v_exp_f32_e32 v12, v12
	s_nop 0
	v_add_f32_e32 v12, 1.0, v12
	v_div_scale_f32 v13, s[0:1], v12, v12, v3
	s_nop 0
	v_rcp_f32_e32 v13, v12
	s_nop 0
	v_mul_f32_e32 v3, v3, v13
	v_mul_f32_e32 v3, v11, v3
	v_cvt_pk_bf16_f32 v3, v3, s0
	ds_write_b16 v1, v3 offset:4544
	ds_read_u16 v3, v1 offset:4816
	s_waitcnt lgkmcnt(0)
	v_lshlrev_b32_e32 v3, 16, v3
	v_mul_f32_e32 v11, 0xbfb8aa3b, v3
	v_exp_f32_e32 v11, v11
	s_nop 0
	v_add_f32_e32 v11, 1.0, v11
	v_div_scale_f32 v12, s[0:1], v11, v11, v3
	s_nop 0
	v_rcp_f32_e32 v12, v11
	s_nop 0
	v_mul_f32_e32 v3, v3, v12
	v_mul_f32_e32 v3, v10, v3
	v_cvt_pk_bf16_f32 v3, v3, s0
	ds_write_b16 v1, v3 offset:4816
	ds_read_u16 v3, v1 offset:5088
	s_waitcnt lgkmcnt(0)
	v_lshlrev_b32_e32 v3, 16, v3
	v_mul_f32_e32 v10, 0xbfb8aa3b, v3
	v_exp_f32_e32 v10, v10
	s_nop 0
	v_add_f32_e32 v10, 1.0, v10
	v_div_scale_f32 v11, s[0:1], v10, v10, v3
	s_nop 0
	v_rcp_f32_e32 v11, v10
	s_nop 0
	v_mul_f32_e32 v3, v3, v11
	v_mul_f32_e32 v3, v9, v3
	v_cvt_pk_bf16_f32 v3, v3, s0
	ds_write_b16 v1, v3 offset:5088
	ds_read_u16 v3, v1 offset:5360
	s_waitcnt lgkmcnt(0)
	v_lshlrev_b32_e32 v3, 16, v3
	v_mul_f32_e32 v9, 0xbfb8aa3b, v3
	v_exp_f32_e32 v9, v9
	s_nop 0
	v_add_f32_e32 v9, 1.0, v9
	v_div_scale_f32 v10, s[0:1], v9, v9, v3
	s_nop 0
	v_rcp_f32_e32 v10, v9
	s_nop 0
	v_mul_f32_e32 v3, v3, v10
	v_mul_f32_e32 v3, v8, v3
	v_cvt_pk_bf16_f32 v3, v3, s0
	ds_write_b16 v1, v3 offset:5360
	ds_read_u16 v3, v1 offset:6720
	s_waitcnt lgkmcnt(0)
	v_lshlrev_b32_e32 v3, 16, v3
	v_mul_f32_e32 v8, 0xbfb8aa3b, v3
	v_exp_f32_e32 v8, v8
	s_nop 0
	v_add_f32_e32 v8, 1.0, v8
	v_div_scale_f32 v9, s[0:1], v8, v8, v3
	s_nop 0
	v_rcp_f32_e32 v9, v8
	s_nop 0
	v_mul_f32_e32 v3, v3, v9
	v_mul_f32_e32 v3, v7, v3
	v_cvt_pk_bf16_f32 v3, v3, s0
	ds_write_b16 v1, v3 offset:6720
	ds_read_u16 v3, v1 offset:6992
	s_waitcnt lgkmcnt(0)
	v_lshlrev_b32_e32 v3, 16, v3
	v_mul_f32_e32 v7, 0xbfb8aa3b, v3
	v_exp_f32_e32 v7, v7
	s_nop 0
	v_add_f32_e32 v7, 1.0, v7
	v_div_scale_f32 v8, s[0:1], v7, v7, v3
	s_nop 0
	v_rcp_f32_e32 v8, v7
	s_nop 0
	v_mul_f32_e32 v3, v3, v8
	v_mul_f32_e32 v3, v6, v3
	v_cvt_pk_bf16_f32 v3, v3, s0
	ds_write_b16 v1, v3 offset:6992
	ds_read_u16 v3, v1 offset:7264
	s_waitcnt lgkmcnt(0)
	v_lshlrev_b32_e32 v3, 16, v3
	v_mul_f32_e32 v6, 0xbfb8aa3b, v3
	v_exp_f32_e32 v6, v6
	s_nop 0
	v_add_f32_e32 v6, 1.0, v6
	v_div_scale_f32 v7, s[0:1], v6, v6, v3
	s_nop 0
	v_rcp_f32_e32 v7, v6
	s_nop 0
	v_mul_f32_e32 v3, v3, v7
	v_mul_f32_e32 v3, v5, v3
	v_cvt_pk_bf16_f32 v3, v3, s0
	ds_write_b16 v1, v3 offset:7264
	ds_read_u16 v3, v1 offset:7536
	s_waitcnt lgkmcnt(0)
	v_lshlrev_b32_e32 v3, 16, v3
	v_mul_f32_e32 v4, 0xbfb8aa3b, v3
	v_exp_f32_e32 v4, v4
	s_nop 0
	v_add_f32_e32 v4, 1.0, v4
	v_div_scale_f32 v5, s[0:1], v4, v4, v3
	s_nop 0
	v_rcp_f32_e32 v5, v4
	s_nop 0
	v_mul_f32_e32 v3, v3, v5
	v_mul_f32_e32 v2, v2, v3
	v_cvt_pk_bf16_f32 v2, v2, s0
	ds_write_b16 v1, v2 offset:7536
	s_waitcnt lgkmcnt(0)
	ds_read_b128 v[2:5], v92
	v_lshl_add_u64 v[6:7], v[90:91], 0, s[22:23]
	v_lshl_add_u64 v[8:9], v[6:7], 0, v[66:67]
	s_waitcnt lgkmcnt(0)
	global_store_dwordx4 v[8:9], v[2:5], off
	ds_read_b128 v[2:5], v92 offset:1088
	v_lshl_add_u64 v[8:9], v[6:7], 0, v[68:69]
	s_waitcnt lgkmcnt(0)
	global_store_dwordx4 v[8:9], v[2:5], off
	ds_read_b128 v[2:5], v92 offset:2176
	v_lshl_add_u64 v[8:9], v[6:7], 0, v[70:71]
	s_waitcnt lgkmcnt(0)
	global_store_dwordx4 v[8:9], v[2:5], off
	ds_read_b128 v[2:5], v92 offset:3264
	v_lshl_add_u64 v[8:9], v[6:7], 0, v[72:73]
	s_waitcnt lgkmcnt(0)
	global_store_dwordx4 v[8:9], v[2:5], off
	ds_read_b128 v[2:5], v92 offset:4352
	v_lshl_add_u64 v[8:9], v[6:7], 0, v[74:75]
	s_waitcnt lgkmcnt(0)
	global_store_dwordx4 v[8:9], v[2:5], off
	ds_read_b128 v[2:5], v92 offset:5440
	v_lshl_add_u64 v[8:9], v[6:7], 0, v[76:77]
	s_waitcnt lgkmcnt(0)
	global_store_dwordx4 v[8:9], v[2:5], off
	ds_read_b128 v[2:5], v92 offset:6528
	v_lshl_add_u64 v[8:9], v[6:7], 0, v[78:79]
	v_lshl_add_u64 v[6:7], v[6:7], 0, v[80:81]
	s_waitcnt lgkmcnt(0)
	global_store_dwordx4 v[8:9], v[2:5], off
	ds_read_b128 v[2:5], v92 offset:7616
	s_waitcnt lgkmcnt(0)
	global_store_dwordx4 v[6:7], v[2:5], off
	s_waitcnt lgkmcnt(0)
	s_cbranch_scc1 .LBB0_604

; DI float bflo(unsigned w) { return __uint_as_float(w << 16); }
; DI float bfhi(unsigned w) { return __uint_as_float(w & 0xffff0000u); }
; DI void post_phase(const Ctx& c0, int layer) {
;     ...
;     for (int m = gw; m < T; m += NGW) {
;         float o[16]; float ss = 0.f;
; #pragma unroll
;         for (int j = 0; j < 2; ++j) { const u32x4 w = *(const u32x4*)(ob + (size_t)m * DM + 512 * j + 8 * lane);
;             o[8 * j + 0] = bflo(w.x); o[8 * j + 1] = bfhi(w.x); o[8 * j + 2] = bflo(w.y); o[8 * j + 3] = bfhi(w.y); o[8 * j + 4] = bflo(w.z); o[8 * j + 5] = bfhi(w.z); o[8 * j + 6] = bflo(w.w); o[8 * j + 7] = bfhi(w.w); }
; #pragma unroll
;         for (int e = 0; e < 16; ++e) ss += o[e] * o[e];
;         const float rr = 1.f / sqrtf(wave_sum(ss) * (1.f / 1024.f) + EPS);
;         float xn[16]; float s2 = 0.f;
; #pragma unroll
;         for (int j = 0; j < 2; ++j)
; #pragma unroll
;             for (int q = 0; q < 2; ++q) { const size_t off = (size_t)m * DM + 512 * j + 8 * lane + 4 * q; const f32x4 xv = *(const f32x4*)(xin + off); const f32x4 g = *(const f32x4*)(gp + 512 * j + 8 * lane + 4 * q);
;                 f32x4 y;
; #pragma unroll
;                 for (int k = 0; k < 4; ++k) { y[k] = xv[k] + o[8 * j + 4 * q + k] * rr * g[k]; xn[8 * j + 4 * q + k] = y[k]; s2 += y[k] * y[k]; }
;                 *(f32x4*)(c.out + off) = y; }
.LBB0_835:
	global_load_dwordx4 v[20:23], v[6:7], off
	global_load_dwordx4 v[24:27], v[6:7], off offset:1024
	v_lshl_add_u64 v[36:37], s[12:13], 0, v[8:9]
	global_load_dwordx4 v[28:31], v[2:3], off
	global_load_dwordx4 v[32:35], v[36:37], off
	v_lshl_add_u64 v[10:11], s[0:1], 0, v[8:9]
	s_add_i32 s8, s8, s74
	v_lshl_add_u64 v[8:9], v[8:9], 0, s[4:5]
	s_cmp_lt_i32 s8, 0x8000
	s_waitcnt vmcnt(0) lgkmcnt(0)
	v_lshlrev_b32_e32 v38, 16, v20
	v_and_b32_e32 v39, 0xffff0000, v20
	v_lshlrev_b32_e32 v20, 16, v21
	v_and_b32_e32 v21, 0xffff0000, v21
	v_lshlrev_b32_e32 v46, 16, v24
	v_and_b32_e32 v47, 0xffff0000, v24
	v_lshlrev_b32_e32 v48, 16, v25
	v_and_b32_e32 v49, 0xffff0000, v25
	v_pk_mul_f32 v[24:25], v[38:39], v[38:39]
	v_and_b32_e32 v40, 0xffff0000, v27
	v_lshlrev_b32_e32 v41, 16, v27
	v_lshlrev_b32_e32 v50, 16, v26
	v_and_b32_e32 v51, 0xffff0000, v26
	v_pk_mul_f32 v[26:27], v[20:21], v[20:21]
	v_add_f32_e32 v19, v24, v25
	v_lshlrev_b32_e32 v42, 16, v22
	v_and_b32_e32 v43, 0xffff0000, v22
	v_add_f32_e32 v19, v26, v19
	v_pk_mul_f32 v[52:53], v[42:43], v[42:43]
	v_add_f32_e32 v19, v27, v19
	v_lshlrev_b32_e32 v44, 16, v23
	v_and_b32_e32 v45, 0xffff0000, v23
	v_add_f32_e32 v19, v52, v19
	v_pk_mul_f32 v[54:55], v[44:45], v[44:45]
	v_add_f32_e32 v19, v53, v19
	v_add_f32_e32 v19, v54, v19
	v_pk_mul_f32 v[56:57], v[46:47], v[46:47]
	v_add_f32_e32 v19, v55, v19
	v_add_f32_e32 v19, v56, v19
	v_pk_mul_f32 v[58:59], v[48:49], v[48:49]
	v_add_f32_e32 v19, v57, v19
	v_add_f32_e32 v19, v58, v19
	v_pk_mul_f32 v[60:61], v[50:51], v[50:51]
	v_add_f32_e32 v19, v59, v19
	v_add_f32_e32 v19, v60, v19
	v_pk_mul_f32 v[22:23], v[40:41], v[40:41]
	v_add_f32_e32 v19, v61, v19
	v_add_f32_e32 v19, v23, v19
	v_add_f32_e32 v19, v22, v19
	ds_bpermute_b32 v22, v1, v19
	s_waitcnt lgkmcnt(0)
	v_add_f32_e32 v19, v19, v22
	ds_bpermute_b32 v22, v12, v19
	s_waitcnt lgkmcnt(0)
	v_add_f32_e32 v19, v19, v22
	ds_bpermute_b32 v22, v13, v19
	s_waitcnt lgkmcnt(0)
	v_add_f32_e32 v19, v19, v22
	ds_bpermute_b32 v22, v14, v19
	s_waitcnt lgkmcnt(0)
	v_add_f32_e32 v19, v19, v22
	ds_bpermute_b32 v22, v15, v19
	s_waitcnt lgkmcnt(0)
	v_add_f32_e32 v19, v19, v22
	ds_bpermute_b32 v22, v16, v19
	s_waitcnt lgkmcnt(0)
	v_add_f32_e32 v19, v19, v22
	v_fmamk_f32 v19, v19, 0x3a800000, v17
	v_mul_f32_e32 v22, 0x4f800000, v19
	v_cmp_gt_f32_e32 vcc, s6, v19
	s_nop 1
	v_cndmask_b32_e32 v19, v19, v22, vcc
	v_sqrt_f32_e32 v22, v19
	s_nop 0
	v_add_u32_e32 v23, -1, v22
	v_add_u32_e32 v24, 1, v22
	v_fma_f32 v25, -v23, v22, v19
	v_fma_f32 v26, -v24, v22, v19
	v_cmp_ge_f32_e64 s[10:11], 0, v25
	s_nop 1
	v_cndmask_b32_e64 v22, v22, v23, s[10:11]
	v_cmp_lt_f32_e64 s[10:11], 0, v26
	s_nop 1
	v_cndmask_b32_e64 v22, v22, v24, s[10:11]
	v_mul_f32_e32 v23, 0x37800000, v22
	v_cndmask_b32_e32 v22, v22, v23, vcc
	v_cmp_class_f32_e32 vcc, v19, v18
	s_nop 1
	v_cndmask_b32_e32 v19, v22, v19, vcc
	v_rcp_f32_e32 v52, v19
	s_nop 0
	v_pk_mul_f32 v[22:23], v[52:53], v[38:39] op_sel_hi:[0,1]
	v_pk_mul_f32 v[24:25], v[52:53], v[20:21] op_sel_hi:[0,1]
	v_pk_fma_f32 v[20:21], v[28:29], v[22:23], v[32:33]
	v_pk_fma_f32 v[22:23], v[30:31], v[24:25], v[34:35]
	global_store_dwordx4 v[10:11], v[20:23], off
	global_load_dwordx4 v[24:27], v[36:37], off offset:16
	global_load_dwordx4 v[28:31], v[2:3], off offset:16
	v_pk_mul_f32 v[32:33], v[52:53], v[42:43] op_sel_hi:[0,1]
	v_pk_mul_f32 v[34:35], v[52:53], v[44:45] op_sel_hi:[0,1]
	v_pk_mul_f32 v[38:39], v[52:53], v[46:47] op_sel_hi:[0,1]
	v_pk_mul_f32 v[42:43], v[52:53], v[48:49] op_sel_hi:[0,1]
	v_pk_mul_f32 v[40:41], v[52:53], v[40:41] op_sel_hi:[0,1]
	v_pk_mul_f32 v[46:47], v[20:21], v[20:21]
	v_pk_mul_f32 v[48:49], v[22:23], v[22:23]
	v_add_f32_e32 v19, v46, v47
	v_add_f32_e32 v19, v48, v19
	v_add_f32_e32 v19, v49, v19
	v_add_co_u32_e32 v44, vcc, s7, v6
	s_waitcnt vmcnt(0)
	v_pk_fma_f32 v[24:25], v[28:29], v[32:33], v[24:25]
	v_pk_fma_f32 v[26:27], v[30:31], v[34:35], v[26:27]
	global_store_dwordx4 v[10:11], v[24:27], off offset:16
	global_load_dwordx4 v[28:31], v[36:37], off offset:2048
	global_load_dwordx4 v[32:35], v[2:3], off offset:2048
	v_pk_mul_f32 v[46:47], v[24:25], v[24:25]
	v_pk_mul_f32 v[48:49], v[26:27], v[26:27]
	v_add_f32_e32 v19, v46, v19
	v_add_f32_e32 v19, v47, v19
	v_add_f32_e32 v19, v48, v19
	v_add_f32_e32 v19, v49, v19
	v_addc_co_u32_e32 v45, vcc, -1, v7, vcc
	s_waitcnt vmcnt(0)
; DI unsigned cvtpk(float lo, float hi) { f32x2 v = {lo, hi}; bf16x2_t b = __builtin_convertvector(v, bf16x2_t); return __builtin_bit_cast(unsigned, b); }
; DI void post_phase(const Ctx& c0, int layer) {
;     ...
;         for (int e = 0; e < 16; ++e) ss += o[e] * o[e];
;         const float rr = 1.f / sqrtf(wave_sum(ss) * (1.f / 1024.f) + EPS);
;         float xn[16]; float s2 = 0.f;
; #pragma unroll
;         for (int j = 0; j < 2; ++j)
; #pragma unroll
;             for (int q = 0; q < 2; ++q) { const size_t off = (size_t)m * DM + 512 * j + 8 * lane + 4 * q; const f32x4 xv = *(const f32x4*)(xin + off); const f32x4 g = *(const f32x4*)(gp + 512 * j + 8 * lane + 4 * q);
;                 f32x4 y;
; #pragma unroll
;                 for (int k = 0; k < 4; ++k) { y[k] = xv[k] + o[8 * j + 4 * q + k] * rr * g[k]; xn[8 * j + 4 * q + k] = y[k]; s2 += y[k] * y[k]; }
;                 *(f32x4*)(c.out + off) = y; }
;         if (layer == 0) {
;             const float r2 = 1.f / sqrtf(wave_sum(s2) * (1.f / 1024.f) + EPS);
;             bf16* hb = (bf16*)(c.ws + O_HB) + (size_t)m * DM;
; #pragma unroll
;             for (int j = 0; j < 2; ++j) { const f32x4 g0 = *(const f32x4*)(gn + 512 * j + 8 * lane), g1 = *(const f32x4*)(gn + 512 * j + 8 * lane + 4);
;                 u32x4 w; w.x = cvtpk(xn[8 * j] * r2 * g0[0], xn[8 * j + 1] * r2 * g0[1]); w.y = cvtpk(xn[8 * j + 2] * r2 * g0[2], xn[8 * j + 3] * r2 * g0[3]);
;                 w.z = cvtpk(xn[8 * j + 4] * r2 * g1[0], xn[8 * j + 5] * r2 * g1[1]); w.w = cvtpk(xn[8 * j + 6] * r2 * g1[2], xn[8 * j + 7] * r2 * g1[3]);
;                 *(u32x4*)(hb + 512 * j + 8 * lane) = w; }
	v_pk_fma_f32 v[28:29], v[32:33], v[38:39], v[28:29]
	v_pk_fma_f32 v[30:31], v[34:35], v[42:43], v[30:31]
	global_store_dwordx4 v[10:11], v[28:31], off offset:2048
	global_load_dwordx4 v[32:35], v[36:37], off offset:2064
	s_nop 0
	global_load_dwordx4 v[36:39], v[2:3], off offset:2064
	v_pk_mul_f32 v[42:43], v[52:53], v[50:51] op_sel_hi:[0,1]
	v_pk_mul_f32 v[46:47], v[28:29], v[28:29]
	v_pk_mul_f32 v[48:49], v[30:31], v[30:31]
	v_add_f32_e32 v19, v46, v19
	v_add_f32_e32 v19, v47, v19
	v_add_f32_e32 v19, v48, v19
	v_add_f32_e32 v19, v49, v19
	s_waitcnt vmcnt(0)
	v_pk_fma_f32 v[32:33], v[36:37], v[42:43], v[32:33]
	v_pk_fma_f32 v[34:35], v[38:39], v[40:41], v[34:35] op_sel:[0,1,0] op_sel_hi:[1,0,1]
	global_store_dwordx4 v[10:11], v[32:35], off offset:2064
	global_load_dwordx4 v[36:39], v[4:5], off offset:16
	global_load_dwordx4 v[40:43], v[4:5], off
	v_pk_mul_f32 v[10:11], v[32:33], v[32:33]
	v_pk_mul_f32 v[46:47], v[34:35], v[34:35]
	v_add_f32_e32 v10, v10, v19
	v_add_f32_e32 v10, v11, v10
	v_add_f32_e32 v10, v46, v10
	v_add_f32_e32 v10, v47, v10
	ds_bpermute_b32 v11, v1, v10
	s_waitcnt lgkmcnt(0)
	v_add_f32_e32 v10, v10, v11
	ds_bpermute_b32 v11, v12, v10
	s_waitcnt lgkmcnt(0)
	v_add_f32_e32 v10, v10, v11
	ds_bpermute_b32 v11, v13, v10
	s_waitcnt lgkmcnt(0)
	v_add_f32_e32 v10, v10, v11
	ds_bpermute_b32 v11, v14, v10
	s_waitcnt lgkmcnt(0)
	v_add_f32_e32 v10, v10, v11
	ds_bpermute_b32 v11, v15, v10
	s_waitcnt lgkmcnt(0)
	v_add_f32_e32 v10, v10, v11
	ds_bpermute_b32 v11, v16, v10
	s_waitcnt lgkmcnt(0)
	v_add_f32_e32 v10, v10, v11
	v_fmamk_f32 v10, v10, 0x3a800000, v17
	v_mul_f32_e32 v11, 0x4f800000, v10
	v_cmp_gt_f32_e32 vcc, s6, v10
	s_nop 1
	v_cndmask_b32_e32 v10, v10, v11, vcc
	v_sqrt_f32_e32 v11, v10
	s_nop 0
	v_add_u32_e32 v19, -1, v11
	v_add_u32_e32 v46, 1, v11
	v_fma_f32 v47, -v19, v11, v10
	v_fma_f32 v48, -v46, v11, v10
	v_cmp_ge_f32_e64 s[10:11], 0, v47
	s_nop 1
	v_cndmask_b32_e64 v11, v11, v19, s[10:11]
	v_cmp_lt_f32_e64 s[10:11], 0, v48
	s_nop 1
	v_cndmask_b32_e64 v11, v11, v46, s[10:11]
	v_mul_f32_e32 v19, 0x37800000, v11
	v_cndmask_b32_e32 v11, v11, v19, vcc
	v_cmp_class_f32_e32 vcc, v10, v18
	s_nop 1
	v_cndmask_b32_e32 v10, v11, v10, vcc
	v_div_scale_f32 v11, s[10:11], v10, v10, 1.0
	v_rcp_f32_e32 v46, v11
	v_div_scale_f32 v19, vcc, 1.0, v10, 1.0
	v_fma_f32 v47, -v11, v46, 1.0
	v_fmac_f32_e32 v46, v47, v46
	v_mul_f32_e32 v47, v19, v46
	v_fma_f32 v48, -v11, v47, v19
	v_fmac_f32_e32 v47, v48, v46
	v_fma_f32 v11, -v11, v47, v19
	v_div_fmas_f32 v11, v11, v46, v47
	v_rcp_f32_e32 v10, v10
	s_nop 0
	v_pk_mul_f32 v[20:21], v[20:21], v[10:11] op_sel_hi:[1,0]
	v_pk_mul_f32 v[22:23], v[22:23], v[10:11] op_sel_hi:[1,0]
	v_pk_mul_f32 v[24:25], v[24:25], v[10:11] op_sel_hi:[1,0]
	v_pk_mul_f32 v[26:27], v[26:27], v[10:11] op_sel_hi:[1,0]
	s_waitcnt vmcnt(0)
	v_pk_mul_f32 v[20:21], v[40:41], v[20:21]
	v_pk_mul_f32 v[22:23], v[42:43], v[22:23]
	v_pk_mul_f32 v[24:25], v[36:37], v[24:25]
	v_pk_mul_f32 v[26:27], v[38:39], v[26:27]
	v_cvt_pk_bf16_f32 v20, v20, v21
	v_cvt_pk_bf16_f32 v21, v22, v23
	v_cvt_pk_bf16_f32 v22, v24, v25
	v_cvt_pk_bf16_f32 v23, v26, v27
	global_store_dwordx4 v[44:45], v[20:23], off
	global_load_dwordx4 v[20:23], v[4:5], off offset:2048
	s_nop 0
	global_load_dwordx4 v[24:27], v[4:5], off offset:2064
	v_pk_mul_f32 v[28:29], v[28:29], v[10:11] op_sel_hi:[1,0]
	v_pk_mul_f32 v[30:31], v[30:31], v[10:11] op_sel_hi:[1,0]
	v_pk_mul_f32 v[32:33], v[32:33], v[10:11] op_sel_hi:[1,0]
	v_pk_mul_f32 v[10:11], v[34:35], v[10:11] op_sel_hi:[1,0]
	v_add_co_u32_e32 v36, vcc, 0xf4f00400, v6
	s_waitcnt vmcnt(0)
	v_pk_mul_f32 v[20:21], v[20:21], v[28:29]
	v_pk_mul_f32 v[22:23], v[22:23], v[30:31]
	v_pk_mul_f32 v[24:25], v[24:25], v[32:33]
	v_pk_mul_f32 v[10:11], v[26:27], v[10:11]
	v_addc_co_u32_e32 v37, vcc, -1, v7, vcc
	v_lshl_add_u64 v[6:7], v[6:7], 0, s[2:3]
	v_cvt_pk_bf16_f32 v20, v20, v21
	v_cvt_pk_bf16_f32 v21, v22, v23
	v_cvt_pk_bf16_f32 v22, v24, v25
	v_cvt_pk_bf16_f32 v23, v10, v11
	global_store_dwordx4 v[36:37], v[20:23], off
	s_cbranch_scc1 .LBB0_835

; #define LAS __attribute__((address_space(3)))
; DI float bflo(unsigned w) { return __uint_as_float(w << 16); }
; DI float bfhi(unsigned w) { return __uint_as_float(w & 0xffff0000u); }
; DI void gla_stage1(const Ctx& c0, int layer, int unit, LAS unsigned char* lds) {
;     ...
;     const int cc = tid >> 3, ch = tid & 7;
; #pragma unroll
;     for (int it = 0; it < 2; ++it) { const int idx = tid + 512 * it, vc_ = idx & 15, c_ = idx >> 4;
;         const u32x4 v = *(const u32x4*)(gv + (row0 + c_) * 512 + h * 128 + vc_ * 8);
;         *(LAS u32x4*)(lds + G1_VI + (vc_ >> 2) * 4096 + c_ * 64 + (vc_ & 3) * 16) = v; }
;     {
;         float ga[16];
;         { const u32x4 g0 = *(const u32x4*)(misc + (row0 + cc) * 64 + 32), g1 = *(const u32x4*)(misc + (row0 + cc) * 64 + 40);
;           ga[0] = bflo(g0.x); ga[1] = bfhi(g0.x); ga[2] = bflo(g0.y); ga[3] = bfhi(g0.y); ga[4] = bflo(g0.z); ga[5] = bfhi(g0.z); ga[6] = bflo(g0.w); ga[7] = bfhi(g0.w);
;           ga[8] = bflo(g1.x); ga[9] = bfhi(g1.x); ga[10] = bflo(g1.y); ga[11] = bfhi(g1.y); ga[12] = bflo(g1.z); ga[13] = bfhi(g1.z); ga[14] = bflo(g1.w); ga[15] = bfhi(g1.w); }
;         f32x4 a0 = *(const f32x4*)(ba + 8 * ch), a1 = *(const f32x4*)(ba + 8 * ch + 4);
;         const float* wap = Wa + 8 * ch; asm volatile("" : "+v"(wap));
; #pragma unroll
;         for (int rr = 0; rr < 16; ++rr) { const f32x4 w0 = *(const f32x4*)(wap + rr * 256), w1 = *(const f32x4*)(wap + rr * 256 + 4); a0 += w0 * ga[rr]; a1 += w1 * ga[rr]; }
.LBB0_1016:
	s_mov_b64 s[98:99], 0x1000
	v_mov_b32_e32 v10, v151
	s_mov_b64 s[74:75], s[84:85]
	s_mov_b64 s[84:85], s[86:87]
	s_ashr_i32 s74, s82, 8
	s_ashr_i32 s75, s74, 31
	s_lshl_b32 s0, s82, 6
	s_bfe_u32 s81, s82, 0x20006
	s_lshl_b64 s[86:87], s[74:75], 12
	s_and_b32 s0, s0, 0xfc0
	s_or_b32 s86, s86, s0
	s_lshl_b32 s0, s81, 8
	v_and_b32_e32 v2, 15, v10
	s_add_u32 s74, s84, s0
	s_addc_u32 s75, s85, 0
	v_lshlrev_b32_e32 v48, 4, v2
	v_lshl_add_u64 v[2:3], s[74:75], 0, v[48:49]
	s_mov_b64 s[74:75], 0xf500000
	v_lshl_add_u64 v[6:7], v[2:3], 0, s[74:75]
	v_lshlrev_b32_e32 v2, 10, v10
	v_lshlrev_b32_e32 v3, 4, v10
	v_ashrrev_i32_e32 v8, 4, v10
	v_and_b32_e32 v2, 0x3000, v2
	v_and_b32_e32 v11, 48, v3
	v_ashrrev_i32_e32 v9, 31, v8
	v_add3_u32 v13, 0, v2, v11
	v_lshl_add_u64 v[2:3], s[86:87], 0, v[8:9]
	v_lshlrev_b64 v[2:3], 10, v[2:3]
	v_lshl_add_u64 v[2:3], v[6:7], 0, v[2:3]
	global_load_dwordx4 v[2:5], v[2:3], off
	v_add_u32_e32 v72, 0x200, v10
	v_ashrrev_i32_e32 v78, 4, v72
	v_ashrrev_i32_e32 v79, 31, v78
	v_lshl_add_u64 v[76:77], s[86:87], 0, v[78:79]
	v_lshlrev_b64 v[74:75], 10, v[76:77]
	v_lshl_add_u64 v[80:81], v[6:7], 0, v[74:75]
	global_load_dwordx4 v[68:71], v[80:81], off
	v_lshl_add_u32 v8, v8, 6, v13
	v_ashrrev_i32_e32 v12, 3, v10
	s_mov_b64 vcc, 0x1b500000
	s_add_u32 s74, s33, s0
	s_addc_u32 s75, s77, 0
	v_and_b32_e32 v32, 7, v10
	v_lshlrev_b32_e32 v48, 5, v32
	v_lshl_add_u64 v[24:25], s[74:75], 0, v[48:49]
	global_load_dwordx4 v[54:57], v[24:25], off offset:16
	global_load_dwordx4 v[42:45], v[24:25], off
	s_add_u32 s88, s78, s0
	s_addc_u32 s89, s79, 0
	global_load_dwordx4 v[38:41], v48, s[88:89] offset:1024
	global_load_dwordx4 v[72:75], v48, s[88:89] offset:1040
	v_lshl_add_u64 v[244:245], v[24:25], 0, s[98:99]
	v_lshl_add_u64 v[246:247], v[244:245], 0, s[98:99]
	v_lshl_add_u64 v[248:249], v[246:247], 0, s[98:99]
	s_movk_i32 s0, 0x104
	v_lshl_add_u32 v33, v10, 2, 0
	s_waitcnt vmcnt(5) lgkmcnt(0)
	global_load_dwordx4 v[180:183], v[248:249], off offset:3072
	global_load_dwordx4 v[176:179], v[248:249], off offset:2064
	global_load_dwordx4 v[172:175], v[248:249], off offset:2048
	global_load_dwordx4 v[168:171], v[248:249], off offset:1040
	global_load_dwordx4 v[164:167], v[248:249], off offset:1024
	global_load_dwordx4 v[114:117], v[244:245], off offset:3088
	global_load_dwordx4 v[110:113], v[244:245], off offset:3072
	global_load_dwordx4 v[106:109], v[244:245], off offset:2064
	global_load_dwordx4 v[96:99], v[244:245], off offset:2048
	global_load_dwordx4 v[90:93], v[244:245], off offset:1040
	global_load_dwordx4 v[84:87], v[244:245], off offset:1024
	ds_write_b128 v8, v[2:5] offset:43264
	v_lshl_add_u32 v6, v78, 6, v13
	v_ashrrev_i32_e32 v13, 31, v12
	s_waitcnt vmcnt(15) lgkmcnt(0)
	global_load_dwordx4 v[138:141], v[246:247], off offset:2064
	global_load_dwordx4 v[134:137], v[246:247], off offset:2048
	global_load_dwordx4 v[130:133], v[246:247], off offset:1040
	global_load_dwordx4 v[126:129], v[246:247], off offset:1024
	global_load_dwordx4 v[122:125], v[246:247], off offset:16
	global_load_dwordx4 v[118:121], v[246:247], off
	ds_write_b128 v6, v[68:71] offset:43264
	v_lshl_add_u64 v[2:3], s[86:87], 0, v[12:13]
	v_lshlrev_b64 v[4:5], 7, v[2:3]
	v_lshl_add_u64 v[4:5], s[84:85], 0, v[4:5]
	v_lshl_add_u64 v[8:9], v[4:5], 0, vcc
	global_load_dwordx4 v[4:7], v[8:9], off offset:64
	global_load_dwordx4 v[34:37], v[8:9], off offset:80
	v_mul_lo_u32 v13, v12, s0
	v_add3_u32 v13, 0, v13, v48
	s_movk_i32 s0, 0x820
	s_waitcnt vmcnt(0) lgkmcnt(0)
	global_load_dwordx4 v[160:163], v[248:249], off offset:16
	global_load_dwordx4 v[156:159], v[248:249], off
	global_load_dwordx4 v[146:149], v[246:247], off offset:3088
	global_load_dwordx4 v[142:145], v[246:247], off offset:3072
	global_load_dwordx4 v[76:79], v[24:25], off offset:1040
	global_load_dwordx4 v[68:71], v[24:25], off offset:1024
	v_lshlrev_b32_e32 v58, 16, v4
	v_and_b32_e32 v60, 0xffff0000, v4
	v_lshlrev_b32_e32 v66, 16, v6
	v_and_b32_e32 v30, 0xffff0000, v6
	v_lshlrev_b32_e32 v22, 16, v34
	v_and_b32_e32 v20, 0xffff0000, v34
	v_lshlrev_b32_e32 v18, 16, v35
	v_and_b32_e32 v16, 0xffff0000, v35
	v_lshlrev_b32_e32 v14, 16, v36
	v_and_b32_e32 v8, 0xffff0000, v36
	v_lshlrev_b32_e32 v4, 16, v37
	v_and_b32_e32 v6, 0xffff0000, v37
	v_lshlrev_b32_e32 v62, 16, v5
	v_and_b32_e32 v64, 0xffff0000, v5
	v_lshlrev_b32_e32 v28, 16, v7
	v_and_b32_e32 v26, 0xffff0000, v7
	s_waitcnt vmcnt(6) lgkmcnt(0)
	global_load_dwordx4 v[80:83], v[24:25], off offset:2064
	global_load_dwordx4 v[34:37], v[24:25], off offset:2048
	v_pk_fma_f32 v[42:43], v[58:59], v[42:43], v[38:39] op_sel_hi:[0,1,1]
	v_pk_fma_f32 v[44:45], v[58:59], v[44:45], v[40:41] op_sel_hi:[0,1,1]
	v_pk_fma_f32 v[54:55], v[58:59], v[54:55], v[72:73] op_sel_hi:[0,1,1]
	v_pk_fma_f32 v[56:57], v[58:59], v[56:57], v[74:75] op_sel_hi:[0,1,1]
	v_lshl_add_u64 v[58:59], v[24:25], 0, s[98:99]
	s_waitcnt vmcnt(2) lgkmcnt(0)
	global_load_dwordx4 v[38:41], v[24:25], off offset:3088
	global_load_dwordx4 v[72:75], v[24:25], off offset:3072
	v_pk_fma_f32 v[44:45], v[60:61], v[70:71], v[44:45] op_sel_hi:[0,1,1]
	v_pk_fma_f32 v[42:43], v[60:61], v[68:69], v[42:43] op_sel_hi:[0,1,1]
	v_pk_fma_f32 v[56:57], v[60:61], v[78:79], v[56:57] op_sel_hi:[0,1,1]
	v_pk_fma_f32 v[54:55], v[60:61], v[76:77], v[54:55] op_sel_hi:[0,1,1]
	s_waitcnt vmcnt(2) lgkmcnt(0)
	global_load_dwordx4 v[76:79], v[244:245], off offset:16
	global_load_dwordx4 v[68:71], v[244:245], off
	v_pk_fma_f32 v[42:43], v[62:63], v[34:35], v[42:43] op_sel_hi:[0,1,1]
	v_pk_fma_f32 v[44:45], v[62:63], v[36:37], v[44:45] op_sel_hi:[0,1,1]
	v_pk_fma_f32 v[54:55], v[62:63], v[80:81], v[54:55] op_sel_hi:[0,1,1]
	v_pk_fma_f32 v[56:57], v[62:63], v[82:83], v[56:57] op_sel_hi:[0,1,1]
	s_waitcnt vmcnt(2) lgkmcnt(0)
; DI void gla_stage1(const Ctx& c0, int layer, int unit, LAS unsigned char* lds) {
;     ...
;         for (int rr = 0; rr < 16; ++rr) { const f32x4 w0 = *(const f32x4*)(wap + rr * 256), w1 = *(const f32x4*)(wap + rr * 256 + 4); a0 += w0 * ga[rr]; a1 += w1 * ga[rr]; }
	v_pk_fma_f32 v[44:45], v[64:65], v[74:75], v[44:45] op_sel_hi:[0,1,1]
	v_pk_fma_f32 v[42:43], v[64:65], v[72:73], v[42:43] op_sel_hi:[0,1,1]
	v_pk_fma_f32 v[56:57], v[64:65], v[40:41], v[56:57] op_sel_hi:[0,1,1]
	v_pk_fma_f32 v[54:55], v[64:65], v[38:39], v[54:55] op_sel_hi:[0,1,1]
	s_waitcnt vmcnt(0) lgkmcnt(0)
	v_pk_fma_f32 v[42:43], v[66:67], v[68:69], v[42:43] op_sel_hi:[0,1,1]
	v_pk_fma_f32 v[44:45], v[66:67], v[70:71], v[44:45] op_sel_hi:[0,1,1]
	v_pk_fma_f32 v[54:55], v[66:67], v[76:77], v[54:55] op_sel_hi:[0,1,1]
	v_pk_fma_f32 v[56:57], v[66:67], v[78:79], v[56:57] op_sel_hi:[0,1,1]
	s_waitcnt vmcnt(20) lgkmcnt(0)
	v_pk_fma_f32 v[44:45], v[30:31], v[86:87], v[44:45] op_sel_hi:[0,1,1]
	v_pk_fma_f32 v[42:43], v[30:31], v[84:85], v[42:43] op_sel_hi:[0,1,1]
	v_pk_fma_f32 v[56:57], v[30:31], v[92:93], v[56:57] op_sel_hi:[0,1,1]
	v_pk_fma_f32 v[30:31], v[30:31], v[90:91], v[54:55] op_sel_hi:[0,1,1]
	s_waitcnt vmcnt(3) lgkmcnt(0)
	v_pk_fma_f32 v[42:43], v[28:29], v[96:97], v[42:43] op_sel_hi:[0,1,1]
	v_pk_fma_f32 v[44:45], v[28:29], v[98:99], v[44:45] op_sel_hi:[0,1,1]
	v_pk_fma_f32 v[38:39], v[28:29], v[106:107], v[30:31] op_sel_hi:[0,1,1]
	v_pk_fma_f32 v[40:41], v[28:29], v[108:109], v[56:57] op_sel_hi:[0,1,1]
	s_waitcnt vmcnt(3) lgkmcnt(0)
	v_pk_fma_f32 v[30:31], v[26:27], v[112:113], v[44:45] op_sel_hi:[0,1,1]
	v_lshl_add_u64 v[44:45], v[58:59], 0, s[98:99]
	v_pk_fma_f32 v[42:43], v[26:27], v[110:111], v[42:43] op_sel_hi:[0,1,1]
	s_nop 0
	v_pk_fma_f32 v[40:41], v[26:27], v[116:117], v[40:41] op_sel_hi:[0,1,1]
	v_pk_fma_f32 v[38:39], v[26:27], v[114:115], v[38:39] op_sel_hi:[0,1,1]
	v_lshl_add_u64 v[24:25], v[44:45], 0, s[98:99]
	s_waitcnt vmcnt(3) lgkmcnt(0)
	v_pk_fma_f32 v[42:43], v[22:23], v[118:119], v[42:43] op_sel_hi:[0,1,1]
	v_pk_fma_f32 v[30:31], v[22:23], v[120:121], v[30:31] op_sel_hi:[0,1,1]
	v_pk_fma_f32 v[38:39], v[22:23], v[122:123], v[38:39] op_sel_hi:[0,1,1]
	v_pk_fma_f32 v[22:23], v[22:23], v[124:125], v[40:41] op_sel_hi:[0,1,1]
	s_waitcnt vmcnt(3) lgkmcnt(0)
	v_pk_fma_f32 v[30:31], v[20:21], v[128:129], v[30:31] op_sel_hi:[0,1,1]
	v_pk_fma_f32 v[40:41], v[20:21], v[126:127], v[42:43] op_sel_hi:[0,1,1]
	v_pk_fma_f32 v[36:37], v[20:21], v[132:133], v[22:23] op_sel_hi:[0,1,1]
	v_pk_fma_f32 v[34:35], v[20:21], v[130:131], v[38:39] op_sel_hi:[0,1,1]
	s_waitcnt vmcnt(3) lgkmcnt(0)
	v_pk_fma_f32 v[38:39], v[18:19], v[134:135], v[40:41] op_sel_hi:[0,1,1]
	v_pk_fma_f32 v[22:23], v[18:19], v[136:137], v[30:31] op_sel_hi:[0,1,1]
	v_pk_fma_f32 v[30:31], v[18:19], v[138:139], v[34:35] op_sel_hi:[0,1,1]
	v_pk_fma_f32 v[34:35], v[18:19], v[140:141], v[36:37] op_sel_hi:[0,1,1]
	s_waitcnt vmcnt(3) lgkmcnt(0)
	v_pk_fma_f32 v[36:37], v[16:17], v[144:145], v[22:23] op_sel_hi:[0,1,1]
	v_pk_fma_f32 v[38:39], v[16:17], v[142:143], v[38:39] op_sel_hi:[0,1,1]
	v_pk_fma_f32 v[28:29], v[16:17], v[148:149], v[34:35] op_sel_hi:[0,1,1]
	v_pk_fma_f32 v[26:27], v[16:17], v[146:147], v[30:31] op_sel_hi:[0,1,1]
	s_waitcnt vmcnt(3) lgkmcnt(0)
	v_pk_fma_f32 v[30:31], v[14:15], v[156:157], v[38:39] op_sel_hi:[0,1,1]
	v_pk_fma_f32 v[34:35], v[14:15], v[158:159], v[36:37] op_sel_hi:[0,1,1]
	v_pk_fma_f32 v[26:27], v[14:15], v[160:161], v[26:27] op_sel_hi:[0,1,1]
	v_pk_fma_f32 v[22:23], v[14:15], v[162:163], v[28:29] op_sel_hi:[0,1,1]
	s_waitcnt vmcnt(4) lgkmcnt(0)
	v_pk_fma_f32 v[28:29], v[8:9], v[166:167], v[34:35] op_sel_hi:[0,1,1]
	v_pk_fma_f32 v[30:31], v[8:9], v[164:165], v[30:31] op_sel_hi:[0,1,1]
	v_pk_fma_f32 v[22:23], v[8:9], v[170:171], v[22:23] op_sel_hi:[0,1,1]
	v_pk_fma_f32 v[8:9], v[8:9], v[168:169], v[26:27] op_sel_hi:[0,1,1]
	s_waitcnt vmcnt(13) lgkmcnt(0)
	v_pk_fma_f32 v[26:27], v[4:5], v[172:173], v[30:31] op_sel_hi:[0,1,1]
	v_pk_fma_f32 v[28:29], v[4:5], v[174:175], v[28:29] op_sel_hi:[0,1,1]
	v_pk_fma_f32 v[30:31], v[4:5], v[176:177], v[8:9] op_sel_hi:[0,1,1]
	v_pk_fma_f32 v[4:5], v[4:5], v[178:179], v[22:23] op_sel_hi:[0,1,1]
	global_load_dwordx4 v[18:21], v[248:249], off offset:3088
	s_waitcnt vmcnt(0) lgkmcnt(0)
; DI void gla_stage1(const Ctx& c0, int layer, int unit, LAS unsigned char* lds) {
;     ...
;         for (int rr = 0; rr < 16; ++rr) { const f32x4 w0 = *(const f32x4*)(wap + rr * 256), w1 = *(const f32x4*)(wap + rr * 256 + 4); a0 += w0 * ga[rr]; a1 += w1 * ga[rr]; }
; #pragma unroll
;         for (int j = 0; j < 8; ++j) { const float x = j < 4 ? a0[j & 3] : a1[j & 3];
;             const float ls = fminf(x, 0.f) - __logf(1.f + __expf(-fabsf(x)));
;             LA[cc * 65 + 8 * ch + j] = ls * (1.f / 16.f); }
;     }
;     __syncthreads();
;     {
;         const int d = tid & 63, part = tid >> 6; float v[8]; float run = 0.f;
; #pragma unroll
;         for (int j = 0; j < 8; ++j) { run += LA[(8 * part + j) * 65 + d]; v[j] = run; }
;         PART[part * 64 + d] = run;
;         __syncthreads();
;         float off = 0.f;
; #pragma unroll
;         for (int p = 0; p < 8; ++p) off += (p < part) ? PART[p * 64 + d] : 0.f;
; #pragma unroll
;         for (int j = 0; j < 8; ++j) LA[(8 * part + j) * 65 + d] = v[j] + off;
	v_pk_fma_f32 v[14:15], v[6:7], v[180:181], v[26:27] op_sel_hi:[0,1,1]
	v_pk_fma_f32 v[8:9], v[6:7], v[182:183], v[28:29] op_sel_hi:[0,1,1]
	v_min_f32_e32 v16, 0, v14
	v_mul_f32_e64 v14, |v14|, s96
	v_exp_f32_e32 v14, v14
	v_pk_fma_f32 v[4:5], v[6:7], v[20:21], v[4:5] op_sel_hi:[0,1,1]
	v_pk_fma_f32 v[6:7], v[6:7], v[18:19], v[30:31] op_sel_hi:[0,1,1]
	v_mov_b32_e32 v20, 0
	v_add_f32_e32 v14, 1.0, v14
	v_cmp_gt_f32_e32 vcc, s97, v14
	v_mov_b32_e32 v21, 0
	s_nop 0
	v_cndmask_b32_e64 v17, 0, 32, vcc
	v_ldexp_f32 v14, v14, v17
	v_log_f32_e32 v14, v14
	s_nop 0
	v_mul_f32_e32 v17, 0x3f317217, v14
	v_fma_f32 v17, v14, s92, -v17
	v_fmac_f32_e32 v17, 0x3377d1cf, v14
	v_fmac_f32_e32 v17, 0x3f317217, v14
	v_cmp_lt_f32_e64 s[74:75], |v14|, s8
	s_nop 1
	v_cndmask_b32_e64 v14, v14, v17, s[74:75]
	v_cndmask_b32_e32 v17, 0, v47, vcc
	v_sub_f32_e32 v14, v14, v17
	v_min_f32_e32 v17, 0, v15
	v_mul_f32_e64 v15, |v15|, s96
	v_exp_f32_e32 v15, v15
	s_nop 0
	v_add_f32_e32 v15, 1.0, v15
	v_cmp_gt_f32_e32 vcc, s97, v15
	s_nop 1
	v_cndmask_b32_e64 v18, 0, 32, vcc
	v_ldexp_f32 v15, v15, v18
	v_log_f32_e32 v15, v15
	s_nop 0
	v_mul_f32_e32 v18, 0x3f317217, v15
	v_fma_f32 v18, v15, s92, -v18
	v_fmac_f32_e32 v18, 0x3377d1cf, v15
	v_fmac_f32_e32 v18, 0x3f317217, v15
	v_cmp_lt_f32_e64 s[74:75], |v15|, s8
	s_nop 1
	v_cndmask_b32_e64 v15, v15, v18, s[74:75]
	v_cndmask_b32_e32 v18, 0, v47, vcc
	v_sub_f32_e32 v15, v15, v18
	v_pk_add_f32 v[14:15], v[16:17], v[14:15] neg_lo:[0,1] neg_hi:[0,1]
	v_ashrrev_i32_e32 v17, 6, v10
	v_pk_mul_f32 v[14:15], v[14:15], s[6:7] op_sel_hi:[1,0]
	ds_write2_b32 v13, v14, v15 offset1:1
	v_min_f32_e32 v14, 0, v8
	v_mul_f32_e64 v8, |v8|, s96
	v_exp_f32_e32 v8, v8
	s_nop 0
	v_add_f32_e32 v8, 1.0, v8
	v_cmp_gt_f32_e32 vcc, s97, v8
	s_nop 1
	v_cndmask_b32_e64 v15, 0, 32, vcc
	v_ldexp_f32 v8, v8, v15
	v_log_f32_e32 v8, v8
	s_nop 0
	v_mul_f32_e32 v15, 0x3f317217, v8
	v_fma_f32 v15, v8, s92, -v15
	v_fmac_f32_e32 v15, 0x3377d1cf, v8
	v_fmac_f32_e32 v15, 0x3f317217, v8
	v_cmp_lt_f32_e64 s[74:75], |v8|, s8
	s_nop 1
	v_cndmask_b32_e64 v8, v8, v15, s[74:75]
	v_cndmask_b32_e32 v15, 0, v47, vcc
	v_sub_f32_e32 v8, v8, v15
	v_min_f32_e32 v15, 0, v9
	v_mul_f32_e64 v9, |v9|, s96
	v_exp_f32_e32 v9, v9
	s_nop 0
	v_add_f32_e32 v9, 1.0, v9
	v_cmp_gt_f32_e32 vcc, s97, v9
	s_nop 1
	v_cndmask_b32_e64 v16, 0, 32, vcc
	v_ldexp_f32 v9, v9, v16
	v_log_f32_e32 v9, v9
	s_nop 0
	v_mul_f32_e32 v16, 0x3f317217, v9
	v_fma_f32 v16, v9, s92, -v16
	v_fmac_f32_e32 v16, 0x3377d1cf, v9
	v_fmac_f32_e32 v16, 0x3f317217, v9
	v_cmp_lt_f32_e64 s[74:75], |v9|, s8
	s_nop 1
	v_cndmask_b32_e64 v9, v9, v16, s[74:75]
	v_cndmask_b32_e32 v16, 0, v47, vcc
	v_sub_f32_e32 v9, v9, v16
	v_pk_add_f32 v[8:9], v[14:15], v[8:9] neg_lo:[0,1] neg_hi:[0,1]
	s_nop 0
	v_pk_mul_f32 v[8:9], v[8:9], s[6:7] op_sel_hi:[1,0]
	ds_write2_b32 v13, v8, v9 offset0:2 offset1:3
	v_min_f32_e32 v8, 0, v6
	v_mul_f32_e64 v6, |v6|, s96
	v_exp_f32_e32 v6, v6
	s_nop 0
	v_add_f32_e32 v6, 1.0, v6
	v_cmp_gt_f32_e32 vcc, s97, v6
	s_nop 1
	v_cndmask_b32_e64 v9, 0, 32, vcc
	v_ldexp_f32 v6, v6, v9
	v_log_f32_e32 v6, v6
	s_nop 0
	v_mul_f32_e32 v9, 0x3f317217, v6
	v_fma_f32 v9, v6, s92, -v9
	v_fmac_f32_e32 v9, 0x3377d1cf, v6
	v_fmac_f32_e32 v9, 0x3f317217, v6
	v_cmp_lt_f32_e64 s[74:75], |v6|, s8
	s_nop 1
	v_cndmask_b32_e64 v6, v6, v9, s[74:75]
	v_cndmask_b32_e32 v9, 0, v47, vcc
	v_sub_f32_e32 v6, v6, v9
	v_min_f32_e32 v9, 0, v7
	v_mul_f32_e64 v7, |v7|, s96
	v_exp_f32_e32 v7, v7
	s_nop 0
	v_add_f32_e32 v7, 1.0, v7
	v_cmp_gt_f32_e32 vcc, s97, v7
	s_nop 1
	v_cndmask_b32_e64 v14, 0, 32, vcc
	v_ldexp_f32 v7, v7, v14
	v_log_f32_e32 v7, v7
	s_nop 0
	v_mul_f32_e32 v14, 0x3f317217, v7
	v_fma_f32 v14, v7, s92, -v14
	v_fmac_f32_e32 v14, 0x3377d1cf, v7
	v_fmac_f32_e32 v14, 0x3f317217, v7
	v_cmp_lt_f32_e64 s[74:75], |v7|, s8
	s_nop 1
	v_cndmask_b32_e64 v7, v7, v14, s[74:75]
	v_cndmask_b32_e32 v14, 0, v47, vcc
	v_sub_f32_e32 v7, v7, v14
	v_pk_add_f32 v[6:7], v[8:9], v[6:7] neg_lo:[0,1] neg_hi:[0,1]
	s_nop 0
	v_pk_mul_f32 v[6:7], v[6:7], s[6:7] op_sel_hi:[1,0]
	ds_write2_b32 v13, v6, v7 offset0:4 offset1:5
	v_min_f32_e32 v6, 0, v4
	v_mul_f32_e64 v4, |v4|, s96
	v_exp_f32_e32 v4, v4
	s_nop 0
	v_add_f32_e32 v4, 1.0, v4
	v_cmp_gt_f32_e32 vcc, s97, v4
	s_nop 1
	v_cndmask_b32_e64 v7, 0, 32, vcc
	v_ldexp_f32 v4, v4, v7
	v_log_f32_e32 v4, v4
	s_nop 0
	v_mul_f32_e32 v7, 0x3f317217, v4
	v_fma_f32 v7, v4, s92, -v7
	v_fmac_f32_e32 v7, 0x3377d1cf, v4
	v_fmac_f32_e32 v7, 0x3f317217, v4
	v_cmp_lt_f32_e64 s[74:75], |v4|, s8
	s_nop 1
	v_cndmask_b32_e64 v4, v4, v7, s[74:75]
	v_cndmask_b32_e32 v7, 0, v47, vcc
	v_sub_f32_e32 v4, v4, v7
	v_min_f32_e32 v7, 0, v5
	v_mul_f32_e64 v5, |v5|, s96
	v_exp_f32_e32 v5, v5
	s_nop 0
	v_add_f32_e32 v5, 1.0, v5
	v_cmp_gt_f32_e32 vcc, s97, v5
	s_nop 1
	v_cndmask_b32_e64 v8, 0, 32, vcc
	v_ldexp_f32 v5, v5, v8
	v_log_f32_e32 v5, v5
	s_nop 0
	v_mul_f32_e32 v8, 0x3f317217, v5
	v_fma_f32 v8, v5, s92, -v8
	v_fmac_f32_e32 v8, 0x3377d1cf, v5
	v_fmac_f32_e32 v8, 0x3f317217, v5
	v_cmp_lt_f32_e64 s[74:75], |v5|, s8
	s_nop 1
	v_cndmask_b32_e64 v5, v5, v8, s[74:75]
	v_cndmask_b32_e32 v8, 0, v47, vcc
	v_sub_f32_e32 v5, v5, v8
	v_pk_add_f32 v[4:5], v[6:7], v[4:5] neg_lo:[0,1] neg_hi:[0,1]
	v_cmp_lt_i32_e32 vcc, 0, v17
	v_pk_mul_f32 v[4:5], v[4:5], s[6:7] op_sel_hi:[1,0]
	ds_write2_b32 v13, v4, v5 offset0:6 offset1:7
	v_and_b32_e32 v4, 63, v10
	v_lshl_add_u32 v14, v4, 2, 0
	v_mul_lo_u32 v4, v17, s0
	v_add_u32_e32 v4, v14, v4
	s_waitcnt lgkmcnt(0)
	s_barrier
	ds_read2_b32 v[6:7], v4 offset1:65
	ds_read2_b32 v[8:9], v4 offset0:130 offset1:195
	s_waitcnt lgkmcnt(1)
	v_add_f32_e32 v5, 0, v6
	v_add_f32_e32 v6, v5, v7
	s_waitcnt lgkmcnt(0)
	v_add_f32_e32 v7, v6, v8
	v_add_f32_e32 v8, v7, v9
	v_add_u32_e32 v9, 0x400, v4
	ds_read2_b32 v[18:19], v9 offset0:4 offset1:69
	s_waitcnt lgkmcnt(0)
	v_add_f32_e32 v15, v8, v18
	v_add_f32_e32 v16, v15, v19
	ds_read2_b32 v[18:19], v9 offset0:134 offset1:199
	s_waitcnt lgkmcnt(0)
	v_add_f32_e32 v18, v16, v18
	v_add_f32_e32 v19, v18, v19
	ds_write_b32 v33, v19 offset:16640
	s_waitcnt lgkmcnt(0)
	s_barrier
	s_and_saveexec_b64 s[74:75], vcc
	s_cbranch_execz .LBB0_1018
	ds_read_b32 v21, v14 offset:16640
	s_waitcnt lgkmcnt(0)
	v_add_f32_e32 v21, 0, v21

; DI float siluf_(float x) { return x / (1.f + __expf(-x)); }
; DI void cmp_stage2(const Ctx& c0, int layer) {
;     ...
;         for (int h4 = 0; h4 < 128; h4 += 4) {
;             f32x4 s = *(const f32x4*)(p0 + h4);
; #pragma unroll
;             for (int ks = 1; ks < 4; ++ks) s += *(const f32x4*)(p0 + (size_t)ks * 4 * 2048 * 128 + h4);
;             s += *(const f32x4*)(cb + kv * 128 + h4);
; #pragma unroll
;             for (int j = 0; j < 4; ++j) { const float hv = siluf_(s[j]); const f32x4 w0 = *(const f32x4*)(w2 + (size_t)(h4 + j) * 64), w1 = *(const f32x4*)(w2 + (size_t)(h4 + j) * 64 + 4);
;                 acc[0] += hv * w0[0]; acc[1] += hv * w0[1]; acc[2] += hv * w0[2]; acc[3] += hv * w0[3]; acc[4] += hv * w1[0]; acc[5] += hv * w1[1]; acc[6] += hv * w1[2]; acc[7] += hv * w1[3]; }
;         }
.Lc2p_loop_LBB0_1092:
	s_waitcnt vmcnt(0) lgkmcnt(0)
	v_lshl_add_u64 v[126:127], s[16:17], 0, v[12:13]
	v_add_co_u32_e32 v114, vcc, s22, v126
	global_load_dwordx4 v[90:93], v[18:19], off offset:16
	global_load_dwordx4 v[96:99], v[18:19], off
	global_load_dwordx4 v[106:109], v[18:19], off offset:272
	global_load_dwordx4 v[110:113], v[18:19], off offset:256
	v_addc_co_u32_e32 v115, vcc, 0, v127, vcc
	v_add_co_u32_e32 v118, vcc, s23, v126
	v_lshl_add_u64 v[130:131], s[16:17], 0, v[14:15]
	s_nop 0
	v_addc_co_u32_e32 v119, vcc, 0, v127, vcc
	v_add_co_u32_e32 v122, vcc, s24, v126
	global_load_dwordx4 v[114:117], v[114:115], off
	s_nop 0
	global_load_dwordx4 v[118:121], v[118:119], off
	v_addc_co_u32_e32 v123, vcc, 0, v127, vcc
	global_load_dwordx4 v[122:125], v[122:123], off
	v_add_co_u32_e32 v126, vcc, s25, v126
	s_add_i32 s27, s27, 4
	s_nop 0
	v_addc_co_u32_e32 v127, vcc, 0, v127, vcc
	global_load_dwordx4 v[126:129], v[126:127], off
	s_nop 0
	global_load_dwordx4 v[130:133], v[130:131], off
	s_nop 0
	global_load_dwordx4 v[134:137], v[18:19], off offset:528
	global_load_dwordx4 v[138:141], v[18:19], off offset:512
	global_load_dwordx4 v[142:145], v[18:19], off offset:784
	global_load_dwordx4 v[146:149], v[18:19], off offset:768
	s_add_u32 s16, s16, 16
	s_addc_u32 s17, s17, 0
	v_lshl_add_u64 v[18:19], v[18:19], 0, s[14:15]
	v_pk_add_f32 v[42:43], v[42:43], v[46:47]
	v_pk_add_f32 v[44:45], v[44:45], v[48:49]
	v_pk_add_f32 v[42:43], v[42:43], v[50:51]
	v_pk_add_f32 v[44:45], v[44:45], v[52:53]
	v_pk_add_f32 v[42:43], v[42:43], v[54:55]
	v_pk_add_f32 v[44:45], v[44:45], v[56:57]
	v_add_f32_e32 v4, v42, v58
	v_add_f32_e32 v42, v43, v59
	v_add_f32_e32 v43, v44, v60
	v_add_f32_e32 v44, v45, v61
	v_mul_f32_e32 v45, 0xbfb8aa3b, v4
	v_mul_f32_e32 v46, 0xbfb8aa3b, v42
	v_exp_f32_e32 v45, v45
	v_mul_f32_e32 v47, 0xbfb8aa3b, v43
	v_exp_f32_e32 v46, v46
	v_mul_f32_e32 v48, 0xbfb8aa3b, v44
	v_exp_f32_e32 v47, v47
	v_exp_f32_e32 v48, v48
	v_add_f32_e32 v45, 1.0, v45
	v_add_f32_e32 v46, 1.0, v46
	v_add_f32_e32 v47, 1.0, v47
	v_add_f32_e32 v48, 1.0, v48
	v_rcp_f32_e32 v49, v45
	s_nop 0
	v_mul_f32_e32 v4, v4, v49
	v_rcp_f32_e32 v45, v46
	s_nop 0
	v_mul_f32_e32 v42, v42, v45
	v_pk_fma_f32 v[22:23], v[30:31], v[4:5], v[22:23] op_sel_hi:[1,0,1]
	v_pk_fma_f32 v[20:21], v[32:33], v[4:5], v[20:21] op_sel_hi:[1,0,1]
	v_pk_fma_f32 v[16:17], v[26:27], v[4:5], v[16:17] op_sel_hi:[1,0,1]
	v_pk_fma_f32 v[10:11], v[28:29], v[4:5], v[10:11] op_sel_hi:[1,0,1]
	v_rcp_f32_e32 v4, v47
	s_nop 0
	v_mul_f32_e32 v4, v43, v4
	v_pk_fma_f32 v[22:23], v[38:39], v[42:43], v[22:23] op_sel_hi:[1,0,1]
	v_pk_fma_f32 v[20:21], v[40:41], v[42:43], v[20:21] op_sel_hi:[1,0,1]
	v_pk_fma_f32 v[16:17], v[34:35], v[42:43], v[16:17] op_sel_hi:[1,0,1]
	v_pk_fma_f32 v[10:11], v[36:37], v[42:43], v[10:11] op_sel_hi:[1,0,1]
	v_rcp_f32_e32 v26, v48
	s_nop 0
	v_mul_f32_e32 v26, v44, v26
	v_pk_fma_f32 v[22:23], v[4:5], v[66:67], v[22:23] op_sel_hi:[0,1,1]
	v_pk_fma_f32 v[20:21], v[4:5], v[68:69], v[20:21] op_sel_hi:[0,1,1]
	v_pk_fma_f32 v[16:17], v[4:5], v[62:63], v[16:17] op_sel_hi:[0,1,1]
	v_pk_fma_f32 v[10:11], v[4:5], v[64:65], v[10:11] op_sel_hi:[0,1,1]
	v_pk_fma_f32 v[22:23], v[26:27], v[74:75], v[22:23] op_sel_hi:[0,1,1]
	v_pk_fma_f32 v[20:21], v[26:27], v[76:77], v[20:21] op_sel_hi:[0,1,1]
	v_pk_fma_f32 v[16:17], v[26:27], v[70:71], v[16:17] op_sel_hi:[0,1,1]
	v_pk_fma_f32 v[10:11], v[26:27], v[72:73], v[10:11] op_sel_hi:[0,1,1]
	s_waitcnt vmcnt(0)
	s_cmpk_gt_u32 s27, 0x7b
	s_cselect_b32 s100, 1, 0
	s_cbranch_scc1 .Lc2p_skip_LBB0_1092
	v_lshl_add_u64 v[54:55], s[16:17], 0, v[12:13]
	v_add_co_u32_e32 v42, vcc, s22, v54
	global_load_dwordx4 v[26:29], v[18:19], off offset:16
	global_load_dwordx4 v[30:33], v[18:19], off
	global_load_dwordx4 v[34:37], v[18:19], off offset:272
	global_load_dwordx4 v[38:41], v[18:19], off offset:256
	v_addc_co_u32_e32 v43, vcc, 0, v55, vcc
	v_add_co_u32_e32 v46, vcc, s23, v54
	v_lshl_add_u64 v[58:59], s[16:17], 0, v[14:15]
	s_nop 0
	v_addc_co_u32_e32 v47, vcc, 0, v55, vcc
	v_add_co_u32_e32 v50, vcc, s24, v54
	global_load_dwordx4 v[42:45], v[42:43], off
	s_nop 0
	global_load_dwordx4 v[46:49], v[46:47], off
	v_addc_co_u32_e32 v51, vcc, 0, v55, vcc
	global_load_dwordx4 v[50:53], v[50:51], off
	v_add_co_u32_e32 v54, vcc, s25, v54
	s_add_i32 s27, s27, 4
	s_nop 0
	v_addc_co_u32_e32 v55, vcc, 0, v55, vcc
	global_load_dwordx4 v[54:57], v[54:55], off
	s_nop 0
	global_load_dwordx4 v[58:61], v[58:59], off
	s_nop 0
	global_load_dwordx4 v[62:65], v[18:19], off offset:528
	global_load_dwordx4 v[66:69], v[18:19], off offset:512
	global_load_dwordx4 v[70:73], v[18:19], off offset:784
	global_load_dwordx4 v[74:77], v[18:19], off offset:768
	s_add_u32 s16, s16, 16
	s_addc_u32 s17, s17, 0
	v_lshl_add_u64 v[18:19], v[18:19], 0, s[14:15]
; DI unsigned cvtpk(float lo, float hi) { f32x2 v = {lo, hi}; bf16x2_t b = __builtin_convertvector(v, bf16x2_t); return __builtin_bit_cast(unsigned, b); }
; DI float siluf_(float x) { return x / (1.f + __expf(-x)); }
; DI void cmp_stage2(const Ctx& c0, int layer) {
;     ...
;         for (int h4 = 0; h4 < 128; h4 += 4) {
;             f32x4 s = *(const f32x4*)(p0 + h4);
; #pragma unroll
;             for (int ks = 1; ks < 4; ++ks) s += *(const f32x4*)(p0 + (size_t)ks * 4 * 2048 * 128 + h4);
;             s += *(const f32x4*)(cb + kv * 128 + h4);
; #pragma unroll
;             for (int j = 0; j < 4; ++j) { const float hv = siluf_(s[j]); const f32x4 w0 = *(const f32x4*)(w2 + (size_t)(h4 + j) * 64), w1 = *(const f32x4*)(w2 + (size_t)(h4 + j) * 64 + 4);
;                 acc[0] += hv * w0[0]; acc[1] += hv * w0[1]; acc[2] += hv * w0[2]; acc[3] += hv * w0[3]; acc[4] += hv * w1[0]; acc[5] += hv * w1[1]; acc[6] += hv * w1[2]; acc[7] += hv * w1[3]; }
;         }
;         u32x4 w; w.x = cvtpk(acc[0], acc[1]); w.y = cvtpk(acc[2], acc[3]); w.z = cvtpk(acc[4], acc[5]); w.w = cvtpk(acc[6], acc[7]);
;         *(u32x4*)(out + ((size_t)which * 2048 + row) * 64 + 8 * oct) = w;
.Lc2p_skip_LBB0_1092:
	v_pk_add_f32 v[114:115], v[114:115], v[118:119]
	v_pk_add_f32 v[116:117], v[116:117], v[120:121]
	v_pk_add_f32 v[114:115], v[114:115], v[122:123]
	v_pk_add_f32 v[116:117], v[116:117], v[124:125]
	v_pk_add_f32 v[114:115], v[114:115], v[126:127]
	v_pk_add_f32 v[116:117], v[116:117], v[128:129]
	v_add_f32_e32 v4, v114, v130
	v_add_f32_e32 v114, v115, v131
	v_add_f32_e32 v115, v116, v132
	v_add_f32_e32 v116, v117, v133
	v_mul_f32_e32 v117, 0xbfb8aa3b, v4
	v_mul_f32_e32 v118, 0xbfb8aa3b, v114
	v_exp_f32_e32 v117, v117
	v_mul_f32_e32 v119, 0xbfb8aa3b, v115
	v_exp_f32_e32 v118, v118
	v_mul_f32_e32 v120, 0xbfb8aa3b, v116
	v_exp_f32_e32 v119, v119
	v_exp_f32_e32 v120, v120
	v_add_f32_e32 v117, 1.0, v117
	v_add_f32_e32 v118, 1.0, v118
	v_add_f32_e32 v119, 1.0, v119
	v_add_f32_e32 v120, 1.0, v120
	v_rcp_f32_e32 v121, v117
	s_nop 0
	v_mul_f32_e32 v4, v4, v121
	v_rcp_f32_e32 v117, v118
	s_nop 0
	v_mul_f32_e32 v114, v114, v117
	v_pk_fma_f32 v[22:23], v[96:97], v[4:5], v[22:23] op_sel_hi:[1,0,1]
	v_pk_fma_f32 v[20:21], v[98:99], v[4:5], v[20:21] op_sel_hi:[1,0,1]
	v_pk_fma_f32 v[16:17], v[90:91], v[4:5], v[16:17] op_sel_hi:[1,0,1]
	v_pk_fma_f32 v[10:11], v[92:93], v[4:5], v[10:11] op_sel_hi:[1,0,1]
	v_rcp_f32_e32 v4, v119
	s_nop 0
	v_mul_f32_e32 v4, v115, v4
	v_pk_fma_f32 v[22:23], v[110:111], v[114:115], v[22:23] op_sel_hi:[1,0,1]
	v_pk_fma_f32 v[20:21], v[112:113], v[114:115], v[20:21] op_sel_hi:[1,0,1]
	v_pk_fma_f32 v[16:17], v[106:107], v[114:115], v[16:17] op_sel_hi:[1,0,1]
	v_pk_fma_f32 v[10:11], v[108:109], v[114:115], v[10:11] op_sel_hi:[1,0,1]
	v_rcp_f32_e32 v90, v120
	s_nop 0
	v_mul_f32_e32 v90, v116, v90
	v_pk_fma_f32 v[22:23], v[4:5], v[138:139], v[22:23] op_sel_hi:[0,1,1]
	v_pk_fma_f32 v[20:21], v[4:5], v[140:141], v[20:21] op_sel_hi:[0,1,1]
	v_pk_fma_f32 v[16:17], v[4:5], v[134:135], v[16:17] op_sel_hi:[0,1,1]
	v_pk_fma_f32 v[10:11], v[4:5], v[136:137], v[10:11] op_sel_hi:[0,1,1]
	v_pk_fma_f32 v[22:23], v[90:91], v[146:147], v[22:23] op_sel_hi:[0,1,1]
	v_pk_fma_f32 v[20:21], v[90:91], v[148:149], v[20:21] op_sel_hi:[0,1,1]
	v_pk_fma_f32 v[16:17], v[90:91], v[142:143], v[16:17] op_sel_hi:[0,1,1]
	v_pk_fma_f32 v[10:11], v[90:91], v[144:145], v[10:11] op_sel_hi:[0,1,1]
	s_cmp_lg_u32 s100, 0
	s_cbranch_scc0 .Lc2p_loop_LBB0_1092
	v_and_b32_e32 v4, 0x7ff, v25
	v_lshlrev_b64 v[8:9], 18, v[8:9]
	v_lshl_or_b32 v8, v4, 7, v8
	v_lshlrev_b32_e32 v4, 4, v1
	v_add_u32_e32 v1, s18, v1
	v_lshl_add_u64 v[8:9], v[2:3], 0, v[8:9]
	v_and_b32_e32 v4, 0x70, v4
	v_cmp_lt_i32_e32 vcc, s26, v1
	v_cvt_pk_bf16_f32 v12, v22, v23
	v_cvt_pk_bf16_f32 v13, v20, v21
	v_cvt_pk_bf16_f32 v14, v16, v17
	v_cvt_pk_bf16_f32 v15, v10, v11
	v_lshl_add_u64 v[8:9], v[8:9], 0, v[4:5]
	s_or_b64 s[4:5], vcc, s[4:5]
	v_add_u32_e32 v24, s19, v24
	global_store_dwordx4 v[8:9], v[12:15], off
	s_andn2_b64 exec, exec, s[4:5]
	s_cbranch_execnz .LBB0_1091

; #define LAS __attribute__((address_space(3)))
; DI float bflo(unsigned w) { return __uint_as_float(w << 16); }
; DI float bfhi(unsigned w) { return __uint_as_float(w & 0xffff0000u); }
; DI void nsa_unit(const Ctx& c0, int b, int g, int i, LAS unsigned char* lds) {
;     ...
;         branch_fold(st, g_w2, false, wsf, lane);
; #pragma unroll
;         for (int rg = 0; rg < 16; ++rg) { const unsigned w = OC[rg * 64]; ca0[rg] = (OACC[rg * 64] + st.o0[rg]) + bflo(w); ca1[rg] = (OACC[(16 + rg) * 64] + st.o1[rg]) + bfhi(w); }
;         __syncthreads();
;     }
;     ...
;     { const size_t g0 = ((size_t)b * SEQ + i * 64 + 32 * qh) * 512 + head * 64;
;       const bf16* nzg = (const bf16*)(c.ws + O_NZ) + g0; bf16* ong = (bf16*)(c.ws + O_ONSA) + g0;
;       LAS unsigned char* S = lds + A_OC + wid * 4096;
; #pragma unroll
;       for (int it = 0; it < 4; ++it) { const int rw = 8 * it + (lane >> 3), ch = lane & 7;
;           *(LAS u32x4*)(S + rw * 128 + ch * 16) = *(const u32x4*)(nzg + (size_t)rw * 512 + ch * 8); }
.LBB0_1153:
	s_or_b64 exec, exec, s[14:15]
	s_waitcnt lgkmcnt(0)
	ds_read_b128 v[48:51], v192 offset:32768
	ds_read_b128 v[44:47], v192 offset:32800
	ds_read_b128 v[40:43], v192 offset:32832
	ds_read_b128 v[36:39], v192 offset:32864
	ds_read2st64_b32 v[52:53], v203 offset1:1
	ds_read2st64_b32 v[54:55], v190 offset0:144 offset1:145
	ds_read2st64_b32 v[56:57], v190 offset0:160 offset1:161
	s_or_b32 s6, s26, s33
	s_add_u32 s14, s4, s6
	s_waitcnt lgkmcnt(0)
	v_lshlrev_b32_e32 v2, 16, v52
	v_fma_f32 v1, v20, v48, v54
	v_add_f32_e32 v60, v1, v2
	v_fma_f32 v1, v4, v48, v56
	v_fmac_f32_e32 v55, v21, v49
	v_fmac_f32_e32 v57, v5, v49
	ds_read2st64_b32 v[4:5], v203 offset0:2 offset1:3
	ds_read2st64_b32 v[20:21], v190 offset0:146 offset1:147
	ds_read2st64_b32 v[48:49], v190 offset0:162 offset1:163
	v_and_b32_e32 v2, 0xffff0000, v52
	v_add_f32_e32 v59, v1, v2
	v_lshlrev_b32_e32 v1, 16, v53
	v_add_f32_e32 v58, v55, v1
	v_and_b32_e32 v1, 0xffff0000, v53
	v_add_f32_e32 v57, v57, v1
	s_waitcnt lgkmcnt(0)
	v_fma_f32 v1, v22, v50, v20
	v_lshlrev_b32_e32 v2, 16, v4
	v_add_f32_e32 v56, v1, v2
	v_fma_f32 v1, v6, v50, v48
	v_and_b32_e32 v2, 0xffff0000, v4
	v_add_f32_e32 v55, v1, v2
	v_fmac_f32_e32 v21, v23, v51
	v_lshlrev_b32_e32 v1, 16, v5
	v_add_f32_e32 v54, v21, v1
	v_fmac_f32_e32 v49, v7, v51
	v_and_b32_e32 v1, 0xffff0000, v5
	ds_read2st64_b32 v[4:5], v203 offset0:4 offset1:5
	ds_read2st64_b32 v[6:7], v190 offset0:148 offset1:149
	ds_read2st64_b32 v[20:21], v190 offset0:164 offset1:165
	v_add_f32_e32 v53, v49, v1
	s_addc_u32 s15, s5, 0
	s_waitcnt lgkmcnt(0)
	v_lshlrev_b32_e32 v2, 16, v4
	v_fma_f32 v1, v24, v44, v6
	v_add_f32_e32 v52, v1, v2
	v_fma_f32 v1, v8, v44, v20
	v_and_b32_e32 v2, 0xffff0000, v4
	v_add_f32_e32 v51, v1, v2
	v_fmac_f32_e32 v7, v25, v45
	v_lshlrev_b32_e32 v1, 16, v5
	v_add_f32_e32 v50, v7, v1
	v_and_b32_e32 v1, 0xffff0000, v5
	ds_read2st64_b32 v[4:5], v203 offset0:6 offset1:7
	ds_read2st64_b32 v[6:7], v190 offset0:150 offset1:151
	v_fmac_f32_e32 v21, v9, v45
	ds_read2st64_b32 v[8:9], v190 offset0:166 offset1:167
	v_add_f32_e32 v49, v21, v1
	s_waitcnt lgkmcnt(0)
	v_lshlrev_b32_e32 v2, 16, v4
	v_fma_f32 v1, v26, v46, v6
	v_add_f32_e32 v48, v1, v2
	v_fma_f32 v1, v10, v46, v8
	v_and_b32_e32 v2, 0xffff0000, v4
	v_add_f32_e32 v46, v1, v2
	v_fmac_f32_e32 v7, v27, v47
	v_lshlrev_b32_e32 v1, 16, v5
	v_add_f32_e32 v45, v7, v1
	v_fmac_f32_e32 v9, v11, v47
	v_and_b32_e32 v1, 0xffff0000, v5
	ds_read2st64_b32 v[4:5], v203 offset0:8 offset1:9
	ds_read2st64_b32 v[6:7], v190 offset0:152 offset1:153
	v_add_f32_e32 v44, v9, v1
	ds_read2st64_b32 v[8:9], v190 offset0:168 offset1:169
	s_lshl_b64 s[14:15], s[14:15], 9
	s_waitcnt lgkmcnt(0)
	v_lshlrev_b32_e32 v2, 16, v4
	v_fma_f32 v1, v28, v40, v6
	v_add_f32_e32 v27, v1, v2
	v_fma_f32 v1, v12, v40, v8
	v_and_b32_e32 v2, 0xffff0000, v4
	v_add_f32_e32 v26, v1, v2
	v_fmac_f32_e32 v7, v29, v41
	v_lshlrev_b32_e32 v1, 16, v5
	v_add_f32_e32 v25, v7, v1
	v_fmac_f32_e32 v9, v13, v41
	v_and_b32_e32 v1, 0xffff0000, v5
	ds_read2st64_b32 v[4:5], v203 offset0:10 offset1:11
	ds_read2st64_b32 v[6:7], v190 offset0:154 offset1:155
	v_add_f32_e32 v24, v9, v1
	ds_read2st64_b32 v[8:9], v190 offset0:170 offset1:171
	s_add_u32 s14, s14, s22
	s_waitcnt lgkmcnt(0)
	v_lshlrev_b32_e32 v2, 16, v4
	v_fma_f32 v1, v30, v42, v6
	v_add_f32_e32 v23, v1, v2
	v_fma_f32 v1, v14, v42, v8
	v_and_b32_e32 v2, 0xffff0000, v4
	v_add_f32_e32 v22, v1, v2
	v_fmac_f32_e32 v7, v31, v43
	v_lshlrev_b32_e32 v1, 16, v5
	v_add_f32_e32 v21, v7, v1
	v_fmac_f32_e32 v9, v15, v43
	v_and_b32_e32 v1, 0xffff0000, v5
	ds_read2st64_b32 v[4:5], v203 offset0:12 offset1:13
	ds_read2st64_b32 v[6:7], v190 offset0:156 offset1:157
	v_add_f32_e32 v15, v9, v1
	ds_read2st64_b32 v[8:9], v190 offset0:172 offset1:173
	s_addc_u32 s15, s15, 0
	s_waitcnt lgkmcnt(0)
	v_lshlrev_b32_e32 v2, 16, v4
	v_fma_f32 v1, v32, v36, v6
	v_add_f32_e32 v20, v1, v2
	v_fma_f32 v1, v16, v36, v8
	v_and_b32_e32 v2, 0xffff0000, v4
	v_add_f32_e32 v14, v1, v2
	v_fmac_f32_e32 v7, v33, v37
	v_lshlrev_b32_e32 v1, 16, v5
	v_add_f32_e32 v13, v7, v1
	v_fmac_f32_e32 v9, v17, v37
	v_and_b32_e32 v1, 0xffff0000, v5
	ds_read2st64_b32 v[4:5], v203 offset0:14 offset1:15
	ds_read2st64_b32 v[6:7], v190 offset0:158 offset1:159
	v_add_f32_e32 v12, v9, v1
	ds_read2st64_b32 v[8:9], v190 offset0:174 offset1:175
	s_lshl_b64 s[14:15], s[14:15], 1
	s_waitcnt lgkmcnt(0)
	v_lshlrev_b32_e32 v2, 16, v4
	v_fma_f32 v1, v34, v38, v6
	v_add_f32_e32 v10, v1, v2
	v_fma_f32 v1, v18, v38, v8
	v_and_b32_e32 v2, 0xffff0000, v4
	v_add_f32_e32 v11, v1, v2
	v_fmac_f32_e32 v7, v35, v39
	v_lshlrev_b32_e32 v1, 16, v5
	s_add_u32 s0, s0, s14
	v_add_f32_e32 v2, v7, v1
	v_fmac_f32_e32 v9, v19, v39
	v_and_b32_e32 v1, 0xffff0000, v5
	v_mov_b32_e32 v135, v3
	s_addc_u32 s1, s1, s15
	v_add_f32_e32 v1, v9, v1
	v_lshl_add_u64 v[8:9], s[0:1], 0, v[134:135]
	s_mov_b64 s[0:1], 0xb500000
	v_lshl_add_u64 v[16:17], v[8:9], 0, s[0:1]
	v_lshl_add_u64 v[4:5], v[16:17], 0, v[126:127]
	s_barrier
; #define LAS __attribute__((address_space(3)))
; #define LDS_WAIT() asm volatile("s_waitcnt lgkmcnt(0)" ::: "memory")
; DI unsigned cvtpk(float lo, float hi) { f32x2 v = {lo, hi}; bf16x2_t b = __builtin_convertvector(v, bf16x2_t); return __builtin_bit_cast(unsigned, b); }
; DI float bf2f(bf16 b) { return __uint_as_float(((unsigned)b) << 16); }
; DI float siluf_(float x) { return x / (1.f + __expf(-x)); }
; DI void nsa_unit(const Ctx& c0, int b, int g, int i, LAS unsigned char* lds) {
;     ...
;       for (int it = 0; it < 4; ++it) { const int rw = 8 * it + (lane >> 3), ch = lane & 7;
;           *(LAS u32x4*)(S + rw * 128 + ch * 16) = *(const u32x4*)(nzg + (size_t)rw * 512 + ch * 8); }
;       LDS_WAIT();
; #pragma unroll
;       for (int rg = 0; rg < 16; ++rg) { LAS bf16* e = (LAS bf16*)(S + ((rg & 3) + 8 * (rg >> 2) + 4 * hi) * 128 + r * 2);
;           const float z0 = bf2f(e[0]), z1 = bf2f(e[32]);
;           e[0] = (bf16)(cvtpk(ca0[rg] * siluf_(z0), 0.f) & 0xffffu);
;           e[32] = (bf16)(cvtpk(ca1[rg] * siluf_(z1), 0.f) & 0xffffu); }
	global_load_dwordx4 v[4:7], v[4:5], off
	s_add_i32 s25, s25, 1
	s_cmp_eq_u32 s25, 4
	s_waitcnt vmcnt(0) lgkmcnt(0)
	ds_write_b128 v211, v[4:7]
	v_lshl_add_u64 v[4:5], v[16:17], 0, v[128:129]
	global_load_dwordx4 v[4:7], v[4:5], off
	s_waitcnt vmcnt(0) lgkmcnt(0)
	ds_write_b128 v212, v[4:7]
	v_lshl_add_u64 v[4:5], v[16:17], 0, v[130:131]
	global_load_dwordx4 v[4:7], v[4:5], off
	s_waitcnt vmcnt(0) lgkmcnt(0)
	ds_write_b128 v213, v[4:7]
	v_lshl_add_u64 v[4:5], v[16:17], 0, v[132:133]
	global_load_dwordx4 v[4:7], v[4:5], off
	s_waitcnt vmcnt(0) lgkmcnt(0)
	ds_write_b128 v214, v[4:7]
	s_waitcnt lgkmcnt(0)
	ds_read_u16 v4, v215
	ds_read_u16 v5, v215 offset:64
	s_waitcnt lgkmcnt(1)
	v_lshlrev_b32_e32 v4, 16, v4
	v_mul_f32_e32 v6, 0xbfb8aa3b, v4
	v_exp_f32_e32 v6, v6
	s_waitcnt lgkmcnt(0)
	v_lshlrev_b32_e32 v5, 16, v5
	v_add_f32_e32 v6, 1.0, v6
	v_div_scale_f32 v7, s[0:1], v6, v6, v4
	s_nop 0
	v_rcp_f32_e32 v7, v6
	s_nop 0
	v_mul_f32_e32 v4, v4, v7
	v_mul_f32_e32 v4, v60, v4
	v_cvt_pk_bf16_f32 v4, v4, s0
	ds_write_b16 v215, v4
	v_mul_f32_e32 v4, 0xbfb8aa3b, v5
	v_exp_f32_e32 v4, v4
	s_nop 0
	v_add_f32_e32 v4, 1.0, v4
	v_div_scale_f32 v6, s[0:1], v4, v4, v5
	s_nop 0
	v_rcp_f32_e32 v4, v4
	s_nop 0
	v_mul_f32_e32 v4, v5, v4
	v_mul_f32_e32 v4, v59, v4
	v_cvt_pk_bf16_f32 v4, v4, s0
	ds_write_b16 v215, v4 offset:64
	ds_read_u16 v4, v215 offset:128
	ds_read_u16 v5, v215 offset:192
	s_waitcnt lgkmcnt(1)
	v_lshlrev_b32_e32 v4, 16, v4
	v_mul_f32_e32 v6, 0xbfb8aa3b, v4
	v_exp_f32_e32 v6, v6
	s_waitcnt lgkmcnt(0)
	v_lshlrev_b32_e32 v5, 16, v5
	v_add_f32_e32 v6, 1.0, v6
	v_div_scale_f32 v7, s[0:1], v6, v6, v4
	s_nop 0
	v_rcp_f32_e32 v7, v6
	s_nop 0
	v_mul_f32_e32 v4, v4, v7
	v_mul_f32_e32 v4, v58, v4
	v_cvt_pk_bf16_f32 v4, v4, s0
	ds_write_b16 v215, v4 offset:128
	v_mul_f32_e32 v4, 0xbfb8aa3b, v5
	v_exp_f32_e32 v4, v4
	s_nop 0
	v_add_f32_e32 v4, 1.0, v4
	v_div_scale_f32 v6, s[0:1], v4, v4, v5
	s_nop 0
	v_rcp_f32_e32 v4, v4
	s_nop 0
	v_mul_f32_e32 v4, v5, v4
	v_mul_f32_e32 v4, v57, v4
	v_cvt_pk_bf16_f32 v4, v4, s0
	ds_write_b16 v215, v4 offset:192
	ds_read_u16 v4, v215 offset:256
	ds_read_u16 v5, v215 offset:320
	s_waitcnt lgkmcnt(1)
	v_lshlrev_b32_e32 v4, 16, v4
	v_mul_f32_e32 v6, 0xbfb8aa3b, v4
	v_exp_f32_e32 v6, v6
	s_waitcnt lgkmcnt(0)
	v_lshlrev_b32_e32 v5, 16, v5
	v_add_f32_e32 v6, 1.0, v6
	v_div_scale_f32 v7, s[0:1], v6, v6, v4
	s_nop 0
	v_rcp_f32_e32 v7, v6
	s_nop 0
	v_mul_f32_e32 v4, v4, v7
	v_mul_f32_e32 v4, v56, v4
	v_cvt_pk_bf16_f32 v4, v4, s0
	ds_write_b16 v215, v4 offset:256
	v_mul_f32_e32 v4, 0xbfb8aa3b, v5
	v_exp_f32_e32 v4, v4
	s_nop 0
	v_add_f32_e32 v4, 1.0, v4
	v_div_scale_f32 v6, s[0:1], v4, v4, v5
	s_nop 0
	v_rcp_f32_e32 v4, v4
	s_nop 0
	v_mul_f32_e32 v4, v5, v4
	v_mul_f32_e32 v4, v55, v4
	v_cvt_pk_bf16_f32 v4, v4, s0
	ds_write_b16 v215, v4 offset:320
	ds_read_u16 v4, v215 offset:384
	ds_read_u16 v5, v215 offset:448
	s_waitcnt lgkmcnt(1)
	v_lshlrev_b32_e32 v4, 16, v4
	v_mul_f32_e32 v6, 0xbfb8aa3b, v4
	v_exp_f32_e32 v6, v6
	s_waitcnt lgkmcnt(0)
	v_lshlrev_b32_e32 v5, 16, v5
	v_add_f32_e32 v6, 1.0, v6
	v_div_scale_f32 v7, s[0:1], v6, v6, v4
	s_nop 0
	v_rcp_f32_e32 v7, v6
	s_nop 0
	v_mul_f32_e32 v4, v4, v7
	v_mul_f32_e32 v4, v54, v4
	v_cvt_pk_bf16_f32 v4, v4, s0
	ds_write_b16 v215, v4 offset:384
	v_mul_f32_e32 v4, 0xbfb8aa3b, v5
	v_exp_f32_e32 v4, v4
	s_nop 0
	v_add_f32_e32 v4, 1.0, v4
	v_div_scale_f32 v6, s[0:1], v4, v4, v5
	s_nop 0
	v_rcp_f32_e32 v4, v4
	s_nop 0
	v_mul_f32_e32 v4, v5, v4
	v_mul_f32_e32 v4, v53, v4
	v_cvt_pk_bf16_f32 v4, v4, s0
	ds_write_b16 v215, v4 offset:448
	ds_read_u16 v4, v215 offset:1024
	ds_read_u16 v5, v215 offset:1088
	s_waitcnt lgkmcnt(1)
	v_lshlrev_b32_e32 v4, 16, v4
	v_mul_f32_e32 v6, 0xbfb8aa3b, v4
	v_exp_f32_e32 v6, v6
	s_waitcnt lgkmcnt(0)
	v_lshlrev_b32_e32 v5, 16, v5
	v_add_f32_e32 v6, 1.0, v6
	v_div_scale_f32 v7, s[0:1], v6, v6, v4
	s_nop 0
	v_rcp_f32_e32 v7, v6
	s_nop 0
	v_mul_f32_e32 v4, v4, v7
	v_mul_f32_e32 v4, v52, v4
	v_cvt_pk_bf16_f32 v4, v4, s0
	ds_write_b16 v215, v4 offset:1024
	v_mul_f32_e32 v4, 0xbfb8aa3b, v5
	v_exp_f32_e32 v4, v4
	s_nop 0
	v_add_f32_e32 v4, 1.0, v4
	v_div_scale_f32 v6, s[0:1], v4, v4, v5
	s_nop 0
	v_rcp_f32_e32 v4, v4
	s_nop 0
	v_mul_f32_e32 v4, v5, v4
	v_mul_f32_e32 v4, v51, v4
	v_cvt_pk_bf16_f32 v4, v4, s0
	ds_write_b16 v215, v4 offset:1088
	ds_read_u16 v4, v215 offset:1152
	ds_read_u16 v5, v215 offset:1216
	s_waitcnt lgkmcnt(1)
	v_lshlrev_b32_e32 v4, 16, v4
	v_mul_f32_e32 v6, 0xbfb8aa3b, v4
	v_exp_f32_e32 v6, v6
	s_waitcnt lgkmcnt(0)
	v_lshlrev_b32_e32 v5, 16, v5
	v_add_f32_e32 v6, 1.0, v6
	v_div_scale_f32 v7, s[0:1], v6, v6, v4
	s_nop 0
	v_rcp_f32_e32 v7, v6
	s_nop 0
	v_mul_f32_e32 v4, v4, v7
	v_mul_f32_e32 v4, v50, v4
	v_cvt_pk_bf16_f32 v4, v4, s0
	ds_write_b16 v215, v4 offset:1152
	v_mul_f32_e32 v4, 0xbfb8aa3b, v5
	v_exp_f32_e32 v4, v4
	s_nop 0
	v_add_f32_e32 v4, 1.0, v4
	v_div_scale_f32 v6, s[0:1], v4, v4, v5
	s_nop 0
	v_rcp_f32_e32 v4, v4
	s_nop 0
	v_mul_f32_e32 v4, v5, v4
	v_mul_f32_e32 v4, v49, v4
	v_cvt_pk_bf16_f32 v4, v4, s0
	ds_write_b16 v215, v4 offset:1216
	ds_read_u16 v4, v215 offset:1280
	ds_read_u16 v5, v215 offset:1344
	s_waitcnt lgkmcnt(1)
	v_lshlrev_b32_e32 v4, 16, v4
	v_mul_f32_e32 v6, 0xbfb8aa3b, v4
	v_exp_f32_e32 v6, v6
	s_waitcnt lgkmcnt(0)
	v_lshlrev_b32_e32 v5, 16, v5
	v_add_f32_e32 v6, 1.0, v6
	v_div_scale_f32 v7, s[0:1], v6, v6, v4
	s_nop 0
	v_rcp_f32_e32 v7, v6
	s_nop 0
	v_mul_f32_e32 v4, v4, v7
	v_mul_f32_e32 v4, v48, v4
	v_cvt_pk_bf16_f32 v4, v4, s0
	ds_write_b16 v215, v4 offset:1280
	v_mul_f32_e32 v4, 0xbfb8aa3b, v5
	v_exp_f32_e32 v4, v4
	s_nop 0
	v_add_f32_e32 v4, 1.0, v4
	v_div_scale_f32 v6, s[0:1], v4, v4, v5
	s_nop 0
	v_rcp_f32_e32 v4, v4
	s_nop 0
	v_mul_f32_e32 v4, v5, v4
	v_mul_f32_e32 v4, v46, v4
	v_cvt_pk_bf16_f32 v4, v4, s0
	ds_write_b16 v215, v4 offset:1344
	ds_read_u16 v4, v215 offset:1408
	s_waitcnt lgkmcnt(0)
; #define LAS __attribute__((address_space(3)))
; DI unsigned cvtpk(float lo, float hi) { f32x2 v = {lo, hi}; bf16x2_t b = __builtin_convertvector(v, bf16x2_t); return __builtin_bit_cast(unsigned, b); }
; DI float bf2f(bf16 b) { return __uint_as_float(((unsigned)b) << 16); }
; DI float siluf_(float x) { return x / (1.f + __expf(-x)); }
; DI void nsa_unit(const Ctx& c0, int b, int g, int i, LAS unsigned char* lds) {
;     ...
;       for (int rg = 0; rg < 16; ++rg) { LAS bf16* e = (LAS bf16*)(S + ((rg & 3) + 8 * (rg >> 2) + 4 * hi) * 128 + r * 2);
;           const float z0 = bf2f(e[0]), z1 = bf2f(e[32]);
;           e[0] = (bf16)(cvtpk(ca0[rg] * siluf_(z0), 0.f) & 0xffffu);
;           e[32] = (bf16)(cvtpk(ca1[rg] * siluf_(z1), 0.f) & 0xffffu); }
	v_lshlrev_b32_e32 v5, 16, v4
	v_mul_f32_e32 v6, 0xbfb8aa3b, v5
	v_exp_f32_e32 v6, v6
	ds_read_u16 v4, v215 offset:1472
	v_add_f32_e32 v6, 1.0, v6
	v_div_scale_f32 v7, s[0:1], v6, v6, v5
	s_waitcnt lgkmcnt(0)
	v_lshlrev_b32_e32 v4, 16, v4
	v_rcp_f32_e32 v7, v6
	s_nop 0
	v_mul_f32_e32 v5, v5, v7
	v_mul_f32_e32 v5, v45, v5
	v_cvt_pk_bf16_f32 v5, v5, s0
	ds_write_b16 v215, v5 offset:1408
	v_mul_f32_e32 v5, 0xbfb8aa3b, v4
	v_exp_f32_e32 v5, v5
	s_nop 0
	v_add_f32_e32 v5, 1.0, v5
	v_div_scale_f32 v6, s[0:1], v5, v5, v4
	s_nop 0
	v_rcp_f32_e32 v6, v5
	s_nop 0
	v_mul_f32_e32 v4, v4, v6
	v_mul_f32_e32 v4, v44, v4
	v_cvt_pk_bf16_f32 v4, v4, s0
	ds_write_b16 v215, v4 offset:1472
	ds_read_u16 v4, v215 offset:2048
	ds_read_u16 v5, v215 offset:2112
	s_waitcnt lgkmcnt(1)
	v_lshlrev_b32_e32 v4, 16, v4
	v_mul_f32_e32 v6, 0xbfb8aa3b, v4
	v_exp_f32_e32 v6, v6
	s_waitcnt lgkmcnt(0)
	v_lshlrev_b32_e32 v5, 16, v5
	v_add_f32_e32 v6, 1.0, v6
	v_div_scale_f32 v7, s[0:1], v6, v6, v4
	s_nop 0
	v_rcp_f32_e32 v7, v6
	s_nop 0
	v_mul_f32_e32 v4, v4, v7
	v_mul_f32_e32 v4, v27, v4
	v_cvt_pk_bf16_f32 v4, v4, s0
	ds_write_b16 v215, v4 offset:2048
	v_mul_f32_e32 v4, 0xbfb8aa3b, v5
	v_exp_f32_e32 v4, v4
	s_nop 0
	v_add_f32_e32 v4, 1.0, v4
	v_div_scale_f32 v6, s[0:1], v4, v4, v5
	s_nop 0
	v_rcp_f32_e32 v4, v4
	s_nop 0
	v_mul_f32_e32 v4, v5, v4
	v_mul_f32_e32 v4, v26, v4
	v_cvt_pk_bf16_f32 v4, v4, s0
	ds_write_b16 v215, v4 offset:2112
	ds_read_u16 v4, v215 offset:2176
	ds_read_u16 v5, v215 offset:2240
	s_waitcnt lgkmcnt(1)
	v_lshlrev_b32_e32 v4, 16, v4
	v_mul_f32_e32 v6, 0xbfb8aa3b, v4
	v_exp_f32_e32 v6, v6
	s_waitcnt lgkmcnt(0)
	v_lshlrev_b32_e32 v5, 16, v5
	v_add_f32_e32 v6, 1.0, v6
	v_div_scale_f32 v7, s[0:1], v6, v6, v4
	s_nop 0
	v_rcp_f32_e32 v7, v6
	s_nop 0
	v_mul_f32_e32 v4, v4, v7
	v_mul_f32_e32 v4, v25, v4
	v_cvt_pk_bf16_f32 v4, v4, s0
	ds_write_b16 v215, v4 offset:2176
	v_mul_f32_e32 v4, 0xbfb8aa3b, v5
	v_exp_f32_e32 v4, v4
	s_nop 0
	v_add_f32_e32 v4, 1.0, v4
	v_div_scale_f32 v6, s[0:1], v4, v4, v5
	s_nop 0
	v_rcp_f32_e32 v4, v4
	s_nop 0
	v_mul_f32_e32 v4, v5, v4
	v_mul_f32_e32 v4, v24, v4
	v_cvt_pk_bf16_f32 v4, v4, s0
	ds_write_b16 v215, v4 offset:2240
	ds_read_u16 v4, v215 offset:2304
	ds_read_u16 v5, v215 offset:2368
	s_waitcnt lgkmcnt(1)
	v_lshlrev_b32_e32 v4, 16, v4
	v_mul_f32_e32 v6, 0xbfb8aa3b, v4
	v_exp_f32_e32 v6, v6
	s_waitcnt lgkmcnt(0)
	v_lshlrev_b32_e32 v5, 16, v5
	v_add_f32_e32 v6, 1.0, v6
	v_div_scale_f32 v7, s[0:1], v6, v6, v4
	s_nop 0
	v_rcp_f32_e32 v7, v6
	s_nop 0
	v_mul_f32_e32 v4, v4, v7
	v_mul_f32_e32 v4, v23, v4
	v_cvt_pk_bf16_f32 v4, v4, s0
	ds_write_b16 v215, v4 offset:2304
	v_mul_f32_e32 v4, 0xbfb8aa3b, v5
	v_exp_f32_e32 v4, v4
	s_nop 0
	v_add_f32_e32 v4, 1.0, v4
	v_div_scale_f32 v6, s[0:1], v4, v4, v5
	s_nop 0
	v_rcp_f32_e32 v4, v4
	s_nop 0
	v_mul_f32_e32 v4, v5, v4
	v_mul_f32_e32 v4, v22, v4
	v_cvt_pk_bf16_f32 v4, v4, s0
	ds_write_b16 v215, v4 offset:2368
	ds_read_u16 v4, v215 offset:2432
	ds_read_u16 v5, v215 offset:2496
	s_waitcnt lgkmcnt(1)
	v_lshlrev_b32_e32 v4, 16, v4
	v_mul_f32_e32 v6, 0xbfb8aa3b, v4
	v_exp_f32_e32 v6, v6
	s_waitcnt lgkmcnt(0)
	v_lshlrev_b32_e32 v5, 16, v5
	v_add_f32_e32 v6, 1.0, v6
	v_div_scale_f32 v7, s[0:1], v6, v6, v4
	s_nop 0
	v_rcp_f32_e32 v7, v6
	s_nop 0
	v_mul_f32_e32 v4, v4, v7
	v_mul_f32_e32 v4, v21, v4
	v_cvt_pk_bf16_f32 v4, v4, s0
	ds_write_b16 v215, v4 offset:2432
	v_mul_f32_e32 v4, 0xbfb8aa3b, v5
	v_exp_f32_e32 v4, v4
	s_nop 0
	v_add_f32_e32 v4, 1.0, v4
	v_div_scale_f32 v6, s[0:1], v4, v4, v5
	s_nop 0
	v_rcp_f32_e32 v4, v4
	s_nop 0
	v_mul_f32_e32 v4, v5, v4
	v_mul_f32_e32 v4, v15, v4
	v_cvt_pk_bf16_f32 v4, v4, s0
	ds_write_b16 v215, v4 offset:2496
	ds_read_u16 v4, v215 offset:3072
	ds_read_u16 v5, v215 offset:3136
	s_waitcnt lgkmcnt(1)
; #define LAS __attribute__((address_space(3)))
; #define LDS_WAIT() asm volatile("s_waitcnt lgkmcnt(0)" ::: "memory")
; DI unsigned cvtpk(float lo, float hi) { f32x2 v = {lo, hi}; bf16x2_t b = __builtin_convertvector(v, bf16x2_t); return __builtin_bit_cast(unsigned, b); }
; DI float bf2f(bf16 b) { return __uint_as_float(((unsigned)b) << 16); }
; DI float siluf_(float x) { return x / (1.f + __expf(-x)); }
; DI void nsa_unit(const Ctx& c0, int b, int g, int i, LAS unsigned char* lds) {
;     ...
;       for (int rg = 0; rg < 16; ++rg) { LAS bf16* e = (LAS bf16*)(S + ((rg & 3) + 8 * (rg >> 2) + 4 * hi) * 128 + r * 2);
;           const float z0 = bf2f(e[0]), z1 = bf2f(e[32]);
;           e[0] = (bf16)(cvtpk(ca0[rg] * siluf_(z0), 0.f) & 0xffffu);
;           e[32] = (bf16)(cvtpk(ca1[rg] * siluf_(z1), 0.f) & 0xffffu); }
;       LDS_WAIT();
; #pragma unroll
;       for (int it = 0; it < 4; ++it) { const int rw = 8 * it + (lane >> 3), ch = lane & 7;
;           *(u32x4*)(ong + (size_t)rw * 512 + ch * 8) = *(const LAS u32x4*)(S + rw * 128 + ch * 16); }
;       LDS_WAIT(); }
	v_lshlrev_b32_e32 v4, 16, v4
	v_mul_f32_e32 v6, 0xbfb8aa3b, v4
	v_exp_f32_e32 v6, v6
	s_waitcnt lgkmcnt(0)
	v_lshlrev_b32_e32 v5, 16, v5
	v_add_f32_e32 v6, 1.0, v6
	v_div_scale_f32 v7, s[0:1], v6, v6, v4
	s_nop 0
	v_rcp_f32_e32 v7, v6
	s_nop 0
	v_mul_f32_e32 v4, v4, v7
	v_mul_f32_e32 v4, v20, v4
	v_cvt_pk_bf16_f32 v4, v4, s0
	ds_write_b16 v215, v4 offset:3072
	v_mul_f32_e32 v4, 0xbfb8aa3b, v5
	v_exp_f32_e32 v4, v4
	s_nop 0
	v_add_f32_e32 v4, 1.0, v4
	v_div_scale_f32 v6, s[0:1], v4, v4, v5
	s_nop 0
	v_rcp_f32_e32 v4, v4
	s_nop 0
	v_mul_f32_e32 v4, v5, v4
	v_mul_f32_e32 v4, v14, v4
	v_cvt_pk_bf16_f32 v4, v4, s0
	ds_write_b16 v215, v4 offset:3136
	ds_read_u16 v4, v215 offset:3200
	ds_read_u16 v5, v215 offset:3264
	s_waitcnt lgkmcnt(1)
	v_lshlrev_b32_e32 v4, 16, v4
	v_mul_f32_e32 v6, 0xbfb8aa3b, v4
	v_exp_f32_e32 v6, v6
	s_waitcnt lgkmcnt(0)
	v_lshlrev_b32_e32 v5, 16, v5
	v_add_f32_e32 v6, 1.0, v6
	v_div_scale_f32 v7, s[0:1], v6, v6, v4
	s_nop 0
	v_rcp_f32_e32 v7, v6
	s_nop 0
	v_mul_f32_e32 v4, v4, v7
	v_mul_f32_e32 v4, v13, v4
	v_cvt_pk_bf16_f32 v4, v4, s0
	ds_write_b16 v215, v4 offset:3200
	v_mul_f32_e32 v4, 0xbfb8aa3b, v5
	v_exp_f32_e32 v4, v4
	s_nop 0
	v_add_f32_e32 v4, 1.0, v4
	v_div_scale_f32 v6, s[0:1], v4, v4, v5
	s_nop 0
	v_rcp_f32_e32 v4, v4
	s_nop 0
	v_mul_f32_e32 v4, v5, v4
	v_mul_f32_e32 v4, v12, v4
	v_cvt_pk_bf16_f32 v4, v4, s0
	ds_write_b16 v215, v4 offset:3264
	ds_read_u16 v4, v215 offset:3328
	ds_read_u16 v5, v215 offset:3392
	s_waitcnt lgkmcnt(1)
	v_lshlrev_b32_e32 v4, 16, v4
	v_mul_f32_e32 v6, 0xbfb8aa3b, v4
	v_exp_f32_e32 v6, v6
	s_waitcnt lgkmcnt(0)
	v_lshlrev_b32_e32 v5, 16, v5
	v_add_f32_e32 v6, 1.0, v6
	v_div_scale_f32 v7, s[0:1], v6, v6, v4
	s_nop 0
	v_rcp_f32_e32 v7, v6
	s_nop 0
	v_mul_f32_e32 v4, v4, v7
	v_mul_f32_e32 v4, v10, v4
	v_cvt_pk_bf16_f32 v4, v4, s0
	ds_write_b16 v215, v4 offset:3328
	v_mul_f32_e32 v4, 0xbfb8aa3b, v5
	v_exp_f32_e32 v4, v4
	s_nop 0
	v_add_f32_e32 v4, 1.0, v4
	v_div_scale_f32 v6, s[0:1], v4, v4, v5
	s_nop 0
	v_rcp_f32_e32 v4, v4
	s_nop 0
	v_mul_f32_e32 v4, v5, v4
	v_mul_f32_e32 v4, v11, v4
	v_cvt_pk_bf16_f32 v4, v4, s0
	ds_write_b16 v215, v4 offset:3392
	ds_read_u16 v4, v215 offset:3456
	ds_read_u16 v5, v215 offset:3520
	s_waitcnt lgkmcnt(1)
	v_lshlrev_b32_e32 v4, 16, v4
	v_mul_f32_e32 v6, 0xbfb8aa3b, v4
	v_exp_f32_e32 v6, v6
	s_waitcnt lgkmcnt(0)
	v_lshlrev_b32_e32 v5, 16, v5
	v_add_f32_e32 v6, 1.0, v6
	v_div_scale_f32 v7, s[0:1], v6, v6, v4
	s_nop 0
	v_rcp_f32_e32 v7, v6
	s_nop 0
	v_mul_f32_e32 v4, v4, v7
	v_mul_f32_e32 v2, v2, v4
	v_cvt_pk_bf16_f32 v2, v2, s0
	ds_write_b16 v215, v2 offset:3456
	v_mul_f32_e32 v2, 0xbfb8aa3b, v5
	v_exp_f32_e32 v2, v2
	s_nop 0
	v_add_f32_e32 v2, 1.0, v2
	v_div_scale_f32 v4, s[0:1], v2, v2, v5
	s_nop 0
	v_rcp_f32_e32 v2, v2
	s_nop 0
	v_mul_f32_e32 v2, v5, v2
	v_mul_f32_e32 v1, v1, v2
	v_cvt_pk_bf16_f32 v1, v1, s0
	ds_write_b16 v215, v1 offset:3520
	s_waitcnt lgkmcnt(0)
	ds_read_b128 v[4:7], v211
	s_mov_b64 s[0:1], 0xd500000
	v_lshl_add_u64 v[8:9], v[8:9], 0, s[0:1]
	v_lshl_add_u64 v[10:11], v[8:9], 0, v[126:127]
	s_waitcnt lgkmcnt(0)
	global_store_dwordx4 v[10:11], v[4:7], off
	ds_read_b128 v[4:7], v212
	v_lshl_add_u64 v[10:11], v[8:9], 0, v[128:129]
	s_waitcnt lgkmcnt(0)
	global_store_dwordx4 v[10:11], v[4:7], off
	ds_read_b128 v[4:7], v213
	v_lshl_add_u64 v[10:11], v[8:9], 0, v[130:131]
	v_lshl_add_u64 v[8:9], v[8:9], 0, v[132:133]
	s_waitcnt lgkmcnt(0)
	global_store_dwordx4 v[10:11], v[4:7], off
	ds_read_b128 v[4:7], v214
	s_waitcnt lgkmcnt(0)
	global_store_dwordx4 v[8:9], v[4:7], off
	s_waitcnt lgkmcnt(0)
	s_cbranch_scc1 .LBB0_1151

; #define LAS __attribute__((address_space(3)))
; DI float bf2f(bf16 b) { return __uint_as_float(((unsigned)b) << 16); }
; DI float sigmoidf_(float x) { return 1.f / (1.f + __expf(-x)); }
; DI void branch_fold(ASt& st, float gate, bool may_be_empty, LAS float* wsf, int lane) {
;     const int r = lane & 31, hi = lane >> 5;
;     const float lt = st.l + __shfl_xor(st.l, 32);
;     float inv = 1.f / lt; if (may_be_empty && !(st.m > -1e29f)) inv = 0.f;
;     if (hi == 0) { wsf[r] = inv * gate; wsf[32 + r] = inv; }
; DI void nsa_unit(const Ctx& c0, int b, int g, int i, LAS unsigned char* lds) {
;     ...
;     const float g_c = sigmoidf_(bf2f(misc[row * 64 + head * 3 + 0])), g_s = sigmoidf_(bf2f(misc[row * 64 + head * 3 + 1])), g_w = sigmoidf_(bf2f(misc[row * 64 + head * 3 + 2]));
.LBB0_1170:
	ds_bpermute_b32 v68, v135, v84
	s_waitcnt vmcnt(0)
	v_add_u32_e32 v118, 0x8000, v204
	s_and_saveexec_b64 s[14:15], s[8:9]
	s_cbranch_execz .LBB0_1172
	v_lshlrev_b32_e32 v69, 16, v142
	v_mul_f32_e32 v69, 0xbfb8aa3b, v69
	v_exp_f32_e32 v69, v69
	s_waitcnt lgkmcnt(0)
	v_add_f32_e32 v68, v84, v68
	v_add_f32_e32 v69, 1.0, v69
	v_div_scale_f32 v70, s[16:17], v69, v69, 1.0
	s_mov_b32 s6, 0xefa18f08
	v_rcp_f32_e32 v69, v69
	v_div_scale_f32 v70, vcc, 1.0, v68, 1.0
	v_rcp_f32_e32 v68, v68
	v_cmp_lt_f32_e32 vcc, s6, v141
	s_nop 1
	v_cndmask_b32_e32 v68, 0, v68, vcc
	v_mul_f32_e32 v69, v69, v68
	ds_write2_b32 v118, v69, v68 offset1:32

; DI void nsa_unit(const Ctx& c0, int b, int g, int i, LAS unsigned char* lds) {
;     ...
;             for (int qq = 8 * wid; qq < 8 * wid + 8; ++qq) {
;                 const int n = lane;
;                 const float v = ((IMP[(0 * 64 + qq) * 64 + n] + IMP[(1 * 64 + qq) * 64 + n]) + IMP[(2 * 64 + qq) * 64 + n]) + IMP[(3 * 64 + qq) * 64 + n];
;                 unsigned key = (__float_as_uint(fmaxf(v, 0.f)) & ~63u) | (unsigned)(63 - n);
;                 if (n == 0 || n == i || n == i - 1) key = 0xFFFFFFFFu;
;                 if (n > i) key = 0u;
;                 unsigned thr = 0u;
;     ...
;                     const int cnt = __builtin_popcountll(__builtin_amdgcn_ballot_w64(key >= cand)); if (cnt >= 16) thr = cand; }
;                 const unsigned long long sm = __builtin_amdgcn_ballot_w64(key >= thr) & validm;
;                 if (lane == 0) SEL[qq] = sm;
.LBB0_1175:
	v_add_u32_e32 v5, 0, v4
	ds_read2st64_b32 v[6:7], v5 offset0:144 offset1:208
	s_waitcnt lgkmcnt(0)
	v_add_f32_e32 v6, v6, v7
	v_add_u32_e32 v7, 0x11000, v5
	ds_read_b32 v7, v7
	v_add_u32_e32 v5, 0x15000, v5
	ds_read_b32 v5, v5
	s_waitcnt lgkmcnt(1)
	v_add_f32_e32 v6, v6, v7
	s_waitcnt lgkmcnt(0)
	v_add_f32_e32 v5, v6, v5
	v_max_f32_e32 v5, 0, v5
	v_and_b32_e32 v5, 0xffffffc0, v5
	v_bitop3_b32 v5, v5, 63, v150 bitop3:0x36
	v_cndmask_b32_e64 v5, v5, -1, s[82:83]
	v_cndmask_b32_e64 v5, v5, 0, vcc
	v_cmp_gt_i32_e64 s[80:81], 0, v5
	s_bcnt1_i32_b64 s6, s[80:81]
	s_cmp_gt_u32 s6, 15
	s_cselect_b32 s86, 0x80000000, 0
	s_or_b32 s87, s86, 2.0
	v_cmp_le_u32_e64 s[80:81], s87, v5
	s_bcnt1_i32_b64 s6, s[80:81]
	s_cmp_gt_u32 s6, 15
	s_cselect_b32 s86, s87, s86
	s_or_b32 s87, s86, 0x20000000
	v_cmp_le_u32_e64 s[80:81], s87, v5
	s_bcnt1_i32_b64 s6, s[80:81]
	s_cmp_gt_u32 s6, 15
	s_cselect_b32 s86, s87, s86
	s_or_b32 s87, s86, 0x10000000
	v_cmp_le_u32_e64 s[80:81], s87, v5
	s_bcnt1_i32_b64 s6, s[80:81]
	s_cmp_gt_u32 s6, 15
	s_cselect_b32 s86, s87, s86
	s_or_b32 s87, s86, 0x8000000
	v_cmp_le_u32_e64 s[80:81], s87, v5
	s_bcnt1_i32_b64 s6, s[80:81]
	s_cmp_gt_u32 s6, 15
	s_cselect_b32 s86, s87, s86
	s_or_b32 s87, s86, 0x4000000
	v_cmp_le_u32_e64 s[80:81], s87, v5
	s_bcnt1_i32_b64 s6, s[80:81]
	s_cmp_gt_u32 s6, 15
	s_cselect_b32 s86, s87, s86
	s_or_b32 s87, s86, 0x2000000
	v_cmp_le_u32_e64 s[80:81], s87, v5
	s_bcnt1_i32_b64 s6, s[80:81]
	s_cmp_gt_u32 s6, 15
	s_cselect_b32 s86, s87, s86
	s_or_b32 s87, s86, 0x1000000
	v_cmp_le_u32_e64 s[80:81], s87, v5
	s_bcnt1_i32_b64 s6, s[80:81]
	s_cmp_gt_u32 s6, 15
	s_cselect_b32 s86, s87, s86
	s_or_b32 s87, s86, 0x800000
	v_cmp_le_u32_e64 s[80:81], s87, v5
	s_bcnt1_i32_b64 s6, s[80:81]
	s_cmp_gt_u32 s6, 15
	s_cselect_b32 s86, s87, s86
	s_or_b32 s87, s86, 0x400000
	v_cmp_le_u32_e64 s[80:81], s87, v5
	s_bcnt1_i32_b64 s6, s[80:81]
	s_cmp_gt_u32 s6, 15
	s_cselect_b32 s86, s87, s86
	s_or_b32 s87, s86, 0x200000
	v_cmp_le_u32_e64 s[80:81], s87, v5
	s_bcnt1_i32_b64 s6, s[80:81]
	s_cmp_gt_u32 s6, 15
	s_cselect_b32 s86, s87, s86
	s_or_b32 s87, s86, 0x100000
	v_cmp_le_u32_e64 s[80:81], s87, v5
	s_bcnt1_i32_b64 s6, s[80:81]
	s_cmp_gt_u32 s6, 15
	s_cselect_b32 s86, s87, s86
	s_or_b32 s87, s86, 0x80000
	v_cmp_le_u32_e64 s[80:81], s87, v5
	s_bcnt1_i32_b64 s6, s[80:81]
	s_cmp_gt_u32 s6, 15
	s_cselect_b32 s86, s87, s86
	s_or_b32 s87, s86, 0x40000
	v_cmp_le_u32_e64 s[80:81], s87, v5
	s_bcnt1_i32_b64 s6, s[80:81]
	s_cmp_gt_u32 s6, 15
	s_cselect_b32 s86, s87, s86
	s_or_b32 s87, s86, 0x20000
	v_cmp_le_u32_e64 s[80:81], s87, v5
	s_bcnt1_i32_b64 s6, s[80:81]
	s_cmp_gt_u32 s6, 15
	s_cselect_b32 s86, s87, s86
	s_or_b32 s87, s86, 0x10000
	v_cmp_le_u32_e64 s[80:81], s87, v5
	s_bcnt1_i32_b64 s6, s[80:81]
	s_cmp_gt_u32 s6, 15
	s_cselect_b32 s86, s87, s86
	s_or_b32 s87, s86, 0x8000
	v_cmp_le_u32_e64 s[80:81], s87, v5
	s_bcnt1_i32_b64 s6, s[80:81]
	s_cmp_gt_u32 s6, 15
	s_cselect_b32 s86, s87, s86
	s_or_b32 s87, s86, 0x4000
	v_cmp_le_u32_e64 s[80:81], s87, v5
	s_bcnt1_i32_b64 s6, s[80:81]
	s_cmp_gt_u32 s6, 15
	s_cselect_b32 s86, s87, s86
	s_or_b32 s87, s86, 0x2000
	v_cmp_le_u32_e64 s[80:81], s87, v5
	s_bcnt1_i32_b64 s6, s[80:81]
	s_cmp_gt_u32 s6, 15
	s_cselect_b32 s86, s87, s86
	s_or_b32 s87, s86, 0x1000
	v_cmp_le_u32_e64 s[80:81], s87, v5
	s_bcnt1_i32_b64 s6, s[80:81]
	s_cmp_gt_u32 s6, 15
	s_cselect_b32 s86, s87, s86
	s_or_b32 s87, s86, 0x800
	v_cmp_le_u32_e64 s[80:81], s87, v5
	s_bcnt1_i32_b64 s6, s[80:81]
	s_cmp_gt_u32 s6, 15
	s_cselect_b32 s86, s87, s86
	s_or_b32 s87, s86, 0x400
	v_cmp_le_u32_e64 s[80:81], s87, v5
	s_bcnt1_i32_b64 s6, s[80:81]
	s_cmp_gt_u32 s6, 15
	s_cselect_b32 s86, s87, s86
	s_or_b32 s87, s86, 0x200
	v_cmp_le_u32_e64 s[80:81], s87, v5
	s_bcnt1_i32_b64 s6, s[80:81]
	s_cmp_gt_u32 s6, 15
	s_cselect_b32 s86, s87, s86
	s_or_b32 s87, s86, 0x100
	v_cmp_le_u32_e64 s[80:81], s87, v5
	s_bcnt1_i32_b64 s6, s[80:81]
	s_cmp_gt_u32 s6, 15
	s_cselect_b32 s86, s87, s86
	s_or_b32 s87, s86, 0x80
	v_cmp_le_u32_e64 s[80:81], s87, v5
	s_bcnt1_i32_b64 s6, s[80:81]
	s_cmp_gt_u32 s6, 15
	s_cselect_b32 s86, s87, s86
	s_or_b32 s87, s86, 64
	v_cmp_le_u32_e64 s[80:81], s87, v5
	s_bcnt1_i32_b64 s6, s[80:81]
	s_cmp_gt_u32 s6, 15
	s_cselect_b32 s86, s87, s86
	s_or_b32 s87, s86, 32
	v_cmp_le_u32_e64 s[80:81], s87, v5
	s_bcnt1_i32_b64 s6, s[80:81]
	s_cmp_gt_u32 s6, 15
	s_cselect_b32 s86, s87, s86
	s_or_b32 s87, s86, 16
	v_cmp_le_u32_e64 s[80:81], s87, v5
	s_bcnt1_i32_b64 s6, s[80:81]
	s_cmp_gt_u32 s6, 15
	s_cselect_b32 s86, s87, s86
	s_or_b32 s87, s86, 8
	v_cmp_le_u32_e64 s[80:81], s87, v5
	s_bcnt1_i32_b64 s6, s[80:81]
	s_cmp_gt_u32 s6, 15
	s_cselect_b32 s86, s87, s86
	s_or_b32 s87, s86, 4
	v_cmp_le_u32_e64 s[80:81], s87, v5
	s_bcnt1_i32_b64 s6, s[80:81]
	s_cmp_gt_u32 s6, 15
	s_cselect_b32 s86, s87, s86
	s_or_b32 s87, s86, 2
	v_cmp_le_u32_e64 s[80:81], s87, v5
	s_bcnt1_i32_b64 s6, s[80:81]
	s_cmp_gt_u32 s6, 15
	s_cselect_b32 s86, s87, s86
	s_or_b32 s87, s86, 1
	v_cmp_le_u32_e64 s[80:81], s87, v5
	s_bcnt1_i32_b64 s6, s[80:81]
	s_cmp_gt_u32 s6, 15
	s_cselect_b32 s6, s87, s86
	v_cmp_le_u32_e64 s[80:81], s6, v5
	s_and_saveexec_b64 s[16:17], s[10:11]
	s_cbranch_execz .LBB0_1174
	s_and_b64 s[80:81], s[80:81], s[14:15]
	s_add_i32 s6, s29, 0
	v_mov_b32_e32 v5, s6
	v_mov_b64_e32 v[6:7], s[80:81]
	ds_write_b64 v5, v[6:7]
	s_branch .LBB0_1174

; #define LAS __attribute__((address_space(3)))
; DI float bf2f(bf16 b) { return __uint_as_float(((unsigned)b) << 16); }
; DI float sigmoidf_(float x) { return 1.f / (1.f + __expf(-x)); }
; DI void branch_fold(ASt& st, float gate, bool may_be_empty, LAS float* wsf, int lane) {
;     const int r = lane & 31, hi = lane >> 5;
;     const float lt = st.l + __shfl_xor(st.l, 32);
;     float inv = 1.f / lt; if (may_be_empty && !(st.m > -1e29f)) inv = 0.f;
;     if (hi == 0) { wsf[r] = inv * gate; wsf[32 + r] = inv; }
; DI void nsa_unit(const Ctx& c0, int b, int g, int i, LAS unsigned char* lds) {
;     ...
;     const float g_c = sigmoidf_(bf2f(misc[row * 64 + head * 3 + 0])), g_s = sigmoidf_(bf2f(misc[row * 64 + head * 3 + 1])), g_w = sigmoidf_(bf2f(misc[row * 64 + head * 3 + 2]));
.LBB0_1188:
	s_or_b64 exec, exec, s[14:15]
	ds_bpermute_b32 v2, v135, v11
	s_and_saveexec_b64 s[14:15], s[8:9]
	s_cbranch_execz .LBB0_1190
	v_and_b32_e32 v4, 0xffff0000, v142
	v_mul_f32_e32 v4, 0xbfb8aa3b, v4
	v_exp_f32_e32 v4, v4
	s_waitcnt lgkmcnt(0)
	v_add_f32_e32 v2, v11, v2
	v_add_f32_e32 v4, 1.0, v4
	v_div_scale_f32 v5, s[16:17], v4, v4, 1.0
	v_rcp_f32_e32 v4, v4
	v_rcp_f32_e32 v2, v2
	s_nop 0
	v_mul_f32_e32 v4, v4, v2
	ds_write2_b32 v118, v4, v2 offset1:32

; #define LAS __attribute__((address_space(3)))
; DI float bf2f(bf16 b) { return __uint_as_float(((unsigned)b) << 16); }
; DI float sigmoidf_(float x) { return 1.f / (1.f + __expf(-x)); }
; DI void branch_fold(ASt& st, float gate, bool may_be_empty, LAS float* wsf, int lane) {
;     const int r = lane & 31, hi = lane >> 5;
;     const float lt = st.l + __shfl_xor(st.l, 32);
;     float inv = 1.f / lt; if (may_be_empty && !(st.m > -1e29f)) inv = 0.f;
;     if (hi == 0) { wsf[r] = inv * gate; wsf[32 + r] = inv; }
; DI void nsa_unit(const Ctx& c0, int b, int g, int i, LAS unsigned char* lds) {
;     ...
;     const float g_c = sigmoidf_(bf2f(misc[row * 64 + head * 3 + 0])), g_s = sigmoidf_(bf2f(misc[row * 64 + head * 3 + 1])), g_w = sigmoidf_(bf2f(misc[row * 64 + head * 3 + 2]));
.LBB0_1212:
	ds_bpermute_b32 v2, v135, v40
	s_and_saveexec_b64 s[14:15], s[8:9]
	s_cbranch_execz .LBB0_1153
	v_lshlrev_b32_e32 v1, 16, v1
	v_mul_f32_e32 v1, 0xbfb8aa3b, v1
	v_exp_f32_e32 v1, v1
	s_waitcnt lgkmcnt(0)
	v_add_f32_e32 v2, v40, v2
	v_add_f32_e32 v1, 1.0, v1
	v_div_scale_f32 v36, s[16:17], v1, v1, 1.0
	v_rcp_f32_e32 v1, v1
	v_rcp_f32_e32 v2, v2
	s_nop 0
	v_mul_f32_e32 v1, v1, v2
	ds_write2_b32 v118, v1, v2 offset1:32
	s_branch .LBB0_1153

; #define MFMA32(a, b, c) __builtin_amdgcn_mfma_f32_32x32x16_bf16((a), (b), (c), 0, 0, 0)
; DI void gla_stage3(const Ctx& c0, int layer, int unit, int cb, LAS unsigned char* lds) {
;     ...
;     const bf16* qgp = (const bf16*)(c.ws + O_QG) + (row0 + r) * 256 + h * 64 + 8 * hi;
;     const float* sp = (const float*)(c.ws + O_UPD) + (size_t)unit * 8192;
;     const float* gn = c.a->in[I_GNORM] + (size_t)layer * 128;
;     bf16x8 qf[4];
; #pragma unroll
;     for (int s = 0; s < 4; ++s) qf[s] = *(const bf16x8*)(qgp + 16 * s);
;     f32x16 o[4];
; #pragma unroll
;     for (int vb = 0; vb < 4; ++vb) {
;         o[vb] = f32x16{};
; #pragma unroll
;         for (int s = 0; s < 4; ++s) { const float* s0 = sp + (size_t)(16 * s + 8 * hi) * 128 + 32 * vb + r;
;             const bf16x8 bfv = pack8(s0[0], s0[128], s0[256], s0[384], s0[512], s0[640], s0[768], s0[896]);
;             o[vb] = MFMA32(qf[s], bfv, o[vb]); }
;         asm volatile("" ::: "memory");
;     }
.LBB0_1216:
	s_mov_b64 s[0:1], s[74:75]
	s_mov_b64 s[2:3], s[72:73]
	s_ashr_i32 s2, s34, 8
	s_ashr_i32 s3, s2, 31
	s_lshl_b64 s[2:3], s[2:3], 12
	s_and_b32 s9, s4, 0xfc0
	s_or_b32 s2, s2, s9
	s_or_b64 s[2:3], s[2:3], s[10:11]
	v_mov_b32_e32 v3, s3
	v_or_b32_e32 v2, s2, v152
	s_bfe_u32 s8, s34, 0x20006
	v_lshlrev_b64 v[2:3], 9, v[2:3]
	v_lshl_add_u64 v[2:3], s[0:1], 0, v[2:3]
	s_lshl_b32 s12, s8, 7
	v_lshl_add_u64 v[2:3], v[2:3], 0, s[12:13]
	v_lshl_add_u64 v[2:3], v[2:3], 0, v[86:87]
	v_lshl_add_u64 v[4:5], v[2:3], 0, s[18:19]
	v_add_co_u32_e32 v2, vcc, s6, v2
	v_lshl_add_u64 v[90:91], s[0:1], 0, v[84:85]
	s_nop 0
	v_addc_co_u32_e32 v3, vcc, 0, v3, vcc
	global_load_dwordx4 v[50:53], v[2:3], off
	global_load_dwordx4 v[110:113], v[4:5], off offset:96
	global_load_dwordx4 v[106:109], v[4:5], off offset:64
	global_load_dwordx4 v[102:105], v[4:5], off offset:32
	v_add_co_u32_e32 v2, vcc, s7, v90
	s_lshl_b64 s[2:3], s[2:3], 10
	s_nop 0
	v_addc_co_u32_e32 v3, vcc, -1, v91, vcc
	v_add_co_u32_e32 v58, vcc, s28, v90
	global_load_dword v2, v[2:3], off
	s_nop 0
	v_addc_co_u32_e32 v59, vcc, -1, v91, vcc
	global_load_dword v3, v[58:59], off offset:384
	global_load_dword v4, v[58:59], off offset:896
	global_load_dword v5, v[58:59], off offset:1408
	global_load_dword v6, v[58:59], off offset:1920
	global_load_dword v7, v[58:59], off offset:2432
	global_load_dword v8, v[58:59], off offset:2944
	global_load_dword v9, v[58:59], off offset:3456
	v_add_co_u32_e32 v18, vcc, s15, v90
	s_lshl_b32 s8, s8, 8
	s_nop 0
	v_addc_co_u32_e32 v19, vcc, -1, v91, vcc
	v_add_co_u32_e32 v114, vcc, s29, v90
	global_load_dword v18, v[18:19], off
	s_nop 0
	v_addc_co_u32_e32 v115, vcc, -1, v91, vcc
	global_load_dword v19, v[114:115], off offset:384
	global_load_dword v20, v[114:115], off offset:896
	global_load_dword v21, v[114:115], off offset:1408
	global_load_dword v22, v[114:115], off offset:1920
	global_load_dword v23, v[114:115], off offset:2432
	global_load_dword v24, v[114:115], off offset:2944
	global_load_dword v25, v[114:115], off offset:3456
	s_add_u32 s0, s0, s2
	s_addc_u32 s1, s1, s3
	s_add_u32 s0, s0, s8
	s_addc_u32 s1, s1, 0
	s_add_i32 s34, s34, s14
	s_add_i32 s4, s4, s5
	v_lshl_add_u64 v[84:85], v[84:85], 0, s[16:17]
	s_cmpk_lt_i32 s34, 0x800
	s_waitcnt vmcnt(0) lgkmcnt(0)
	global_load_dword v41, v[114:115], off offset:3584
	global_load_dword v40, v[114:115], off offset:3072
	global_load_dword v39, v[114:115], off offset:2560
	global_load_dword v38, v[114:115], off offset:2048
	global_load_dword v37, v[114:115], off offset:1536
	global_load_dword v36, v[114:115], off offset:1024
	global_load_dword v35, v[114:115], off offset:512
	global_load_dword v34, v[114:115], off
	global_load_dword v145, v[58:59], off offset:3584
	global_load_dword v146, v[58:59], off offset:3072
	global_load_dword v143, v[58:59], off offset:2560
	global_load_dword v144, v[58:59], off offset:2048
	global_load_dword v141, v[58:59], off offset:1536
	global_load_dword v142, v[58:59], off offset:1024
	global_load_dword v139, v[58:59], off offset:512
	global_load_dword v140, v[58:59], off
	v_cvt_pk_bf16_f32 v2, v2, v3
	v_cvt_pk_bf16_f32 v3, v4, v5
	v_cvt_pk_bf16_f32 v4, v6, v7
	v_cvt_pk_bf16_f32 v5, v8, v9
	v_cvt_pk_bf16_f32 v18, v18, v19
	s_nop 0
	v_mfma_f32_32x32x16_bf16 v[2:17], v[50:53], v[2:5], 0
	v_cvt_pk_bf16_f32 v19, v20, v21
	v_cvt_pk_bf16_f32 v20, v22, v23
	v_cvt_pk_bf16_f32 v21, v24, v25
	s_nop 1
	v_mfma_f32_32x32x16_bf16 v[2:17], v[102:105], v[18:21], v[2:17]
	v_add_co_u32_e32 v18, vcc, s26, v90
	s_nop 1
	v_addc_co_u32_e32 v19, vcc, -1, v91, vcc
	v_add_co_u32_e32 v118, vcc, s30, v90
	global_load_dword v18, v[18:19], off
	s_nop 0
	v_addc_co_u32_e32 v119, vcc, -1, v91, vcc
	global_load_dword v19, v[118:119], off offset:384
	global_load_dword v20, v[118:119], off offset:896
	global_load_dword v21, v[118:119], off offset:1408
	global_load_dword v22, v[118:119], off offset:1920
	global_load_dword v23, v[118:119], off offset:2432
	global_load_dword v24, v[118:119], off offset:2944
	global_load_dword v25, v[118:119], off offset:3456
	s_waitcnt vmcnt(0) lgkmcnt(0)
	global_load_dword v63, v[114:115], off offset:3712
	global_load_dword v62, v[114:115], off offset:3200
	global_load_dword v61, v[114:115], off offset:2688
	global_load_dword v60, v[114:115], off offset:2176
	global_load_dword v57, v[114:115], off offset:1664
	global_load_dword v56, v[114:115], off offset:1152
	global_load_dword v55, v[114:115], off offset:640
	global_load_dword v54, v[114:115], off offset:128
	global_load_dword v173, v[58:59], off offset:3712
	global_load_dword v176, v[58:59], off offset:3200
	global_load_dword v171, v[58:59], off offset:2688
	global_load_dword v174, v[58:59], off offset:2176
	global_load_dword v169, v[58:59], off offset:1664
	global_load_dword v172, v[58:59], off offset:1152
	global_load_dword v167, v[58:59], off offset:640
	global_load_dword v170, v[58:59], off offset:128
	global_load_dword v157, v[118:119], off offset:3584
	global_load_dword v160, v[118:119], off offset:3072
	global_load_dword v155, v[118:119], off offset:2560
	global_load_dword v158, v[118:119], off offset:2048
	global_load_dword v149, v[118:119], off offset:1536
	global_load_dword v156, v[118:119], off offset:1024
	global_load_dword v147, v[118:119], off offset:512
	global_load_dword v148, v[118:119], off
	v_cvt_pk_bf16_f32 v18, v18, v19
	v_cvt_pk_bf16_f32 v19, v20, v21
	v_cvt_pk_bf16_f32 v20, v22, v23
	v_cvt_pk_bf16_f32 v21, v24, v25
	s_nop 1
	v_mfma_f32_32x32x16_bf16 v[2:17], v[106:109], v[18:21], v[2:17]
	v_add_co_u32_e32 v18, vcc, s27, v90
	s_nop 1
	v_addc_co_u32_e32 v19, vcc, -1, v91, vcc
	v_add_co_u32_e32 v120, vcc, s31, v90
	global_load_dword v18, v[18:19], off
	s_nop 0
	v_addc_co_u32_e32 v121, vcc, -1, v91, vcc
	global_load_dword v19, v[120:121], off offset:384
	global_load_dword v20, v[120:121], off offset:896
	global_load_dword v21, v[120:121], off offset:1408
	global_load_dword v22, v[120:121], off offset:1920
	global_load_dword v23, v[120:121], off offset:2432
	global_load_dword v24, v[120:121], off offset:2944
	global_load_dword v25, v[120:121], off offset:3456
	v_cmp_lt_i32_e32 vcc, v94, v95
	s_waitcnt vmcnt(0) lgkmcnt(0)
; #define MFMA32(a, b, c) __builtin_amdgcn_mfma_f32_32x32x16_bf16((a), (b), (c), 0, 0, 0)
; DI void gla_stage3(const Ctx& c0, int layer, int unit, int cb, LAS unsigned char* lds) {
;     ...
;     f32x16 o[4];
; #pragma unroll
;     for (int vb = 0; vb < 4; ++vb) {
;         o[vb] = f32x16{};
; #pragma unroll
;         for (int s = 0; s < 4; ++s) { const float* s0 = sp + (size_t)(16 * s + 8 * hi) * 128 + 32 * vb + r;
;             const bf16x8 bfv = pack8(s0[0], s0[128], s0[256], s0[384], s0[512], s0[640], s0[768], s0[896]);
;             o[vb] = MFMA32(qf[s], bfv, o[vb]); }
;         asm volatile("" ::: "memory");
;     }
;     ...
;     for (int vb = 0; vb < 4; ++vb) { const float g = gn[32 * vb + r];
	global_load_dword v127, v[114:115], off offset:3840
	global_load_dword v126, v[114:115], off offset:3328
	global_load_dword v125, v[114:115], off offset:2816
	global_load_dword v124, v[114:115], off offset:2304
	global_load_dword v123, v[114:115], off offset:1792
	global_load_dword v122, v[114:115], off offset:1280
	global_load_dword v117, v[114:115], off offset:768
	global_load_dword v116, v[114:115], off offset:256
	global_load_dword v214, v[58:59], off offset:3840
	global_load_dword v212, v[58:59], off offset:3328
	global_load_dword v205, v[58:59], off offset:2816
	global_load_dword v210, v[58:59], off offset:2304
	global_load_dword v203, v[58:59], off offset:1792
	global_load_dword v208, v[58:59], off offset:1280
	global_load_dword v201, v[58:59], off offset:768
	global_load_dword v206, v[58:59], off offset:256
	global_load_dword v199, v[120:121], off offset:3712
	global_load_dword v204, v[120:121], off offset:3200
	global_load_dword v197, v[120:121], off offset:2688
	global_load_dword v202, v[120:121], off offset:2176
	global_load_dword v195, v[120:121], off offset:1664
	global_load_dword v200, v[120:121], off offset:1152
	global_load_dword v183, v[120:121], off offset:640
	global_load_dword v198, v[120:121], off offset:128
	global_load_dword v181, v[118:119], off offset:3712
	global_load_dword v196, v[118:119], off offset:3200
	global_load_dword v179, v[118:119], off offset:2688
	global_load_dword v182, v[118:119], off offset:2176
	global_load_dword v177, v[118:119], off offset:1664
	global_load_dword v180, v[118:119], off offset:1152
	global_load_dword v175, v[118:119], off offset:640
	global_load_dword v178, v[118:119], off offset:128
	global_load_dword v165, v[120:121], off offset:3584
	global_load_dword v168, v[120:121], off offset:3072
	global_load_dword v163, v[120:121], off offset:2560
	global_load_dword v166, v[120:121], off offset:2048
	global_load_dword v161, v[120:121], off offset:1536
	global_load_dword v164, v[120:121], off offset:1024
	global_load_dword v159, v[120:121], off offset:512
	global_load_dword v162, v[120:121], off
	v_cvt_pk_bf16_f32 v18, v18, v19
	v_cvt_pk_bf16_f32 v19, v20, v21
	v_cvt_pk_bf16_f32 v20, v22, v23
	v_cvt_pk_bf16_f32 v21, v24, v25
	s_nop 1
	v_mfma_f32_32x32x16_bf16 v[2:17], v[110:113], v[18:21], v[2:17]
	s_waitcnt vmcnt(40) lgkmcnt(0)
	global_load_dword v238, v[82:83], off offset:896
	global_load_dword v236, v[82:83], off offset:768
	global_load_dword v234, v[82:83], off offset:640
	global_load_dword v232, v[82:83], off offset:512
	global_load_dword v90, v[90:91], off
	global_load_dword v230, v[120:121], off offset:3328
	global_load_dword v219, v[120:121], off offset:2816
	global_load_dword v228, v[120:121], off offset:2304
	global_load_dword v217, v[120:121], off offset:1792
	global_load_dword v226, v[120:121], off offset:1280
	global_load_dword v215, v[120:121], off offset:768
	global_load_dword v224, v[120:121], off offset:256
	global_load_dword v213, v[118:119], off offset:3840
	global_load_dword v222, v[118:119], off offset:3328
	global_load_dword v211, v[118:119], off offset:2816
	global_load_dword v220, v[118:119], off offset:2304
	global_load_dword v209, v[118:119], off offset:1792
	global_load_dword v218, v[118:119], off offset:1280
	global_load_dword v207, v[118:119], off offset:768
	global_load_dword v216, v[118:119], off offset:256
	v_cvt_pk_bf16_f32 v18, v140, v139
	v_cvt_pk_bf16_f32 v34, v34, v35
	v_cvt_pk_bf16_f32 v19, v142, v141
	v_cvt_pk_bf16_f32 v35, v36, v37
	v_cvt_pk_bf16_f32 v20, v144, v143
	v_cvt_pk_bf16_f32 v36, v38, v39
	v_cvt_pk_bf16_f32 v21, v146, v145
	v_cvt_pk_bf16_f32 v37, v40, v41
	s_nop 0
	v_mfma_f32_32x32x16_bf16 v[18:33], v[50:53], v[18:21], 0
	v_mfma_f32_32x32x16_bf16 v[18:33], v[102:105], v[34:37], v[18:33]
	s_waitcnt vmcnt(60) lgkmcnt(0)
	v_cvt_pk_bf16_f32 v34, v148, v147
	v_cvt_pk_bf16_f32 v35, v156, v149
	v_cvt_pk_bf16_f32 v36, v158, v155
	v_cvt_pk_bf16_f32 v37, v160, v157
	s_nop 1
	v_mfma_f32_32x32x16_bf16 v[18:33], v[106:109], v[34:37], v[18:33]
	s_waitcnt vmcnt(20) lgkmcnt(0)
	v_cvt_pk_bf16_f32 v34, v162, v159
	v_cvt_pk_bf16_f32 v35, v164, v161
	v_cvt_pk_bf16_f32 v36, v166, v163
	v_cvt_pk_bf16_f32 v37, v168, v165
	s_nop 1
	v_mfma_f32_32x32x16_bf16 v[18:33], v[110:113], v[34:37], v[18:33]
	s_waitcnt vmcnt(62) lgkmcnt(0)
	v_cvt_pk_bf16_f32 v34, v170, v167
	v_cvt_pk_bf16_f32 v54, v54, v55
	v_cvt_pk_bf16_f32 v35, v172, v169
	v_cvt_pk_bf16_f32 v55, v56, v57
	v_cvt_pk_bf16_f32 v36, v174, v171
	v_cvt_pk_bf16_f32 v56, v60, v61
	v_cvt_pk_bf16_f32 v37, v176, v173
	v_cvt_pk_bf16_f32 v57, v62, v63
	s_nop 0
	v_mfma_f32_32x32x16_bf16 v[34:49], v[50:53], v[34:37], 0
	v_mfma_f32_32x32x16_bf16 v[34:49], v[102:105], v[54:57], v[34:49]
	s_waitcnt vmcnt(28) lgkmcnt(0)
	v_cvt_pk_bf16_f32 v54, v178, v175
	v_cvt_pk_bf16_f32 v55, v180, v177
	v_cvt_pk_bf16_f32 v56, v182, v179
	v_cvt_pk_bf16_f32 v57, v196, v181
	s_nop 1
	v_mfma_f32_32x32x16_bf16 v[34:49], v[106:109], v[54:57], v[34:49]
	s_waitcnt vmcnt(36) lgkmcnt(0)
	v_cvt_pk_bf16_f32 v54, v198, v183
	v_cvt_pk_bf16_f32 v55, v200, v195
	v_cvt_pk_bf16_f32 v56, v202, v197
	v_cvt_pk_bf16_f32 v57, v204, v199
	s_nop 1
	v_mfma_f32_32x32x16_bf16 v[34:49], v[110:113], v[54:57], v[34:49]
	s_nop 0
	s_nop 0
	s_waitcnt vmcnt(44) lgkmcnt(0)
	v_cvt_pk_bf16_f32 v54, v206, v201
	v_cvt_pk_bf16_f32 v114, v116, v117
	v_cvt_pk_bf16_f32 v55, v208, v203
	v_cvt_pk_bf16_f32 v115, v122, v123
	v_cvt_pk_bf16_f32 v56, v210, v205
	v_cvt_pk_bf16_f32 v116, v124, v125
	v_cvt_pk_bf16_f32 v57, v212, v214
	v_cvt_pk_bf16_f32 v117, v126, v127
	s_nop 0
	v_mfma_f32_32x32x16_bf16 v[50:65], v[50:53], v[54:57], 0
	v_mfma_f32_32x32x16_bf16 v[50:65], v[102:105], v[114:117], v[50:65]
	s_waitcnt vmcnt(0) lgkmcnt(0)
; #define LAS __attribute__((address_space(3)))
; #define LDS_WAIT() asm volatile("s_waitcnt lgkmcnt(0)" ::: "memory")
; DI float bf2f(bf16 b) { return __uint_as_float(((unsigned)b) << 16); }
; #define MFMA32(a, b, c) __builtin_amdgcn_mfma_f32_32x32x16_bf16((a), (b), (c), 0, 0, 0)
; DI void g3_tile_in(const bf16* g, LAS unsigned char* R, int lane) {
; #pragma unroll
;     for (int it = 0; it < 8; ++it) { const int row = 4 * it + (lane >> 4), ch = lane & 15;
;         *(LAS u32x4*)(R + row * G3_PITCH + ch * 16) = *(const u32x4*)(g + (size_t)row * 512 + ch * 8); }
;     LDS_WAIT();
; DI void gla_stage3(const Ctx& c0, int layer, int unit, int cb, LAS unsigned char* lds) {
;     ...
;         for (int s = 0; s < 4; ++s) { const float* s0 = sp + (size_t)(16 * s + 8 * hi) * 128 + 32 * vb + r;
;             const bf16x8 bfv = pack8(s0[0], s0[128], s0[256], s0[384], s0[512], s0[640], s0[768], s0[896]);
;             o[vb] = MFMA32(qf[s], bfv, o[vb]); }
;         asm volatile("" ::: "memory");
;     }
;     g3_tile_in((const bf16*)(c.ws + O_OINTRA) + row0 * 512 + h * 128, R, lane);
; #pragma unroll
;     for (int vb = 0; vb < 4; ++vb) {
; #pragma unroll
;         for (int rg = 0; rg < 16; ++rg) o[vb][rg] += bf2f(*(const LAS bf16*)(Re + ((rg & 3) + 8 * (rg >> 2)) * G3_PITCH + 64 * vb));
;         asm volatile("" ::: "memory");
;     }
	v_cvt_pk_bf16_f32 v102, v216, v207
	v_cvt_pk_bf16_f32 v103, v218, v209
	v_cvt_pk_bf16_f32 v104, v220, v211
	v_cvt_pk_bf16_f32 v105, v222, v213
	s_nop 1
	v_mfma_f32_32x32x16_bf16 v[50:65], v[106:109], v[102:105], v[50:65]
	s_nop 0
	s_waitcnt vmcnt(8) lgkmcnt(0)
	v_cvt_pk_bf16_f32 v102, v224, v215
	v_cvt_pk_bf16_f32 v103, v226, v217
	v_cvt_pk_bf16_f32 v104, v228, v219
	v_cvt_pk_bf16_f32 v105, v230, v90
	v_lshl_add_u64 v[90:91], s[0:1], 0, v[88:89]
	v_lshl_add_u64 v[106:107], v[90:91], 0, s[20:21]
	v_mfma_f32_32x32x16_bf16 v[50:65], v[110:113], v[102:105], v[50:65]
	v_lshl_add_u64 v[102:103], v[106:107], 0, v[66:67]
	global_load_dwordx4 v[102:105], v[102:103], off
	s_waitcnt vmcnt(0) lgkmcnt(0)
	v_lshl_add_u64 v[168:169], v[90:91], 0, s[22:23]
	v_lshl_add_u64 v[140:141], v[168:169], 0, v[70:71]
	global_load_dwordx4 v[174:177], v[140:141], off
	v_lshl_add_u64 v[140:141], v[106:107], 0, v[70:71]
	global_load_dwordx4 v[146:149], v[140:141], off
	v_lshl_add_u64 v[144:145], v[106:107], 0, v[68:69]
	global_load_dwordx4 v[140:143], v[144:145], off
	ds_write_b128 v92, v[102:105]
	s_waitcnt vmcnt(0) lgkmcnt(0)
	v_lshl_add_u64 v[144:145], v[168:169], 0, v[76:77]
	global_load_dwordx4 v[200:203], v[144:145], off
	v_lshl_add_u64 v[144:145], v[168:169], 0, v[74:75]
	global_load_dwordx4 v[196:199], v[144:145], off
	v_lshl_add_u64 v[144:145], v[168:169], 0, v[72:73]
	global_load_dwordx4 v[178:181], v[144:145], off
	v_lshl_add_u64 v[144:145], v[106:107], 0, v[74:75]
	global_load_dwordx4 v[156:159], v[144:145], off
	v_lshl_add_u64 v[102:103], v[106:107], 0, v[72:73]
	global_load_dwordx4 v[102:105], v[102:103], off
	ds_write_b128 v92, v[140:143] offset:1088
	s_waitcnt vmcnt(5) lgkmcnt(0)
	v_lshl_add_u64 v[140:141], v[168:169], 0, v[78:79]
	global_load_dwordx4 v[204:207], v[140:141], off
	v_lshl_add_u64 v[140:141], v[106:107], 0, v[78:79]
	global_load_dwordx4 v[160:163], v[140:141], off
	v_lshl_add_u64 v[144:145], v[106:107], 0, v[76:77]
	global_load_dwordx4 v[140:143], v[144:145], off
	ds_write_b128 v92, v[146:149] offset:2176
	s_waitcnt vmcnt(3) lgkmcnt(0)
	v_lshl_add_u64 v[144:145], v[168:169], 0, v[66:67]
	global_load_dwordx4 v[164:167], v[144:145], off
	v_lshl_add_u64 v[148:149], v[106:107], 0, v[80:81]
	global_load_dwordx4 v[144:147], v[148:149], off
	ds_write_b128 v92, v[102:105] offset:3264
	s_waitcnt vmcnt(6) lgkmcnt(0)
	v_lshl_add_u64 v[148:149], v[168:169], 0, v[68:69]
	global_load_dwordx4 v[170:173], v[148:149], off
	ds_write_b128 v92, v[156:159] offset:4352
	s_waitcnt vmcnt(3) lgkmcnt(0)
	ds_write_b128 v92, v[140:143] offset:5440
	s_waitcnt vmcnt(4) lgkmcnt(0)
	ds_write_b128 v92, v[160:163] offset:6528
	s_waitcnt vmcnt(1) lgkmcnt(0)
	ds_write_b128 v92, v[144:147] offset:7616
	s_waitcnt lgkmcnt(0)
	ds_read_u16 v102, v1
	s_waitcnt lgkmcnt(0)
	v_lshlrev_b32_e32 v102, 16, v102
	v_add_f32_e32 v138, v2, v102
	ds_read_u16 v2, v1 offset:272
	s_waitcnt lgkmcnt(0)
	v_lshlrev_b32_e32 v2, 16, v2
	v_add_f32_e32 v137, v3, v2
	ds_read_u16 v2, v1 offset:544
	s_waitcnt lgkmcnt(0)
	v_lshlrev_b32_e32 v2, 16, v2
	v_add_f32_e32 v136, v4, v2
	ds_read_u16 v2, v1 offset:816
	s_waitcnt lgkmcnt(0)
	v_lshlrev_b32_e32 v2, 16, v2
	v_add_f32_e32 v135, v5, v2
	ds_read_u16 v2, v1 offset:2176
	s_waitcnt lgkmcnt(0)
	v_lshlrev_b32_e32 v2, 16, v2
	v_add_f32_e32 v134, v6, v2
	ds_read_u16 v2, v1 offset:2448
	s_waitcnt lgkmcnt(0)
	v_lshlrev_b32_e32 v2, 16, v2
	v_add_f32_e32 v133, v7, v2
	ds_read_u16 v2, v1 offset:2720
	s_waitcnt lgkmcnt(0)
	v_lshlrev_b32_e32 v2, 16, v2
	v_add_f32_e32 v132, v8, v2
	ds_read_u16 v2, v1 offset:2992
	s_waitcnt lgkmcnt(0)
	v_lshlrev_b32_e32 v2, 16, v2
	v_add_f32_e32 v131, v9, v2
	ds_read_u16 v2, v1 offset:4352
	s_waitcnt lgkmcnt(0)
	v_lshlrev_b32_e32 v2, 16, v2
	v_add_f32_e32 v130, v10, v2
	ds_read_u16 v2, v1 offset:4624
	s_waitcnt lgkmcnt(0)
	v_lshlrev_b32_e32 v2, 16, v2
	v_add_f32_e32 v129, v11, v2
	ds_read_u16 v2, v1 offset:4896
	s_waitcnt lgkmcnt(0)
	v_lshlrev_b32_e32 v2, 16, v2
	v_add_f32_e32 v128, v12, v2
	ds_read_u16 v2, v1 offset:5168
	s_waitcnt lgkmcnt(0)
	v_lshlrev_b32_e32 v2, 16, v2
	v_add_f32_e32 v127, v13, v2
	ds_read_u16 v2, v1 offset:6528
	s_waitcnt lgkmcnt(0)
	v_lshlrev_b32_e32 v2, 16, v2
	v_add_f32_e32 v126, v14, v2
	ds_read_u16 v2, v1 offset:6800
	s_waitcnt lgkmcnt(0)
	v_lshlrev_b32_e32 v2, 16, v2
	v_add_f32_e32 v125, v15, v2
	ds_read_u16 v2, v1 offset:7072
	s_waitcnt lgkmcnt(0)
	v_lshlrev_b32_e32 v2, 16, v2
	v_add_f32_e32 v124, v16, v2
	ds_read_u16 v2, v1 offset:7344
	s_waitcnt lgkmcnt(0)
	v_lshlrev_b32_e32 v2, 16, v2
	v_add_f32_e32 v123, v17, v2
	ds_read_u16 v2, v1 offset:64
	s_waitcnt lgkmcnt(0)
	v_lshlrev_b32_e32 v2, 16, v2
	v_add_f32_e32 v122, v18, v2
	ds_read_u16 v2, v1 offset:336
	s_waitcnt lgkmcnt(0)
	v_lshlrev_b32_e32 v2, 16, v2
	v_add_f32_e32 v121, v19, v2
	ds_read_u16 v2, v1 offset:608
	s_waitcnt lgkmcnt(0)
	v_lshlrev_b32_e32 v2, 16, v2
	v_add_f32_e32 v120, v20, v2
	ds_read_u16 v2, v1 offset:880
	s_waitcnt lgkmcnt(0)
	v_lshlrev_b32_e32 v2, 16, v2
	v_add_f32_e32 v119, v21, v2
	ds_read_u16 v2, v1 offset:2240
	s_waitcnt lgkmcnt(0)
	v_lshlrev_b32_e32 v2, 16, v2
	v_add_f32_e32 v118, v22, v2
	ds_read_u16 v2, v1 offset:2512
	s_waitcnt lgkmcnt(0)
	v_lshlrev_b32_e32 v2, 16, v2
	v_add_f32_e32 v117, v23, v2
	ds_read_u16 v2, v1 offset:2784
	s_waitcnt lgkmcnt(0)
	v_lshlrev_b32_e32 v2, 16, v2
	v_add_f32_e32 v116, v24, v2
	ds_read_u16 v2, v1 offset:3056
	s_waitcnt lgkmcnt(0)
	v_lshlrev_b32_e32 v2, 16, v2
	v_add_f32_e32 v115, v25, v2
	ds_read_u16 v2, v1 offset:4416
	s_waitcnt lgkmcnt(0)
	v_lshlrev_b32_e32 v2, 16, v2
	v_add_f32_e32 v114, v26, v2
	ds_read_u16 v2, v1 offset:4688
	s_waitcnt lgkmcnt(0)
; #define LAS __attribute__((address_space(3)))
; DI float bf2f(bf16 b) { return __uint_as_float(((unsigned)b) << 16); }
; DI void gla_stage3(const Ctx& c0, int layer, int unit, int cb, LAS unsigned char* lds) {
;     ...
;     for (int vb = 0; vb < 4; ++vb) {
; #pragma unroll
;         for (int rg = 0; rg < 16; ++rg) o[vb][rg] += bf2f(*(const LAS bf16*)(Re + ((rg & 3) + 8 * (rg >> 2)) * G3_PITCH + 64 * vb));
;         asm volatile("" ::: "memory");
;     }
;     float rs[16];
; #pragma unroll
;     for (int rg = 0; rg < 16; ++rg) { float ss = o[0][rg] * o[0][rg] + o[1][rg] * o[1][rg] + o[2][rg] * o[2][rg] + o[3][rg] * o[3][rg];
;         ss += __shfl_xor(ss, 1); ss += __shfl_xor(ss, 2); ss += __shfl_xor(ss, 4); ss += __shfl_xor(ss, 8); ss += __shfl_xor(ss, 16);
;         rs[rg] = 1.f / sqrtf(ss * (1.f / 128.f) + EPS); }
	v_lshlrev_b32_e32 v2, 16, v2
	v_add_f32_e32 v113, v27, v2
	ds_read_u16 v2, v1 offset:4960
	s_waitcnt lgkmcnt(0)
	v_lshlrev_b32_e32 v2, 16, v2
	v_add_f32_e32 v112, v28, v2
	ds_read_u16 v2, v1 offset:5232
	s_waitcnt lgkmcnt(0)
	v_lshlrev_b32_e32 v2, 16, v2
	v_add_f32_e32 v111, v29, v2
	ds_read_u16 v2, v1 offset:6592
	s_waitcnt lgkmcnt(0)
	v_lshlrev_b32_e32 v2, 16, v2
	v_add_f32_e32 v110, v30, v2
	ds_read_u16 v2, v1 offset:6864
	s_waitcnt lgkmcnt(0)
	v_lshlrev_b32_e32 v2, 16, v2
	v_add_f32_e32 v109, v31, v2
	ds_read_u16 v2, v1 offset:7136
	s_waitcnt lgkmcnt(0)
	v_lshlrev_b32_e32 v2, 16, v2
	v_add_f32_e32 v108, v32, v2
	ds_read_u16 v2, v1 offset:7408
	s_waitcnt lgkmcnt(0)
	v_lshlrev_b32_e32 v2, 16, v2
	v_add_f32_e32 v107, v33, v2
	ds_read_u16 v2, v1 offset:128
	s_waitcnt lgkmcnt(0)
	v_lshlrev_b32_e32 v2, 16, v2
	v_add_f32_e32 v106, v34, v2
	ds_read_u16 v2, v1 offset:400
	s_waitcnt lgkmcnt(0)
	v_lshlrev_b32_e32 v2, 16, v2
	v_add_f32_e32 v105, v35, v2
	ds_read_u16 v2, v1 offset:672
	s_waitcnt lgkmcnt(0)
	v_lshlrev_b32_e32 v2, 16, v2
	v_add_f32_e32 v104, v36, v2
	ds_read_u16 v2, v1 offset:944
	s_waitcnt lgkmcnt(0)
	v_lshlrev_b32_e32 v2, 16, v2
	v_add_f32_e32 v103, v37, v2
	ds_read_u16 v2, v1 offset:2304
	s_waitcnt lgkmcnt(0)
	v_lshlrev_b32_e32 v2, 16, v2
	v_add_f32_e32 v102, v38, v2
	ds_read_u16 v2, v1 offset:2576
	s_waitcnt lgkmcnt(0)
	v_lshlrev_b32_e32 v2, 16, v2
	v_add_f32_e32 v39, v39, v2
	ds_read_u16 v2, v1 offset:2848
	s_waitcnt lgkmcnt(0)
	v_lshlrev_b32_e32 v2, 16, v2
	v_add_f32_e32 v38, v40, v2
	ds_read_u16 v2, v1 offset:3120
	s_waitcnt lgkmcnt(0)
	v_lshlrev_b32_e32 v2, 16, v2
	v_add_f32_e32 v37, v41, v2
	ds_read_u16 v2, v1 offset:4480
	s_waitcnt lgkmcnt(0)
	v_lshlrev_b32_e32 v2, 16, v2
	v_add_f32_e32 v36, v42, v2
	ds_read_u16 v2, v1 offset:4752
	s_waitcnt lgkmcnt(0)
	v_lshlrev_b32_e32 v2, 16, v2
	v_add_f32_e32 v34, v43, v2
	ds_read_u16 v2, v1 offset:5024
	s_waitcnt lgkmcnt(0)
	v_lshlrev_b32_e32 v2, 16, v2
	v_add_f32_e32 v33, v44, v2
	ds_read_u16 v2, v1 offset:5296
	s_waitcnt lgkmcnt(0)
	v_lshlrev_b32_e32 v2, 16, v2
	v_add_f32_e32 v32, v45, v2
	ds_read_u16 v2, v1 offset:6656
	s_waitcnt lgkmcnt(0)
	v_lshlrev_b32_e32 v2, 16, v2
	v_add_f32_e32 v30, v46, v2
	ds_read_u16 v2, v1 offset:6928
	s_waitcnt lgkmcnt(0)
	v_lshlrev_b32_e32 v2, 16, v2
	v_add_f32_e32 v29, v47, v2
	ds_read_u16 v2, v1 offset:7200
	s_waitcnt lgkmcnt(0)
	v_lshlrev_b32_e32 v2, 16, v2
	v_add_f32_e32 v28, v48, v2
	ds_read_u16 v2, v1 offset:7472
	s_waitcnt lgkmcnt(0)
	v_lshlrev_b32_e32 v2, 16, v2
	v_add_f32_e32 v26, v49, v2
	ds_read_u16 v2, v1 offset:192
	s_waitcnt lgkmcnt(0)
	v_lshlrev_b32_e32 v2, 16, v2
	v_add_f32_e32 v19, v50, v2
	ds_read_u16 v2, v1 offset:464
	s_waitcnt lgkmcnt(0)
	v_lshlrev_b32_e32 v2, 16, v2
	v_add_f32_e32 v18, v51, v2
	ds_read_u16 v2, v1 offset:736
	s_waitcnt lgkmcnt(0)
	v_lshlrev_b32_e32 v2, 16, v2
	v_add_f32_e32 v17, v52, v2
	ds_read_u16 v2, v1 offset:1008
	s_waitcnt lgkmcnt(0)
	v_lshlrev_b32_e32 v2, 16, v2
	v_add_f32_e32 v16, v53, v2
	ds_read_u16 v2, v1 offset:2368
	s_waitcnt lgkmcnt(0)
	v_lshlrev_b32_e32 v2, 16, v2
	v_add_f32_e32 v15, v54, v2
	ds_read_u16 v2, v1 offset:2640
	s_waitcnt lgkmcnt(0)
	v_lshlrev_b32_e32 v2, 16, v2
	v_add_f32_e32 v14, v55, v2
	ds_read_u16 v2, v1 offset:2912
	s_waitcnt lgkmcnt(0)
	v_lshlrev_b32_e32 v2, 16, v2
	v_add_f32_e32 v13, v56, v2
	ds_read_u16 v2, v1 offset:3184
	s_waitcnt lgkmcnt(0)
	v_lshlrev_b32_e32 v2, 16, v2
	v_add_f32_e32 v12, v57, v2
	ds_read_u16 v2, v1 offset:4544
	s_waitcnt lgkmcnt(0)
	v_lshlrev_b32_e32 v2, 16, v2
	v_add_f32_e32 v11, v58, v2
	ds_read_u16 v2, v1 offset:4816
	s_waitcnt lgkmcnt(0)
	v_lshlrev_b32_e32 v2, 16, v2
	v_add_f32_e32 v10, v59, v2
	ds_read_u16 v2, v1 offset:5088
	s_waitcnt lgkmcnt(0)
	v_lshlrev_b32_e32 v2, 16, v2
	v_add_f32_e32 v9, v60, v2
	ds_read_u16 v2, v1 offset:5360
	s_waitcnt lgkmcnt(0)
	v_lshlrev_b32_e32 v2, 16, v2
	v_add_f32_e32 v8, v61, v2
	ds_read_u16 v2, v1 offset:6720
	s_waitcnt lgkmcnt(0)
	v_lshlrev_b32_e32 v2, 16, v2
	v_add_f32_e32 v7, v62, v2
	ds_read_u16 v2, v1 offset:6992
	s_waitcnt lgkmcnt(0)
	v_lshlrev_b32_e32 v2, 16, v2
	v_add_f32_e32 v6, v63, v2
	ds_read_u16 v2, v1 offset:7264
	s_waitcnt lgkmcnt(0)
	v_lshlrev_b32_e32 v2, 16, v2
	v_add_f32_e32 v5, v64, v2
	ds_read_u16 v2, v1 offset:7536
	s_waitcnt lgkmcnt(0)
	s_waitcnt lgkmcnt(0)
	v_lshlrev_b32_e32 v2, 16, v2
	v_add_f32_e32 v4, v65, v2
	v_cndmask_b32_e32 v2, v93, v94, vcc
	v_cmp_lt_i32_e32 vcc, v96, v95
	v_lshlrev_b32_e32 v2, 2, v2
	s_nop 0
	v_cndmask_b32_e32 v3, v93, v96, vcc
	v_cmp_lt_i32_e32 vcc, v97, v95
	v_lshlrev_b32_e32 v3, 2, v3
	s_nop 0
	v_cndmask_b32_e32 v20, v93, v97, vcc
	v_cmp_lt_i32_e32 vcc, v98, v95
	v_lshlrev_b32_e32 v20, 2, v20
	s_nop 0
	v_cndmask_b32_e32 v21, v93, v98, vcc
	v_cmp_lt_i32_e32 vcc, v99, v95
	v_lshlrev_b32_e32 v47, 2, v21
	s_nop 0
	v_cndmask_b32_e32 v21, v93, v99, vcc
	v_lshlrev_b32_e32 v48, 2, v21
	v_mul_f32_e32 v21, v122, v122
	v_fmac_f32_e32 v21, v138, v138
	v_fmac_f32_e32 v21, v106, v106
	v_fmac_f32_e32 v21, v19, v19
	ds_bpermute_b32 v22, v2, v21
	s_waitcnt lgkmcnt(0)
	v_add_f32_e32 v21, v21, v22
	ds_bpermute_b32 v22, v3, v21
	s_waitcnt lgkmcnt(0)
	v_add_f32_e32 v21, v21, v22
	ds_bpermute_b32 v22, v20, v21
	s_waitcnt lgkmcnt(0)
	v_add_f32_e32 v21, v21, v22
	ds_bpermute_b32 v22, v47, v21
	s_waitcnt lgkmcnt(0)
	v_add_f32_e32 v21, v21, v22
	ds_bpermute_b32 v22, v48, v21
	s_waitcnt lgkmcnt(0)
; DI void gla_stage3(const Ctx& c0, int layer, int unit, int cb, LAS unsigned char* lds) {
;     ...
;     float rs[16];
; #pragma unroll
;     for (int rg = 0; rg < 16; ++rg) { float ss = o[0][rg] * o[0][rg] + o[1][rg] * o[1][rg] + o[2][rg] * o[2][rg] + o[3][rg] * o[3][rg];
;         ss += __shfl_xor(ss, 1); ss += __shfl_xor(ss, 2); ss += __shfl_xor(ss, 4); ss += __shfl_xor(ss, 8); ss += __shfl_xor(ss, 16);
;         rs[rg] = 1.f / sqrtf(ss * (1.f / 128.f) + EPS); }
	v_add_f32_e32 v21, v21, v22
	v_fmamk_f32 v21, v21, 0x3c000000, v100
	v_cmp_gt_f32_e32 vcc, s33, v21
	v_mul_f32_e32 v22, 0x4f800000, v21
	s_nop 0
	v_cndmask_b32_e32 v21, v21, v22, vcc
	v_sqrt_f32_e32 v22, v21
	s_nop 0
	v_add_u32_e32 v23, -1, v22
	v_fma_f32 v24, -v23, v22, v21
	v_cmp_ge_f32_e64 s[8:9], 0, v24
	v_add_u32_e32 v24, 1, v22
	s_nop 0
	v_cndmask_b32_e64 v23, v22, v23, s[8:9]
	v_fma_f32 v22, -v24, v22, v21
	v_cmp_lt_f32_e64 s[8:9], 0, v22
	s_nop 1
	v_cndmask_b32_e64 v22, v23, v24, s[8:9]
	v_mul_f32_e32 v23, 0x37800000, v22
	v_cndmask_b32_e32 v22, v22, v23, vcc
	v_cmp_class_f32_e32 vcc, v21, v101
	s_nop 1
	v_cndmask_b32_e32 v21, v22, v21, vcc
	s_nop 0
	v_div_scale_f32 v24, vcc, 1.0, v21, 1.0
	v_rcp_f32_e32 v46, v21
	v_mul_f32_e32 v21, v121, v121
	v_fmac_f32_e32 v21, v137, v137
	v_fmac_f32_e32 v21, v105, v105
	v_fmac_f32_e32 v21, v18, v18
	ds_bpermute_b32 v22, v2, v21
	v_mul_f32_e32 v19, v19, v46
	s_waitcnt lgkmcnt(0)
	v_add_f32_e32 v21, v21, v22
	ds_bpermute_b32 v22, v3, v21
	s_waitcnt lgkmcnt(0)
	v_add_f32_e32 v21, v21, v22
	ds_bpermute_b32 v22, v20, v21
	s_waitcnt lgkmcnt(0)
	v_add_f32_e32 v21, v21, v22
	ds_bpermute_b32 v22, v47, v21
	s_waitcnt lgkmcnt(0)
	v_add_f32_e32 v21, v21, v22
	ds_bpermute_b32 v22, v48, v21
	s_waitcnt lgkmcnt(0)
	v_add_f32_e32 v21, v21, v22
	v_fmamk_f32 v21, v21, 0x3c000000, v100
	v_cmp_gt_f32_e32 vcc, s33, v21
	v_mul_f32_e32 v22, 0x4f800000, v21
	s_nop 0
	v_cndmask_b32_e32 v21, v21, v22, vcc
	v_sqrt_f32_e32 v22, v21
	s_nop 0
	v_add_u32_e32 v23, -1, v22
	v_fma_f32 v24, -v23, v22, v21
	v_cmp_ge_f32_e64 s[8:9], 0, v24
	v_add_u32_e32 v24, 1, v22
	s_nop 0
	v_cndmask_b32_e64 v23, v22, v23, s[8:9]
	v_fma_f32 v22, -v24, v22, v21
	v_cmp_lt_f32_e64 s[8:9], 0, v22
	s_nop 1
	v_cndmask_b32_e64 v22, v23, v24, s[8:9]
	v_mul_f32_e32 v23, 0x37800000, v22
	v_cndmask_b32_e32 v22, v22, v23, vcc
	v_cmp_class_f32_e32 vcc, v21, v101
	s_nop 1
	v_cndmask_b32_e32 v21, v22, v21, vcc
	s_nop 0
	v_div_scale_f32 v24, vcc, 1.0, v21, 1.0
	v_rcp_f32_e32 v45, v21
	v_mul_f32_e32 v21, v120, v120
	v_fmac_f32_e32 v21, v136, v136
	v_fmac_f32_e32 v21, v104, v104
	v_fmac_f32_e32 v21, v17, v17
	ds_bpermute_b32 v22, v2, v21
	v_mul_f32_e32 v18, v18, v45
	s_waitcnt lgkmcnt(0)
	v_add_f32_e32 v21, v21, v22
	ds_bpermute_b32 v22, v3, v21
	s_waitcnt lgkmcnt(0)
	v_add_f32_e32 v21, v21, v22
	ds_bpermute_b32 v22, v20, v21
	s_waitcnt lgkmcnt(0)
	v_add_f32_e32 v21, v21, v22
	ds_bpermute_b32 v22, v47, v21
	s_waitcnt lgkmcnt(0)
	v_add_f32_e32 v21, v21, v22
	ds_bpermute_b32 v22, v48, v21
	s_waitcnt lgkmcnt(0)
	v_add_f32_e32 v21, v21, v22
	v_fmamk_f32 v21, v21, 0x3c000000, v100
	v_cmp_gt_f32_e32 vcc, s33, v21
	v_mul_f32_e32 v22, 0x4f800000, v21
	s_nop 0
	v_cndmask_b32_e32 v21, v21, v22, vcc
	v_sqrt_f32_e32 v22, v21
	s_nop 0
	v_add_u32_e32 v23, -1, v22
	v_fma_f32 v24, -v23, v22, v21
	v_cmp_ge_f32_e64 s[8:9], 0, v24
	v_add_u32_e32 v24, 1, v22
	s_nop 0
	v_cndmask_b32_e64 v23, v22, v23, s[8:9]
	v_fma_f32 v22, -v24, v22, v21
	v_cmp_lt_f32_e64 s[8:9], 0, v22
	s_nop 1
	v_cndmask_b32_e64 v22, v23, v24, s[8:9]
	v_mul_f32_e32 v23, 0x37800000, v22
	v_cndmask_b32_e32 v22, v22, v23, vcc
	v_cmp_class_f32_e32 vcc, v21, v101
	s_nop 1
	v_cndmask_b32_e32 v21, v22, v21, vcc
	s_nop 0
	v_div_scale_f32 v24, vcc, 1.0, v21, 1.0
	v_rcp_f32_e32 v44, v21
	v_mul_f32_e32 v21, v119, v119
	v_fmac_f32_e32 v21, v135, v135
	v_fmac_f32_e32 v21, v103, v103
	v_fmac_f32_e32 v21, v16, v16
	ds_bpermute_b32 v22, v2, v21
	v_mul_f32_e32 v17, v17, v44
	s_waitcnt lgkmcnt(0)
	v_add_f32_e32 v21, v21, v22
	ds_bpermute_b32 v22, v3, v21
	s_waitcnt lgkmcnt(0)
	v_add_f32_e32 v21, v21, v22
	ds_bpermute_b32 v22, v20, v21
	s_waitcnt lgkmcnt(0)
	v_add_f32_e32 v21, v21, v22
	ds_bpermute_b32 v22, v47, v21
	s_waitcnt lgkmcnt(0)
	v_add_f32_e32 v21, v21, v22
	ds_bpermute_b32 v22, v48, v21
	s_waitcnt lgkmcnt(0)
	v_add_f32_e32 v21, v21, v22
	v_fmamk_f32 v21, v21, 0x3c000000, v100
	v_cmp_gt_f32_e32 vcc, s33, v21
	v_mul_f32_e32 v22, 0x4f800000, v21
	s_nop 0
	v_cndmask_b32_e32 v21, v21, v22, vcc
	v_sqrt_f32_e32 v22, v21
	s_nop 0
	v_add_u32_e32 v23, -1, v22
	v_fma_f32 v24, -v23, v22, v21
	v_cmp_ge_f32_e64 s[8:9], 0, v24
	v_add_u32_e32 v24, 1, v22
	s_nop 0
	v_cndmask_b32_e64 v23, v22, v23, s[8:9]
	v_fma_f32 v22, -v24, v22, v21
	v_cmp_lt_f32_e64 s[8:9], 0, v22
	s_nop 1
	v_cndmask_b32_e64 v22, v23, v24, s[8:9]
	v_mul_f32_e32 v23, 0x37800000, v22
	v_cndmask_b32_e32 v22, v22, v23, vcc
	v_cmp_class_f32_e32 vcc, v21, v101
	s_nop 1
	v_cndmask_b32_e32 v21, v22, v21, vcc
	s_nop 0
	v_div_scale_f32 v24, vcc, 1.0, v21, 1.0
	v_rcp_f32_e32 v43, v21
	v_mul_f32_e32 v21, v118, v118
	v_fmac_f32_e32 v21, v134, v134
	v_fmac_f32_e32 v21, v102, v102
	v_fmac_f32_e32 v21, v15, v15
	ds_bpermute_b32 v22, v2, v21
	v_mul_f32_e32 v16, v16, v43
	s_waitcnt lgkmcnt(0)
	v_add_f32_e32 v21, v21, v22
	ds_bpermute_b32 v22, v3, v21
	s_waitcnt lgkmcnt(0)
	v_add_f32_e32 v21, v21, v22
	ds_bpermute_b32 v22, v20, v21
	s_waitcnt lgkmcnt(0)
	v_add_f32_e32 v21, v21, v22
	ds_bpermute_b32 v22, v47, v21
	s_waitcnt lgkmcnt(0)
	v_add_f32_e32 v21, v21, v22
	ds_bpermute_b32 v22, v48, v21
	s_waitcnt lgkmcnt(0)
	v_add_f32_e32 v21, v21, v22
	v_fmamk_f32 v21, v21, 0x3c000000, v100
	v_cmp_gt_f32_e32 vcc, s33, v21
	v_mul_f32_e32 v22, 0x4f800000, v21
	s_nop 0
	v_cndmask_b32_e32 v21, v21, v22, vcc
	v_sqrt_f32_e32 v22, v21
	s_nop 0
	v_add_u32_e32 v23, -1, v22
	v_fma_f32 v24, -v23, v22, v21
	v_cmp_ge_f32_e64 s[8:9], 0, v24
	v_add_u32_e32 v24, 1, v22
	s_nop 0
	v_cndmask_b32_e64 v23, v22, v23, s[8:9]
	v_fma_f32 v22, -v24, v22, v21
	v_cmp_lt_f32_e64 s[8:9], 0, v22
	s_nop 1
	v_cndmask_b32_e64 v22, v23, v24, s[8:9]
	v_mul_f32_e32 v23, 0x37800000, v22
	v_cndmask_b32_e32 v22, v22, v23, vcc
	v_cmp_class_f32_e32 vcc, v21, v101
	s_nop 1
	v_cndmask_b32_e32 v21, v22, v21, vcc
	s_nop 0
	v_div_scale_f32 v24, vcc, 1.0, v21, 1.0
	v_rcp_f32_e32 v42, v21
	v_mul_f32_e32 v21, v117, v117
	v_fmac_f32_e32 v21, v133, v133
	v_fmac_f32_e32 v21, v39, v39
	v_fmac_f32_e32 v21, v14, v14
	ds_bpermute_b32 v22, v2, v21
	v_mul_f32_e32 v15, v15, v42
	s_waitcnt lgkmcnt(0)
; DI void gla_stage3(const Ctx& c0, int layer, int unit, int cb, LAS unsigned char* lds) {
;     ...
;     float rs[16];
; #pragma unroll
;     for (int rg = 0; rg < 16; ++rg) { float ss = o[0][rg] * o[0][rg] + o[1][rg] * o[1][rg] + o[2][rg] * o[2][rg] + o[3][rg] * o[3][rg];
;         ss += __shfl_xor(ss, 1); ss += __shfl_xor(ss, 2); ss += __shfl_xor(ss, 4); ss += __shfl_xor(ss, 8); ss += __shfl_xor(ss, 16);
;         rs[rg] = 1.f / sqrtf(ss * (1.f / 128.f) + EPS); }
	v_add_f32_e32 v21, v21, v22
	ds_bpermute_b32 v22, v3, v21
	s_waitcnt lgkmcnt(0)
	v_add_f32_e32 v21, v21, v22
	ds_bpermute_b32 v22, v20, v21
	s_waitcnt lgkmcnt(0)
	v_add_f32_e32 v21, v21, v22
	ds_bpermute_b32 v22, v47, v21
	s_waitcnt lgkmcnt(0)
	v_add_f32_e32 v21, v21, v22
	ds_bpermute_b32 v22, v48, v21
	s_waitcnt lgkmcnt(0)
	v_add_f32_e32 v21, v21, v22
	v_fmamk_f32 v21, v21, 0x3c000000, v100
	v_cmp_gt_f32_e32 vcc, s33, v21
	v_mul_f32_e32 v22, 0x4f800000, v21
	s_nop 0
	v_cndmask_b32_e32 v21, v21, v22, vcc
	v_sqrt_f32_e32 v22, v21
	s_nop 0
	v_add_u32_e32 v23, -1, v22
	v_fma_f32 v24, -v23, v22, v21
	v_cmp_ge_f32_e64 s[8:9], 0, v24
	v_add_u32_e32 v24, 1, v22
	s_nop 0
	v_cndmask_b32_e64 v23, v22, v23, s[8:9]
	v_fma_f32 v22, -v24, v22, v21
	v_cmp_lt_f32_e64 s[8:9], 0, v22
	s_nop 1
	v_cndmask_b32_e64 v22, v23, v24, s[8:9]
	v_mul_f32_e32 v23, 0x37800000, v22
	v_cndmask_b32_e32 v22, v22, v23, vcc
	v_cmp_class_f32_e32 vcc, v21, v101
	s_nop 1
	v_cndmask_b32_e32 v21, v22, v21, vcc
	s_nop 0
	v_div_scale_f32 v24, vcc, 1.0, v21, 1.0
	v_rcp_f32_e32 v41, v21
	v_mul_f32_e32 v21, v116, v116
	v_fmac_f32_e32 v21, v132, v132
	v_fmac_f32_e32 v21, v38, v38
	v_fmac_f32_e32 v21, v13, v13
	ds_bpermute_b32 v22, v2, v21
	v_mul_f32_e32 v39, v39, v41
	v_mul_f32_e32 v14, v14, v41
	s_waitcnt lgkmcnt(0)
	v_add_f32_e32 v21, v21, v22
	ds_bpermute_b32 v22, v3, v21
	s_waitcnt lgkmcnt(0)
	v_add_f32_e32 v21, v21, v22
	ds_bpermute_b32 v22, v20, v21
	s_waitcnt lgkmcnt(0)
	v_add_f32_e32 v21, v21, v22
	ds_bpermute_b32 v22, v47, v21
	s_waitcnt lgkmcnt(0)
	v_add_f32_e32 v21, v21, v22
	ds_bpermute_b32 v22, v48, v21
	s_waitcnt lgkmcnt(0)
	v_add_f32_e32 v21, v21, v22
	v_fmamk_f32 v21, v21, 0x3c000000, v100
	v_cmp_gt_f32_e32 vcc, s33, v21
	v_mul_f32_e32 v22, 0x4f800000, v21
	s_nop 0
	v_cndmask_b32_e32 v21, v21, v22, vcc
	v_sqrt_f32_e32 v22, v21
	s_nop 0
	v_add_u32_e32 v23, -1, v22
	v_fma_f32 v24, -v23, v22, v21
	v_cmp_ge_f32_e64 s[8:9], 0, v24
	v_add_u32_e32 v24, 1, v22
	s_nop 0
	v_cndmask_b32_e64 v23, v22, v23, s[8:9]
	v_fma_f32 v22, -v24, v22, v21
	v_cmp_lt_f32_e64 s[8:9], 0, v22
	s_nop 1
	v_cndmask_b32_e64 v22, v23, v24, s[8:9]
	v_mul_f32_e32 v23, 0x37800000, v22
	v_cndmask_b32_e32 v22, v22, v23, vcc
	v_cmp_class_f32_e32 vcc, v21, v101
	s_nop 1
	v_cndmask_b32_e32 v21, v22, v21, vcc
	s_nop 0
	v_div_scale_f32 v24, vcc, 1.0, v21, 1.0
	v_rcp_f32_e32 v40, v21
	v_mul_f32_e32 v21, v115, v115
	v_fmac_f32_e32 v21, v131, v131
	v_fmac_f32_e32 v21, v37, v37
	v_fmac_f32_e32 v21, v12, v12
	ds_bpermute_b32 v22, v2, v21
	v_mul_f32_e32 v38, v38, v40
	v_mul_f32_e32 v13, v13, v40
	s_waitcnt lgkmcnt(0)
	v_add_f32_e32 v21, v21, v22
	ds_bpermute_b32 v22, v3, v21
	s_waitcnt lgkmcnt(0)
	v_add_f32_e32 v21, v21, v22
	ds_bpermute_b32 v22, v20, v21
	s_waitcnt lgkmcnt(0)
	v_add_f32_e32 v21, v21, v22
	ds_bpermute_b32 v22, v47, v21
	s_waitcnt lgkmcnt(0)
	v_add_f32_e32 v21, v21, v22
	ds_bpermute_b32 v22, v48, v21
	s_waitcnt lgkmcnt(0)
	v_add_f32_e32 v21, v21, v22
	v_fmamk_f32 v21, v21, 0x3c000000, v100
	v_cmp_gt_f32_e32 vcc, s33, v21
	v_mul_f32_e32 v22, 0x4f800000, v21
	s_nop 0
	v_cndmask_b32_e32 v21, v21, v22, vcc
	v_sqrt_f32_e32 v22, v21
	s_nop 0
	v_add_u32_e32 v23, -1, v22
	v_fma_f32 v24, -v23, v22, v21
	v_cmp_ge_f32_e64 s[8:9], 0, v24
	v_add_u32_e32 v24, 1, v22
	s_nop 0
	v_cndmask_b32_e64 v23, v22, v23, s[8:9]
	v_fma_f32 v22, -v24, v22, v21
	v_cmp_lt_f32_e64 s[8:9], 0, v22
	s_nop 1
	v_cndmask_b32_e64 v22, v23, v24, s[8:9]
	v_mul_f32_e32 v23, 0x37800000, v22
	v_cndmask_b32_e32 v22, v22, v23, vcc
	v_cmp_class_f32_e32 vcc, v21, v101
	s_nop 1
	v_cndmask_b32_e32 v21, v22, v21, vcc
	s_nop 0
	v_div_scale_f32 v24, vcc, 1.0, v21, 1.0
	v_rcp_f32_e32 v35, v21
	v_mul_f32_e32 v21, v114, v114
	v_fmac_f32_e32 v21, v130, v130
	v_fmac_f32_e32 v21, v36, v36
	v_fmac_f32_e32 v21, v11, v11
	ds_bpermute_b32 v22, v2, v21
	v_mul_f32_e32 v37, v37, v35
	v_mul_f32_e32 v12, v12, v35
	s_waitcnt lgkmcnt(0)
	v_add_f32_e32 v21, v21, v22
	ds_bpermute_b32 v22, v3, v21
	s_waitcnt lgkmcnt(0)
	v_add_f32_e32 v21, v21, v22
	ds_bpermute_b32 v22, v20, v21
	s_waitcnt lgkmcnt(0)
	v_add_f32_e32 v21, v21, v22
	ds_bpermute_b32 v22, v47, v21
	s_waitcnt lgkmcnt(0)
	v_add_f32_e32 v21, v21, v22
	ds_bpermute_b32 v22, v48, v21
	s_waitcnt lgkmcnt(0)
	v_add_f32_e32 v21, v21, v22
	v_fmamk_f32 v21, v21, 0x3c000000, v100
	v_cmp_gt_f32_e32 vcc, s33, v21
	v_mul_f32_e32 v22, 0x4f800000, v21
	s_nop 0
	v_cndmask_b32_e32 v21, v21, v22, vcc
	v_sqrt_f32_e32 v22, v21
	s_nop 0
	v_add_u32_e32 v23, -1, v22
	v_fma_f32 v24, -v23, v22, v21
	v_cmp_ge_f32_e64 s[8:9], 0, v24
	v_add_u32_e32 v24, 1, v22
	s_nop 0
	v_cndmask_b32_e64 v23, v22, v23, s[8:9]
	v_fma_f32 v22, -v24, v22, v21
	v_cmp_lt_f32_e64 s[8:9], 0, v22
	s_nop 1
	v_cndmask_b32_e64 v22, v23, v24, s[8:9]
	v_mul_f32_e32 v23, 0x37800000, v22
	v_cndmask_b32_e32 v22, v22, v23, vcc
	v_cmp_class_f32_e32 vcc, v21, v101
	s_nop 1
	v_cndmask_b32_e32 v21, v22, v21, vcc
	s_nop 0
	v_div_scale_f32 v24, vcc, 1.0, v21, 1.0
	v_rcp_f32_e32 v31, v21
	v_mul_f32_e32 v21, v113, v113
	v_fmac_f32_e32 v21, v129, v129
	v_fmac_f32_e32 v21, v34, v34
	v_fmac_f32_e32 v21, v10, v10
	ds_bpermute_b32 v22, v2, v21
	v_mul_f32_e32 v36, v36, v31
	v_mul_f32_e32 v11, v11, v31
	s_waitcnt lgkmcnt(0)
	v_add_f32_e32 v21, v21, v22
	ds_bpermute_b32 v22, v3, v21
	s_waitcnt lgkmcnt(0)
	v_add_f32_e32 v21, v21, v22
	ds_bpermute_b32 v22, v20, v21
	s_waitcnt lgkmcnt(0)
	v_add_f32_e32 v21, v21, v22
	ds_bpermute_b32 v22, v47, v21
	s_waitcnt lgkmcnt(0)
	v_add_f32_e32 v21, v21, v22
	ds_bpermute_b32 v22, v48, v21
	s_waitcnt lgkmcnt(0)
; DI void gla_stage3(const Ctx& c0, int layer, int unit, int cb, LAS unsigned char* lds) {
;     ...
;     float rs[16];
; #pragma unroll
;     for (int rg = 0; rg < 16; ++rg) { float ss = o[0][rg] * o[0][rg] + o[1][rg] * o[1][rg] + o[2][rg] * o[2][rg] + o[3][rg] * o[3][rg];
;         ss += __shfl_xor(ss, 1); ss += __shfl_xor(ss, 2); ss += __shfl_xor(ss, 4); ss += __shfl_xor(ss, 8); ss += __shfl_xor(ss, 16);
;         rs[rg] = 1.f / sqrtf(ss * (1.f / 128.f) + EPS); }
	v_add_f32_e32 v21, v21, v22
	v_fmamk_f32 v21, v21, 0x3c000000, v100
	v_cmp_gt_f32_e32 vcc, s33, v21
	v_mul_f32_e32 v22, 0x4f800000, v21
	s_nop 0
	v_cndmask_b32_e32 v21, v21, v22, vcc
	v_sqrt_f32_e32 v22, v21
	s_nop 0
	v_add_u32_e32 v23, -1, v22
	v_fma_f32 v24, -v23, v22, v21
	v_cmp_ge_f32_e64 s[8:9], 0, v24
	v_add_u32_e32 v24, 1, v22
	s_nop 0
	v_cndmask_b32_e64 v23, v22, v23, s[8:9]
	v_fma_f32 v22, -v24, v22, v21
	v_cmp_lt_f32_e64 s[8:9], 0, v22
	s_nop 1
	v_cndmask_b32_e64 v22, v23, v24, s[8:9]
	v_mul_f32_e32 v23, 0x37800000, v22
	v_cndmask_b32_e32 v22, v22, v23, vcc
	v_cmp_class_f32_e32 vcc, v21, v101
	s_nop 1
	v_cndmask_b32_e32 v21, v22, v21, vcc
	s_nop 0
	v_div_scale_f32 v24, vcc, 1.0, v21, 1.0
	v_rcp_f32_e32 v27, v21
	v_mul_f32_e32 v21, v112, v112
	v_fmac_f32_e32 v21, v128, v128
	v_fmac_f32_e32 v21, v33, v33
	v_fmac_f32_e32 v21, v9, v9
	ds_bpermute_b32 v22, v2, v21
	v_mul_f32_e32 v34, v34, v27
	v_mul_f32_e32 v10, v10, v27
	s_waitcnt lgkmcnt(0)
	v_add_f32_e32 v21, v21, v22
	ds_bpermute_b32 v22, v3, v21
	s_waitcnt lgkmcnt(0)
	v_add_f32_e32 v21, v21, v22
	ds_bpermute_b32 v22, v20, v21
	s_waitcnt lgkmcnt(0)
	v_add_f32_e32 v21, v21, v22
	ds_bpermute_b32 v22, v47, v21
	s_waitcnt lgkmcnt(0)
	v_add_f32_e32 v21, v21, v22
	ds_bpermute_b32 v22, v48, v21
	s_waitcnt lgkmcnt(0)
	v_add_f32_e32 v21, v21, v22
	v_fmamk_f32 v21, v21, 0x3c000000, v100
	v_cmp_gt_f32_e32 vcc, s33, v21
	v_mul_f32_e32 v22, 0x4f800000, v21
	s_nop 0
	v_cndmask_b32_e32 v21, v21, v22, vcc
	v_sqrt_f32_e32 v22, v21
	s_nop 0
	v_add_u32_e32 v23, -1, v22
	v_fma_f32 v24, -v23, v22, v21
	v_cmp_ge_f32_e64 s[8:9], 0, v24
	v_add_u32_e32 v24, 1, v22
	s_nop 0
	v_cndmask_b32_e64 v23, v22, v23, s[8:9]
	v_fma_f32 v22, -v24, v22, v21
	v_cmp_lt_f32_e64 s[8:9], 0, v22
	s_nop 1
	v_cndmask_b32_e64 v22, v23, v24, s[8:9]
	v_mul_f32_e32 v23, 0x37800000, v22
	v_cndmask_b32_e32 v22, v22, v23, vcc
	v_cmp_class_f32_e32 vcc, v21, v101
	s_nop 1
	v_cndmask_b32_e32 v21, v22, v21, vcc
	s_nop 0
	v_div_scale_f32 v24, vcc, 1.0, v21, 1.0
	v_rcp_f32_e32 v25, v21
	v_mul_f32_e32 v21, v111, v111
	v_fmac_f32_e32 v21, v127, v127
	v_fmac_f32_e32 v21, v32, v32
	v_fmac_f32_e32 v21, v8, v8
	ds_bpermute_b32 v22, v2, v21
	v_mul_f32_e32 v33, v33, v25
	v_mul_f32_e32 v9, v9, v25
	s_waitcnt lgkmcnt(0)
	v_add_f32_e32 v21, v21, v22
	ds_bpermute_b32 v22, v3, v21
	s_waitcnt lgkmcnt(0)
	v_add_f32_e32 v21, v21, v22
	ds_bpermute_b32 v22, v20, v21
	s_waitcnt lgkmcnt(0)
	v_add_f32_e32 v21, v21, v22
	ds_bpermute_b32 v22, v47, v21
	s_waitcnt lgkmcnt(0)
	v_add_f32_e32 v21, v21, v22
	ds_bpermute_b32 v22, v48, v21
	s_waitcnt lgkmcnt(0)
	v_add_f32_e32 v21, v21, v22
	v_fmamk_f32 v21, v21, 0x3c000000, v100
	v_cmp_gt_f32_e32 vcc, s33, v21
	v_mul_f32_e32 v22, 0x4f800000, v21
	s_nop 0
	v_cndmask_b32_e32 v21, v21, v22, vcc
	v_sqrt_f32_e32 v22, v21
	s_nop 0
	v_add_u32_e32 v23, -1, v22
	v_fma_f32 v24, -v23, v22, v21
	v_cmp_ge_f32_e64 s[8:9], 0, v24
	v_add_u32_e32 v24, 1, v22
	s_nop 0
	v_cndmask_b32_e64 v23, v22, v23, s[8:9]
	v_fma_f32 v22, -v24, v22, v21
	v_cmp_lt_f32_e64 s[8:9], 0, v22
	s_nop 1
	v_cndmask_b32_e64 v22, v23, v24, s[8:9]
	v_mul_f32_e32 v23, 0x37800000, v22
	v_cndmask_b32_e32 v22, v22, v23, vcc
	v_cmp_class_f32_e32 vcc, v21, v101
	s_nop 1
	v_cndmask_b32_e32 v21, v22, v21, vcc
	s_nop 0
	v_div_scale_f32 v24, vcc, 1.0, v21, 1.0
	v_rcp_f32_e32 v24, v21
	v_mul_f32_e32 v21, v110, v110
	v_fmac_f32_e32 v21, v126, v126
	v_fmac_f32_e32 v21, v30, v30
	v_fmac_f32_e32 v21, v7, v7
	ds_bpermute_b32 v22, v2, v21
	v_mul_f32_e32 v32, v32, v24
	v_mul_f32_e32 v8, v8, v24
	s_waitcnt lgkmcnt(0)
	v_add_f32_e32 v21, v21, v22
	ds_bpermute_b32 v22, v3, v21
	s_waitcnt lgkmcnt(0)
	v_add_f32_e32 v21, v21, v22
	ds_bpermute_b32 v22, v20, v21
	s_waitcnt lgkmcnt(0)
	v_add_f32_e32 v21, v21, v22
	ds_bpermute_b32 v22, v47, v21
	s_waitcnt lgkmcnt(0)
	v_add_f32_e32 v21, v21, v22
	ds_bpermute_b32 v22, v48, v21
	s_waitcnt lgkmcnt(0)
	v_add_f32_e32 v21, v21, v22
	v_fmamk_f32 v21, v21, 0x3c000000, v100
	v_cmp_gt_f32_e32 vcc, s33, v21
	v_mul_f32_e32 v22, 0x4f800000, v21
	s_nop 0
	v_cndmask_b32_e32 v21, v21, v22, vcc
	v_sqrt_f32_e32 v22, v21
	s_nop 0
	v_add_u32_e32 v23, -1, v22
	v_fma_f32 v49, -v23, v22, v21
	v_cmp_ge_f32_e64 s[8:9], 0, v49
	v_add_u32_e32 v49, 1, v22
	s_nop 0
	v_cndmask_b32_e64 v23, v22, v23, s[8:9]
	v_fma_f32 v22, -v49, v22, v21
	v_cmp_lt_f32_e64 s[8:9], 0, v22
	s_nop 1
	v_cndmask_b32_e64 v22, v23, v49, s[8:9]
	v_mul_f32_e32 v23, 0x37800000, v22
	v_cndmask_b32_e32 v22, v22, v23, vcc
	v_cmp_class_f32_e32 vcc, v21, v101
	s_nop 1
	v_cndmask_b32_e32 v21, v22, v21, vcc
	s_nop 0
	v_div_scale_f32 v49, vcc, 1.0, v21, 1.0
	v_rcp_f32_e32 v23, v21
	v_mul_f32_e32 v21, v109, v109
	v_fmac_f32_e32 v21, v125, v125
	v_fmac_f32_e32 v21, v29, v29
	v_fmac_f32_e32 v21, v6, v6
	ds_bpermute_b32 v22, v2, v21
	v_mul_f32_e32 v30, v30, v23
	v_mul_f32_e32 v7, v7, v23
	s_waitcnt lgkmcnt(0)
	v_add_f32_e32 v21, v21, v22
	ds_bpermute_b32 v22, v3, v21
	s_waitcnt lgkmcnt(0)
	v_add_f32_e32 v21, v21, v22
	ds_bpermute_b32 v22, v20, v21
	s_waitcnt lgkmcnt(0)
	v_add_f32_e32 v21, v21, v22
	ds_bpermute_b32 v22, v47, v21
	s_waitcnt lgkmcnt(0)
	v_add_f32_e32 v21, v21, v22
	ds_bpermute_b32 v22, v48, v21
	s_waitcnt lgkmcnt(0)
	v_add_f32_e32 v21, v21, v22
	v_fmamk_f32 v21, v21, 0x3c000000, v100
	v_cmp_gt_f32_e32 vcc, s33, v21
	v_mul_f32_e32 v22, 0x4f800000, v21
	s_nop 0
	v_cndmask_b32_e32 v21, v21, v22, vcc
	v_sqrt_f32_e32 v22, v21
	s_nop 0
	v_add_u32_e32 v49, -1, v22
	v_fma_f32 v50, -v49, v22, v21
	v_cmp_ge_f32_e64 s[8:9], 0, v50
	v_add_u32_e32 v50, 1, v22
	s_nop 0
	v_cndmask_b32_e64 v49, v22, v49, s[8:9]
	v_fma_f32 v22, -v50, v22, v21
	v_cmp_lt_f32_e64 s[8:9], 0, v22
	s_nop 1
	v_cndmask_b32_e64 v22, v49, v50, s[8:9]
	v_mul_f32_e32 v49, 0x37800000, v22
	v_cndmask_b32_e32 v22, v22, v49, vcc
	v_cmp_class_f32_e32 vcc, v21, v101
	s_nop 1
	v_cndmask_b32_e32 v21, v22, v21, vcc
	s_nop 0
	v_div_scale_f32 v50, vcc, 1.0, v21, 1.0
	v_rcp_f32_e32 v22, v21
	v_mul_f32_e32 v21, v108, v108
	v_fmac_f32_e32 v21, v124, v124
	v_fmac_f32_e32 v21, v28, v28
	v_fmac_f32_e32 v21, v5, v5
	ds_bpermute_b32 v49, v2, v21
	v_mul_f32_e32 v29, v29, v22
	v_mul_f32_e32 v6, v6, v22
	s_waitcnt lgkmcnt(0)
; #define LAS __attribute__((address_space(3)))
; #define LDS_WAIT() asm volatile("s_waitcnt lgkmcnt(0)" ::: "memory")
; DI unsigned cvtpk(float lo, float hi) { f32x2 v = {lo, hi}; bf16x2_t b = __builtin_convertvector(v, bf16x2_t); return __builtin_bit_cast(unsigned, b); }
; DI float bf2f(bf16 b) { return __uint_as_float(((unsigned)b) << 16); }
; DI float siluf_(float x) { return x / (1.f + __expf(-x)); }
; DI void gla_stage3(const Ctx& c0, int layer, int unit, int cb, LAS unsigned char* lds) {
;     ...
;     for (int rg = 0; rg < 16; ++rg) { float ss = o[0][rg] * o[0][rg] + o[1][rg] * o[1][rg] + o[2][rg] * o[2][rg] + o[3][rg] * o[3][rg];
;         ss += __shfl_xor(ss, 1); ss += __shfl_xor(ss, 2); ss += __shfl_xor(ss, 4); ss += __shfl_xor(ss, 8); ss += __shfl_xor(ss, 16);
;         rs[rg] = 1.f / sqrtf(ss * (1.f / 128.f) + EPS); }
;     LDS_WAIT();
;     g3_tile_in((const bf16*)(c.ws + O_GR) + row0 * 512 + h * 128, R, lane);
; #pragma unroll
;     for (int vb = 0; vb < 4; ++vb) { const float g = gn[32 * vb + r];
; #pragma unroll
;         for (int rg = 0; rg < 16; ++rg) { LAS bf16* e = (LAS bf16*)(R + (4 * hi) * G3_PITCH + r * 2 + ((rg & 3) + 8 * (rg >> 2)) * G3_PITCH + 64 * vb);
;             const float z = bf2f(*e);
;             *e = (bf16)(cvtpk(o[vb][rg] * rs[rg] * g * siluf_(z), 0.f) & 0xffffu); }
;         asm volatile("" ::: "memory"); }
	v_add_f32_e32 v21, v21, v49
	ds_bpermute_b32 v49, v3, v21
	s_waitcnt lgkmcnt(0)
	v_add_f32_e32 v21, v21, v49
	ds_bpermute_b32 v49, v20, v21
	s_waitcnt lgkmcnt(0)
	v_add_f32_e32 v21, v21, v49
	ds_bpermute_b32 v49, v47, v21
	s_waitcnt lgkmcnt(0)
	v_add_f32_e32 v21, v21, v49
	ds_bpermute_b32 v49, v48, v21
	s_waitcnt lgkmcnt(0)
	v_add_f32_e32 v21, v21, v49
	v_fmamk_f32 v21, v21, 0x3c000000, v100
	v_cmp_gt_f32_e32 vcc, s33, v21
	v_mul_f32_e32 v49, 0x4f800000, v21
	s_nop 0
	v_cndmask_b32_e32 v21, v21, v49, vcc
	v_sqrt_f32_e32 v49, v21
	s_nop 0
	v_add_u32_e32 v50, -1, v49
	v_fma_f32 v51, -v50, v49, v21
	v_cmp_ge_f32_e64 s[8:9], 0, v51
	v_add_u32_e32 v51, 1, v49
	s_nop 0
	v_cndmask_b32_e64 v50, v49, v50, s[8:9]
	v_fma_f32 v49, -v51, v49, v21
	v_cmp_lt_f32_e64 s[8:9], 0, v49
	s_nop 1
	v_cndmask_b32_e64 v49, v50, v51, s[8:9]
	v_mul_f32_e32 v50, 0x37800000, v49
	v_cndmask_b32_e32 v49, v49, v50, vcc
	v_cmp_class_f32_e32 vcc, v21, v101
	s_nop 1
	v_cndmask_b32_e32 v21, v49, v21, vcc
	s_nop 0
	v_div_scale_f32 v51, vcc, 1.0, v21, 1.0
	v_rcp_f32_e32 v21, v21
	v_mul_f32_e32 v49, v107, v107
	v_fmac_f32_e32 v49, v123, v123
	v_fmac_f32_e32 v49, v26, v26
	v_fmac_f32_e32 v49, v4, v4
	ds_bpermute_b32 v2, v2, v49
	v_mul_f32_e32 v28, v28, v21
	v_mul_f32_e32 v5, v5, v21
	s_waitcnt lgkmcnt(0)
	v_add_f32_e32 v2, v49, v2
	ds_bpermute_b32 v3, v3, v2
	s_waitcnt lgkmcnt(0)
	v_add_f32_e32 v2, v2, v3
	ds_bpermute_b32 v3, v20, v2
	s_waitcnt lgkmcnt(0)
	v_add_f32_e32 v2, v2, v3
	ds_bpermute_b32 v3, v47, v2
	s_waitcnt lgkmcnt(0)
	v_add_f32_e32 v2, v2, v3
	ds_bpermute_b32 v3, v48, v2
	s_waitcnt lgkmcnt(0)
	v_add_f32_e32 v2, v2, v3
	v_fmamk_f32 v2, v2, 0x3c000000, v100
	v_cmp_gt_f32_e32 vcc, s33, v2
	v_mul_f32_e32 v3, 0x4f800000, v2
	s_nop 0
	v_cndmask_b32_e32 v2, v2, v3, vcc
	v_sqrt_f32_e32 v3, v2
	s_nop 0
	v_add_u32_e32 v20, -1, v3
	v_fma_f32 v47, -v20, v3, v2
	v_cmp_ge_f32_e64 s[8:9], 0, v47
	v_add_u32_e32 v47, 1, v3
	s_nop 0
	v_cndmask_b32_e64 v20, v3, v20, s[8:9]
	v_fma_f32 v3, -v47, v3, v2
	v_cmp_lt_f32_e64 s[8:9], 0, v3
	s_nop 1
	v_cndmask_b32_e64 v3, v20, v47, s[8:9]
	v_mul_f32_e32 v20, 0x37800000, v3
	v_cndmask_b32_e32 v3, v3, v20, vcc
	v_cmp_class_f32_e32 vcc, v2, v101
	s_nop 1
	v_cndmask_b32_e32 v2, v3, v2, vcc
	s_nop 0
	v_rcp_f32_e32 v20, v2
	v_mul_f32_e32 v47, v138, v46
	v_mul_f32_e32 v26, v26, v20
	v_mul_f32_e32 v4, v4, v20
	s_waitcnt vmcnt(2) lgkmcnt(0)
	ds_write_b128 v92, v[164:167]
	s_waitcnt vmcnt(0) lgkmcnt(0)
	ds_write_b128 v92, v[170:173] offset:1088
	s_waitcnt vmcnt(13) lgkmcnt(0)
	ds_write_b128 v92, v[174:177] offset:2176
	s_waitcnt vmcnt(8) lgkmcnt(0)
	ds_write_b128 v92, v[178:181] offset:3264
	s_waitcnt vmcnt(9) lgkmcnt(0)
	ds_write_b128 v92, v[196:199] offset:4352
	s_waitcnt vmcnt(10) lgkmcnt(0)
	ds_write_b128 v92, v[200:203] offset:5440
	v_lshl_add_u64 v[2:3], v[168:169], 0, v[80:81]
	s_waitcnt vmcnt(5) lgkmcnt(0)
	ds_write_b128 v92, v[204:207] offset:6528
	global_load_dwordx4 v[48:51], v[2:3], off
	s_waitcnt vmcnt(0) lgkmcnt(0)
	ds_write_b128 v92, v[48:51] offset:7616
	s_waitcnt lgkmcnt(0)
	ds_read_u16 v3, v1
	s_waitcnt lgkmcnt(0)
	v_lshlrev_b32_e32 v3, 16, v3
	v_mul_f32_e32 v48, 0xbfb8aa3b, v3
	v_exp_f32_e32 v48, v48
	s_waitcnt vmcnt(0)
	v_mul_f32_e32 v47, v47, v232
	v_add_f32_e32 v48, 1.0, v48
	v_div_scale_f32 v49, s[0:1], v48, v48, v3
	s_nop 0
	v_rcp_f32_e32 v49, v48
	s_nop 0
	v_mul_f32_e32 v3, v3, v49
	v_mul_f32_e32 v3, v47, v3
	v_cvt_pk_bf16_f32 v3, v3, s0
	ds_write_b16 v1, v3
	ds_read_u16 v3, v1 offset:272
	v_mul_f32_e32 v47, v137, v45
	v_mul_f32_e32 v47, v47, v232
	s_waitcnt lgkmcnt(0)
	v_lshlrev_b32_e32 v3, 16, v3
	v_mul_f32_e32 v48, 0xbfb8aa3b, v3
	v_exp_f32_e32 v48, v48
	s_nop 0
	v_add_f32_e32 v48, 1.0, v48
	v_div_scale_f32 v49, s[0:1], v48, v48, v3
	s_nop 0
	v_rcp_f32_e32 v49, v48
	s_nop 0
	v_mul_f32_e32 v3, v3, v49
	v_mul_f32_e32 v3, v47, v3
	v_cvt_pk_bf16_f32 v3, v3, s0
	ds_write_b16 v1, v3 offset:272
	ds_read_u16 v3, v1 offset:544
	v_mul_f32_e32 v47, v136, v44
	v_mul_f32_e32 v47, v47, v232
	s_waitcnt lgkmcnt(0)
	v_lshlrev_b32_e32 v3, 16, v3
	v_mul_f32_e32 v48, 0xbfb8aa3b, v3
	v_exp_f32_e32 v48, v48
	s_nop 0
	v_add_f32_e32 v48, 1.0, v48
	v_div_scale_f32 v49, s[0:1], v48, v48, v3
	s_nop 0
	v_rcp_f32_e32 v49, v48
	s_nop 0
	v_mul_f32_e32 v3, v3, v49
	v_mul_f32_e32 v3, v47, v3
	v_cvt_pk_bf16_f32 v3, v3, s0
	ds_write_b16 v1, v3 offset:544
	ds_read_u16 v3, v1 offset:816
	v_mul_f32_e32 v47, v135, v43
	v_mul_f32_e32 v47, v47, v232
	s_waitcnt lgkmcnt(0)
	v_lshlrev_b32_e32 v3, 16, v3
	v_mul_f32_e32 v48, 0xbfb8aa3b, v3
	v_exp_f32_e32 v48, v48
	s_nop 0
	v_add_f32_e32 v48, 1.0, v48
	v_div_scale_f32 v49, s[0:1], v48, v48, v3
	s_nop 0
	v_rcp_f32_e32 v49, v48
	s_nop 0
	v_mul_f32_e32 v3, v3, v49
	v_mul_f32_e32 v3, v47, v3
	v_cvt_pk_bf16_f32 v3, v3, s0
	ds_write_b16 v1, v3 offset:816
	ds_read_u16 v3, v1 offset:2176
	v_mul_f32_e32 v47, v134, v42
	v_mul_f32_e32 v47, v47, v232
	s_waitcnt lgkmcnt(0)
	v_lshlrev_b32_e32 v3, 16, v3
	v_mul_f32_e32 v48, 0xbfb8aa3b, v3
	v_exp_f32_e32 v48, v48
	s_nop 0
	v_add_f32_e32 v48, 1.0, v48
	v_div_scale_f32 v49, s[0:1], v48, v48, v3
	s_nop 0
	v_rcp_f32_e32 v49, v48
	s_nop 0
	v_mul_f32_e32 v3, v3, v49
	v_mul_f32_e32 v3, v47, v3
	v_cvt_pk_bf16_f32 v3, v3, s0
	ds_write_b16 v1, v3 offset:2176
	ds_read_u16 v3, v1 offset:2448
	v_mul_f32_e32 v47, v133, v41
	v_mul_f32_e32 v47, v47, v232
	s_waitcnt lgkmcnt(0)
	v_lshlrev_b32_e32 v3, 16, v3
	v_mul_f32_e32 v48, 0xbfb8aa3b, v3
	v_exp_f32_e32 v48, v48
	s_nop 0
	v_add_f32_e32 v48, 1.0, v48
	v_div_scale_f32 v49, s[0:1], v48, v48, v3
	s_nop 0
	v_rcp_f32_e32 v49, v48
	s_nop 0
	v_mul_f32_e32 v3, v3, v49
	v_mul_f32_e32 v3, v47, v3
	v_cvt_pk_bf16_f32 v3, v3, s0
	ds_write_b16 v1, v3 offset:2448
	ds_read_u16 v3, v1 offset:2720
	v_mul_f32_e32 v47, v132, v40
	v_mul_f32_e32 v47, v47, v232
	s_waitcnt lgkmcnt(0)
; #define LAS __attribute__((address_space(3)))
; DI unsigned cvtpk(float lo, float hi) { f32x2 v = {lo, hi}; bf16x2_t b = __builtin_convertvector(v, bf16x2_t); return __builtin_bit_cast(unsigned, b); }
; DI float bf2f(bf16 b) { return __uint_as_float(((unsigned)b) << 16); }
; DI float siluf_(float x) { return x / (1.f + __expf(-x)); }
; DI void gla_stage3(const Ctx& c0, int layer, int unit, int cb, LAS unsigned char* lds) {
;     ...
; #pragma unroll
;     for (int vb = 0; vb < 4; ++vb) { const float g = gn[32 * vb + r];
; #pragma unroll
;         for (int rg = 0; rg < 16; ++rg) { LAS bf16* e = (LAS bf16*)(R + (4 * hi) * G3_PITCH + r * 2 + ((rg & 3) + 8 * (rg >> 2)) * G3_PITCH + 64 * vb);
;             const float z = bf2f(*e);
;             *e = (bf16)(cvtpk(o[vb][rg] * rs[rg] * g * siluf_(z), 0.f) & 0xffffu); }
;         asm volatile("" ::: "memory"); }
	v_lshlrev_b32_e32 v3, 16, v3
	v_mul_f32_e32 v48, 0xbfb8aa3b, v3
	v_exp_f32_e32 v48, v48
	s_nop 0
	v_add_f32_e32 v48, 1.0, v48
	v_div_scale_f32 v49, s[0:1], v48, v48, v3
	s_nop 0
	v_rcp_f32_e32 v49, v48
	s_nop 0
	v_mul_f32_e32 v3, v3, v49
	v_mul_f32_e32 v3, v47, v3
	v_cvt_pk_bf16_f32 v3, v3, s0
	ds_write_b16 v1, v3 offset:2720
	ds_read_u16 v3, v1 offset:2992
	v_mul_f32_e32 v47, v131, v35
	v_mul_f32_e32 v47, v47, v232
	s_waitcnt lgkmcnt(0)
	v_lshlrev_b32_e32 v3, 16, v3
	v_mul_f32_e32 v48, 0xbfb8aa3b, v3
	v_exp_f32_e32 v48, v48
	s_nop 0
	v_add_f32_e32 v48, 1.0, v48
	v_div_scale_f32 v49, s[0:1], v48, v48, v3
	s_nop 0
	v_rcp_f32_e32 v49, v48
	s_nop 0
	v_mul_f32_e32 v3, v3, v49
	v_mul_f32_e32 v3, v47, v3
	v_cvt_pk_bf16_f32 v3, v3, s0
	ds_write_b16 v1, v3 offset:2992
	ds_read_u16 v3, v1 offset:4352
	v_mul_f32_e32 v47, v130, v31
	v_mul_f32_e32 v47, v47, v232
	s_waitcnt lgkmcnt(0)
	v_lshlrev_b32_e32 v3, 16, v3
	v_mul_f32_e32 v48, 0xbfb8aa3b, v3
	v_exp_f32_e32 v48, v48
	s_nop 0
	v_add_f32_e32 v48, 1.0, v48
	v_div_scale_f32 v49, s[0:1], v48, v48, v3
	s_nop 0
	v_rcp_f32_e32 v49, v48
	s_nop 0
	v_mul_f32_e32 v3, v3, v49
	v_mul_f32_e32 v3, v47, v3
	v_cvt_pk_bf16_f32 v3, v3, s0
	ds_write_b16 v1, v3 offset:4352
	ds_read_u16 v3, v1 offset:4624
	v_mul_f32_e32 v47, v129, v27
	v_mul_f32_e32 v47, v47, v232
	s_waitcnt lgkmcnt(0)
	v_lshlrev_b32_e32 v3, 16, v3
	v_mul_f32_e32 v48, 0xbfb8aa3b, v3
	v_exp_f32_e32 v48, v48
	s_nop 0
	v_add_f32_e32 v48, 1.0, v48
	v_div_scale_f32 v49, s[0:1], v48, v48, v3
	s_nop 0
	v_rcp_f32_e32 v49, v48
	s_nop 0
	v_mul_f32_e32 v3, v3, v49
	v_mul_f32_e32 v3, v47, v3
	v_cvt_pk_bf16_f32 v3, v3, s0
	ds_write_b16 v1, v3 offset:4624
	ds_read_u16 v3, v1 offset:4896
	v_mul_f32_e32 v47, v128, v25
	v_mul_f32_e32 v47, v47, v232
	s_waitcnt lgkmcnt(0)
	v_lshlrev_b32_e32 v3, 16, v3
	v_mul_f32_e32 v48, 0xbfb8aa3b, v3
	v_exp_f32_e32 v48, v48
	s_nop 0
	v_add_f32_e32 v48, 1.0, v48
	v_div_scale_f32 v49, s[0:1], v48, v48, v3
	s_nop 0
	v_rcp_f32_e32 v49, v48
	s_nop 0
	v_mul_f32_e32 v3, v3, v49
	v_mul_f32_e32 v3, v47, v3
	v_cvt_pk_bf16_f32 v3, v3, s0
	ds_write_b16 v1, v3 offset:4896
	ds_read_u16 v3, v1 offset:5168
	v_mul_f32_e32 v47, v127, v24
	v_mul_f32_e32 v47, v47, v232
	s_waitcnt lgkmcnt(0)
	v_lshlrev_b32_e32 v3, 16, v3
	v_mul_f32_e32 v48, 0xbfb8aa3b, v3
	v_exp_f32_e32 v48, v48
	s_nop 0
	v_add_f32_e32 v48, 1.0, v48
	v_div_scale_f32 v49, s[0:1], v48, v48, v3
	s_nop 0
	v_rcp_f32_e32 v49, v48
	s_nop 0
	v_mul_f32_e32 v3, v3, v49
	v_mul_f32_e32 v3, v47, v3
	v_cvt_pk_bf16_f32 v3, v3, s0
	ds_write_b16 v1, v3 offset:5168
	ds_read_u16 v3, v1 offset:6528
	v_mul_f32_e32 v47, v126, v23
	v_mul_f32_e32 v47, v47, v232
	s_waitcnt lgkmcnt(0)
	v_lshlrev_b32_e32 v3, 16, v3
	v_mul_f32_e32 v48, 0xbfb8aa3b, v3
	v_exp_f32_e32 v48, v48
	s_nop 0
	v_add_f32_e32 v48, 1.0, v48
	v_div_scale_f32 v49, s[0:1], v48, v48, v3
	s_nop 0
	v_rcp_f32_e32 v49, v48
	s_nop 0
	v_mul_f32_e32 v3, v3, v49
	v_mul_f32_e32 v3, v47, v3
	v_cvt_pk_bf16_f32 v3, v3, s0
	ds_write_b16 v1, v3 offset:6528
	ds_read_u16 v3, v1 offset:6800
	v_mul_f32_e32 v47, v125, v22
	v_mul_f32_e32 v47, v47, v232
	s_waitcnt lgkmcnt(0)
	v_lshlrev_b32_e32 v3, 16, v3
	v_mul_f32_e32 v48, 0xbfb8aa3b, v3
	v_exp_f32_e32 v48, v48
	s_nop 0
	v_add_f32_e32 v48, 1.0, v48
	v_div_scale_f32 v49, s[0:1], v48, v48, v3
	s_nop 0
	v_rcp_f32_e32 v49, v48
	s_nop 0
	v_mul_f32_e32 v3, v3, v49
	v_mul_f32_e32 v3, v47, v3
	v_cvt_pk_bf16_f32 v3, v3, s0
	ds_write_b16 v1, v3 offset:6800
	ds_read_u16 v3, v1 offset:7072
	v_mul_f32_e32 v47, v124, v21
	v_mul_f32_e32 v47, v47, v232
	s_waitcnt lgkmcnt(0)
	v_lshlrev_b32_e32 v3, 16, v3
	v_mul_f32_e32 v48, 0xbfb8aa3b, v3
	v_exp_f32_e32 v48, v48
	s_nop 0
	v_add_f32_e32 v48, 1.0, v48
	v_div_scale_f32 v49, s[0:1], v48, v48, v3
	s_nop 0
	v_rcp_f32_e32 v49, v48
	s_nop 0
	v_mul_f32_e32 v3, v3, v49
	v_mul_f32_e32 v3, v47, v3
	v_cvt_pk_bf16_f32 v3, v3, s0
	ds_write_b16 v1, v3 offset:7072
	ds_read_u16 v3, v1 offset:7344
	v_mul_f32_e32 v47, v123, v20
	v_mul_f32_e32 v2, v47, v232
	s_waitcnt lgkmcnt(0)
	v_lshlrev_b32_e32 v3, 16, v3
	v_mul_f32_e32 v47, 0xbfb8aa3b, v3
	v_exp_f32_e32 v47, v47
	s_nop 0
	v_add_f32_e32 v47, 1.0, v47
	v_div_scale_f32 v48, s[0:1], v47, v47, v3
	s_nop 0
	v_rcp_f32_e32 v48, v47
	s_nop 0
	v_mul_f32_e32 v3, v3, v48
	v_mul_f32_e32 v2, v2, v3
	v_cvt_pk_bf16_f32 v2, v2, s0
	ds_write_b16 v1, v2 offset:7344
	ds_read_u16 v3, v1 offset:64
	v_mul_f32_e32 v47, v122, v46
	s_waitcnt lgkmcnt(0)
	v_lshlrev_b32_e32 v3, 16, v3
	v_mul_f32_e32 v48, 0xbfb8aa3b, v3
	v_exp_f32_e32 v48, v48
	s_waitcnt vmcnt(0)
	v_mul_f32_e32 v47, v47, v234
	v_add_f32_e32 v48, 1.0, v48
	v_div_scale_f32 v49, s[0:1], v48, v48, v3
	s_nop 0
	v_rcp_f32_e32 v49, v48
	s_nop 0
	v_mul_f32_e32 v3, v3, v49
	v_mul_f32_e32 v3, v47, v3
	v_cvt_pk_bf16_f32 v3, v3, s0
	ds_write_b16 v1, v3 offset:64
	ds_read_u16 v3, v1 offset:336
	v_mul_f32_e32 v47, v121, v45
	v_mul_f32_e32 v47, v47, v234
	s_waitcnt lgkmcnt(0)
	v_lshlrev_b32_e32 v3, 16, v3
	v_mul_f32_e32 v48, 0xbfb8aa3b, v3
	v_exp_f32_e32 v48, v48
	s_nop 0
	v_add_f32_e32 v48, 1.0, v48
	v_div_scale_f32 v49, s[0:1], v48, v48, v3
	s_nop 0
	v_rcp_f32_e32 v49, v48
	s_nop 0
	v_mul_f32_e32 v3, v3, v49
	v_mul_f32_e32 v3, v47, v3
	v_cvt_pk_bf16_f32 v3, v3, s0
	ds_write_b16 v1, v3 offset:336
	ds_read_u16 v3, v1 offset:608
	v_mul_f32_e32 v47, v120, v44
	v_mul_f32_e32 v47, v47, v234
	s_waitcnt lgkmcnt(0)
	v_lshlrev_b32_e32 v3, 16, v3
	v_mul_f32_e32 v48, 0xbfb8aa3b, v3
	v_exp_f32_e32 v48, v48
	s_nop 0
	v_add_f32_e32 v48, 1.0, v48
	v_div_scale_f32 v49, s[0:1], v48, v48, v3
	s_nop 0
	v_rcp_f32_e32 v49, v48
	s_nop 0
	v_mul_f32_e32 v3, v3, v49
	v_mul_f32_e32 v3, v47, v3
	v_cvt_pk_bf16_f32 v3, v3, s0
	ds_write_b16 v1, v3 offset:608
	ds_read_u16 v3, v1 offset:880
	v_mul_f32_e32 v47, v119, v43
	v_mul_f32_e32 v47, v47, v234
	s_waitcnt lgkmcnt(0)
; #define LAS __attribute__((address_space(3)))
; DI unsigned cvtpk(float lo, float hi) { f32x2 v = {lo, hi}; bf16x2_t b = __builtin_convertvector(v, bf16x2_t); return __builtin_bit_cast(unsigned, b); }
; DI float bf2f(bf16 b) { return __uint_as_float(((unsigned)b) << 16); }
; DI float siluf_(float x) { return x / (1.f + __expf(-x)); }
; DI void gla_stage3(const Ctx& c0, int layer, int unit, int cb, LAS unsigned char* lds) {
;     ...
; #pragma unroll
;     for (int vb = 0; vb < 4; ++vb) { const float g = gn[32 * vb + r];
; #pragma unroll
;         for (int rg = 0; rg < 16; ++rg) { LAS bf16* e = (LAS bf16*)(R + (4 * hi) * G3_PITCH + r * 2 + ((rg & 3) + 8 * (rg >> 2)) * G3_PITCH + 64 * vb);
;             const float z = bf2f(*e);
;             *e = (bf16)(cvtpk(o[vb][rg] * rs[rg] * g * siluf_(z), 0.f) & 0xffffu); }
;         asm volatile("" ::: "memory"); }
	v_lshlrev_b32_e32 v3, 16, v3
	v_mul_f32_e32 v48, 0xbfb8aa3b, v3
	v_exp_f32_e32 v48, v48
	s_nop 0
	v_add_f32_e32 v48, 1.0, v48
	v_div_scale_f32 v49, s[0:1], v48, v48, v3
	s_nop 0
	v_rcp_f32_e32 v49, v48
	s_nop 0
	v_mul_f32_e32 v3, v3, v49
	v_mul_f32_e32 v3, v47, v3
	v_cvt_pk_bf16_f32 v3, v3, s0
	ds_write_b16 v1, v3 offset:880
	ds_read_u16 v3, v1 offset:2240
	v_mul_f32_e32 v47, v118, v42
	v_mul_f32_e32 v47, v47, v234
	s_waitcnt lgkmcnt(0)
	v_lshlrev_b32_e32 v3, 16, v3
	v_mul_f32_e32 v48, 0xbfb8aa3b, v3
	v_exp_f32_e32 v48, v48
	s_nop 0
	v_add_f32_e32 v48, 1.0, v48
	v_div_scale_f32 v49, s[0:1], v48, v48, v3
	s_nop 0
	v_rcp_f32_e32 v49, v48
	s_nop 0
	v_mul_f32_e32 v3, v3, v49
	v_mul_f32_e32 v3, v47, v3
	v_cvt_pk_bf16_f32 v3, v3, s0
	ds_write_b16 v1, v3 offset:2240
	ds_read_u16 v3, v1 offset:2512
	v_mul_f32_e32 v47, v117, v41
	v_mul_f32_e32 v47, v47, v234
	s_waitcnt lgkmcnt(0)
	v_lshlrev_b32_e32 v3, 16, v3
	v_mul_f32_e32 v48, 0xbfb8aa3b, v3
	v_exp_f32_e32 v48, v48
	s_nop 0
	v_add_f32_e32 v48, 1.0, v48
	v_div_scale_f32 v49, s[0:1], v48, v48, v3
	s_nop 0
	v_rcp_f32_e32 v49, v48
	s_nop 0
	v_mul_f32_e32 v3, v3, v49
	v_mul_f32_e32 v3, v47, v3
	v_cvt_pk_bf16_f32 v3, v3, s0
	ds_write_b16 v1, v3 offset:2512
	ds_read_u16 v3, v1 offset:2784
	v_mul_f32_e32 v47, v116, v40
	v_mul_f32_e32 v47, v47, v234
	s_waitcnt lgkmcnt(0)
	v_lshlrev_b32_e32 v3, 16, v3
	v_mul_f32_e32 v48, 0xbfb8aa3b, v3
	v_exp_f32_e32 v48, v48
	s_nop 0
	v_add_f32_e32 v48, 1.0, v48
	v_div_scale_f32 v49, s[0:1], v48, v48, v3
	s_nop 0
	v_rcp_f32_e32 v49, v48
	s_nop 0
	v_mul_f32_e32 v3, v3, v49
	v_mul_f32_e32 v3, v47, v3
	v_cvt_pk_bf16_f32 v3, v3, s0
	ds_write_b16 v1, v3 offset:2784
	ds_read_u16 v3, v1 offset:3056
	v_mul_f32_e32 v47, v115, v35
	v_mul_f32_e32 v47, v47, v234
	s_waitcnt lgkmcnt(0)
	v_lshlrev_b32_e32 v3, 16, v3
	v_mul_f32_e32 v48, 0xbfb8aa3b, v3
	v_exp_f32_e32 v48, v48
	s_nop 0
	v_add_f32_e32 v48, 1.0, v48
	v_div_scale_f32 v49, s[0:1], v48, v48, v3
	s_nop 0
	v_rcp_f32_e32 v49, v48
	s_nop 0
	v_mul_f32_e32 v3, v3, v49
	v_mul_f32_e32 v3, v47, v3
	v_cvt_pk_bf16_f32 v3, v3, s0
	ds_write_b16 v1, v3 offset:3056
	ds_read_u16 v3, v1 offset:4416
	v_mul_f32_e32 v47, v114, v31
	v_mul_f32_e32 v47, v47, v234
	s_waitcnt lgkmcnt(0)
	v_lshlrev_b32_e32 v3, 16, v3
	v_mul_f32_e32 v48, 0xbfb8aa3b, v3
	v_exp_f32_e32 v48, v48
	s_nop 0
	v_add_f32_e32 v48, 1.0, v48
	v_div_scale_f32 v49, s[0:1], v48, v48, v3
	s_nop 0
	v_rcp_f32_e32 v49, v48
	s_nop 0
	v_mul_f32_e32 v3, v3, v49
	v_mul_f32_e32 v3, v47, v3
	v_cvt_pk_bf16_f32 v3, v3, s0
	ds_write_b16 v1, v3 offset:4416
	ds_read_u16 v3, v1 offset:4688
	v_mul_f32_e32 v47, v113, v27
	v_mul_f32_e32 v47, v47, v234
	s_waitcnt lgkmcnt(0)
	v_lshlrev_b32_e32 v3, 16, v3
	v_mul_f32_e32 v48, 0xbfb8aa3b, v3
	v_exp_f32_e32 v48, v48
	s_nop 0
	v_add_f32_e32 v48, 1.0, v48
	v_div_scale_f32 v49, s[0:1], v48, v48, v3
	s_nop 0
	v_rcp_f32_e32 v49, v48
	s_nop 0
	v_mul_f32_e32 v3, v3, v49
	v_mul_f32_e32 v3, v47, v3
	v_cvt_pk_bf16_f32 v3, v3, s0
	ds_write_b16 v1, v3 offset:4688
	ds_read_u16 v3, v1 offset:4960
	v_mul_f32_e32 v47, v112, v25
	v_mul_f32_e32 v47, v47, v234
	s_waitcnt lgkmcnt(0)
	v_lshlrev_b32_e32 v3, 16, v3
	v_mul_f32_e32 v48, 0xbfb8aa3b, v3
	v_exp_f32_e32 v48, v48
	s_nop 0
	v_add_f32_e32 v48, 1.0, v48
	v_div_scale_f32 v49, s[0:1], v48, v48, v3
	s_nop 0
	v_rcp_f32_e32 v49, v48
	s_nop 0
	v_mul_f32_e32 v3, v3, v49
	v_mul_f32_e32 v3, v47, v3
	v_cvt_pk_bf16_f32 v3, v3, s0
	ds_write_b16 v1, v3 offset:4960
	ds_read_u16 v3, v1 offset:5232
	v_mul_f32_e32 v47, v111, v24
	v_mul_f32_e32 v47, v47, v234
	s_waitcnt lgkmcnt(0)
	v_lshlrev_b32_e32 v3, 16, v3
	v_mul_f32_e32 v48, 0xbfb8aa3b, v3
	v_exp_f32_e32 v48, v48
	s_nop 0
	v_add_f32_e32 v48, 1.0, v48
	v_div_scale_f32 v49, s[0:1], v48, v48, v3
	s_nop 0
	v_rcp_f32_e32 v49, v48
	s_nop 0
	v_mul_f32_e32 v3, v3, v49
	v_mul_f32_e32 v3, v47, v3
	v_cvt_pk_bf16_f32 v3, v3, s0
	ds_write_b16 v1, v3 offset:5232
	ds_read_u16 v3, v1 offset:6592
	v_mul_f32_e32 v47, v110, v23
	v_mul_f32_e32 v47, v47, v234
	s_waitcnt lgkmcnt(0)
	v_lshlrev_b32_e32 v3, 16, v3
	v_mul_f32_e32 v48, 0xbfb8aa3b, v3
	v_exp_f32_e32 v48, v48
	s_nop 0
	v_add_f32_e32 v48, 1.0, v48
	v_div_scale_f32 v49, s[0:1], v48, v48, v3
	s_nop 0
	v_rcp_f32_e32 v49, v48
	s_nop 0
	v_mul_f32_e32 v3, v3, v49
	v_mul_f32_e32 v3, v47, v3
	v_cvt_pk_bf16_f32 v3, v3, s0
	ds_write_b16 v1, v3 offset:6592
	ds_read_u16 v3, v1 offset:6864
	v_mul_f32_e32 v47, v109, v22
	v_mul_f32_e32 v47, v47, v234
	s_waitcnt lgkmcnt(0)
	v_lshlrev_b32_e32 v3, 16, v3
	v_mul_f32_e32 v48, 0xbfb8aa3b, v3
	v_exp_f32_e32 v48, v48
	s_nop 0
	v_add_f32_e32 v48, 1.0, v48
	v_div_scale_f32 v49, s[0:1], v48, v48, v3
	s_nop 0
	v_rcp_f32_e32 v49, v48
	s_nop 0
	v_mul_f32_e32 v3, v3, v49
	v_mul_f32_e32 v3, v47, v3
	v_cvt_pk_bf16_f32 v3, v3, s0
	ds_write_b16 v1, v3 offset:6864
	ds_read_u16 v3, v1 offset:7136
	v_mul_f32_e32 v47, v108, v21
	v_mul_f32_e32 v47, v47, v234
	s_waitcnt lgkmcnt(0)
	v_lshlrev_b32_e32 v3, 16, v3
	v_mul_f32_e32 v48, 0xbfb8aa3b, v3
	v_exp_f32_e32 v48, v48
	s_nop 0
	v_add_f32_e32 v48, 1.0, v48
	v_div_scale_f32 v49, s[0:1], v48, v48, v3
	s_nop 0
	v_rcp_f32_e32 v49, v48
	s_nop 0
	v_mul_f32_e32 v3, v3, v49
	v_mul_f32_e32 v3, v47, v3
	v_cvt_pk_bf16_f32 v3, v3, s0
	ds_write_b16 v1, v3 offset:7136
	ds_read_u16 v3, v1 offset:7408
	v_mul_f32_e32 v47, v107, v20
	v_mul_f32_e32 v2, v47, v234
	s_waitcnt lgkmcnt(0)
	v_lshlrev_b32_e32 v3, 16, v3
	v_mul_f32_e32 v47, 0xbfb8aa3b, v3
	v_exp_f32_e32 v47, v47
	s_nop 0
	v_add_f32_e32 v47, 1.0, v47
	v_div_scale_f32 v48, s[0:1], v47, v47, v3
	s_nop 0
	v_rcp_f32_e32 v48, v47
	s_nop 0
	v_mul_f32_e32 v3, v3, v48
	v_mul_f32_e32 v2, v2, v3
	v_cvt_pk_bf16_f32 v2, v2, s0
	ds_write_b16 v1, v2 offset:7408
	ds_read_u16 v3, v1 offset:128
	v_mul_f32_e32 v47, v106, v46
	s_waitcnt lgkmcnt(0)
; #define LAS __attribute__((address_space(3)))
; DI unsigned cvtpk(float lo, float hi) { f32x2 v = {lo, hi}; bf16x2_t b = __builtin_convertvector(v, bf16x2_t); return __builtin_bit_cast(unsigned, b); }
; DI float bf2f(bf16 b) { return __uint_as_float(((unsigned)b) << 16); }
; DI float siluf_(float x) { return x / (1.f + __expf(-x)); }
; DI void gla_stage3(const Ctx& c0, int layer, int unit, int cb, LAS unsigned char* lds) {
;     ...
; #pragma unroll
;     for (int vb = 0; vb < 4; ++vb) { const float g = gn[32 * vb + r];
; #pragma unroll
;         for (int rg = 0; rg < 16; ++rg) { LAS bf16* e = (LAS bf16*)(R + (4 * hi) * G3_PITCH + r * 2 + ((rg & 3) + 8 * (rg >> 2)) * G3_PITCH + 64 * vb);
;             const float z = bf2f(*e);
;             *e = (bf16)(cvtpk(o[vb][rg] * rs[rg] * g * siluf_(z), 0.f) & 0xffffu); }
;         asm volatile("" ::: "memory"); }
	v_lshlrev_b32_e32 v3, 16, v3
	v_mul_f32_e32 v48, 0xbfb8aa3b, v3
	v_exp_f32_e32 v48, v48
	s_waitcnt vmcnt(0)
	v_mul_f32_e32 v47, v47, v236
	v_add_f32_e32 v48, 1.0, v48
	v_div_scale_f32 v49, s[0:1], v48, v48, v3
	v_mul_f32_e32 v39, v39, v236
	v_mul_f32_e32 v38, v38, v236
	v_mul_f32_e32 v37, v37, v236
	v_rcp_f32_e32 v49, v48
	s_nop 0
	v_mul_f32_e32 v3, v3, v49
	v_mul_f32_e32 v3, v47, v3
	v_cvt_pk_bf16_f32 v3, v3, s0
	ds_write_b16 v1, v3 offset:128
	ds_read_u16 v3, v1 offset:400
	v_mul_f32_e32 v47, v105, v45
	v_mul_f32_e32 v47, v47, v236
	v_mul_f32_e32 v36, v36, v236
	v_mul_f32_e32 v34, v34, v236
	s_waitcnt lgkmcnt(0)
	v_lshlrev_b32_e32 v3, 16, v3
	v_mul_f32_e32 v48, 0xbfb8aa3b, v3
	v_exp_f32_e32 v48, v48
	v_mul_f32_e32 v33, v33, v236
	v_mul_f32_e32 v32, v32, v236
	v_mul_f32_e32 v30, v30, v236
	v_add_f32_e32 v48, 1.0, v48
	v_div_scale_f32 v49, s[0:1], v48, v48, v3
	v_mul_f32_e32 v29, v29, v236
	v_mul_f32_e32 v28, v28, v236
	v_rcp_f32_e32 v49, v48
	s_nop 0
	v_mul_f32_e32 v3, v3, v49
	v_mul_f32_e32 v3, v47, v3
	v_cvt_pk_bf16_f32 v3, v3, s0
	ds_write_b16 v1, v3 offset:400
	ds_read_u16 v3, v1 offset:672
	v_mul_f32_e32 v47, v104, v44
	v_mul_f32_e32 v47, v47, v236
	s_waitcnt lgkmcnt(0)
	v_lshlrev_b32_e32 v3, 16, v3
	v_mul_f32_e32 v48, 0xbfb8aa3b, v3
	v_exp_f32_e32 v48, v48
	s_nop 0
	v_add_f32_e32 v48, 1.0, v48
	v_div_scale_f32 v49, s[0:1], v48, v48, v3
	s_nop 0
	v_rcp_f32_e32 v49, v48
	s_nop 0
	v_mul_f32_e32 v3, v3, v49
	v_mul_f32_e32 v3, v47, v3
	v_cvt_pk_bf16_f32 v3, v3, s0
	ds_write_b16 v1, v3 offset:672
	ds_read_u16 v3, v1 offset:944
	v_mul_f32_e32 v47, v103, v43
	v_mul_f32_e32 v47, v47, v236
	s_waitcnt lgkmcnt(0)
	v_lshlrev_b32_e32 v3, 16, v3
	v_mul_f32_e32 v48, 0xbfb8aa3b, v3
	v_exp_f32_e32 v48, v48
	s_nop 0
	v_add_f32_e32 v48, 1.0, v48
	v_div_scale_f32 v49, s[0:1], v48, v48, v3
	s_nop 0
	v_rcp_f32_e32 v49, v48
	s_nop 0
	v_mul_f32_e32 v3, v3, v49
	v_mul_f32_e32 v3, v47, v3
	v_cvt_pk_bf16_f32 v3, v3, s0
	ds_write_b16 v1, v3 offset:944
	ds_read_u16 v3, v1 offset:2304
	v_mul_f32_e32 v47, v102, v42
	v_mul_f32_e32 v47, v47, v236
	v_mul_f32_e32 v2, v26, v236
	s_waitcnt lgkmcnt(0)
	v_lshlrev_b32_e32 v3, 16, v3
	v_mul_f32_e32 v48, 0xbfb8aa3b, v3
	v_exp_f32_e32 v48, v48
	s_nop 0
	v_add_f32_e32 v48, 1.0, v48
	v_div_scale_f32 v49, s[0:1], v48, v48, v3
	s_nop 0
	v_rcp_f32_e32 v49, v48
	s_nop 0
	v_mul_f32_e32 v3, v3, v49
	v_mul_f32_e32 v3, v47, v3
	v_cvt_pk_bf16_f32 v3, v3, s0
	ds_write_b16 v1, v3 offset:2304
	ds_read_u16 v3, v1 offset:2576
	s_waitcnt lgkmcnt(0)
	v_lshlrev_b32_e32 v3, 16, v3
	v_mul_f32_e32 v47, 0xbfb8aa3b, v3
	v_exp_f32_e32 v47, v47
	s_nop 0
	v_add_f32_e32 v47, 1.0, v47
	v_div_scale_f32 v48, s[0:1], v47, v47, v3
	s_nop 0
	v_rcp_f32_e32 v48, v47
	s_nop 0
	v_mul_f32_e32 v3, v3, v48
	v_mul_f32_e32 v3, v39, v3
	v_cvt_pk_bf16_f32 v3, v3, s0
	ds_write_b16 v1, v3 offset:2576
	ds_read_u16 v3, v1 offset:2848
	s_waitcnt lgkmcnt(0)
	v_lshlrev_b32_e32 v3, 16, v3
	v_mul_f32_e32 v39, 0xbfb8aa3b, v3
	v_exp_f32_e32 v39, v39
	s_nop 0
	v_add_f32_e32 v39, 1.0, v39
	v_div_scale_f32 v47, s[0:1], v39, v39, v3
	s_nop 0
	v_rcp_f32_e32 v47, v39
	s_nop 0
	v_mul_f32_e32 v3, v3, v47
	v_mul_f32_e32 v3, v38, v3
	v_cvt_pk_bf16_f32 v3, v3, s0
	ds_write_b16 v1, v3 offset:2848
	ds_read_u16 v3, v1 offset:3120
	s_waitcnt lgkmcnt(0)
	v_lshlrev_b32_e32 v3, 16, v3
	v_mul_f32_e32 v38, 0xbfb8aa3b, v3
	v_exp_f32_e32 v38, v38
	s_nop 0
	v_add_f32_e32 v38, 1.0, v38
	v_div_scale_f32 v39, s[0:1], v38, v38, v3
	s_nop 0
	v_rcp_f32_e32 v39, v38
	s_nop 0
	v_mul_f32_e32 v3, v3, v39
	v_mul_f32_e32 v3, v37, v3
	v_cvt_pk_bf16_f32 v3, v3, s0
	ds_write_b16 v1, v3 offset:3120
	ds_read_u16 v3, v1 offset:4480
	s_waitcnt lgkmcnt(0)
	v_lshlrev_b32_e32 v3, 16, v3
	v_mul_f32_e32 v37, 0xbfb8aa3b, v3
	v_exp_f32_e32 v37, v37
	s_nop 0
	v_add_f32_e32 v37, 1.0, v37
	v_div_scale_f32 v38, s[0:1], v37, v37, v3
	s_nop 0
	v_rcp_f32_e32 v38, v37
	s_nop 0
	v_mul_f32_e32 v3, v3, v38
	v_mul_f32_e32 v3, v36, v3
	v_cvt_pk_bf16_f32 v3, v3, s0
	ds_write_b16 v1, v3 offset:4480
	ds_read_u16 v3, v1 offset:4752
	s_waitcnt lgkmcnt(0)
	v_lshlrev_b32_e32 v3, 16, v3
	v_mul_f32_e32 v36, 0xbfb8aa3b, v3
	v_exp_f32_e32 v36, v36
	s_nop 0
	v_add_f32_e32 v36, 1.0, v36
	v_div_scale_f32 v37, s[0:1], v36, v36, v3
	s_nop 0
	v_rcp_f32_e32 v37, v36
	s_nop 0
	v_mul_f32_e32 v3, v3, v37
	v_mul_f32_e32 v3, v34, v3
	v_cvt_pk_bf16_f32 v3, v3, s0
	ds_write_b16 v1, v3 offset:4752
	ds_read_u16 v3, v1 offset:5024
	s_waitcnt lgkmcnt(0)
	v_lshlrev_b32_e32 v3, 16, v3
	v_mul_f32_e32 v34, 0xbfb8aa3b, v3
	v_exp_f32_e32 v34, v34
	s_nop 0
	v_add_f32_e32 v34, 1.0, v34
	v_div_scale_f32 v36, s[0:1], v34, v34, v3
	s_nop 0
	v_rcp_f32_e32 v36, v34
	s_nop 0
	v_mul_f32_e32 v3, v3, v36
	v_mul_f32_e32 v3, v33, v3
	v_cvt_pk_bf16_f32 v3, v3, s0
	ds_write_b16 v1, v3 offset:5024
	ds_read_u16 v3, v1 offset:5296
	s_waitcnt lgkmcnt(0)
	v_lshlrev_b32_e32 v3, 16, v3
	v_mul_f32_e32 v33, 0xbfb8aa3b, v3
	v_exp_f32_e32 v33, v33
	s_nop 0
	v_add_f32_e32 v33, 1.0, v33
	v_div_scale_f32 v34, s[0:1], v33, v33, v3
	s_nop 0
	v_rcp_f32_e32 v34, v33
	s_nop 0
	v_mul_f32_e32 v3, v3, v34
	v_mul_f32_e32 v3, v32, v3
	v_cvt_pk_bf16_f32 v3, v3, s0
	ds_write_b16 v1, v3 offset:5296
	ds_read_u16 v3, v1 offset:6656
	s_waitcnt lgkmcnt(0)
	v_lshlrev_b32_e32 v3, 16, v3
	v_mul_f32_e32 v32, 0xbfb8aa3b, v3
	v_exp_f32_e32 v32, v32
	s_nop 0
	v_add_f32_e32 v32, 1.0, v32
	v_div_scale_f32 v33, s[0:1], v32, v32, v3
	s_nop 0
	v_rcp_f32_e32 v33, v32
	s_nop 0
	v_mul_f32_e32 v3, v3, v33
	v_mul_f32_e32 v3, v30, v3
	v_cvt_pk_bf16_f32 v3, v3, s0
	ds_write_b16 v1, v3 offset:6656
	ds_read_u16 v3, v1 offset:6928
	s_waitcnt lgkmcnt(0)
; #define LAS __attribute__((address_space(3)))
; DI unsigned cvtpk(float lo, float hi) { f32x2 v = {lo, hi}; bf16x2_t b = __builtin_convertvector(v, bf16x2_t); return __builtin_bit_cast(unsigned, b); }
; DI float bf2f(bf16 b) { return __uint_as_float(((unsigned)b) << 16); }
; DI float siluf_(float x) { return x / (1.f + __expf(-x)); }
; DI void gla_stage3(const Ctx& c0, int layer, int unit, int cb, LAS unsigned char* lds) {
;     ...
; #pragma unroll
;     for (int vb = 0; vb < 4; ++vb) { const float g = gn[32 * vb + r];
; #pragma unroll
;         for (int rg = 0; rg < 16; ++rg) { LAS bf16* e = (LAS bf16*)(R + (4 * hi) * G3_PITCH + r * 2 + ((rg & 3) + 8 * (rg >> 2)) * G3_PITCH + 64 * vb);
;             const float z = bf2f(*e);
;             *e = (bf16)(cvtpk(o[vb][rg] * rs[rg] * g * siluf_(z), 0.f) & 0xffffu); }
;         asm volatile("" ::: "memory"); }
	v_lshlrev_b32_e32 v3, 16, v3
	v_mul_f32_e32 v30, 0xbfb8aa3b, v3
	v_exp_f32_e32 v30, v30
	s_nop 0
	v_add_f32_e32 v30, 1.0, v30
	v_div_scale_f32 v32, s[0:1], v30, v30, v3
	s_nop 0
	v_rcp_f32_e32 v32, v30
	s_nop 0
	v_mul_f32_e32 v3, v3, v32
	v_mul_f32_e32 v3, v29, v3
	v_cvt_pk_bf16_f32 v3, v3, s0
	ds_write_b16 v1, v3 offset:6928
	ds_read_u16 v3, v1 offset:7200
	s_waitcnt lgkmcnt(0)
	v_lshlrev_b32_e32 v3, 16, v3
	v_mul_f32_e32 v29, 0xbfb8aa3b, v3
	v_exp_f32_e32 v29, v29
	s_nop 0
	v_add_f32_e32 v29, 1.0, v29
	v_div_scale_f32 v30, s[0:1], v29, v29, v3
	s_nop 0
	v_rcp_f32_e32 v30, v29
	s_nop 0
	v_mul_f32_e32 v3, v3, v30
	v_mul_f32_e32 v3, v28, v3
	v_cvt_pk_bf16_f32 v3, v3, s0
	ds_write_b16 v1, v3 offset:7200
	ds_read_u16 v3, v1 offset:7472
	s_waitcnt lgkmcnt(0)
	v_lshlrev_b32_e32 v3, 16, v3
	v_mul_f32_e32 v26, 0xbfb8aa3b, v3
	v_exp_f32_e32 v26, v26
	s_nop 0
	v_add_f32_e32 v26, 1.0, v26
	v_div_scale_f32 v28, s[0:1], v26, v26, v3
	s_nop 0
	v_rcp_f32_e32 v28, v26
	s_nop 0
	v_mul_f32_e32 v3, v3, v28
	v_mul_f32_e32 v2, v2, v3
	v_cvt_pk_bf16_f32 v2, v2, s0
	ds_write_b16 v1, v2 offset:7472
	ds_read_u16 v3, v1 offset:192
	s_waitcnt lgkmcnt(0)
	v_lshlrev_b32_e32 v3, 16, v3
	v_mul_f32_e32 v26, 0xbfb8aa3b, v3
	v_exp_f32_e32 v26, v26
	s_waitcnt vmcnt(31)
	v_mul_f32_e32 v19, v19, v238
	v_add_f32_e32 v26, 1.0, v26
	v_div_scale_f32 v28, s[0:1], v26, v26, v3
	v_mul_f32_e32 v18, v18, v238
	v_mul_f32_e32 v17, v17, v238
	v_mul_f32_e32 v16, v16, v238
	v_rcp_f32_e32 v28, v26
	s_nop 0
	v_mul_f32_e32 v3, v3, v28
	v_mul_f32_e32 v3, v19, v3
	v_cvt_pk_bf16_f32 v3, v3, s0
	ds_write_b16 v1, v3 offset:192
	ds_read_u16 v3, v1 offset:464
	v_mul_f32_e32 v15, v15, v238
	v_mul_f32_e32 v14, v14, v238
	v_mul_f32_e32 v13, v13, v238
	v_mul_f32_e32 v12, v12, v238
	s_waitcnt lgkmcnt(0)
	v_lshlrev_b32_e32 v3, 16, v3
	v_mul_f32_e32 v19, 0xbfb8aa3b, v3
	v_exp_f32_e32 v19, v19
	v_mul_f32_e32 v11, v11, v238
	v_mul_f32_e32 v10, v10, v238
	v_mul_f32_e32 v9, v9, v238
	v_add_f32_e32 v19, 1.0, v19
	v_div_scale_f32 v26, s[0:1], v19, v19, v3
	v_mul_f32_e32 v8, v8, v238
	v_mul_f32_e32 v7, v7, v238
	v_mul_f32_e32 v6, v6, v238
	v_rcp_f32_e32 v26, v19
	s_nop 0
	v_mul_f32_e32 v3, v3, v26
	v_mul_f32_e32 v3, v18, v3
	v_cvt_pk_bf16_f32 v3, v3, s0
	ds_write_b16 v1, v3 offset:464
	ds_read_u16 v3, v1 offset:736
	v_mul_f32_e32 v5, v5, v238
	v_mul_f32_e32 v2, v4, v238
	s_waitcnt lgkmcnt(0)
	v_lshlrev_b32_e32 v3, 16, v3
	v_mul_f32_e32 v18, 0xbfb8aa3b, v3
	v_exp_f32_e32 v18, v18
	s_nop 0
	v_add_f32_e32 v18, 1.0, v18
	v_div_scale_f32 v19, s[0:1], v18, v18, v3
	s_nop 0
	v_rcp_f32_e32 v19, v18
	s_nop 0
	v_mul_f32_e32 v3, v3, v19
	v_mul_f32_e32 v3, v17, v3
	v_cvt_pk_bf16_f32 v3, v3, s0
	ds_write_b16 v1, v3 offset:736
	ds_read_u16 v3, v1 offset:1008
	s_waitcnt lgkmcnt(0)
	v_lshlrev_b32_e32 v3, 16, v3
	v_mul_f32_e32 v17, 0xbfb8aa3b, v3
	v_exp_f32_e32 v17, v17
	s_nop 0
	v_add_f32_e32 v17, 1.0, v17
	v_div_scale_f32 v18, s[0:1], v17, v17, v3
	s_nop 0
	v_rcp_f32_e32 v18, v17
	s_nop 0
	v_mul_f32_e32 v3, v3, v18
	v_mul_f32_e32 v3, v16, v3
	v_cvt_pk_bf16_f32 v3, v3, s0
	ds_write_b16 v1, v3 offset:1008
	ds_read_u16 v3, v1 offset:2368
	s_waitcnt lgkmcnt(0)
	v_lshlrev_b32_e32 v3, 16, v3
	v_mul_f32_e32 v16, 0xbfb8aa3b, v3
	v_exp_f32_e32 v16, v16
	s_nop 0
	v_add_f32_e32 v16, 1.0, v16
	v_div_scale_f32 v17, s[0:1], v16, v16, v3
	s_nop 0
	v_rcp_f32_e32 v17, v16
	s_nop 0
	v_mul_f32_e32 v3, v3, v17
	v_mul_f32_e32 v3, v15, v3
	v_cvt_pk_bf16_f32 v3, v3, s0
	ds_write_b16 v1, v3 offset:2368
	ds_read_u16 v3, v1 offset:2640
	s_waitcnt lgkmcnt(0)
	v_lshlrev_b32_e32 v3, 16, v3
	v_mul_f32_e32 v15, 0xbfb8aa3b, v3
	v_exp_f32_e32 v15, v15
	s_nop 0
	v_add_f32_e32 v15, 1.0, v15
	v_div_scale_f32 v16, s[0:1], v15, v15, v3
	s_nop 0
	v_rcp_f32_e32 v16, v15
	s_nop 0
	v_mul_f32_e32 v3, v3, v16
	v_mul_f32_e32 v3, v14, v3
	v_cvt_pk_bf16_f32 v3, v3, s0
	ds_write_b16 v1, v3 offset:2640
	ds_read_u16 v3, v1 offset:2912
	s_waitcnt lgkmcnt(0)
	v_lshlrev_b32_e32 v3, 16, v3
	v_mul_f32_e32 v14, 0xbfb8aa3b, v3
	v_exp_f32_e32 v14, v14
	s_nop 0
	v_add_f32_e32 v14, 1.0, v14
	v_div_scale_f32 v15, s[0:1], v14, v14, v3
	s_nop 0
	v_rcp_f32_e32 v15, v14
	s_nop 0
	v_mul_f32_e32 v3, v3, v15
	v_mul_f32_e32 v3, v13, v3
	v_cvt_pk_bf16_f32 v3, v3, s0
	ds_write_b16 v1, v3 offset:2912
	ds_read_u16 v3, v1 offset:3184
	s_waitcnt lgkmcnt(0)
; #define LAS __attribute__((address_space(3)))
; #define LDS_WAIT() asm volatile("s_waitcnt lgkmcnt(0)" ::: "memory")
; DI unsigned cvtpk(float lo, float hi) { f32x2 v = {lo, hi}; bf16x2_t b = __builtin_convertvector(v, bf16x2_t); return __builtin_bit_cast(unsigned, b); }
; DI float bf2f(bf16 b) { return __uint_as_float(((unsigned)b) << 16); }
; DI float siluf_(float x) { return x / (1.f + __expf(-x)); }
; DI void g3_tile_out(bf16* g, const LAS unsigned char* R, int lane) {
;     LDS_WAIT();
; #pragma unroll
;     for (int it = 0; it < 8; ++it) { const int row = 4 * it + (lane >> 4), ch = lane & 15;
;         *(u32x4*)(g + (size_t)row * 512 + ch * 8) = *(const LAS u32x4*)(R + row * G3_PITCH + ch * 16); }
;     LDS_WAIT();
; }
; DI void gla_stage3(const Ctx& c0, int layer, int unit, int cb, LAS unsigned char* lds) {
;     ...
;     for (int vb = 0; vb < 4; ++vb) { const float g = gn[32 * vb + r];
; #pragma unroll
;         for (int rg = 0; rg < 16; ++rg) { LAS bf16* e = (LAS bf16*)(R + (4 * hi) * G3_PITCH + r * 2 + ((rg & 3) + 8 * (rg >> 2)) * G3_PITCH + 64 * vb);
;             const float z = bf2f(*e);
;             *e = (bf16)(cvtpk(o[vb][rg] * rs[rg] * g * siluf_(z), 0.f) & 0xffffu); }
;         asm volatile("" ::: "memory"); }
;     g3_tile_out((bf16*)(c.ws + O_OGLA) + row0 * 512 + h * 128, R, lane);
	v_lshlrev_b32_e32 v3, 16, v3
	v_mul_f32_e32 v13, 0xbfb8aa3b, v3
	v_exp_f32_e32 v13, v13
	s_nop 0
	v_add_f32_e32 v13, 1.0, v13
	v_div_scale_f32 v14, s[0:1], v13, v13, v3
	s_nop 0
	v_rcp_f32_e32 v14, v13
	s_nop 0
	v_mul_f32_e32 v3, v3, v14
	v_mul_f32_e32 v3, v12, v3
	v_cvt_pk_bf16_f32 v3, v3, s0
	ds_write_b16 v1, v3 offset:3184
	ds_read_u16 v3, v1 offset:4544
	s_waitcnt lgkmcnt(0)
	v_lshlrev_b32_e32 v3, 16, v3
	v_mul_f32_e32 v12, 0xbfb8aa3b, v3
	v_exp_f32_e32 v12, v12
	s_nop 0
	v_add_f32_e32 v12, 1.0, v12
	v_div_scale_f32 v13, s[0:1], v12, v12, v3
	s_nop 0
	v_rcp_f32_e32 v13, v12
	s_nop 0
	v_mul_f32_e32 v3, v3, v13
	v_mul_f32_e32 v3, v11, v3
	v_cvt_pk_bf16_f32 v3, v3, s0
	ds_write_b16 v1, v3 offset:4544
	ds_read_u16 v3, v1 offset:4816
	s_waitcnt lgkmcnt(0)
	v_lshlrev_b32_e32 v3, 16, v3
	v_mul_f32_e32 v11, 0xbfb8aa3b, v3
	v_exp_f32_e32 v11, v11
	s_nop 0
	v_add_f32_e32 v11, 1.0, v11
	v_div_scale_f32 v12, s[0:1], v11, v11, v3
	s_nop 0
	v_rcp_f32_e32 v12, v11
	s_nop 0
	v_mul_f32_e32 v3, v3, v12
	v_mul_f32_e32 v3, v10, v3
	v_cvt_pk_bf16_f32 v3, v3, s0
	ds_write_b16 v1, v3 offset:4816
	ds_read_u16 v3, v1 offset:5088
	s_waitcnt lgkmcnt(0)
	v_lshlrev_b32_e32 v3, 16, v3
	v_mul_f32_e32 v10, 0xbfb8aa3b, v3
	v_exp_f32_e32 v10, v10
	s_nop 0
	v_add_f32_e32 v10, 1.0, v10
	v_div_scale_f32 v11, s[0:1], v10, v10, v3
	s_nop 0
	v_rcp_f32_e32 v11, v10
	s_nop 0
	v_mul_f32_e32 v3, v3, v11
	v_mul_f32_e32 v3, v9, v3
	v_cvt_pk_bf16_f32 v3, v3, s0
	ds_write_b16 v1, v3 offset:5088
	ds_read_u16 v3, v1 offset:5360
	s_waitcnt lgkmcnt(0)
	v_lshlrev_b32_e32 v3, 16, v3
	v_mul_f32_e32 v9, 0xbfb8aa3b, v3
	v_exp_f32_e32 v9, v9
	s_nop 0
	v_add_f32_e32 v9, 1.0, v9
	v_div_scale_f32 v10, s[0:1], v9, v9, v3
	s_nop 0
	v_rcp_f32_e32 v10, v9
	s_nop 0
	v_mul_f32_e32 v3, v3, v10
	v_mul_f32_e32 v3, v8, v3
	v_cvt_pk_bf16_f32 v3, v3, s0
	ds_write_b16 v1, v3 offset:5360
	ds_read_u16 v3, v1 offset:6720
	s_waitcnt lgkmcnt(0)
	v_lshlrev_b32_e32 v3, 16, v3
	v_mul_f32_e32 v8, 0xbfb8aa3b, v3
	v_exp_f32_e32 v8, v8
	s_nop 0
	v_add_f32_e32 v8, 1.0, v8
	v_div_scale_f32 v9, s[0:1], v8, v8, v3
	s_nop 0
	v_rcp_f32_e32 v9, v8
	s_nop 0
	v_mul_f32_e32 v3, v3, v9
	v_mul_f32_e32 v3, v7, v3
	v_cvt_pk_bf16_f32 v3, v3, s0
	ds_write_b16 v1, v3 offset:6720
	ds_read_u16 v3, v1 offset:6992
	s_waitcnt lgkmcnt(0)
	v_lshlrev_b32_e32 v3, 16, v3
	v_mul_f32_e32 v7, 0xbfb8aa3b, v3
	v_exp_f32_e32 v7, v7
	s_nop 0
	v_add_f32_e32 v7, 1.0, v7
	v_div_scale_f32 v8, s[0:1], v7, v7, v3
	s_nop 0
	v_rcp_f32_e32 v8, v7
	s_nop 0
	v_mul_f32_e32 v3, v3, v8
	v_mul_f32_e32 v3, v6, v3
	v_cvt_pk_bf16_f32 v3, v3, s0
	ds_write_b16 v1, v3 offset:6992
	ds_read_u16 v3, v1 offset:7264
	s_waitcnt lgkmcnt(0)
	v_lshlrev_b32_e32 v3, 16, v3
	v_mul_f32_e32 v6, 0xbfb8aa3b, v3
	v_exp_f32_e32 v6, v6
	s_nop 0
	v_add_f32_e32 v6, 1.0, v6
	v_div_scale_f32 v7, s[0:1], v6, v6, v3
	s_nop 0
	v_rcp_f32_e32 v7, v6
	s_nop 0
	v_mul_f32_e32 v3, v3, v7
	v_mul_f32_e32 v3, v5, v3
	v_cvt_pk_bf16_f32 v3, v3, s0
	ds_write_b16 v1, v3 offset:7264
	ds_read_u16 v3, v1 offset:7536
	s_waitcnt lgkmcnt(0)
	v_lshlrev_b32_e32 v3, 16, v3
	v_mul_f32_e32 v4, 0xbfb8aa3b, v3
	v_exp_f32_e32 v4, v4
	s_nop 0
	v_add_f32_e32 v4, 1.0, v4
	v_div_scale_f32 v5, s[0:1], v4, v4, v3
	s_nop 0
	v_rcp_f32_e32 v5, v4
	s_nop 0
	v_mul_f32_e32 v3, v3, v5
	v_mul_f32_e32 v2, v2, v3
	v_cvt_pk_bf16_f32 v2, v2, s0
	ds_write_b16 v1, v2 offset:7536
	s_waitcnt lgkmcnt(0)
	ds_read_b128 v[2:5], v92
	v_lshl_add_u64 v[6:7], v[90:91], 0, s[24:25]
	v_lshl_add_u64 v[8:9], v[6:7], 0, v[66:67]
	s_waitcnt lgkmcnt(0)
	global_store_dwordx4 v[8:9], v[2:5], off
	ds_read_b128 v[2:5], v92 offset:1088
	v_lshl_add_u64 v[8:9], v[6:7], 0, v[68:69]
	s_waitcnt lgkmcnt(0)
	global_store_dwordx4 v[8:9], v[2:5], off
	ds_read_b128 v[2:5], v92 offset:2176
	v_lshl_add_u64 v[8:9], v[6:7], 0, v[70:71]
	s_waitcnt lgkmcnt(0)
	global_store_dwordx4 v[8:9], v[2:5], off
	ds_read_b128 v[2:5], v92 offset:3264
	v_lshl_add_u64 v[8:9], v[6:7], 0, v[72:73]
	s_waitcnt lgkmcnt(0)
	global_store_dwordx4 v[8:9], v[2:5], off
	ds_read_b128 v[2:5], v92 offset:4352
	v_lshl_add_u64 v[8:9], v[6:7], 0, v[74:75]
	s_waitcnt lgkmcnt(0)
	global_store_dwordx4 v[8:9], v[2:5], off
	ds_read_b128 v[2:5], v92 offset:5440
	v_lshl_add_u64 v[8:9], v[6:7], 0, v[76:77]
	s_waitcnt lgkmcnt(0)
	global_store_dwordx4 v[8:9], v[2:5], off
	ds_read_b128 v[2:5], v92 offset:6528
	v_lshl_add_u64 v[8:9], v[6:7], 0, v[78:79]
	v_lshl_add_u64 v[6:7], v[6:7], 0, v[80:81]
	s_waitcnt lgkmcnt(0)
	global_store_dwordx4 v[8:9], v[2:5], off
	ds_read_b128 v[2:5], v92 offset:7616
	s_waitcnt lgkmcnt(0)
	global_store_dwordx4 v[6:7], v[2:5], off
	s_waitcnt lgkmcnt(0)
	s_cbranch_scc1 .LBB0_1216

; DI float bflo(unsigned w) { return __uint_as_float(w << 16); }
; DI float bfhi(unsigned w) { return __uint_as_float(w & 0xffff0000u); }
; DI void post_phase(const Ctx& c0, int layer) {
;     ...
;     for (int m = gw; m < T; m += NGW) {
;         float o[16]; float ss = 0.f;
; #pragma unroll
;         for (int j = 0; j < 2; ++j) { const u32x4 w = *(const u32x4*)(ob + (size_t)m * DM + 512 * j + 8 * lane);
;             o[8 * j + 0] = bflo(w.x); o[8 * j + 1] = bfhi(w.x); o[8 * j + 2] = bflo(w.y); o[8 * j + 3] = bfhi(w.y); o[8 * j + 4] = bflo(w.z); o[8 * j + 5] = bfhi(w.z); o[8 * j + 6] = bflo(w.w); o[8 * j + 7] = bfhi(w.w); }
; #pragma unroll
;         for (int e = 0; e < 16; ++e) ss += o[e] * o[e];
;         const float rr = 1.f / sqrtf(wave_sum(ss) * (1.f / 1024.f) + EPS);
;         float xn[16]; float s2 = 0.f;
; #pragma unroll
;         for (int j = 0; j < 2; ++j)
; #pragma unroll
;             for (int q = 0; q < 2; ++q) { const size_t off = (size_t)m * DM + 512 * j + 8 * lane + 4 * q; const f32x4 xv = *(const f32x4*)(xin + off); const f32x4 g = *(const f32x4*)(gp + 512 * j + 8 * lane + 4 * q);
;                 f32x4 y;
; #pragma unroll
;                 for (int k = 0; k < 4; ++k) { y[k] = xv[k] + o[8 * j + 4 * q + k] * rr * g[k]; xn[8 * j + 4 * q + k] = y[k]; s2 += y[k] * y[k]; }
;                 *(f32x4*)(c.out + off) = y; }
.LBB0_1447:
	global_load_dwordx4 v[16:19], v[4:5], off
	global_load_dwordx4 v[20:23], v[4:5], off offset:1024
	global_load_dwordx4 v[24:27], v[2:3], off
	global_load_dwordx4 v[28:31], v[6:7], off
	global_load_dwordx4 v[32:35], v[6:7], off offset:16
	s_add_i32 s66, s66, s68
	v_lshl_add_u64 v[4:5], v[4:5], 0, s[2:3]
	s_cmp_lt_i32 s66, 0x8000
	s_waitcnt vmcnt(1) lgkmcnt(0)
	v_lshlrev_b32_e32 v38, 16, v16
	v_and_b32_e32 v39, 0xffff0000, v16
	v_lshlrev_b32_e32 v16, 16, v17
	v_and_b32_e32 v17, 0xffff0000, v17
	v_lshlrev_b32_e32 v44, 16, v20
	v_and_b32_e32 v45, 0xffff0000, v20
	v_lshlrev_b32_e32 v46, 16, v21
	v_and_b32_e32 v47, 0xffff0000, v21
	v_pk_mul_f32 v[20:21], v[38:39], v[38:39]
	v_and_b32_e32 v36, 0xffff0000, v23
	v_lshlrev_b32_e32 v37, 16, v23
	v_lshlrev_b32_e32 v48, 16, v22
	v_and_b32_e32 v49, 0xffff0000, v22
	v_pk_mul_f32 v[22:23], v[16:17], v[16:17]
	v_add_f32_e32 v15, v20, v21
	v_lshlrev_b32_e32 v40, 16, v18
	v_and_b32_e32 v41, 0xffff0000, v18
	v_add_f32_e32 v15, v22, v15
	v_pk_mul_f32 v[50:51], v[40:41], v[40:41]
	v_add_f32_e32 v15, v23, v15
	v_lshlrev_b32_e32 v42, 16, v19
	v_and_b32_e32 v43, 0xffff0000, v19
	v_add_f32_e32 v15, v50, v15
	v_pk_mul_f32 v[52:53], v[42:43], v[42:43]
	v_add_f32_e32 v15, v51, v15
	v_add_f32_e32 v15, v52, v15
	v_pk_mul_f32 v[54:55], v[44:45], v[44:45]
	v_add_f32_e32 v15, v53, v15
	v_add_f32_e32 v15, v54, v15
	v_pk_mul_f32 v[56:57], v[46:47], v[46:47]
	v_add_f32_e32 v15, v55, v15
	v_add_f32_e32 v15, v56, v15
	v_pk_mul_f32 v[58:59], v[48:49], v[48:49]
	v_add_f32_e32 v15, v57, v15
	v_add_f32_e32 v15, v58, v15
	v_pk_mul_f32 v[18:19], v[36:37], v[36:37]
	v_add_f32_e32 v15, v59, v15
	v_add_f32_e32 v15, v19, v15
	v_add_f32_e32 v15, v18, v15
	ds_bpermute_b32 v18, v1, v15
	s_waitcnt lgkmcnt(0)
	v_add_f32_e32 v15, v15, v18
	ds_bpermute_b32 v18, v8, v15
	s_waitcnt lgkmcnt(0)
	v_add_f32_e32 v15, v15, v18
	ds_bpermute_b32 v18, v9, v15
	s_waitcnt lgkmcnt(0)
	v_add_f32_e32 v15, v15, v18
	ds_bpermute_b32 v18, v10, v15
	s_waitcnt lgkmcnt(0)
	v_add_f32_e32 v15, v15, v18
	ds_bpermute_b32 v18, v11, v15
	s_waitcnt lgkmcnt(0)
	v_add_f32_e32 v15, v15, v18
	ds_bpermute_b32 v18, v12, v15
	s_waitcnt lgkmcnt(0)
	v_add_f32_e32 v15, v15, v18
	v_fmamk_f32 v15, v15, 0x3a800000, v13
	v_mul_f32_e32 v18, 0x4f800000, v15
	v_cmp_gt_f32_e32 vcc, s6, v15
	s_nop 1
	v_cndmask_b32_e32 v15, v15, v18, vcc
	v_sqrt_f32_e32 v18, v15
	s_nop 0
	v_add_u32_e32 v19, -1, v18
	v_add_u32_e32 v20, 1, v18
	v_fma_f32 v21, -v19, v18, v15
	v_fma_f32 v22, -v20, v18, v15
	v_cmp_ge_f32_e64 s[0:1], 0, v21
	s_nop 1
	v_cndmask_b32_e64 v18, v18, v19, s[0:1]
	v_cmp_lt_f32_e64 s[0:1], 0, v22
	s_nop 1
	v_cndmask_b32_e64 v18, v18, v20, s[0:1]
	v_mul_f32_e32 v19, 0x37800000, v18
	v_cndmask_b32_e32 v18, v18, v19, vcc
	v_cmp_class_f32_e32 vcc, v15, v14
	s_nop 1
	v_cndmask_b32_e32 v15, v18, v15, vcc
	v_div_scale_f32 v18, s[0:1], v15, v15, 1.0
	v_rcp_f32_e32 v50, v15
	s_nop 0
	v_pk_mul_f32 v[20:21], v[50:51], v[38:39] op_sel_hi:[0,1]
	v_pk_mul_f32 v[16:17], v[50:51], v[16:17] op_sel_hi:[0,1]
	v_pk_fma_f32 v[18:19], v[26:27], v[16:17], v[30:31]
	v_pk_fma_f32 v[16:17], v[24:25], v[20:21], v[28:29]
	global_store_dwordx4 v[6:7], v[16:19], off
	global_load_dwordx4 v[16:19], v[2:3], off offset:16
	s_nop 0
	global_load_dwordx4 v[20:23], v[6:7], off offset:2048
	v_pk_mul_f32 v[24:25], v[50:51], v[42:43] op_sel_hi:[0,1]
	v_pk_mul_f32 v[26:27], v[50:51], v[40:41] op_sel_hi:[0,1]
	v_pk_mul_f32 v[28:29], v[50:51], v[46:47] op_sel_hi:[0,1]
	v_pk_mul_f32 v[30:31], v[50:51], v[44:45] op_sel_hi:[0,1]
	s_waitcnt vmcnt(1)
	v_pk_fma_f32 v[16:17], v[16:17], v[26:27], v[32:33]
	v_pk_fma_f32 v[18:19], v[18:19], v[24:25], v[34:35]
	global_store_dwordx4 v[6:7], v[16:19], off offset:16
	global_load_dwordx4 v[16:19], v[2:3], off offset:2048
	s_nop 0
	global_load_dwordx4 v[24:27], v[6:7], off offset:2064
	s_waitcnt vmcnt(1) lgkmcnt(0)
	v_pk_fma_f32 v[16:17], v[16:17], v[30:31], v[20:21]
	v_pk_fma_f32 v[18:19], v[18:19], v[28:29], v[22:23]
	global_store_dwordx4 v[6:7], v[16:19], off offset:2048
	global_load_dwordx4 v[16:19], v[2:3], off offset:2064
	v_pk_mul_f32 v[20:21], v[50:51], v[48:49] op_sel_hi:[0,1]
	v_pk_mul_f32 v[22:23], v[50:51], v[36:37] op_sel_hi:[0,1]
	s_waitcnt vmcnt(0)
	v_pk_fma_f32 v[16:17], v[16:17], v[20:21], v[24:25]
	v_pk_fma_f32 v[18:19], v[18:19], v[22:23], v[26:27] op_sel:[0,1,0] op_sel_hi:[1,0,1]
	global_store_dwordx4 v[6:7], v[16:19], off offset:2064
	v_lshl_add_u64 v[6:7], v[6:7], 0, s[4:5]
	s_cbranch_scc1 .LBB0_1447

; #define LAS __attribute__((address_space(3)))
; __global__ void __launch_bounds__(512, 2) nsa_gla_fwd(Args a) {
;     extern __shared__ __attribute__((aligned(16))) unsigned char lds_raw[];
;     LAS unsigned char* lds = (LAS unsigned char*)lds_raw;
;     cg::grid_group grid = cg::this_grid();
;     const Ctx cb = make_ctx(a);
;     volatile LAS unsigned* bst = (volatile LAS unsigned*)(lds + LDS_BYTES - 64);
;     if (threadIdx.x == 0) { bst[0] = 0u; bst[1] = 0u; }
;     __syncthreads();
;     const XcdBarrier xbar = xcd_barrier_post((unsigned*)(a.ws + O_BAR), bst);
;     run_phase<0>(cb, lds, 0);
;     xcd_barrier(xbar);
;     run_layer<0>(cb, lds, xbar, false);
;     run_layer<1>(cb, lds, xbar, true);
;     if (gridDim.x > 100000u) grid.sync();
; }
	.amdhsa_kernel _Z11nsa_gla_fwd4Args
		.amdhsa_group_segment_fixed_size 0
		.amdhsa_private_segment_fixed_size 0
		.amdhsa_kernarg_size 400
		.amdhsa_user_sgpr_count 2
		.amdhsa_user_sgpr_dispatch_ptr 0
		.amdhsa_user_sgpr_queue_ptr 0
		.amdhsa_user_sgpr_kernarg_segment_ptr 1
		.amdhsa_user_sgpr_dispatch_id 0
		.amdhsa_user_sgpr_kernarg_preload_length 0
		.amdhsa_user_sgpr_kernarg_preload_offset 0
		.amdhsa_user_sgpr_private_segment_size 0
		.amdhsa_uses_dynamic_stack 0
		.amdhsa_enable_private_segment 0
		.amdhsa_system_sgpr_workgroup_id_x 1
		.amdhsa_system_sgpr_workgroup_id_y 0
		.amdhsa_system_sgpr_workgroup_id_z 0
		.amdhsa_system_sgpr_workgroup_info 0
		.amdhsa_system_vgpr_workitem_id 2
		.amdhsa_next_free_vgpr 251
		.amdhsa_next_free_sgpr 102
		.amdhsa_accum_offset 252
		.amdhsa_reserve_vcc 1
		.amdhsa_float_round_mode_32 0
		.amdhsa_float_round_mode_16_64 0
		.amdhsa_float_denorm_mode_32 3
		.amdhsa_float_denorm_mode_16_64 3
		.amdhsa_dx10_clamp 1
		.amdhsa_ieee_mode 1
		.amdhsa_fp16_overflow 0
		.amdhsa_tg_split 0
		.amdhsa_exception_fp_ieee_invalid_op 0
		.amdhsa_exception_fp_denorm_src 0
		.amdhsa_exception_fp_ieee_div_zero 0
		.amdhsa_exception_fp_ieee_overflow 0
		.amdhsa_exception_fp_ieee_underflow 0
		.amdhsa_exception_fp_ieee_inexact 0
		.amdhsa_exception_int_div_zero 0
	.end_amdhsa_kernel

; #define LAS __attribute__((address_space(3)))
; __global__ void __launch_bounds__(512, 2) nsa_gla_fwd(Args a) {
;     extern __shared__ __attribute__((aligned(16))) unsigned char lds_raw[];
;     LAS unsigned char* lds = (LAS unsigned char*)lds_raw;
;     cg::grid_group grid = cg::this_grid();
;     const Ctx cb = make_ctx(a);
;     volatile LAS unsigned* bst = (volatile LAS unsigned*)(lds + LDS_BYTES - 64);
;     if (threadIdx.x == 0) { bst[0] = 0u; bst[1] = 0u; }
;     __syncthreads();
;     const XcdBarrier xbar = xcd_barrier_post((unsigned*)(a.ws + O_BAR), bst);
;     run_phase<0>(cb, lds, 0);
;     xcd_barrier(xbar);
;     run_layer<0>(cb, lds, xbar, false);
;     run_layer<1>(cb, lds, xbar, true);
;     if (gridDim.x > 100000u) grid.sync();
; }
amdhsa.kernels:
  - .agpr_count:     0
    .args:
      - .offset:         0
        .size:           144
        .value_kind:     by_value
      - .offset:         144
        .size:           4
        .value_kind:     hidden_block_count_x
      - .offset:         148
        .size:           4
        .value_kind:     hidden_block_count_y
      - .offset:         152
        .size:           4
        .value_kind:     hidden_block_count_z
      - .offset:         156
        .size:           2
        .value_kind:     hidden_group_size_x
      - .offset:         158
        .size:           2
        .value_kind:     hidden_group_size_y
      - .offset:         160
        .size:           2
        .value_kind:     hidden_group_size_z
      - .offset:         162
        .size:           2
        .value_kind:     hidden_remainder_x
      - .offset:         164
        .size:           2
        .value_kind:     hidden_remainder_y
      - .offset:         166
        .size:           2
        .value_kind:     hidden_remainder_z
      - .offset:         184
        .size:           8
        .value_kind:     hidden_global_offset_x
      - .offset:         192
        .size:           8
        .value_kind:     hidden_global_offset_y
      - .offset:         200
        .size:           8
        .value_kind:     hidden_global_offset_z
      - .offset:         208
        .size:           2
        .value_kind:     hidden_grid_dims
      - .offset:         232
        .size:           8
        .value_kind:     hidden_multigrid_sync_arg
      - .offset:         264
        .size:           4
        .value_kind:     hidden_dynamic_lds_size
    .group_segment_fixed_size: 0
    .kernarg_segment_align: 8
    .kernarg_segment_size: 400
    .language:       OpenCL C
    .language_version:
      - 2
      - 0
    .max_flat_workgroup_size: 512
    .name:           _Z11nsa_gla_fwd4Args
    .private_segment_fixed_size: 0
    .sgpr_count:     108
    .sgpr_spill_count: 91
    .symbol:         _Z11nsa_gla_fwd4Args.kd
    .uniform_work_group_size: 1
    .uses_dynamic_stack: false
    .vgpr_count:     251
    .vgpr_spill_count: 0
    .wavefront_size: 64
